# sub-key table stored in MFMA A-fragment order (16-byte units permuted inside each 32-key block): every part-a fragment load is one contiguous KiB instead of 32 strided 32-byte pieces
# speedup vs baseline: 1.0231x; 1.0146x over previous
; DI int my_tid() { int t = threadIdx.x & 255; asm volatile("" : "+v"(t)); return t; }
; DI void convert_chunk(const float* __restrict__ src, u16* __restrict__ dst, int item) {
;   const int tid = my_tid();
; #pragma unroll
;   for (int i = 0; i < 4; ++i) {
;     size_t idx = (size_t)item * 8192 + i * 2048 + tid * 8;
;     float4 a = *(const float4*)(src + idx);
;     float4 b = *(const float4*)(src + idx + 4);
;     uint4 o;
;     o.x = pack2(a.x, a.y); o.y = pack2(a.z, a.w); o.z = pack2(b.x, b.y); o.w = pack2(b.z, b.w);
;     *(uint4*)(dst + idx) = o;
;   }
; }
.Lp1a_354:
	s_cmpk_gt_i32 s20, 0x3ff
	s_mov_b64 s[12:13], -1
	s_cbranch_scc0 .Lp1a_468
	s_cmpk_gt_u32 s20, 0x7ff
	s_cbranch_scc0 .Lp1a_457
	s_cmpk_gt_u32 s20, 0x87f
	s_cbranch_scc0 .Lp1a_433
	s_cmpk_gt_u32 s20, 0x8ff
	s_cbranch_scc0 .Lp1a_409
	s_cmpk_gt_u32 s20, 0x9ff
	s_cbranch_scc0 .Lp1a_385
	s_cmpk_gt_u32 s20, 0xbff
	s_cbranch_scc0 .Lp1a_361
	v_mov_b32_e32 v0, v210
	s_lshl_b32 s12, s20, 13
	v_lshlrev_b32_e32 v8, 3, v0
	s_add_i32 s2, s12, 0xfe800000
	v_ashrrev_i32_e32 v9, 31, v8
	v_lshl_add_u64 v[10:11], v[8:9], 0, s[2:3]
	v_lshl_add_u64 v[4:5], v[10:11], 2, s[76:77]
	global_load_dwordx4 v[0:3], v[4:5], off
	s_nop 0
	global_load_dwordx4 v[4:7], v[4:5], off offset:16
	s_add_i32 s2, s12, 0xfe800800
	v_lshrrev_b32_e32 v10, 3, v10
	v_and_b32_e32 v14, 15, v10
	v_bfe_u32 v15, v10, 4, 5
	v_and_b32_e32 v10, 0xfffffe00, v10
	v_and_b32_e32 v11, 14, v14
	v_lshlrev_b32_e32 v11, 5, v11
	v_and_b32_e32 v14, 1, v14
	v_lshl_or_b32 v14, v15, 1, v14
	v_or3_b32 v10, v10, v11, v14
	v_lshlrev_b32_e32 v10, 4, v10
	v_mov_b32_e32 v11, 0
	v_lshl_add_u64 v[10:11], v[10:11], 0, s[6:7]
	v_lshl_add_u64 v[12:13], v[8:9], 0, s[2:3]
	v_lshl_add_u64 v[14:15], v[12:13], 2, s[76:77]
	s_add_i32 s2, s12, 0xfe801000
	s_waitcnt vmcnt(1)
	v_cvt_pk_bf16_f32 v0, v0, v1
	v_cvt_pk_bf16_f32 v1, v2, v3
	s_waitcnt vmcnt(0)
	v_cvt_pk_bf16_f32 v2, v4, v5
	v_cvt_pk_bf16_f32 v3, v6, v7
	global_store_dwordx4 v[10:11], v[0:3], off
	global_load_dwordx4 v[0:3], v[14:15], off
	s_nop 0
	global_load_dwordx4 v[4:7], v[14:15], off offset:16
	v_lshrrev_b32_e32 v10, 3, v12
	v_and_b32_e32 v14, 15, v10
	v_bfe_u32 v15, v10, 4, 5
	v_and_b32_e32 v10, 0xfffffe00, v10
	v_and_b32_e32 v11, 14, v14
	v_lshlrev_b32_e32 v11, 5, v11
	v_and_b32_e32 v14, 1, v14
	v_lshl_or_b32 v14, v15, 1, v14
	v_or3_b32 v10, v10, v11, v14
	v_lshlrev_b32_e32 v10, 4, v10
	v_mov_b32_e32 v11, 0
	v_lshl_add_u64 v[10:11], v[10:11], 0, s[6:7]
	v_lshl_add_u64 v[12:13], v[8:9], 0, s[2:3]
	v_lshl_add_u64 v[14:15], v[12:13], 2, s[76:77]
	s_add_i32 s2, s12, 0xfe801800
	v_lshl_add_u64 v[8:9], v[8:9], 0, s[2:3]
	s_mov_b64 s[12:13], 0
	s_waitcnt vmcnt(1)
	v_cvt_pk_bf16_f32 v0, v0, v1
	v_cvt_pk_bf16_f32 v1, v2, v3
	s_waitcnt vmcnt(0)
	v_cvt_pk_bf16_f32 v2, v4, v5
	v_cvt_pk_bf16_f32 v3, v6, v7
	global_store_dwordx4 v[10:11], v[0:3], off
	global_load_dwordx4 v[0:3], v[14:15], off
	s_nop 0
	global_load_dwordx4 v[4:7], v[14:15], off offset:16
	v_lshrrev_b32_e32 v10, 3, v12
	v_and_b32_e32 v14, 15, v10
	v_bfe_u32 v15, v10, 4, 5
	v_and_b32_e32 v10, 0xfffffe00, v10
	v_and_b32_e32 v11, 14, v14
	v_lshlrev_b32_e32 v11, 5, v11
	v_and_b32_e32 v14, 1, v14
	v_lshl_or_b32 v14, v15, 1, v14
	v_or3_b32 v10, v10, v11, v14
	v_lshlrev_b32_e32 v10, 4, v10
	v_mov_b32_e32 v11, 0
	v_lshl_add_u64 v[10:11], v[10:11], 0, s[6:7]
	v_lshl_add_u64 v[12:13], v[8:9], 2, s[76:77]
	v_lshrrev_b32_e32 v8, 3, v8
	v_and_b32_e32 v14, 15, v8
	v_bfe_u32 v15, v8, 4, 5
	v_and_b32_e32 v8, 0xfffffe00, v8
	v_and_b32_e32 v9, 14, v14
	v_lshlrev_b32_e32 v9, 5, v9
	v_and_b32_e32 v14, 1, v14
	v_lshl_or_b32 v14, v15, 1, v14
	v_or3_b32 v8, v8, v9, v14
	v_lshlrev_b32_e32 v8, 4, v8
	v_mov_b32_e32 v9, 0
	v_lshl_add_u64 v[8:9], v[8:9], 0, s[6:7]
	s_waitcnt vmcnt(1)
	v_cvt_pk_bf16_f32 v0, v0, v1
	v_cvt_pk_bf16_f32 v1, v2, v3
	s_waitcnt vmcnt(0)
	v_cvt_pk_bf16_f32 v2, v4, v5
	v_cvt_pk_bf16_f32 v3, v6, v7
	global_store_dwordx4 v[10:11], v[0:3], off
	global_load_dwordx4 v[0:3], v[12:13], off
	s_nop 0
	global_load_dwordx4 v[4:7], v[12:13], off offset:16
	s_waitcnt vmcnt(1)
	v_cvt_pk_bf16_f32 v0, v0, v1
	v_cvt_pk_bf16_f32 v1, v2, v3
	s_waitcnt vmcnt(0)
	v_cvt_pk_bf16_f32 v2, v4, v5
	v_cvt_pk_bf16_f32 v3, v6, v7
	global_store_dwordx4 v[8:9], v[0:3], off

; #define MFMA32(a, b, c) __builtin_amdgcn_mfma_f32_32x32x16_bf16((a), (b), (c), 0, 0, 0)
; DI int my_tid() { int t = threadIdx.x & 255; asm volatile("" : "+v"(t)); return t; }
; DI void hsync() { hsync_impl(false); }
; DI void peer_top16(const u16* __restrict__ PQrow, const u16* __restrict__ SK, unsigned (&top)[16], int lr, int hh) {
;   bf16x8 qf[8];
; #pragma unroll
;   for (int ks = 0; ks < 8; ++ks) qf[ks] = *(const bf16x8*)(PQrow + ks * 16 + hh * 8);
;   unsigned g[4][16];
; #pragma unroll
;   for (int kt = 0; kt < 4; ++kt) {
;     f32x16 acc;
; #pragma unroll
;     for (int e = 0; e < 16; ++e) acc[e] = 0.f;
; #pragma unroll
;     for (int ks = 0; ks < 8; ++ks) {
;       bf16x8 a = *(const bf16x8*)(SK + (size_t)(kt * 32 + lr) * 128 + ks * 16 + hh * 8);
;       acc = MFMA32(a, qf[ks], acc);
; template <bool STORE>
; DI void peer_item(const Params& p, int item, char* smem) {
;   char* ws = p.ws;
;   const u16* PQ = (const u16*)(ws + WS_MG);
;   const u16* SUBK = (const u16*)(ws + WS_SUBK);
;   const u16* XN2 = (const u16*)(ws + WS_Q);
;   int* e_s = (int*)smem;
;   float* g_s = (float*)(e_s + 32 * 128);
;   const int tid = my_tid(), lane = tid & 63, wave = tid >> 6;
;   const int lr = lane & 31, hh = lane >> 5;
;   const int tok0 = item * 32;
;   hsync();
;   for (int hq = 0; hq < 2; ++hq) {
;     const int hd = wave * 2 + hq;
;     unsigned top1[16], top2[16];
;     const u16* pqrow = PQ + (size_t)(tok0 + lr) * 2048 + hd * 256;
;     peer_top16(pqrow, SUBK + (size_t)(hd * 2 + 0) * 128 * 128, top1, lr, hh);
;     peer_top16(pqrow + 128, SUBK + (size_t)(hd * 2 + 1) * 128 * 128, top2, lr, hh);
.LBB0_1045:
	s_or_b64 exec, exec, s[0:1]
	v_writelane_b32 v254, s6, 0
	v_writelane_b32 v254, s7, 1
	v_writelane_b32 v254, s12, 2
	v_writelane_b32 v254, s13, 3
	v_writelane_b32 v254, s14, 4
	v_writelane_b32 v254, s15, 5
	v_writelane_b32 v254, s16, 6
	v_writelane_b32 v254, s17, 7
	v_writelane_b32 v254, s18, 8
	v_writelane_b32 v254, s19, 9
	v_writelane_b32 v254, s20, 10
	v_writelane_b32 v254, s21, 11
	v_writelane_b32 v254, s22, 12
	v_writelane_b32 v254, s23, 13
	v_writelane_b32 v254, s24, 14
	v_writelane_b32 v254, s25, 15
	v_writelane_b32 v254, s26, 16
	v_writelane_b32 v254, s27, 17
	v_writelane_b32 v254, s28, 18
	v_writelane_b32 v254, s29, 19
	v_writelane_b32 v254, s30, 20
	v_writelane_b32 v254, s31, 21
	v_writelane_b32 v254, s33, 22
	v_writelane_b32 v254, s34, 23
	v_writelane_b32 v254, s35, 24
	v_writelane_b32 v254, s36, 25
	v_writelane_b32 v254, s37, 26
	v_writelane_b32 v254, s38, 27
	v_writelane_b32 v254, s39, 28
	v_writelane_b32 v254, s40, 29
	v_writelane_b32 v254, s41, 30
	v_writelane_b32 v254, s42, 31
	v_writelane_b32 v254, s44, 32
	v_writelane_b32 v254, s45, 33
	v_writelane_b32 v254, s48, 34
	v_writelane_b32 v254, s49, 35
	v_writelane_b32 v254, s50, 36
	v_writelane_b32 v254, s51, 37
	v_writelane_b32 v254, s52, 38
	v_writelane_b32 v254, s53, 39
	v_writelane_b32 v254, s55, 40
	v_writelane_b32 v254, s60, 41
	v_writelane_b32 v254, s61, 42
	v_writelane_b32 v254, s62, 43
	v_writelane_b32 v254, s63, 44
	v_writelane_b32 v254, s66, 45
	v_writelane_b32 v254, s67, 46
	v_writelane_b32 v254, s68, 47
	v_writelane_b32 v254, s69, 48
	v_writelane_b32 v254, s74, 49
	v_writelane_b32 v254, s75, 50
	v_writelane_b32 v254, s76, 51
	v_writelane_b32 v254, s77, 52
	v_writelane_b32 v254, s78, 53
	v_writelane_b32 v254, s79, 54
	v_writelane_b32 v254, s88, 55
	s_mov_b32 s16, s33
	s_lshl_b32 s19, s6, 5
	v_readlane_b32 s56, v253, 48
	v_readlane_b32 s57, v253, 49
	v_readfirstlane_b32 s13, v211
	v_mbcnt_lo_u32_b32 v235, -1, 0
	v_mbcnt_hi_u32_b32 v235, -1, v235
	s_nop 3
	s_bfe_u32 s17, s13, 0x20006
	s_add_u32 s0, s56, 0x1180000
	s_addc_u32 s1, s57, 0
	s_add_u32 s2, s56, 0xac80200
	s_addc_u32 s3, s57, 0
	s_lshl_b32 s15, s19, 12
	s_add_u32 s2, s2, s15
	s_addc_u32 s3, s3, 0
	s_lshl_b32 s15, s17, 10
	s_add_u32 s2, s2, s15
	s_addc_u32 s3, s3, 0
	s_lshl_b32 s15, s17, 17
	s_add_u32 s0, s0, s15
	s_addc_u32 s1, s1, 0
	s_mul_i32 s18, s17, 7168
	s_add_u32 s18, s18, s16
	s_add_u32 s18, s18, 49152
	v_and_b32_e32 v236, 31, v235
	v_lshrrev_b32_e32 v237, 5, v235
	v_lshlrev_b32_e32 v243, 2, v235
	v_add_u32_e32 v240, s18, v243
	ds_write_b32 v240, v3 offset:512
	ds_write_b32 v240, v53 offset:768
	ds_write_b32 v240, v64 offset:1024
	ds_write_b32 v240, v65 offset:1280
	ds_write_b32 v240, v66 offset:1536
	ds_write_b32 v240, v67 offset:1792
	ds_write_b32 v240, v68 offset:2048
	ds_write_b32 v240, v69 offset:2304
	ds_write_b32 v240, v70 offset:2560
	ds_write_b32 v240, v71 offset:2816
	ds_write_b32 v240, v72 offset:3072
	ds_write_b32 v240, v73 offset:3328
	ds_write_b32 v240, v74 offset:3584
	ds_write_b32 v240, v75 offset:3840
	ds_write_b32 v240, v76 offset:4096
	ds_write_b32 v240, v77 offset:4352
	ds_write_b32 v240, v78 offset:4608
	ds_write_b32 v240, v79 offset:4864
	ds_write_b32 v240, v80 offset:5120
	ds_write_b32 v240, v81 offset:5376
	ds_write_b32 v240, v82 offset:5632
	ds_write_b32 v240, v83 offset:5888
	ds_write_b32 v240, v84 offset:6144
	ds_write_b32 v240, v96 offset:6400
	v_lshlrev_b32_e32 v244, 4, v237
	v_lshl_add_u32 v238, v236, 5, v244
	v_add_u32_e32 v208, 0x1000, v238
	v_lshl_add_u32 v239, v236, 12, v244
	s_lshl_b32 s15, s17, 11
	s_add_u32 s15, s15, s16
	s_add_u32 s15, s15, 32768
	v_lshl_add_u32 v241, v235, 5, s15
	s_lshl_b32 s15, s17, 7
	s_add_u32 s15, s15, s16
	v_lshl_add_u32 v242, v236, 9, s15
	v_lshl_add_u32 v242, v237, 6, v242
	s_waitcnt lgkmcnt(0)
	global_load_dwordx4 v[176:179], v239, s[2:3] offset:0
	global_load_dwordx4 v[180:183], v239, s[2:3] offset:32
	global_load_dwordx4 v[184:187], v239, s[2:3] offset:64
	global_load_dwordx4 v[188:191], v239, s[2:3] offset:96
	global_load_dwordx4 v[192:195], v239, s[2:3] offset:128
	global_load_dwordx4 v[196:199], v239, s[2:3] offset:160
	global_load_dwordx4 v[200:203], v239, s[2:3] offset:192
	global_load_dwordx4 v[204:207], v239, s[2:3] offset:224
	s_add_u32 s4, s0, 0
	s_addc_u32 s5, s1, 0
	global_load_dwordx4 v[144:147], v238, s[4:5] offset:0
	global_load_dwordx4 v[148:151], v238, s[4:5] offset:1024
	global_load_dwordx4 v[152:155], v238, s[4:5] offset:2048
	global_load_dwordx4 v[156:159], v238, s[4:5] offset:3072
	global_load_dwordx4 v[160:163], v208, s[4:5] offset:0
	global_load_dwordx4 v[164:167], v208, s[4:5] offset:1024
	global_load_dwordx4 v[168:171], v208, s[4:5] offset:2048
	global_load_dwordx4 v[172:175], v208, s[4:5] offset:3072
	v_lshlrev_b32_e32 v245, 2, v237
	v_sub_u32_e32 v213, 127, v245
	v_sub_u32_e32 v214, 126, v245
	v_sub_u32_e32 v215, 125, v245
	v_sub_u32_e32 v216, 124, v245
	v_sub_u32_e32 v217, 119, v245
	v_sub_u32_e32 v218, 118, v245
	v_sub_u32_e32 v219, 117, v245
	v_sub_u32_e32 v220, 116, v245
	v_sub_u32_e32 v221, 111, v245
	v_sub_u32_e32 v222, 110, v245
	v_sub_u32_e32 v223, 109, v245
	v_sub_u32_e32 v224, 108, v245
	v_sub_u32_e32 v225, 103, v245
	v_sub_u32_e32 v226, 102, v245
	v_sub_u32_e32 v227, 101, v245
	v_sub_u32_e32 v228, 100, v245
	s_waitcnt vmcnt(7)
	v_mfma_f32_32x32x16_bf16 v[128:143], v[144:147], v[176:179], 0
	s_waitcnt vmcnt(6)
	v_mfma_f32_32x32x16_bf16 v[128:143], v[148:151], v[180:183], v[128:143]
	s_waitcnt vmcnt(5)
	v_mfma_f32_32x32x16_bf16 v[128:143], v[152:155], v[184:187], v[128:143]
	s_waitcnt vmcnt(4)
	v_mfma_f32_32x32x16_bf16 v[128:143], v[156:159], v[188:191], v[128:143]
	s_waitcnt vmcnt(3)
; #define MFMA32(a, b, c) __builtin_amdgcn_mfma_f32_32x32x16_bf16((a), (b), (c), 0, 0, 0)
; DI int crow(int i, int hh) { return (i & 3) + 8 * (i >> 2) + 4 * hh; }
; template <int LOGN>
; DI void bitonic_sort_desc(unsigned (&a)[1 << LOGN]) {
;   constexpr int N = 1 << LOGN;
; #pragma unroll
;   for (int ks = 1; ks <= LOGN; ++ks)
; #pragma unroll
;     ...
; #pragma unroll
;       for (int i = 0; i < N; ++i) {
;         const int k = 1 << ks, j = 1 << js, l = i ^ j;
;         if (l > i) {
;           const bool desc = ((i & k) == 0) || (ks == LOGN);
;           const unsigned x = a[i], y = a[l];
;           const unsigned hi = max(x, y), lo = min(x, y);
;           a[i] = desc ? hi : lo;
;           a[l] = desc ? lo : hi;
;         }
;       }
; }
; DI void peer_top16(const u16* __restrict__ PQrow, const u16* __restrict__ SK, unsigned (&top)[16], int lr, int hh) {
;     ...
;     for (int ks = 0; ks < 8; ++ks) {
;       bf16x8 a = *(const bf16x8*)(SK + (size_t)(kt * 32 + lr) * 128 + ks * 16 + hh * 8);
;       acc = MFMA32(a, qf[ks], acc);
;     }
; #pragma unroll
;     for (int e = 0; e < 16; ++e) {
;       int kidx = kt * 32 + crow(e, hh);
;       g[kt][e] = (f2ord(acc[e]) & ~127u) | (unsigned)(127 - kidx);
;     }
;     bitonic_sort_desc<4>(g[kt]);
	v_mfma_f32_32x32x16_bf16 v[128:143], v[160:163], v[192:195], v[128:143]
	s_waitcnt vmcnt(2)
	v_mfma_f32_32x32x16_bf16 v[128:143], v[164:167], v[196:199], v[128:143]
	s_waitcnt vmcnt(1)
	v_mfma_f32_32x32x16_bf16 v[128:143], v[168:171], v[200:203], v[128:143]
	s_waitcnt vmcnt(0)
	v_mfma_f32_32x32x16_bf16 v[128:143], v[172:175], v[204:207], v[128:143]
	s_add_u32 s4, s0, 8192
	s_addc_u32 s5, s1, 0
	global_load_dwordx4 v[144:147], v238, s[4:5] offset:0
	global_load_dwordx4 v[148:151], v238, s[4:5] offset:1024
	global_load_dwordx4 v[152:155], v238, s[4:5] offset:2048
	global_load_dwordx4 v[156:159], v238, s[4:5] offset:3072
	global_load_dwordx4 v[160:163], v208, s[4:5] offset:0
	global_load_dwordx4 v[164:167], v208, s[4:5] offset:1024
	global_load_dwordx4 v[168:171], v208, s[4:5] offset:2048
	global_load_dwordx4 v[172:175], v208, s[4:5] offset:3072
	s_nop 7
	s_nop 3
	v_ashrrev_i32_e32 v230, 31, v128
	v_or_b32_e32 v230, 0x80000000, v230
	v_xor_b32_e32 v229, v230, v128
	v_and_b32_e32 v229, 0xffffff80, v229
	v_or_b32_e32 v117, v229, v213
	v_ashrrev_i32_e32 v230, 31, v129
	v_or_b32_e32 v230, 0x80000000, v230
	v_xor_b32_e32 v229, v230, v129
	v_and_b32_e32 v229, 0xffffff80, v229
	v_or_b32_e32 v116, v229, v214
	v_ashrrev_i32_e32 v230, 31, v130
	v_or_b32_e32 v230, 0x80000000, v230
	v_xor_b32_e32 v229, v230, v130
	v_and_b32_e32 v229, 0xffffff80, v229
	v_or_b32_e32 v115, v229, v215
	v_ashrrev_i32_e32 v230, 31, v131
	v_or_b32_e32 v230, 0x80000000, v230
	v_xor_b32_e32 v229, v230, v131
	v_and_b32_e32 v229, 0xffffff80, v229
	v_or_b32_e32 v114, v229, v216
	v_ashrrev_i32_e32 v230, 31, v132
	v_or_b32_e32 v230, 0x80000000, v230
	v_xor_b32_e32 v229, v230, v132
	v_and_b32_e32 v229, 0xffffff80, v229
	v_or_b32_e32 v113, v229, v217
	v_ashrrev_i32_e32 v230, 31, v133
	v_or_b32_e32 v230, 0x80000000, v230
	v_xor_b32_e32 v229, v230, v133
	v_and_b32_e32 v229, 0xffffff80, v229
	v_or_b32_e32 v112, v229, v218
	v_ashrrev_i32_e32 v230, 31, v134
	v_or_b32_e32 v230, 0x80000000, v230
	v_xor_b32_e32 v229, v230, v134
	v_and_b32_e32 v229, 0xffffff80, v229
	v_or_b32_e32 v111, v229, v219
	v_ashrrev_i32_e32 v230, 31, v135
	v_or_b32_e32 v230, 0x80000000, v230
	v_xor_b32_e32 v229, v230, v135
	v_and_b32_e32 v229, 0xffffff80, v229
	v_or_b32_e32 v110, v229, v220
	v_ashrrev_i32_e32 v230, 31, v136
	v_or_b32_e32 v230, 0x80000000, v230
	v_xor_b32_e32 v229, v230, v136
	v_and_b32_e32 v229, 0xffffff80, v229
	v_or_b32_e32 v109, v229, v221
	v_ashrrev_i32_e32 v230, 31, v137
	v_or_b32_e32 v230, 0x80000000, v230
	v_xor_b32_e32 v229, v230, v137
	v_and_b32_e32 v229, 0xffffff80, v229
	v_or_b32_e32 v108, v229, v222
	v_ashrrev_i32_e32 v230, 31, v138
	v_or_b32_e32 v230, 0x80000000, v230
	v_xor_b32_e32 v229, v230, v138
	v_and_b32_e32 v229, 0xffffff80, v229
	v_or_b32_e32 v107, v229, v223
	v_ashrrev_i32_e32 v230, 31, v139
	v_or_b32_e32 v230, 0x80000000, v230
	v_xor_b32_e32 v229, v230, v139
	v_and_b32_e32 v229, 0xffffff80, v229
	v_or_b32_e32 v106, v229, v224
	v_ashrrev_i32_e32 v230, 31, v140
	v_or_b32_e32 v230, 0x80000000, v230
	v_xor_b32_e32 v229, v230, v140
	v_and_b32_e32 v229, 0xffffff80, v229
	v_or_b32_e32 v105, v229, v225
	v_ashrrev_i32_e32 v230, 31, v141
	v_or_b32_e32 v230, 0x80000000, v230
	v_xor_b32_e32 v229, v230, v141
	v_and_b32_e32 v229, 0xffffff80, v229
	v_or_b32_e32 v104, v229, v226
	v_ashrrev_i32_e32 v230, 31, v142
	v_or_b32_e32 v230, 0x80000000, v230
	v_xor_b32_e32 v229, v230, v142
	v_and_b32_e32 v229, 0xffffff80, v229
	v_or_b32_e32 v103, v229, v227
	v_ashrrev_i32_e32 v230, 31, v143
	v_or_b32_e32 v230, 0x80000000, v230
	v_xor_b32_e32 v229, v230, v143
	v_and_b32_e32 v229, 0xffffff80, v229
	v_or_b32_e32 v102, v229, v228
	v_subrev_u32_e32 v213, 32, v213
	v_subrev_u32_e32 v214, 32, v214
	v_subrev_u32_e32 v215, 32, v215
	v_subrev_u32_e32 v216, 32, v216
	v_subrev_u32_e32 v217, 32, v217
	v_subrev_u32_e32 v218, 32, v218
	v_subrev_u32_e32 v219, 32, v219
	v_subrev_u32_e32 v220, 32, v220
	v_subrev_u32_e32 v221, 32, v221
	v_subrev_u32_e32 v222, 32, v222
	v_subrev_u32_e32 v223, 32, v223
	v_subrev_u32_e32 v224, 32, v224
	v_subrev_u32_e32 v225, 32, v225
	v_subrev_u32_e32 v226, 32, v226
	v_subrev_u32_e32 v227, 32, v227
	v_subrev_u32_e32 v228, 32, v228
	v_max_u32_e32 v101, v117, v116
	v_min_u32_e32 v116, v117, v116
	v_min_u32_e32 v117, v115, v114
	v_max_u32_e32 v114, v115, v114
	v_max_u32_e32 v115, v113, v112
	v_min_u32_e32 v112, v113, v112
	v_min_u32_e32 v113, v111, v110
	v_max_u32_e32 v110, v111, v110
	v_max_u32_e32 v111, v109, v108
	v_min_u32_e32 v108, v109, v108
	v_min_u32_e32 v109, v107, v106
	v_max_u32_e32 v106, v107, v106
	v_max_u32_e32 v107, v105, v104
	v_min_u32_e32 v104, v105, v104
	v_min_u32_e32 v105, v103, v102
	v_max_u32_e32 v102, v103, v102
	v_max_u32_e32 v103, v101, v117
	v_min_u32_e32 v117, v101, v117
	v_max_u32_e32 v101, v116, v114
	v_min_u32_e32 v114, v116, v114
	v_min_u32_e32 v116, v115, v113
	v_max_u32_e32 v113, v115, v113
	v_min_u32_e32 v115, v112, v110
	v_max_u32_e32 v110, v112, v110
	v_max_u32_e32 v112, v111, v109
	v_min_u32_e32 v109, v111, v109
	v_max_u32_e32 v111, v108, v106
	v_min_u32_e32 v106, v108, v106
	v_min_u32_e32 v108, v107, v105
	v_max_u32_e32 v105, v107, v105
	v_min_u32_e32 v107, v104, v102
	v_max_u32_e32 v102, v104, v102
	v_max_u32_e32 v104, v103, v101
	v_min_u32_e32 v101, v103, v101
	v_max_u32_e32 v103, v117, v114
	v_min_u32_e32 v114, v117, v114
	v_min_u32_e32 v117, v116, v115
	v_max_u32_e32 v115, v116, v115
	v_min_u32_e32 v116, v113, v110
	v_max_u32_e32 v110, v113, v110
	v_max_u32_e32 v113, v112, v111
	v_min_u32_e32 v111, v112, v111
	v_max_u32_e32 v112, v109, v106
	v_min_u32_e32 v106, v109, v106
	v_min_u32_e32 v109, v108, v107
	v_max_u32_e32 v107, v108, v107
; #define MFMA32(a, b, c) __builtin_amdgcn_mfma_f32_32x32x16_bf16((a), (b), (c), 0, 0, 0)
; template <int LOGN>
; DI void bitonic_sort_desc(unsigned (&a)[1 << LOGN]) {
;   constexpr int N = 1 << LOGN;
; #pragma unroll
;   for (int ks = 1; ks <= LOGN; ++ks)
; #pragma unroll
;     ...
; #pragma unroll
;       for (int i = 0; i < N; ++i) {
;         const int k = 1 << ks, j = 1 << js, l = i ^ j;
;         if (l > i) {
;           const bool desc = ((i & k) == 0) || (ks == LOGN);
;           const unsigned x = a[i], y = a[l];
;           const unsigned hi = max(x, y), lo = min(x, y);
;           a[i] = desc ? hi : lo;
;           a[l] = desc ? lo : hi;
;         }
;       }
; }
; DI void peer_top16(const u16* __restrict__ PQrow, const u16* __restrict__ SK, unsigned (&top)[16], int lr, int hh) {
;     ...
;     for (int ks = 0; ks < 8; ++ks) {
;       bf16x8 a = *(const bf16x8*)(SK + (size_t)(kt * 32 + lr) * 128 + ks * 16 + hh * 8);
;       acc = MFMA32(a, qf[ks], acc);
	v_min_u32_e32 v108, v105, v102
	v_max_u32_e32 v102, v105, v102
	v_max_u32_e32 v105, v104, v117
	v_min_u32_e32 v117, v104, v117
	v_max_u32_e32 v104, v101, v115
	v_min_u32_e32 v115, v101, v115
	v_max_u32_e32 v101, v103, v116
	v_min_u32_e32 v116, v103, v116
	v_max_u32_e32 v103, v114, v110
	v_min_u32_e32 v110, v114, v110
	v_min_u32_e32 v114, v113, v109
	v_max_u32_e32 v109, v113, v109
	v_min_u32_e32 v113, v111, v107
	v_max_u32_e32 v107, v111, v107
	v_min_u32_e32 v111, v112, v108
	v_max_u32_e32 v108, v112, v108
	v_min_u32_e32 v112, v106, v102
	v_max_u32_e32 v102, v106, v102
	v_max_u32_e32 v106, v105, v101
	v_min_u32_e32 v101, v105, v101
	v_max_u32_e32 v105, v104, v103
	v_min_u32_e32 v103, v104, v103
	v_max_u32_e32 v104, v117, v116
	v_min_u32_e32 v116, v117, v116
	v_max_u32_e32 v117, v115, v110
	v_min_u32_e32 v110, v115, v110
	v_min_u32_e32 v115, v114, v111
	v_max_u32_e32 v111, v114, v111
	v_min_u32_e32 v114, v113, v112
	v_max_u32_e32 v112, v113, v112
	v_min_u32_e32 v113, v109, v108
	v_max_u32_e32 v108, v109, v108
	v_min_u32_e32 v109, v107, v102
	v_max_u32_e32 v102, v107, v102
	v_max_u32_e32 v107, v106, v105
	v_min_u32_e32 v105, v106, v105
	v_max_u32_e32 v106, v101, v103
	v_min_u32_e32 v103, v101, v103
	v_max_u32_e32 v101, v104, v117
	v_min_u32_e32 v117, v104, v117
	v_max_u32_e32 v104, v116, v110
	v_min_u32_e32 v110, v116, v110
	v_min_u32_e32 v116, v115, v114
	v_max_u32_e32 v114, v115, v114
	v_min_u32_e32 v115, v111, v112
	v_max_u32_e32 v112, v111, v112
	v_min_u32_e32 v111, v113, v109
	v_max_u32_e32 v109, v113, v109
	v_min_u32_e32 v113, v108, v102
	v_max_u32_e32 v102, v108, v102
	v_max_u32_e32 v108, v107, v116
	v_min_u32_e32 v116, v107, v116
	v_max_u32_e32 v107, v105, v114
	v_min_u32_e32 v114, v105, v114
	v_max_u32_e32 v105, v106, v115
	v_min_u32_e32 v115, v106, v115
	v_max_u32_e32 v106, v103, v112
	v_min_u32_e32 v112, v103, v112
	v_max_u32_e32 v103, v101, v111
	v_min_u32_e32 v111, v101, v111
	v_max_u32_e32 v101, v117, v109
	v_min_u32_e32 v109, v117, v109
	v_max_u32_e32 v117, v104, v113
	v_min_u32_e32 v113, v104, v113
	v_max_u32_e32 v104, v110, v102
	v_min_u32_e32 v102, v110, v102
	v_max_u32_e32 v110, v108, v103
	v_min_u32_e32 v103, v108, v103
	v_max_u32_e32 v108, v107, v101
	v_min_u32_e32 v101, v107, v101
	v_max_u32_e32 v107, v105, v117
	v_min_u32_e32 v117, v105, v117
	v_max_u32_e32 v105, v106, v104
	v_min_u32_e32 v104, v106, v104
	v_max_u32_e32 v106, v116, v111
	v_min_u32_e32 v111, v116, v111
	v_max_u32_e32 v116, v114, v109
	v_min_u32_e32 v109, v114, v109
	v_max_u32_e32 v114, v115, v113
	v_min_u32_e32 v113, v115, v113
	v_max_u32_e32 v115, v112, v102
	v_min_u32_e32 v102, v112, v102
	v_max_u32_e32 v112, v110, v107
	v_min_u32_e32 v107, v110, v107
	v_max_u32_e32 v110, v108, v105
	v_min_u32_e32 v105, v108, v105
	v_max_u32_e32 v108, v103, v117
	v_min_u32_e32 v117, v103, v117
	v_max_u32_e32 v103, v101, v104
	v_min_u32_e32 v104, v101, v104
	v_max_u32_e32 v101, v106, v114
	v_min_u32_e32 v114, v106, v114
	v_max_u32_e32 v106, v116, v115
	v_min_u32_e32 v115, v116, v115
	v_max_u32_e32 v116, v111, v113
	v_min_u32_e32 v113, v111, v113
	v_max_u32_e32 v111, v109, v102
	v_min_u32_e32 v102, v109, v102
	v_max_u32_e32 v109, v112, v110
	v_min_u32_e32 v110, v112, v110
	v_max_u32_e32 v112, v107, v105
	v_min_u32_e32 v105, v107, v105
	v_max_u32_e32 v107, v108, v103
	v_min_u32_e32 v103, v108, v103
	v_max_u32_e32 v108, v117, v104
	v_min_u32_e32 v104, v117, v104
	v_max_u32_e32 v117, v101, v106
	v_min_u32_e32 v106, v101, v106
	v_max_u32_e32 v101, v114, v115
	v_min_u32_e32 v115, v114, v115
	v_max_u32_e32 v114, v116, v111
	v_min_u32_e32 v111, v116, v111
	v_max_u32_e32 v116, v113, v102
	v_min_u32_e32 v102, v113, v102
	s_waitcnt vmcnt(7)
	v_mfma_f32_32x32x16_bf16 v[128:143], v[144:147], v[176:179], 0
	s_waitcnt vmcnt(6)
	v_mfma_f32_32x32x16_bf16 v[128:143], v[148:151], v[180:183], v[128:143]
	s_waitcnt vmcnt(5)
	v_mfma_f32_32x32x16_bf16 v[128:143], v[152:155], v[184:187], v[128:143]
	s_waitcnt vmcnt(4)
	v_mfma_f32_32x32x16_bf16 v[128:143], v[156:159], v[188:191], v[128:143]
	s_waitcnt vmcnt(3)
	v_mfma_f32_32x32x16_bf16 v[128:143], v[160:163], v[192:195], v[128:143]
	s_waitcnt vmcnt(2)
	v_mfma_f32_32x32x16_bf16 v[128:143], v[164:167], v[196:199], v[128:143]
	s_waitcnt vmcnt(1)
	v_mfma_f32_32x32x16_bf16 v[128:143], v[168:171], v[200:203], v[128:143]
	s_waitcnt vmcnt(0)
; #define MFMA32(a, b, c) __builtin_amdgcn_mfma_f32_32x32x16_bf16((a), (b), (c), 0, 0, 0)
; DI int crow(int i, int hh) { return (i & 3) + 8 * (i >> 2) + 4 * hh; }
; template <int LOGN>
; DI void bitonic_sort_desc(unsigned (&a)[1 << LOGN]) {
;   constexpr int N = 1 << LOGN;
; #pragma unroll
;   for (int ks = 1; ks <= LOGN; ++ks)
; #pragma unroll
;     ...
; #pragma unroll
;       for (int i = 0; i < N; ++i) {
;         const int k = 1 << ks, j = 1 << js, l = i ^ j;
;         if (l > i) {
;           const bool desc = ((i & k) == 0) || (ks == LOGN);
;           const unsigned x = a[i], y = a[l];
;           const unsigned hi = max(x, y), lo = min(x, y);
;           a[i] = desc ? hi : lo;
;           a[l] = desc ? lo : hi;
;         }
;       }
; }
; DI void peer_top16(const u16* __restrict__ PQrow, const u16* __restrict__ SK, unsigned (&top)[16], int lr, int hh) {
;     ...
;     for (int ks = 0; ks < 8; ++ks) {
;       bf16x8 a = *(const bf16x8*)(SK + (size_t)(kt * 32 + lr) * 128 + ks * 16 + hh * 8);
;       acc = MFMA32(a, qf[ks], acc);
;     }
; #pragma unroll
;     for (int e = 0; e < 16; ++e) {
;       int kidx = kt * 32 + crow(e, hh);
;       g[kt][e] = (f2ord(acc[e]) & ~127u) | (unsigned)(127 - kidx);
;     }
;     bitonic_sort_desc<4>(g[kt]);
	v_mfma_f32_32x32x16_bf16 v[128:143], v[172:175], v[204:207], v[128:143]
	s_add_u32 s4, s0, 16384
	s_addc_u32 s5, s1, 0
	global_load_dwordx4 v[144:147], v238, s[4:5] offset:0
	global_load_dwordx4 v[148:151], v238, s[4:5] offset:1024
	global_load_dwordx4 v[152:155], v238, s[4:5] offset:2048
	global_load_dwordx4 v[156:159], v238, s[4:5] offset:3072
	global_load_dwordx4 v[160:163], v208, s[4:5] offset:0
	global_load_dwordx4 v[164:167], v208, s[4:5] offset:1024
	global_load_dwordx4 v[168:171], v208, s[4:5] offset:2048
	global_load_dwordx4 v[172:175], v208, s[4:5] offset:3072
	s_nop 7
	s_nop 3
	v_ashrrev_i32_e32 v230, 31, v128
	v_or_b32_e32 v230, 0x80000000, v230
	v_xor_b32_e32 v229, v230, v128
	v_and_b32_e32 v229, 0xffffff80, v229
	v_or_b32_e32 v113, v229, v213
	v_ashrrev_i32_e32 v230, 31, v129
	v_or_b32_e32 v230, 0x80000000, v230
	v_xor_b32_e32 v229, v230, v129
	v_and_b32_e32 v229, 0xffffff80, v229
	v_or_b32_e32 v100, v229, v214
	v_ashrrev_i32_e32 v230, 31, v130
	v_or_b32_e32 v230, 0x80000000, v230
	v_xor_b32_e32 v229, v230, v130
	v_and_b32_e32 v229, 0xffffff80, v229
	v_or_b32_e32 v99, v229, v215
	v_ashrrev_i32_e32 v230, 31, v131
	v_or_b32_e32 v230, 0x80000000, v230
	v_xor_b32_e32 v229, v230, v131
	v_and_b32_e32 v229, 0xffffff80, v229
	v_or_b32_e32 v98, v229, v216
	v_ashrrev_i32_e32 v230, 31, v132
	v_or_b32_e32 v230, 0x80000000, v230
	v_xor_b32_e32 v229, v230, v132
	v_and_b32_e32 v229, 0xffffff80, v229
	v_or_b32_e32 v97, v229, v217
	v_ashrrev_i32_e32 v230, 31, v133
	v_or_b32_e32 v230, 0x80000000, v230
	v_xor_b32_e32 v229, v230, v133
	v_and_b32_e32 v229, 0xffffff80, v229
	v_or_b32_e32 v96, v229, v218
	v_ashrrev_i32_e32 v230, 31, v134
	v_or_b32_e32 v230, 0x80000000, v230
	v_xor_b32_e32 v229, v230, v134
	v_and_b32_e32 v229, 0xffffff80, v229
	v_or_b32_e32 v95, v229, v219
	v_ashrrev_i32_e32 v230, 31, v135
	v_or_b32_e32 v230, 0x80000000, v230
	v_xor_b32_e32 v229, v230, v135
	v_and_b32_e32 v229, 0xffffff80, v229
	v_or_b32_e32 v94, v229, v220
	v_ashrrev_i32_e32 v230, 31, v136
	v_or_b32_e32 v230, 0x80000000, v230
	v_xor_b32_e32 v229, v230, v136
	v_and_b32_e32 v229, 0xffffff80, v229
	v_or_b32_e32 v93, v229, v221
	v_ashrrev_i32_e32 v230, 31, v137
	v_or_b32_e32 v230, 0x80000000, v230
	v_xor_b32_e32 v229, v230, v137
	v_and_b32_e32 v229, 0xffffff80, v229
	v_or_b32_e32 v92, v229, v222
	v_ashrrev_i32_e32 v230, 31, v138
	v_or_b32_e32 v230, 0x80000000, v230
	v_xor_b32_e32 v229, v230, v138
	v_and_b32_e32 v229, 0xffffff80, v229
	v_or_b32_e32 v91, v229, v223
	v_ashrrev_i32_e32 v230, 31, v139
	v_or_b32_e32 v230, 0x80000000, v230
	v_xor_b32_e32 v229, v230, v139
	v_and_b32_e32 v229, 0xffffff80, v229
	v_or_b32_e32 v90, v229, v224
	v_ashrrev_i32_e32 v230, 31, v140
	v_or_b32_e32 v230, 0x80000000, v230
	v_xor_b32_e32 v229, v230, v140
	v_and_b32_e32 v229, 0xffffff80, v229
	v_or_b32_e32 v89, v229, v225
	v_ashrrev_i32_e32 v230, 31, v141
	v_or_b32_e32 v230, 0x80000000, v230
	v_xor_b32_e32 v229, v230, v141
	v_and_b32_e32 v229, 0xffffff80, v229
	v_or_b32_e32 v88, v229, v226
	v_ashrrev_i32_e32 v230, 31, v142
	v_or_b32_e32 v230, 0x80000000, v230
	v_xor_b32_e32 v229, v230, v142
	v_and_b32_e32 v229, 0xffffff80, v229
	v_or_b32_e32 v87, v229, v227
	v_ashrrev_i32_e32 v230, 31, v143
	v_or_b32_e32 v230, 0x80000000, v230
	v_xor_b32_e32 v229, v230, v143
	v_and_b32_e32 v229, 0xffffff80, v229
	v_or_b32_e32 v86, v229, v228
	v_subrev_u32_e32 v213, 32, v213
	v_subrev_u32_e32 v214, 32, v214
	v_subrev_u32_e32 v215, 32, v215
	v_subrev_u32_e32 v216, 32, v216
	v_subrev_u32_e32 v217, 32, v217
	v_subrev_u32_e32 v218, 32, v218
	v_subrev_u32_e32 v219, 32, v219
	v_subrev_u32_e32 v220, 32, v220
	v_subrev_u32_e32 v221, 32, v221
	v_subrev_u32_e32 v222, 32, v222
	v_subrev_u32_e32 v223, 32, v223
	v_subrev_u32_e32 v224, 32, v224
	v_subrev_u32_e32 v225, 32, v225
	v_subrev_u32_e32 v226, 32, v226
	v_subrev_u32_e32 v227, 32, v227
	v_subrev_u32_e32 v228, 32, v228
	v_max_u32_e32 v85, v113, v100
	v_min_u32_e32 v100, v113, v100
	v_min_u32_e32 v113, v99, v98
	v_max_u32_e32 v98, v99, v98
	v_max_u32_e32 v99, v97, v96
	v_min_u32_e32 v96, v97, v96
	v_min_u32_e32 v97, v95, v94
	v_max_u32_e32 v94, v95, v94
	v_max_u32_e32 v95, v93, v92
	v_min_u32_e32 v92, v93, v92
	v_min_u32_e32 v93, v91, v90
	v_max_u32_e32 v90, v91, v90
	v_max_u32_e32 v91, v89, v88
	v_min_u32_e32 v88, v89, v88
	v_min_u32_e32 v89, v87, v86
	v_max_u32_e32 v86, v87, v86
	v_max_u32_e32 v87, v85, v113
	v_min_u32_e32 v113, v85, v113
	v_max_u32_e32 v85, v100, v98
	v_min_u32_e32 v98, v100, v98
	v_min_u32_e32 v100, v99, v97
	v_max_u32_e32 v97, v99, v97
	v_min_u32_e32 v99, v96, v94
	v_max_u32_e32 v94, v96, v94
	v_max_u32_e32 v96, v95, v93
	v_min_u32_e32 v93, v95, v93
	v_max_u32_e32 v95, v92, v90
	v_min_u32_e32 v90, v92, v90
	v_min_u32_e32 v92, v91, v89
	v_max_u32_e32 v89, v91, v89
	v_min_u32_e32 v91, v88, v86
	v_max_u32_e32 v86, v88, v86
	v_max_u32_e32 v88, v87, v85
	v_min_u32_e32 v85, v87, v85
	v_max_u32_e32 v87, v113, v98
	v_min_u32_e32 v98, v113, v98
	v_min_u32_e32 v113, v100, v99
	v_max_u32_e32 v99, v100, v99
	v_min_u32_e32 v100, v97, v94
	v_max_u32_e32 v94, v97, v94
	v_max_u32_e32 v97, v96, v95
	v_min_u32_e32 v95, v96, v95
	v_max_u32_e32 v96, v93, v90
	v_min_u32_e32 v90, v93, v90
	v_min_u32_e32 v93, v92, v91
	v_max_u32_e32 v91, v92, v91
	v_min_u32_e32 v92, v89, v86
	v_max_u32_e32 v86, v89, v86
	v_max_u32_e32 v89, v88, v113
	v_min_u32_e32 v113, v88, v113
	v_max_u32_e32 v88, v85, v99
	v_min_u32_e32 v99, v85, v99
	v_max_u32_e32 v85, v87, v100
	v_min_u32_e32 v100, v87, v100
	v_max_u32_e32 v87, v98, v94
	v_min_u32_e32 v94, v98, v94
	v_min_u32_e32 v98, v97, v93
	v_max_u32_e32 v93, v97, v93
	v_min_u32_e32 v97, v95, v91
	v_max_u32_e32 v91, v95, v91
; template <int LOGN>
; DI void bitonic_sort_desc(unsigned (&a)[1 << LOGN]) {
;   constexpr int N = 1 << LOGN;
; #pragma unroll
;   for (int ks = 1; ks <= LOGN; ++ks)
; #pragma unroll
;     ...
; #pragma unroll
;       for (int i = 0; i < N; ++i) {
;         const int k = 1 << ks, j = 1 << js, l = i ^ j;
;         if (l > i) {
;           const bool desc = ((i & k) == 0) || (ks == LOGN);
;           const unsigned x = a[i], y = a[l];
;           const unsigned hi = max(x, y), lo = min(x, y);
;           a[i] = desc ? hi : lo;
;           a[l] = desc ? lo : hi;
;         }
;       }
; }
; DI void merge_top16(unsigned (&a)[16], const unsigned (&b)[16]) {
; #pragma unroll
;   for (int i = 0; i < 16; ++i) a[i] = max(a[i], b[15 - i]);
; #pragma unroll
;     ...
; #pragma unroll
;     for (int i = 0; i < 16; ++i) {
;       const int j = 1 << js, l = i ^ j;
;       if (l > i) {
;         const unsigned x = a[i], y = a[l];
;         a[i] = max(x, y);
;         a[l] = min(x, y);
;       }
;     }
; }
	v_min_u32_e32 v95, v96, v92
	v_max_u32_e32 v92, v96, v92
	v_min_u32_e32 v96, v90, v86
	v_max_u32_e32 v86, v90, v86
	v_max_u32_e32 v90, v89, v85
	v_min_u32_e32 v85, v89, v85
	v_max_u32_e32 v89, v88, v87
	v_min_u32_e32 v87, v88, v87
	v_max_u32_e32 v88, v113, v100
	v_min_u32_e32 v100, v113, v100
	v_max_u32_e32 v113, v99, v94
	v_min_u32_e32 v94, v99, v94
	v_min_u32_e32 v99, v98, v95
	v_max_u32_e32 v95, v98, v95
	v_min_u32_e32 v98, v97, v96
	v_max_u32_e32 v96, v97, v96
	v_min_u32_e32 v97, v93, v92
	v_max_u32_e32 v92, v93, v92
	v_min_u32_e32 v93, v91, v86
	v_max_u32_e32 v86, v91, v86
	v_max_u32_e32 v91, v90, v89
	v_min_u32_e32 v89, v90, v89
	v_max_u32_e32 v90, v85, v87
	v_min_u32_e32 v87, v85, v87
	v_max_u32_e32 v85, v88, v113
	v_min_u32_e32 v113, v88, v113
	v_max_u32_e32 v88, v100, v94
	v_min_u32_e32 v94, v100, v94
	v_min_u32_e32 v100, v99, v98
	v_max_u32_e32 v98, v99, v98
	v_min_u32_e32 v99, v95, v96
	v_max_u32_e32 v96, v95, v96
	v_min_u32_e32 v95, v97, v93
	v_max_u32_e32 v93, v97, v93
	v_min_u32_e32 v97, v92, v86
	v_max_u32_e32 v86, v92, v86
	v_max_u32_e32 v92, v91, v100
	v_min_u32_e32 v100, v91, v100
	v_max_u32_e32 v91, v89, v98
	v_min_u32_e32 v98, v89, v98
	v_max_u32_e32 v89, v90, v99
	v_min_u32_e32 v99, v90, v99
	v_max_u32_e32 v90, v87, v96
	v_min_u32_e32 v96, v87, v96
	v_max_u32_e32 v87, v85, v95
	v_min_u32_e32 v95, v85, v95
	v_max_u32_e32 v85, v113, v93
	v_min_u32_e32 v93, v113, v93
	v_max_u32_e32 v113, v88, v97
	v_min_u32_e32 v97, v88, v97
	v_max_u32_e32 v88, v94, v86
	v_min_u32_e32 v86, v94, v86
	v_max_u32_e32 v94, v92, v87
	v_min_u32_e32 v87, v92, v87
	v_max_u32_e32 v92, v91, v85
	v_min_u32_e32 v85, v91, v85
	v_max_u32_e32 v91, v89, v113
	v_min_u32_e32 v113, v89, v113
	v_max_u32_e32 v89, v90, v88
	v_min_u32_e32 v88, v90, v88
	v_max_u32_e32 v90, v100, v95
	v_min_u32_e32 v95, v100, v95
	v_max_u32_e32 v100, v98, v93
	v_min_u32_e32 v93, v98, v93
	v_max_u32_e32 v98, v99, v97
	v_min_u32_e32 v97, v99, v97
	v_max_u32_e32 v99, v96, v86
	v_min_u32_e32 v86, v96, v86
	v_max_u32_e32 v96, v94, v91
	v_min_u32_e32 v91, v94, v91
	v_max_u32_e32 v94, v92, v89
	v_min_u32_e32 v89, v92, v89
	v_max_u32_e32 v92, v87, v113
	v_min_u32_e32 v113, v87, v113
	v_max_u32_e32 v87, v85, v88
	v_min_u32_e32 v88, v85, v88
	v_max_u32_e32 v85, v90, v98
	v_min_u32_e32 v98, v90, v98
	v_max_u32_e32 v90, v100, v99
	v_min_u32_e32 v99, v100, v99
	v_max_u32_e32 v100, v95, v97
	v_min_u32_e32 v97, v95, v97
	v_max_u32_e32 v95, v93, v86
	v_min_u32_e32 v86, v93, v86
	v_max_u32_e32 v93, v96, v94
	v_min_u32_e32 v94, v96, v94
	v_max_u32_e32 v96, v91, v89
	v_min_u32_e32 v89, v91, v89
	v_max_u32_e32 v91, v92, v87
	v_min_u32_e32 v87, v92, v87
	v_max_u32_e32 v92, v113, v88
	v_min_u32_e32 v88, v113, v88
	v_max_u32_e32 v113, v85, v90
	v_min_u32_e32 v90, v85, v90
	v_max_u32_e32 v85, v98, v99
	v_min_u32_e32 v99, v98, v99
	v_max_u32_e32 v98, v100, v95
	v_min_u32_e32 v95, v100, v95
	v_max_u32_e32 v100, v97, v86
	v_min_u32_e32 v86, v97, v86
	v_max_u32_e32 v97, v109, v86
	v_max_u32_e32 v109, v110, v100
	v_max_u32_e32 v110, v112, v95
	v_max_u32_e32 v112, v105, v98
	v_max_u32_e32 v105, v107, v99
	v_max_u32_e32 v107, v103, v85
	v_max_u32_e32 v103, v108, v90
	v_max_u32_e32 v108, v104, v113
	v_max_u32_e32 v104, v117, v88
	v_max_u32_e32 v117, v106, v92
	v_max_u32_e32 v106, v101, v87
	v_max_u32_e32 v101, v115, v91
	v_max_u32_e32 v115, v114, v89
	v_max_u32_e32 v114, v111, v96
	v_max_u32_e32 v111, v116, v94
	v_max_u32_e32 v116, v102, v93
	v_max_u32_e32 v86, v97, v104
	v_min_u32_e32 v104, v97, v104
	v_max_u32_e32 v97, v109, v117
	v_min_u32_e32 v117, v109, v117
	v_max_u32_e32 v109, v110, v106
	v_min_u32_e32 v106, v110, v106
	v_max_u32_e32 v110, v112, v101
	v_min_u32_e32 v101, v112, v101
	v_max_u32_e32 v112, v105, v115
	v_min_u32_e32 v115, v105, v115
	v_max_u32_e32 v105, v107, v114
	v_min_u32_e32 v114, v107, v114
	v_max_u32_e32 v107, v103, v111
	v_min_u32_e32 v111, v103, v111
	v_max_u32_e32 v103, v108, v116
	v_min_u32_e32 v116, v108, v116
	v_max_u32_e32 v108, v86, v112
	v_min_u32_e32 v112, v86, v112
	v_max_u32_e32 v86, v97, v105
	v_min_u32_e32 v105, v97, v105
	v_max_u32_e32 v97, v109, v107
	v_min_u32_e32 v107, v109, v107
	v_max_u32_e32 v109, v110, v103
	v_min_u32_e32 v103, v110, v103
	v_max_u32_e32 v110, v104, v115
	v_min_u32_e32 v115, v104, v115
	v_max_u32_e32 v104, v117, v114
	v_min_u32_e32 v114, v117, v114
	v_max_u32_e32 v117, v106, v111
	v_min_u32_e32 v111, v106, v111
	v_max_u32_e32 v106, v101, v116
	v_min_u32_e32 v116, v101, v116
	v_max_u32_e32 v101, v108, v97
	v_min_u32_e32 v97, v108, v97
	v_max_u32_e32 v108, v86, v109
	v_min_u32_e32 v109, v86, v109
	v_max_u32_e32 v86, v112, v107
	v_min_u32_e32 v107, v112, v107
	v_max_u32_e32 v112, v105, v103
	v_min_u32_e32 v103, v105, v103
	v_max_u32_e32 v105, v110, v117
	v_min_u32_e32 v117, v110, v117
	v_max_u32_e32 v110, v104, v106
	v_min_u32_e32 v106, v104, v106
	v_max_u32_e32 v104, v115, v111
	v_min_u32_e32 v111, v115, v111
	v_max_u32_e32 v115, v114, v116
	v_min_u32_e32 v116, v114, v116
	v_max_u32_e32 v114, v101, v108
	v_min_u32_e32 v108, v101, v108
	v_max_u32_e32 v101, v97, v109
	v_min_u32_e32 v109, v97, v109
	v_max_u32_e32 v97, v86, v112
	v_min_u32_e32 v112, v86, v112
	v_max_u32_e32 v86, v107, v103
	v_min_u32_e32 v103, v107, v103
	v_max_u32_e32 v107, v105, v110
	v_min_u32_e32 v110, v105, v110
	v_max_u32_e32 v105, v117, v106
	v_min_u32_e32 v106, v117, v106
	v_max_u32_e32 v117, v104, v115
	v_min_u32_e32 v115, v104, v115
	v_max_u32_e32 v104, v111, v116
	v_min_u32_e32 v116, v111, v116
	s_waitcnt vmcnt(7)
	v_mfma_f32_32x32x16_bf16 v[128:143], v[144:147], v[176:179], 0
	s_waitcnt vmcnt(6)
	v_mfma_f32_32x32x16_bf16 v[128:143], v[148:151], v[180:183], v[128:143]
	s_waitcnt vmcnt(5)
; #define MFMA32(a, b, c) __builtin_amdgcn_mfma_f32_32x32x16_bf16((a), (b), (c), 0, 0, 0)
; DI int crow(int i, int hh) { return (i & 3) + 8 * (i >> 2) + 4 * hh; }
; template <int LOGN>
; DI void bitonic_sort_desc(unsigned (&a)[1 << LOGN]) {
;   constexpr int N = 1 << LOGN;
; #pragma unroll
;   for (int ks = 1; ks <= LOGN; ++ks)
; #pragma unroll
;     ...
; #pragma unroll
;       for (int i = 0; i < N; ++i) {
;         const int k = 1 << ks, j = 1 << js, l = i ^ j;
;         if (l > i) {
;           const bool desc = ((i & k) == 0) || (ks == LOGN);
;           const unsigned x = a[i], y = a[l];
;           const unsigned hi = max(x, y), lo = min(x, y);
;           a[i] = desc ? hi : lo;
;           a[l] = desc ? lo : hi;
;         }
;       }
; }
; DI void peer_top16(const u16* __restrict__ PQrow, const u16* __restrict__ SK, unsigned (&top)[16], int lr, int hh) {
;     ...
;     for (int ks = 0; ks < 8; ++ks) {
;       bf16x8 a = *(const bf16x8*)(SK + (size_t)(kt * 32 + lr) * 128 + ks * 16 + hh * 8);
;       acc = MFMA32(a, qf[ks], acc);
;     }
; #pragma unroll
;     for (int e = 0; e < 16; ++e) {
;       int kidx = kt * 32 + crow(e, hh);
;       g[kt][e] = (f2ord(acc[e]) & ~127u) | (unsigned)(127 - kidx);
;     }
;     bitonic_sort_desc<4>(g[kt]);
	v_mfma_f32_32x32x16_bf16 v[128:143], v[152:155], v[184:187], v[128:143]
	s_waitcnt vmcnt(4)
	v_mfma_f32_32x32x16_bf16 v[128:143], v[156:159], v[188:191], v[128:143]
	s_waitcnt vmcnt(3)
	v_mfma_f32_32x32x16_bf16 v[128:143], v[160:163], v[192:195], v[128:143]
	s_waitcnt vmcnt(2)
	v_mfma_f32_32x32x16_bf16 v[128:143], v[164:167], v[196:199], v[128:143]
	s_waitcnt vmcnt(1)
	v_mfma_f32_32x32x16_bf16 v[128:143], v[168:171], v[200:203], v[128:143]
	s_waitcnt vmcnt(0)
	v_mfma_f32_32x32x16_bf16 v[128:143], v[172:175], v[204:207], v[128:143]
	s_add_u32 s4, s0, 24576
	s_addc_u32 s5, s1, 0
	global_load_dwordx4 v[144:147], v238, s[4:5] offset:0
	global_load_dwordx4 v[148:151], v238, s[4:5] offset:1024
	global_load_dwordx4 v[152:155], v238, s[4:5] offset:2048
	global_load_dwordx4 v[156:159], v238, s[4:5] offset:3072
	global_load_dwordx4 v[160:163], v208, s[4:5] offset:0
	global_load_dwordx4 v[164:167], v208, s[4:5] offset:1024
	global_load_dwordx4 v[168:171], v208, s[4:5] offset:2048
	global_load_dwordx4 v[172:175], v208, s[4:5] offset:3072
	s_nop 7
	s_nop 3
	v_ashrrev_i32_e32 v230, 31, v128
	v_or_b32_e32 v230, 0x80000000, v230
	v_xor_b32_e32 v229, v230, v128
	v_and_b32_e32 v229, 0xffffff80, v229
	v_or_b32_e32 v111, v229, v213
	v_ashrrev_i32_e32 v230, 31, v129
	v_or_b32_e32 v230, 0x80000000, v230
	v_xor_b32_e32 v229, v230, v129
	v_and_b32_e32 v229, 0xffffff80, v229
	v_or_b32_e32 v100, v229, v214
	v_ashrrev_i32_e32 v230, 31, v130
	v_or_b32_e32 v230, 0x80000000, v230
	v_xor_b32_e32 v229, v230, v130
	v_and_b32_e32 v229, 0xffffff80, v229
	v_or_b32_e32 v95, v229, v215
	v_ashrrev_i32_e32 v230, 31, v131
	v_or_b32_e32 v230, 0x80000000, v230
	v_xor_b32_e32 v229, v230, v131
	v_and_b32_e32 v229, 0xffffff80, v229
	v_or_b32_e32 v98, v229, v216
	v_ashrrev_i32_e32 v230, 31, v132
	v_or_b32_e32 v230, 0x80000000, v230
	v_xor_b32_e32 v229, v230, v132
	v_and_b32_e32 v229, 0xffffff80, v229
	v_or_b32_e32 v99, v229, v217
	v_ashrrev_i32_e32 v230, 31, v133
	v_or_b32_e32 v230, 0x80000000, v230
	v_xor_b32_e32 v229, v230, v133
	v_and_b32_e32 v229, 0xffffff80, v229
	v_or_b32_e32 v85, v229, v218
	v_ashrrev_i32_e32 v230, 31, v134
	v_or_b32_e32 v230, 0x80000000, v230
	v_xor_b32_e32 v229, v230, v134
	v_and_b32_e32 v229, 0xffffff80, v229
	v_or_b32_e32 v90, v229, v219
	v_ashrrev_i32_e32 v230, 31, v135
	v_or_b32_e32 v230, 0x80000000, v230
	v_xor_b32_e32 v229, v230, v135
	v_and_b32_e32 v229, 0xffffff80, v229
	v_or_b32_e32 v113, v229, v220
	v_ashrrev_i32_e32 v230, 31, v136
	v_or_b32_e32 v230, 0x80000000, v230
	v_xor_b32_e32 v229, v230, v136
	v_and_b32_e32 v229, 0xffffff80, v229
	v_or_b32_e32 v88, v229, v221
	v_ashrrev_i32_e32 v230, 31, v137
	v_or_b32_e32 v230, 0x80000000, v230
	v_xor_b32_e32 v229, v230, v137
	v_and_b32_e32 v229, 0xffffff80, v229
	v_or_b32_e32 v92, v229, v222
	v_ashrrev_i32_e32 v230, 31, v138
	v_or_b32_e32 v230, 0x80000000, v230
	v_xor_b32_e32 v229, v230, v138
	v_and_b32_e32 v229, 0xffffff80, v229
	v_or_b32_e32 v87, v229, v223
	v_ashrrev_i32_e32 v230, 31, v139
	v_or_b32_e32 v230, 0x80000000, v230
	v_xor_b32_e32 v229, v230, v139
	v_and_b32_e32 v229, 0xffffff80, v229
	v_or_b32_e32 v91, v229, v224
	v_ashrrev_i32_e32 v230, 31, v140
	v_or_b32_e32 v230, 0x80000000, v230
	v_xor_b32_e32 v229, v230, v140
	v_and_b32_e32 v229, 0xffffff80, v229
	v_or_b32_e32 v89, v229, v225
	v_ashrrev_i32_e32 v230, 31, v141
	v_or_b32_e32 v230, 0x80000000, v230
	v_xor_b32_e32 v229, v230, v141
	v_and_b32_e32 v229, 0xffffff80, v229
	v_or_b32_e32 v96, v229, v226
	v_ashrrev_i32_e32 v230, 31, v142
	v_or_b32_e32 v230, 0x80000000, v230
	v_xor_b32_e32 v229, v230, v142
	v_and_b32_e32 v229, 0xffffff80, v229
	v_or_b32_e32 v94, v229, v227
	v_ashrrev_i32_e32 v230, 31, v143
	v_or_b32_e32 v230, 0x80000000, v230
	v_xor_b32_e32 v229, v230, v143
	v_and_b32_e32 v229, 0xffffff80, v229
	v_or_b32_e32 v93, v229, v228
	v_subrev_u32_e32 v213, 32, v213
	v_subrev_u32_e32 v214, 32, v214
	v_subrev_u32_e32 v215, 32, v215
	v_subrev_u32_e32 v216, 32, v216
	v_subrev_u32_e32 v217, 32, v217
	v_subrev_u32_e32 v218, 32, v218
	v_subrev_u32_e32 v219, 32, v219
	v_subrev_u32_e32 v220, 32, v220
	v_subrev_u32_e32 v221, 32, v221
	v_subrev_u32_e32 v222, 32, v222
	v_subrev_u32_e32 v223, 32, v223
	v_subrev_u32_e32 v224, 32, v224
	v_subrev_u32_e32 v225, 32, v225
	v_subrev_u32_e32 v226, 32, v226
	v_subrev_u32_e32 v227, 32, v227
	v_subrev_u32_e32 v228, 32, v228
	v_max_u32_e32 v102, v111, v100
	v_min_u32_e32 v100, v111, v100
	v_min_u32_e32 v111, v95, v98
	v_max_u32_e32 v98, v95, v98
	v_max_u32_e32 v95, v99, v85
	v_min_u32_e32 v85, v99, v85
	v_min_u32_e32 v99, v90, v113
	v_max_u32_e32 v113, v90, v113
	v_max_u32_e32 v90, v88, v92
	v_min_u32_e32 v92, v88, v92
	v_min_u32_e32 v88, v87, v91
	v_max_u32_e32 v91, v87, v91
	v_max_u32_e32 v87, v89, v96
	v_min_u32_e32 v96, v89, v96
	v_min_u32_e32 v89, v94, v93
	v_max_u32_e32 v93, v94, v93
	v_max_u32_e32 v94, v102, v111
	v_min_u32_e32 v111, v102, v111
	v_max_u32_e32 v102, v100, v98
	v_min_u32_e32 v98, v100, v98
	v_min_u32_e32 v100, v95, v99
	v_max_u32_e32 v99, v95, v99
	v_min_u32_e32 v95, v85, v113
	v_max_u32_e32 v113, v85, v113
	v_max_u32_e32 v85, v90, v88
	v_min_u32_e32 v88, v90, v88
	v_max_u32_e32 v90, v92, v91
	v_min_u32_e32 v91, v92, v91
	v_min_u32_e32 v92, v87, v89
	v_max_u32_e32 v89, v87, v89
	v_min_u32_e32 v87, v96, v93
	v_max_u32_e32 v93, v96, v93
	v_max_u32_e32 v96, v94, v102
	v_min_u32_e32 v102, v94, v102
	v_max_u32_e32 v94, v111, v98
	v_min_u32_e32 v98, v111, v98
	v_min_u32_e32 v111, v100, v95
	v_max_u32_e32 v95, v100, v95
	v_min_u32_e32 v100, v99, v113
	v_max_u32_e32 v113, v99, v113
	v_max_u32_e32 v99, v85, v90
	v_min_u32_e32 v90, v85, v90
	v_max_u32_e32 v85, v88, v91
	v_min_u32_e32 v91, v88, v91
; #define MFMA32(a, b, c) __builtin_amdgcn_mfma_f32_32x32x16_bf16((a), (b), (c), 0, 0, 0)
; DI int crow(int i, int hh) { return (i & 3) + 8 * (i >> 2) + 4 * hh; }
; template <int LOGN>
; DI void bitonic_sort_desc(unsigned (&a)[1 << LOGN]) {
;   constexpr int N = 1 << LOGN;
; #pragma unroll
;   for (int ks = 1; ks <= LOGN; ++ks)
; #pragma unroll
;     ...
; #pragma unroll
;       for (int i = 0; i < N; ++i) {
;         const int k = 1 << ks, j = 1 << js, l = i ^ j;
;         if (l > i) {
;           const bool desc = ((i & k) == 0) || (ks == LOGN);
;           const unsigned x = a[i], y = a[l];
;           const unsigned hi = max(x, y), lo = min(x, y);
;           a[i] = desc ? hi : lo;
;           a[l] = desc ? lo : hi;
;         }
;       }
; }
; DI void peer_top16(const u16* __restrict__ PQrow, const u16* __restrict__ SK, unsigned (&top)[16], int lr, int hh) {
;     ...
;   for (int ks = 0; ks < 8; ++ks) qf[ks] = *(const bf16x8*)(PQrow + ks * 16 + hh * 8);
;   unsigned g[4][16];
; #pragma unroll
;   for (int kt = 0; kt < 4; ++kt) {
;     f32x16 acc;
; #pragma unroll
;     for (int e = 0; e < 16; ++e) acc[e] = 0.f;
; #pragma unroll
;     for (int ks = 0; ks < 8; ++ks) {
;       bf16x8 a = *(const bf16x8*)(SK + (size_t)(kt * 32 + lr) * 128 + ks * 16 + hh * 8);
;       acc = MFMA32(a, qf[ks], acc);
;     }
; #pragma unroll
;     for (int e = 0; e < 16; ++e) {
;       int kidx = kt * 32 + crow(e, hh);
;       g[kt][e] = (f2ord(acc[e]) & ~127u) | (unsigned)(127 - kidx);
	v_min_u32_e32 v88, v92, v87
	v_max_u32_e32 v87, v92, v87
	v_min_u32_e32 v92, v89, v93
	v_max_u32_e32 v93, v89, v93
	v_max_u32_e32 v89, v96, v111
	v_min_u32_e32 v111, v96, v111
	v_max_u32_e32 v96, v102, v95
	v_min_u32_e32 v95, v102, v95
	v_max_u32_e32 v102, v94, v100
	v_min_u32_e32 v100, v94, v100
	v_max_u32_e32 v94, v98, v113
	v_min_u32_e32 v113, v98, v113
	v_min_u32_e32 v98, v99, v88
	v_max_u32_e32 v88, v99, v88
	v_min_u32_e32 v99, v90, v87
	v_max_u32_e32 v87, v90, v87
	v_min_u32_e32 v90, v85, v92
	v_max_u32_e32 v92, v85, v92
	v_min_u32_e32 v85, v91, v93
	v_max_u32_e32 v93, v91, v93
	v_max_u32_e32 v91, v89, v102
	v_min_u32_e32 v102, v89, v102
	v_max_u32_e32 v89, v96, v94
	v_min_u32_e32 v94, v96, v94
	v_max_u32_e32 v96, v111, v100
	v_min_u32_e32 v100, v111, v100
	v_max_u32_e32 v111, v95, v113
	v_min_u32_e32 v113, v95, v113
	v_min_u32_e32 v95, v98, v90
	v_max_u32_e32 v90, v98, v90
	v_min_u32_e32 v98, v99, v85
	v_max_u32_e32 v85, v99, v85
	v_min_u32_e32 v99, v88, v92
	v_max_u32_e32 v92, v88, v92
	v_min_u32_e32 v88, v87, v93
	v_max_u32_e32 v93, v87, v93
	v_max_u32_e32 v87, v91, v89
	v_min_u32_e32 v89, v91, v89
	v_max_u32_e32 v91, v102, v94
	v_min_u32_e32 v94, v102, v94
	v_max_u32_e32 v102, v96, v111
	v_min_u32_e32 v111, v96, v111
	v_max_u32_e32 v96, v100, v113
	v_min_u32_e32 v113, v100, v113
	v_min_u32_e32 v100, v95, v98
	v_max_u32_e32 v98, v95, v98
	v_min_u32_e32 v95, v90, v85
	v_max_u32_e32 v85, v90, v85
	v_min_u32_e32 v90, v99, v88
	v_max_u32_e32 v88, v99, v88
	v_min_u32_e32 v99, v92, v93
	v_max_u32_e32 v93, v92, v93
	v_max_u32_e32 v92, v87, v100
	v_min_u32_e32 v100, v87, v100
	v_max_u32_e32 v87, v89, v98
	v_min_u32_e32 v98, v89, v98
	v_max_u32_e32 v89, v91, v95
	v_min_u32_e32 v95, v91, v95
	v_max_u32_e32 v91, v94, v85
	v_min_u32_e32 v85, v94, v85
	v_max_u32_e32 v94, v102, v90
	v_min_u32_e32 v90, v102, v90
	v_max_u32_e32 v102, v111, v88
	v_min_u32_e32 v88, v111, v88
	v_max_u32_e32 v111, v96, v99
	v_min_u32_e32 v99, v96, v99
	v_max_u32_e32 v96, v113, v93
	v_min_u32_e32 v93, v113, v93
	v_max_u32_e32 v113, v92, v94
	v_min_u32_e32 v94, v92, v94
	v_max_u32_e32 v92, v87, v102
	v_min_u32_e32 v102, v87, v102
	v_max_u32_e32 v87, v89, v111
	v_min_u32_e32 v111, v89, v111
	v_max_u32_e32 v89, v91, v96
	v_min_u32_e32 v96, v91, v96
	v_max_u32_e32 v91, v100, v90
	v_min_u32_e32 v90, v100, v90
	v_max_u32_e32 v100, v98, v88
	v_min_u32_e32 v88, v98, v88
	v_max_u32_e32 v98, v95, v99
	v_min_u32_e32 v99, v95, v99
	v_max_u32_e32 v95, v85, v93
	v_min_u32_e32 v93, v85, v93
	v_max_u32_e32 v85, v113, v87
	v_min_u32_e32 v87, v113, v87
	v_max_u32_e32 v113, v92, v89
	v_min_u32_e32 v89, v92, v89
	v_max_u32_e32 v92, v94, v111
	v_min_u32_e32 v111, v94, v111
	v_max_u32_e32 v94, v102, v96
	v_min_u32_e32 v96, v102, v96
	v_max_u32_e32 v102, v91, v98
	v_min_u32_e32 v98, v91, v98
	v_max_u32_e32 v91, v100, v95
	v_min_u32_e32 v95, v100, v95
	v_max_u32_e32 v100, v90, v99
	v_min_u32_e32 v99, v90, v99
	v_max_u32_e32 v90, v88, v93
	v_min_u32_e32 v93, v88, v93
	v_max_u32_e32 v88, v85, v113
	v_min_u32_e32 v113, v85, v113
	v_max_u32_e32 v85, v87, v89
	v_min_u32_e32 v89, v87, v89
	v_max_u32_e32 v87, v92, v94
	v_min_u32_e32 v94, v92, v94
	v_max_u32_e32 v92, v111, v96
	v_min_u32_e32 v96, v111, v96
	v_max_u32_e32 v111, v102, v91
	v_min_u32_e32 v91, v102, v91
	v_max_u32_e32 v102, v98, v95
	v_min_u32_e32 v95, v98, v95
	v_max_u32_e32 v98, v100, v90
	v_min_u32_e32 v90, v100, v90
	v_max_u32_e32 v100, v99, v93
	v_min_u32_e32 v93, v99, v93
	s_waitcnt vmcnt(7)
	v_mfma_f32_32x32x16_bf16 v[128:143], v[144:147], v[176:179], 0
	s_waitcnt vmcnt(6)
	v_mfma_f32_32x32x16_bf16 v[128:143], v[148:151], v[180:183], v[128:143]
	s_waitcnt vmcnt(5)
	v_mfma_f32_32x32x16_bf16 v[128:143], v[152:155], v[184:187], v[128:143]
	s_waitcnt vmcnt(4)
	v_mfma_f32_32x32x16_bf16 v[128:143], v[156:159], v[188:191], v[128:143]
	s_waitcnt vmcnt(3)
	v_mfma_f32_32x32x16_bf16 v[128:143], v[160:163], v[192:195], v[128:143]
	s_waitcnt vmcnt(2)
	v_mfma_f32_32x32x16_bf16 v[128:143], v[164:167], v[196:199], v[128:143]
	s_waitcnt vmcnt(1)
	v_mfma_f32_32x32x16_bf16 v[128:143], v[168:171], v[200:203], v[128:143]
	s_waitcnt vmcnt(0)
	v_mfma_f32_32x32x16_bf16 v[128:143], v[172:175], v[204:207], v[128:143]
	global_load_dwordx4 v[176:179], v239, s[2:3] offset:256
	global_load_dwordx4 v[180:183], v239, s[2:3] offset:288
	global_load_dwordx4 v[184:187], v239, s[2:3] offset:320
	global_load_dwordx4 v[188:191], v239, s[2:3] offset:352
	global_load_dwordx4 v[192:195], v239, s[2:3] offset:384
	global_load_dwordx4 v[196:199], v239, s[2:3] offset:416
	global_load_dwordx4 v[200:203], v239, s[2:3] offset:448
	global_load_dwordx4 v[204:207], v239, s[2:3] offset:480
	s_add_u32 s4, s0, 32768
	s_addc_u32 s5, s1, 0
	global_load_dwordx4 v[144:147], v238, s[4:5] offset:0
	global_load_dwordx4 v[148:151], v238, s[4:5] offset:1024
	global_load_dwordx4 v[152:155], v238, s[4:5] offset:2048
	global_load_dwordx4 v[156:159], v238, s[4:5] offset:3072
	global_load_dwordx4 v[160:163], v208, s[4:5] offset:0
	global_load_dwordx4 v[164:167], v208, s[4:5] offset:1024
	global_load_dwordx4 v[168:171], v208, s[4:5] offset:2048
	global_load_dwordx4 v[172:175], v208, s[4:5] offset:3072
	s_nop 7
	s_nop 3
	v_ashrrev_i32_e32 v230, 31, v128
	v_or_b32_e32 v230, 0x80000000, v230
	v_xor_b32_e32 v229, v230, v128
	v_and_b32_e32 v229, 0xffffff80, v229
	v_or_b32_e32 v99, v229, v213
	v_ashrrev_i32_e32 v230, 31, v129
	v_or_b32_e32 v230, 0x80000000, v230
	v_xor_b32_e32 v229, v230, v129
	v_and_b32_e32 v229, 0xffffff80, v229
	v_or_b32_e32 v84, v229, v214
	v_ashrrev_i32_e32 v230, 31, v130
	v_or_b32_e32 v230, 0x80000000, v230
	v_xor_b32_e32 v229, v230, v130
	v_and_b32_e32 v229, 0xffffff80, v229
; DI int crow(int i, int hh) { return (i & 3) + 8 * (i >> 2) + 4 * hh; }
; template <int LOGN>
; DI void bitonic_sort_desc(unsigned (&a)[1 << LOGN]) {
;   constexpr int N = 1 << LOGN;
; #pragma unroll
;   for (int ks = 1; ks <= LOGN; ++ks)
; #pragma unroll
;     ...
; #pragma unroll
;       for (int i = 0; i < N; ++i) {
;         const int k = 1 << ks, j = 1 << js, l = i ^ j;
;         if (l > i) {
;           const bool desc = ((i & k) == 0) || (ks == LOGN);
;           const unsigned x = a[i], y = a[l];
;           const unsigned hi = max(x, y), lo = min(x, y);
;           a[i] = desc ? hi : lo;
;           a[l] = desc ? lo : hi;
;         }
;       }
; }
; DI void peer_top16(const u16* __restrict__ PQrow, const u16* __restrict__ SK, unsigned (&top)[16], int lr, int hh) {
;     ...
;     for (int e = 0; e < 16; ++e) {
;       int kidx = kt * 32 + crow(e, hh);
;       g[kt][e] = (f2ord(acc[e]) & ~127u) | (unsigned)(127 - kidx);
;     }
;     bitonic_sort_desc<4>(g[kt]);
	v_or_b32_e32 v83, v229, v215
	v_ashrrev_i32_e32 v230, 31, v131
	v_or_b32_e32 v230, 0x80000000, v230
	v_xor_b32_e32 v229, v230, v131
	v_and_b32_e32 v229, 0xffffff80, v229
	v_or_b32_e32 v82, v229, v216
	v_ashrrev_i32_e32 v230, 31, v132
	v_or_b32_e32 v230, 0x80000000, v230
	v_xor_b32_e32 v229, v230, v132
	v_and_b32_e32 v229, 0xffffff80, v229
	v_or_b32_e32 v81, v229, v217
	v_ashrrev_i32_e32 v230, 31, v133
	v_or_b32_e32 v230, 0x80000000, v230
	v_xor_b32_e32 v229, v230, v133
	v_and_b32_e32 v229, 0xffffff80, v229
	v_or_b32_e32 v80, v229, v218
	v_ashrrev_i32_e32 v230, 31, v134
	v_or_b32_e32 v230, 0x80000000, v230
	v_xor_b32_e32 v229, v230, v134
	v_and_b32_e32 v229, 0xffffff80, v229
	v_or_b32_e32 v79, v229, v219
	v_ashrrev_i32_e32 v230, 31, v135
	v_or_b32_e32 v230, 0x80000000, v230
	v_xor_b32_e32 v229, v230, v135
	v_and_b32_e32 v229, 0xffffff80, v229
	v_or_b32_e32 v78, v229, v220
	v_ashrrev_i32_e32 v230, 31, v136
	v_or_b32_e32 v230, 0x80000000, v230
	v_xor_b32_e32 v229, v230, v136
	v_and_b32_e32 v229, 0xffffff80, v229
	v_or_b32_e32 v77, v229, v221
	v_ashrrev_i32_e32 v230, 31, v137
	v_or_b32_e32 v230, 0x80000000, v230
	v_xor_b32_e32 v229, v230, v137
	v_and_b32_e32 v229, 0xffffff80, v229
	v_or_b32_e32 v76, v229, v222
	v_ashrrev_i32_e32 v230, 31, v138
	v_or_b32_e32 v230, 0x80000000, v230
	v_xor_b32_e32 v229, v230, v138
	v_and_b32_e32 v229, 0xffffff80, v229
	v_or_b32_e32 v75, v229, v223
	v_ashrrev_i32_e32 v230, 31, v139
	v_or_b32_e32 v230, 0x80000000, v230
	v_xor_b32_e32 v229, v230, v139
	v_and_b32_e32 v229, 0xffffff80, v229
	v_or_b32_e32 v74, v229, v224
	v_ashrrev_i32_e32 v230, 31, v140
	v_or_b32_e32 v230, 0x80000000, v230
	v_xor_b32_e32 v229, v230, v140
	v_and_b32_e32 v229, 0xffffff80, v229
	v_or_b32_e32 v73, v229, v225
	v_ashrrev_i32_e32 v230, 31, v141
	v_or_b32_e32 v230, 0x80000000, v230
	v_xor_b32_e32 v229, v230, v141
	v_and_b32_e32 v229, 0xffffff80, v229
	v_or_b32_e32 v72, v229, v226
	v_ashrrev_i32_e32 v230, 31, v142
	v_or_b32_e32 v230, 0x80000000, v230
	v_xor_b32_e32 v229, v230, v142
	v_and_b32_e32 v229, 0xffffff80, v229
	v_or_b32_e32 v71, v229, v227
	v_ashrrev_i32_e32 v230, 31, v143
	v_or_b32_e32 v230, 0x80000000, v230
	v_xor_b32_e32 v229, v230, v143
	v_and_b32_e32 v229, 0xffffff80, v229
	v_or_b32_e32 v70, v229, v228
	v_max_u32_e32 v69, v99, v84
	v_min_u32_e32 v84, v99, v84
	v_min_u32_e32 v99, v83, v82
	v_max_u32_e32 v82, v83, v82
	v_max_u32_e32 v83, v81, v80
	v_min_u32_e32 v80, v81, v80
	v_min_u32_e32 v81, v79, v78
	v_max_u32_e32 v78, v79, v78
	v_max_u32_e32 v79, v77, v76
	v_min_u32_e32 v76, v77, v76
	v_min_u32_e32 v77, v75, v74
	v_max_u32_e32 v74, v75, v74
	v_max_u32_e32 v75, v73, v72
	v_min_u32_e32 v72, v73, v72
	v_min_u32_e32 v73, v71, v70
	v_max_u32_e32 v70, v71, v70
	v_max_u32_e32 v71, v69, v99
	v_min_u32_e32 v99, v69, v99
	v_max_u32_e32 v69, v84, v82
	v_min_u32_e32 v82, v84, v82
	v_min_u32_e32 v84, v83, v81
	v_max_u32_e32 v81, v83, v81
	v_min_u32_e32 v83, v80, v78
	v_max_u32_e32 v78, v80, v78
	v_max_u32_e32 v80, v79, v77
	v_min_u32_e32 v77, v79, v77
	v_max_u32_e32 v79, v76, v74
	v_min_u32_e32 v74, v76, v74
	v_min_u32_e32 v76, v75, v73
	v_max_u32_e32 v73, v75, v73
	v_min_u32_e32 v75, v72, v70
	v_max_u32_e32 v70, v72, v70
	v_max_u32_e32 v72, v71, v69
	v_min_u32_e32 v69, v71, v69
	v_max_u32_e32 v71, v99, v82
	v_min_u32_e32 v82, v99, v82
	v_min_u32_e32 v99, v84, v83
	v_max_u32_e32 v83, v84, v83
	v_min_u32_e32 v84, v81, v78
	v_max_u32_e32 v78, v81, v78
	v_max_u32_e32 v81, v80, v79
	v_min_u32_e32 v79, v80, v79
	v_max_u32_e32 v80, v77, v74
	v_min_u32_e32 v74, v77, v74
	v_min_u32_e32 v77, v76, v75
	v_max_u32_e32 v75, v76, v75
	v_min_u32_e32 v76, v73, v70
	v_max_u32_e32 v70, v73, v70
	v_max_u32_e32 v73, v72, v99
	v_min_u32_e32 v99, v72, v99
	v_max_u32_e32 v72, v69, v83
	v_min_u32_e32 v83, v69, v83
	v_max_u32_e32 v69, v71, v84
	v_min_u32_e32 v84, v71, v84
	v_max_u32_e32 v71, v82, v78
	v_min_u32_e32 v78, v82, v78
	v_min_u32_e32 v82, v81, v77
	v_max_u32_e32 v77, v81, v77
	v_min_u32_e32 v81, v79, v75
	v_max_u32_e32 v75, v79, v75
	v_min_u32_e32 v79, v80, v76
	v_max_u32_e32 v76, v80, v76
	v_min_u32_e32 v80, v74, v70
	v_max_u32_e32 v70, v74, v70
	v_max_u32_e32 v74, v73, v69
	v_min_u32_e32 v69, v73, v69
	v_max_u32_e32 v73, v72, v71
	v_min_u32_e32 v71, v72, v71
	v_max_u32_e32 v72, v99, v84
	v_min_u32_e32 v84, v99, v84
	v_max_u32_e32 v99, v83, v78
	v_min_u32_e32 v78, v83, v78
	v_min_u32_e32 v83, v82, v79
	v_max_u32_e32 v79, v82, v79
	v_min_u32_e32 v82, v81, v80
	v_max_u32_e32 v80, v81, v80
	v_min_u32_e32 v81, v77, v76
	v_max_u32_e32 v76, v77, v76
	v_min_u32_e32 v77, v75, v70
	v_max_u32_e32 v70, v75, v70
	v_max_u32_e32 v75, v74, v73
	v_min_u32_e32 v73, v74, v73
	v_max_u32_e32 v74, v69, v71
	v_min_u32_e32 v71, v69, v71
	v_max_u32_e32 v69, v72, v99
	v_min_u32_e32 v99, v72, v99
	v_max_u32_e32 v72, v84, v78
	v_min_u32_e32 v78, v84, v78
	v_min_u32_e32 v84, v83, v82
	v_max_u32_e32 v82, v83, v82
	v_min_u32_e32 v83, v79, v80
	v_max_u32_e32 v80, v79, v80
	v_min_u32_e32 v79, v81, v77
	v_max_u32_e32 v77, v81, v77
	v_min_u32_e32 v81, v76, v70
	v_max_u32_e32 v70, v76, v70
	v_max_u32_e32 v76, v75, v84
	v_min_u32_e32 v84, v75, v84
	v_max_u32_e32 v75, v73, v82
	v_min_u32_e32 v82, v73, v82
	v_max_u32_e32 v73, v74, v83
	v_min_u32_e32 v83, v74, v83
	v_max_u32_e32 v74, v71, v80
	v_min_u32_e32 v80, v71, v80
	v_max_u32_e32 v71, v69, v79
	v_min_u32_e32 v79, v69, v79
	v_max_u32_e32 v69, v99, v77
	v_min_u32_e32 v77, v99, v77
	v_max_u32_e32 v99, v72, v81
	v_min_u32_e32 v81, v72, v81
	v_max_u32_e32 v72, v78, v70
	v_min_u32_e32 v70, v78, v70
	v_max_u32_e32 v78, v76, v71
	v_min_u32_e32 v71, v76, v71
	v_max_u32_e32 v76, v75, v69
	v_min_u32_e32 v69, v75, v69
	v_max_u32_e32 v75, v73, v99
; DI int crow(int i, int hh) { return (i & 3) + 8 * (i >> 2) + 4 * hh; }
; template <int LOGN>
; DI void bitonic_sort_desc(unsigned (&a)[1 << LOGN]) {
;   constexpr int N = 1 << LOGN;
; #pragma unroll
;   for (int ks = 1; ks <= LOGN; ++ks)
; #pragma unroll
;     ...
; #pragma unroll
;       for (int i = 0; i < N; ++i) {
;         const int k = 1 << ks, j = 1 << js, l = i ^ j;
;         if (l > i) {
;           const bool desc = ((i & k) == 0) || (ks == LOGN);
;           const unsigned x = a[i], y = a[l];
;           const unsigned hi = max(x, y), lo = min(x, y);
;           a[i] = desc ? hi : lo;
;           a[l] = desc ? lo : hi;
;         }
;       }
; }
; DI void merge_top16(unsigned (&a)[16], const unsigned (&b)[16]) {
; #pragma unroll
;   for (int i = 0; i < 16; ++i) a[i] = max(a[i], b[15 - i]);
; #pragma unroll
;     ...
; #pragma unroll
;     for (int i = 0; i < 16; ++i) {
;       const int j = 1 << js, l = i ^ j;
;       if (l > i) {
;         const unsigned x = a[i], y = a[l];
;         a[i] = max(x, y);
;         a[l] = min(x, y);
;       }
;     }
; }
; DI void peer_top16(const u16* __restrict__ PQrow, const u16* __restrict__ SK, unsigned (&top)[16], int lr, int hh) {
;     ...
;     for (int e = 0; e < 16; ++e) {
;       int kidx = kt * 32 + crow(e, hh);
;       g[kt][e] = (f2ord(acc[e]) & ~127u) | (unsigned)(127 - kidx);
;     }
;     bitonic_sort_desc<4>(g[kt]);
;   }
;   merge_top16(g[0], g[1]);
;   merge_top16(g[2], g[3]);
;   merge_top16(g[0], g[2]);
;   unsigned other[16];
; #pragma unroll
;   for (int i = 0; i < 16; ++i) other[i] = (unsigned)__shfl_xor((int)g[0][i], 32);
;   merge_top16(g[0], other);
; #pragma unroll
;   for (int i = 0; i < 16; ++i) top[i] = g[0][i];
	v_min_u32_e32 v99, v73, v99
	v_max_u32_e32 v73, v74, v72
	v_min_u32_e32 v72, v74, v72
	v_max_u32_e32 v74, v84, v79
	v_min_u32_e32 v79, v84, v79
	v_max_u32_e32 v84, v82, v77
	v_min_u32_e32 v77, v82, v77
	v_max_u32_e32 v82, v83, v81
	v_min_u32_e32 v81, v83, v81
	v_max_u32_e32 v83, v80, v70
	v_min_u32_e32 v70, v80, v70
	v_max_u32_e32 v80, v78, v75
	v_min_u32_e32 v75, v78, v75
	v_max_u32_e32 v78, v76, v73
	v_min_u32_e32 v73, v76, v73
	v_max_u32_e32 v76, v71, v99
	v_min_u32_e32 v99, v71, v99
	v_max_u32_e32 v71, v69, v72
	v_min_u32_e32 v72, v69, v72
	v_max_u32_e32 v69, v74, v82
	v_min_u32_e32 v82, v74, v82
	v_max_u32_e32 v74, v84, v83
	v_min_u32_e32 v83, v84, v83
	v_max_u32_e32 v84, v79, v81
	v_min_u32_e32 v81, v79, v81
	v_max_u32_e32 v79, v77, v70
	v_min_u32_e32 v70, v77, v70
	v_max_u32_e32 v77, v80, v78
	v_min_u32_e32 v78, v80, v78
	v_max_u32_e32 v80, v75, v73
	v_min_u32_e32 v73, v75, v73
	v_max_u32_e32 v75, v76, v71
	v_min_u32_e32 v71, v76, v71
	v_max_u32_e32 v76, v99, v72
	v_min_u32_e32 v72, v99, v72
	v_max_u32_e32 v99, v69, v74
	v_min_u32_e32 v74, v69, v74
	v_max_u32_e32 v69, v82, v83
	v_min_u32_e32 v83, v82, v83
	v_max_u32_e32 v82, v84, v79
	v_min_u32_e32 v79, v84, v79
	v_max_u32_e32 v84, v81, v70
	v_min_u32_e32 v70, v81, v70
	v_max_u32_e32 v81, v88, v70
	v_max_u32_e32 v88, v113, v84
	v_max_u32_e32 v113, v85, v79
	v_max_u32_e32 v85, v89, v82
	v_max_u32_e32 v89, v87, v83
	v_max_u32_e32 v87, v94, v69
	v_max_u32_e32 v94, v92, v74
	v_max_u32_e32 v92, v96, v99
	v_max_u32_e32 v96, v111, v72
	v_max_u32_e32 v111, v91, v76
	v_max_u32_e32 v91, v102, v71
	v_max_u32_e32 v102, v95, v75
	v_max_u32_e32 v95, v98, v73
	v_max_u32_e32 v98, v90, v80
	v_max_u32_e32 v90, v100, v78
	v_max_u32_e32 v100, v93, v77
	v_max_u32_e32 v70, v81, v96
	v_min_u32_e32 v96, v81, v96
	v_max_u32_e32 v81, v88, v111
	v_min_u32_e32 v111, v88, v111
	v_max_u32_e32 v88, v113, v91
	v_min_u32_e32 v91, v113, v91
	v_max_u32_e32 v113, v85, v102
	v_min_u32_e32 v102, v85, v102
	v_max_u32_e32 v85, v89, v95
	v_min_u32_e32 v95, v89, v95
	v_max_u32_e32 v89, v87, v98
	v_min_u32_e32 v98, v87, v98
	v_max_u32_e32 v87, v94, v90
	v_min_u32_e32 v90, v94, v90
	v_max_u32_e32 v94, v92, v100
	v_min_u32_e32 v100, v92, v100
	v_max_u32_e32 v92, v70, v85
	v_min_u32_e32 v85, v70, v85
	v_max_u32_e32 v70, v81, v89
	v_min_u32_e32 v89, v81, v89
	v_max_u32_e32 v81, v88, v87
	v_min_u32_e32 v87, v88, v87
	v_max_u32_e32 v88, v113, v94
	v_min_u32_e32 v94, v113, v94
	v_max_u32_e32 v113, v96, v95
	v_min_u32_e32 v95, v96, v95
	v_max_u32_e32 v96, v111, v98
	v_min_u32_e32 v98, v111, v98
	v_max_u32_e32 v111, v91, v90
	v_min_u32_e32 v90, v91, v90
	v_max_u32_e32 v91, v102, v100
	v_min_u32_e32 v100, v102, v100
	v_max_u32_e32 v102, v92, v81
	v_min_u32_e32 v81, v92, v81
	v_max_u32_e32 v92, v70, v88
	v_min_u32_e32 v88, v70, v88
	v_max_u32_e32 v70, v85, v87
	v_min_u32_e32 v87, v85, v87
	v_max_u32_e32 v85, v89, v94
	v_min_u32_e32 v94, v89, v94
	v_max_u32_e32 v89, v113, v111
	v_min_u32_e32 v111, v113, v111
	v_max_u32_e32 v113, v96, v91
	v_min_u32_e32 v91, v96, v91
	v_max_u32_e32 v96, v95, v90
	v_min_u32_e32 v90, v95, v90
	v_max_u32_e32 v95, v98, v100
	v_min_u32_e32 v100, v98, v100
	v_max_u32_e32 v98, v102, v92
	v_min_u32_e32 v92, v102, v92
	v_max_u32_e32 v102, v81, v88
	v_min_u32_e32 v88, v81, v88
	v_max_u32_e32 v81, v70, v85
	v_min_u32_e32 v85, v70, v85
	v_max_u32_e32 v70, v87, v94
	v_min_u32_e32 v94, v87, v94
	v_max_u32_e32 v87, v89, v113
	v_min_u32_e32 v113, v89, v113
	v_max_u32_e32 v89, v111, v91
	v_min_u32_e32 v91, v111, v91
	v_max_u32_e32 v111, v96, v95
	v_min_u32_e32 v95, v96, v95
	v_max_u32_e32 v96, v90, v100
	v_min_u32_e32 v100, v90, v100
	v_max_u32_e32 v90, v114, v100
	v_max_u32_e32 v114, v108, v96
	v_max_u32_e32 v108, v101, v95
	v_max_u32_e32 v101, v109, v111
	v_max_u32_e32 v109, v97, v91
	v_max_u32_e32 v97, v112, v89
	v_max_u32_e32 v112, v86, v113
	v_max_u32_e32 v86, v103, v87
	v_max_u32_e32 v103, v107, v94
	v_max_u32_e32 v107, v110, v70
	v_max_u32_e32 v110, v105, v85
	v_max_u32_e32 v105, v106, v81
	v_max_u32_e32 v106, v117, v88
	v_max_u32_e32 v117, v115, v102
	v_max_u32_e32 v115, v104, v92
	v_max_u32_e32 v104, v116, v98
	v_max_u32_e32 v100, v90, v103
	v_min_u32_e32 v103, v90, v103
	v_max_u32_e32 v90, v114, v107
	v_min_u32_e32 v107, v114, v107
	v_max_u32_e32 v114, v108, v110
	v_min_u32_e32 v110, v108, v110
	v_max_u32_e32 v108, v101, v105
	v_min_u32_e32 v105, v101, v105
	v_max_u32_e32 v101, v109, v106
	v_min_u32_e32 v106, v109, v106
	v_max_u32_e32 v109, v97, v117
	v_min_u32_e32 v117, v97, v117
	v_max_u32_e32 v97, v112, v115
	v_min_u32_e32 v115, v112, v115
	v_max_u32_e32 v112, v86, v104
	v_min_u32_e32 v104, v86, v104
	v_max_u32_e32 v86, v100, v101
	v_min_u32_e32 v101, v100, v101
	v_max_u32_e32 v100, v90, v109
	v_min_u32_e32 v109, v90, v109
	v_max_u32_e32 v90, v114, v97
	v_min_u32_e32 v97, v114, v97
	v_max_u32_e32 v114, v108, v112
	v_min_u32_e32 v112, v108, v112
	v_max_u32_e32 v108, v103, v106
	v_min_u32_e32 v106, v103, v106
	v_max_u32_e32 v103, v107, v117
	v_min_u32_e32 v117, v107, v117
	v_max_u32_e32 v107, v110, v115
	v_min_u32_e32 v115, v110, v115
	v_max_u32_e32 v110, v105, v104
	v_min_u32_e32 v104, v105, v104
	v_max_u32_e32 v105, v86, v90
	v_min_u32_e32 v90, v86, v90
	v_max_u32_e32 v86, v100, v114
	v_min_u32_e32 v114, v100, v114
	v_max_u32_e32 v100, v101, v97
	v_min_u32_e32 v97, v101, v97
	v_max_u32_e32 v101, v109, v112
	v_min_u32_e32 v112, v109, v112
	v_max_u32_e32 v109, v108, v107
	v_min_u32_e32 v107, v108, v107
	v_max_u32_e32 v108, v103, v110
	v_min_u32_e32 v110, v103, v110
	v_max_u32_e32 v103, v106, v115
	v_min_u32_e32 v115, v106, v115
	v_max_u32_e32 v106, v117, v104
	v_min_u32_e32 v104, v117, v104
	v_max_u32_e32 v117, v105, v86
	v_min_u32_e32 v86, v105, v86
	v_max_u32_e32 v105, v90, v114
	v_min_u32_e32 v114, v90, v114
	v_max_u32_e32 v90, v100, v101
	v_min_u32_e32 v101, v100, v101
	v_max_u32_e32 v100, v97, v112
	v_min_u32_e32 v112, v97, v112
	v_max_u32_e32 v97, v109, v108
	v_min_u32_e32 v108, v109, v108
	v_max_u32_e32 v109, v107, v110
	v_min_u32_e32 v110, v107, v110
	v_max_u32_e32 v107, v103, v106
	v_min_u32_e32 v106, v103, v106
	v_max_u32_e32 v103, v115, v104
	v_min_u32_e32 v104, v115, v104
	v_mov_b32_e32 v0, v117
	v_mov_b32_e32 v1, v86
	v_mov_b32_e32 v2, v105
	v_mov_b32_e32 v3, v114
	v_mov_b32_e32 v4, v90
	v_mov_b32_e32 v5, v101
	v_mov_b32_e32 v6, v100
	v_mov_b32_e32 v7, v112
	v_mov_b32_e32 v8, v97
	v_mov_b32_e32 v9, v108
	v_mov_b32_e32 v10, v109
	v_mov_b32_e32 v11, v110
	v_mov_b32_e32 v12, v107
	v_mov_b32_e32 v13, v106
	v_mov_b32_e32 v14, v103
	v_mov_b32_e32 v15, v104
	v_sub_u32_e32 v213, 127, v245
	v_sub_u32_e32 v214, 126, v245
	v_sub_u32_e32 v215, 125, v245
	v_sub_u32_e32 v216, 124, v245
	v_sub_u32_e32 v217, 119, v245
	v_sub_u32_e32 v218, 118, v245
	v_sub_u32_e32 v219, 117, v245
	v_sub_u32_e32 v220, 116, v245
	v_sub_u32_e32 v221, 111, v245
	v_sub_u32_e32 v222, 110, v245
	v_sub_u32_e32 v223, 109, v245
	v_sub_u32_e32 v224, 108, v245
	v_sub_u32_e32 v225, 103, v245
	v_sub_u32_e32 v226, 102, v245
	v_sub_u32_e32 v227, 101, v245
	v_sub_u32_e32 v228, 100, v245
	s_waitcnt vmcnt(7)
; #define MFMA32(a, b, c) __builtin_amdgcn_mfma_f32_32x32x16_bf16((a), (b), (c), 0, 0, 0)
; DI int crow(int i, int hh) { return (i & 3) + 8 * (i >> 2) + 4 * hh; }
; DI unsigned f2ord(float f) {
;   unsigned u = __float_as_uint(f);
;   return (u & 0x80000000u) ? ~u : (u | 0x80000000u);
; }
; DI void peer_top16(const u16* __restrict__ PQrow, const u16* __restrict__ SK, unsigned (&top)[16], int lr, int hh) {
;     ...
;   for (int kt = 0; kt < 4; ++kt) {
;     f32x16 acc;
; #pragma unroll
;     for (int e = 0; e < 16; ++e) acc[e] = 0.f;
; #pragma unroll
;     for (int ks = 0; ks < 8; ++ks) {
;       bf16x8 a = *(const bf16x8*)(SK + (size_t)(kt * 32 + lr) * 128 + ks * 16 + hh * 8);
;       acc = MFMA32(a, qf[ks], acc);
;     }
; #pragma unroll
;     for (int e = 0; e < 16; ++e) {
;       int kidx = kt * 32 + crow(e, hh);
;       g[kt][e] = (f2ord(acc[e]) & ~127u) | (unsigned)(127 - kidx);
;     }
;     bitonic_sort_desc<4>(g[kt]);
	v_mfma_f32_32x32x16_bf16 v[128:143], v[144:147], v[176:179], 0
	s_waitcnt vmcnt(6)
	v_mfma_f32_32x32x16_bf16 v[128:143], v[148:151], v[180:183], v[128:143]
	s_waitcnt vmcnt(5)
	v_mfma_f32_32x32x16_bf16 v[128:143], v[152:155], v[184:187], v[128:143]
	s_waitcnt vmcnt(4)
	v_mfma_f32_32x32x16_bf16 v[128:143], v[156:159], v[188:191], v[128:143]
	s_waitcnt vmcnt(3)
	v_mfma_f32_32x32x16_bf16 v[128:143], v[160:163], v[192:195], v[128:143]
	s_waitcnt vmcnt(2)
	v_mfma_f32_32x32x16_bf16 v[128:143], v[164:167], v[196:199], v[128:143]
	s_waitcnt vmcnt(1)
	v_mfma_f32_32x32x16_bf16 v[128:143], v[168:171], v[200:203], v[128:143]
	s_waitcnt vmcnt(0)
	v_mfma_f32_32x32x16_bf16 v[128:143], v[172:175], v[204:207], v[128:143]
	s_add_u32 s4, s0, 40960
	s_addc_u32 s5, s1, 0
	global_load_dwordx4 v[144:147], v238, s[4:5] offset:0
	global_load_dwordx4 v[148:151], v238, s[4:5] offset:1024
	global_load_dwordx4 v[152:155], v238, s[4:5] offset:2048
	global_load_dwordx4 v[156:159], v238, s[4:5] offset:3072
	global_load_dwordx4 v[160:163], v208, s[4:5] offset:0
	global_load_dwordx4 v[164:167], v208, s[4:5] offset:1024
	global_load_dwordx4 v[168:171], v208, s[4:5] offset:2048
	global_load_dwordx4 v[172:175], v208, s[4:5] offset:3072
	s_nop 7
	s_nop 3
	v_ashrrev_i32_e32 v230, 31, v128
	v_or_b32_e32 v230, 0x80000000, v230
	v_xor_b32_e32 v229, v230, v128
	v_and_b32_e32 v229, 0xffffff80, v229
	v_or_b32_e32 v104, v229, v213
	v_ashrrev_i32_e32 v230, 31, v129
	v_or_b32_e32 v230, 0x80000000, v230
	v_xor_b32_e32 v229, v230, v129
	v_and_b32_e32 v229, 0xffffff80, v229
	v_or_b32_e32 v103, v229, v214
	v_ashrrev_i32_e32 v230, 31, v130
	v_or_b32_e32 v230, 0x80000000, v230
	v_xor_b32_e32 v229, v230, v130
	v_and_b32_e32 v229, 0xffffff80, v229
	v_or_b32_e32 v106, v229, v215
	v_ashrrev_i32_e32 v230, 31, v131
	v_or_b32_e32 v230, 0x80000000, v230
	v_xor_b32_e32 v229, v230, v131
	v_and_b32_e32 v229, 0xffffff80, v229
	v_or_b32_e32 v107, v229, v216
	v_ashrrev_i32_e32 v230, 31, v132
	v_or_b32_e32 v230, 0x80000000, v230
	v_xor_b32_e32 v229, v230, v132
	v_and_b32_e32 v229, 0xffffff80, v229
	v_or_b32_e32 v110, v229, v217
	v_ashrrev_i32_e32 v230, 31, v133
	v_or_b32_e32 v230, 0x80000000, v230
	v_xor_b32_e32 v229, v230, v133
	v_and_b32_e32 v229, 0xffffff80, v229
	v_or_b32_e32 v109, v229, v218
	v_ashrrev_i32_e32 v230, 31, v134
	v_or_b32_e32 v230, 0x80000000, v230
	v_xor_b32_e32 v229, v230, v134
	v_and_b32_e32 v229, 0xffffff80, v229
	v_or_b32_e32 v108, v229, v219
	v_ashrrev_i32_e32 v230, 31, v135
	v_or_b32_e32 v230, 0x80000000, v230
	v_xor_b32_e32 v229, v230, v135
	v_and_b32_e32 v229, 0xffffff80, v229
	v_or_b32_e32 v97, v229, v220
	v_ashrrev_i32_e32 v230, 31, v136
	v_or_b32_e32 v230, 0x80000000, v230
	v_xor_b32_e32 v229, v230, v136
	v_and_b32_e32 v229, 0xffffff80, v229
	v_or_b32_e32 v112, v229, v221
	v_ashrrev_i32_e32 v230, 31, v137
	v_or_b32_e32 v230, 0x80000000, v230
	v_xor_b32_e32 v229, v230, v137
	v_and_b32_e32 v229, 0xffffff80, v229
	v_or_b32_e32 v100, v229, v222
	v_ashrrev_i32_e32 v230, 31, v138
	v_or_b32_e32 v230, 0x80000000, v230
	v_xor_b32_e32 v229, v230, v138
	v_and_b32_e32 v229, 0xffffff80, v229
	v_or_b32_e32 v101, v229, v223
	v_ashrrev_i32_e32 v230, 31, v139
	v_or_b32_e32 v230, 0x80000000, v230
	v_xor_b32_e32 v229, v230, v139
	v_and_b32_e32 v229, 0xffffff80, v229
	v_or_b32_e32 v90, v229, v224
	v_ashrrev_i32_e32 v230, 31, v140
	v_or_b32_e32 v230, 0x80000000, v230
	v_xor_b32_e32 v229, v230, v140
	v_and_b32_e32 v229, 0xffffff80, v229
	v_or_b32_e32 v114, v229, v225
	v_ashrrev_i32_e32 v230, 31, v141
	v_or_b32_e32 v230, 0x80000000, v230
	v_xor_b32_e32 v229, v230, v141
	v_and_b32_e32 v229, 0xffffff80, v229
	v_or_b32_e32 v105, v229, v226
	v_ashrrev_i32_e32 v230, 31, v142
	v_or_b32_e32 v230, 0x80000000, v230
	v_xor_b32_e32 v229, v230, v142
	v_and_b32_e32 v229, 0xffffff80, v229
	v_or_b32_e32 v86, v229, v227
	v_ashrrev_i32_e32 v230, 31, v143
	v_or_b32_e32 v230, 0x80000000, v230
	v_xor_b32_e32 v229, v230, v143
	v_and_b32_e32 v229, 0xffffff80, v229
	v_or_b32_e32 v117, v229, v228
	v_subrev_u32_e32 v213, 32, v213
	v_subrev_u32_e32 v214, 32, v214
	v_subrev_u32_e32 v215, 32, v215
	v_subrev_u32_e32 v216, 32, v216
	v_subrev_u32_e32 v217, 32, v217
	v_subrev_u32_e32 v218, 32, v218
	v_subrev_u32_e32 v219, 32, v219
	v_subrev_u32_e32 v220, 32, v220
	v_subrev_u32_e32 v221, 32, v221
	v_subrev_u32_e32 v222, 32, v222
	v_subrev_u32_e32 v223, 32, v223
	v_subrev_u32_e32 v224, 32, v224
	v_subrev_u32_e32 v225, 32, v225
	v_subrev_u32_e32 v226, 32, v226
	v_subrev_u32_e32 v227, 32, v227
	v_subrev_u32_e32 v228, 32, v228
	v_max_u32_e32 v115, v104, v103
	v_min_u32_e32 v103, v104, v103
	v_min_u32_e32 v104, v106, v107
	v_max_u32_e32 v107, v106, v107
	v_max_u32_e32 v106, v110, v109
	v_min_u32_e32 v109, v110, v109
	v_min_u32_e32 v110, v108, v97
	v_max_u32_e32 v97, v108, v97
	v_max_u32_e32 v108, v112, v100
	v_min_u32_e32 v100, v112, v100
	v_min_u32_e32 v112, v101, v90
	v_max_u32_e32 v90, v101, v90
	v_max_u32_e32 v101, v114, v105
	v_min_u32_e32 v105, v114, v105
	v_min_u32_e32 v114, v86, v117
	v_max_u32_e32 v117, v86, v117
	v_max_u32_e32 v86, v115, v104
	v_min_u32_e32 v104, v115, v104
	v_max_u32_e32 v115, v103, v107
	v_min_u32_e32 v107, v103, v107
	v_min_u32_e32 v103, v106, v110
	v_max_u32_e32 v110, v106, v110
	v_min_u32_e32 v106, v109, v97
	v_max_u32_e32 v97, v109, v97
	v_max_u32_e32 v109, v108, v112
	v_min_u32_e32 v112, v108, v112
	v_max_u32_e32 v108, v100, v90
	v_min_u32_e32 v90, v100, v90
	v_min_u32_e32 v100, v101, v114
	v_max_u32_e32 v114, v101, v114
	v_min_u32_e32 v101, v105, v117
	v_max_u32_e32 v117, v105, v117
	v_max_u32_e32 v105, v86, v115
	v_min_u32_e32 v115, v86, v115
	v_max_u32_e32 v86, v104, v107
	v_min_u32_e32 v107, v104, v107
; #define MFMA32(a, b, c) __builtin_amdgcn_mfma_f32_32x32x16_bf16((a), (b), (c), 0, 0, 0)
; template <int LOGN>
; DI void bitonic_sort_desc(unsigned (&a)[1 << LOGN]) {
;   constexpr int N = 1 << LOGN;
; #pragma unroll
;   for (int ks = 1; ks <= LOGN; ++ks)
; #pragma unroll
;     ...
; #pragma unroll
;       for (int i = 0; i < N; ++i) {
;         const int k = 1 << ks, j = 1 << js, l = i ^ j;
;         if (l > i) {
;           const bool desc = ((i & k) == 0) || (ks == LOGN);
;           const unsigned x = a[i], y = a[l];
;           const unsigned hi = max(x, y), lo = min(x, y);
;           a[i] = desc ? hi : lo;
;           a[l] = desc ? lo : hi;
;         }
;       }
; }
; DI void peer_top16(const u16* __restrict__ PQrow, const u16* __restrict__ SK, unsigned (&top)[16], int lr, int hh) {
;     ...
;   for (int kt = 0; kt < 4; ++kt) {
;     f32x16 acc;
; #pragma unroll
;     for (int e = 0; e < 16; ++e) acc[e] = 0.f;
; #pragma unroll
;     for (int ks = 0; ks < 8; ++ks) {
;       bf16x8 a = *(const bf16x8*)(SK + (size_t)(kt * 32 + lr) * 128 + ks * 16 + hh * 8);
;       acc = MFMA32(a, qf[ks], acc);
;     }
	v_min_u32_e32 v104, v103, v106
	v_max_u32_e32 v106, v103, v106
	v_min_u32_e32 v103, v110, v97
	v_max_u32_e32 v97, v110, v97
	v_max_u32_e32 v110, v109, v108
	v_min_u32_e32 v108, v109, v108
	v_max_u32_e32 v109, v112, v90
	v_min_u32_e32 v90, v112, v90
	v_min_u32_e32 v112, v100, v101
	v_max_u32_e32 v101, v100, v101
	v_min_u32_e32 v100, v114, v117
	v_max_u32_e32 v117, v114, v117
	v_max_u32_e32 v114, v105, v104
	v_min_u32_e32 v104, v105, v104
	v_max_u32_e32 v105, v115, v106
	v_min_u32_e32 v106, v115, v106
	v_max_u32_e32 v115, v86, v103
	v_min_u32_e32 v103, v86, v103
	v_max_u32_e32 v86, v107, v97
	v_min_u32_e32 v97, v107, v97
	v_min_u32_e32 v107, v110, v112
	v_max_u32_e32 v112, v110, v112
	v_min_u32_e32 v110, v108, v101
	v_max_u32_e32 v101, v108, v101
	v_min_u32_e32 v108, v109, v100
	v_max_u32_e32 v100, v109, v100
	v_min_u32_e32 v109, v90, v117
	v_max_u32_e32 v117, v90, v117
	v_max_u32_e32 v90, v114, v115
	v_min_u32_e32 v115, v114, v115
	v_max_u32_e32 v114, v105, v86
	v_min_u32_e32 v86, v105, v86
	v_max_u32_e32 v105, v104, v103
	v_min_u32_e32 v103, v104, v103
	v_max_u32_e32 v104, v106, v97
	v_min_u32_e32 v97, v106, v97
	v_min_u32_e32 v106, v107, v108
	v_max_u32_e32 v108, v107, v108
	v_min_u32_e32 v107, v110, v109
	v_max_u32_e32 v109, v110, v109
	v_min_u32_e32 v110, v112, v100
	v_max_u32_e32 v100, v112, v100
	v_min_u32_e32 v112, v101, v117
	v_max_u32_e32 v117, v101, v117
	v_max_u32_e32 v101, v90, v114
	v_min_u32_e32 v114, v90, v114
	v_max_u32_e32 v90, v115, v86
	v_min_u32_e32 v86, v115, v86
	v_max_u32_e32 v115, v105, v104
	v_min_u32_e32 v104, v105, v104
	v_max_u32_e32 v105, v103, v97
	v_min_u32_e32 v97, v103, v97
	v_min_u32_e32 v103, v106, v107
	v_max_u32_e32 v107, v106, v107
	v_min_u32_e32 v106, v108, v109
	v_max_u32_e32 v109, v108, v109
	v_min_u32_e32 v108, v110, v112
	v_max_u32_e32 v112, v110, v112
	v_min_u32_e32 v110, v100, v117
	v_max_u32_e32 v117, v100, v117
	v_max_u32_e32 v100, v101, v103
	v_min_u32_e32 v103, v101, v103
	v_max_u32_e32 v101, v114, v107
	v_min_u32_e32 v107, v114, v107
	v_max_u32_e32 v114, v90, v106
	v_min_u32_e32 v106, v90, v106
	v_max_u32_e32 v90, v86, v109
	v_min_u32_e32 v109, v86, v109
	v_max_u32_e32 v86, v115, v108
	v_min_u32_e32 v108, v115, v108
	v_max_u32_e32 v115, v104, v112
	v_min_u32_e32 v112, v104, v112
	v_max_u32_e32 v104, v105, v110
	v_min_u32_e32 v110, v105, v110
	v_max_u32_e32 v105, v97, v117
	v_min_u32_e32 v117, v97, v117
	v_max_u32_e32 v97, v100, v86
	v_min_u32_e32 v86, v100, v86
	v_max_u32_e32 v100, v101, v115
	v_min_u32_e32 v115, v101, v115
	v_max_u32_e32 v101, v114, v104
	v_min_u32_e32 v104, v114, v104
	v_max_u32_e32 v114, v90, v105
	v_min_u32_e32 v105, v90, v105
	v_max_u32_e32 v90, v103, v108
	v_min_u32_e32 v108, v103, v108
	v_max_u32_e32 v103, v107, v112
	v_min_u32_e32 v112, v107, v112
	v_max_u32_e32 v107, v106, v110
	v_min_u32_e32 v110, v106, v110
	v_max_u32_e32 v106, v109, v117
	v_min_u32_e32 v117, v109, v117
	v_max_u32_e32 v109, v97, v101
	v_min_u32_e32 v101, v97, v101
	v_max_u32_e32 v97, v100, v114
	v_min_u32_e32 v114, v100, v114
	v_max_u32_e32 v100, v86, v104
	v_min_u32_e32 v104, v86, v104
	v_max_u32_e32 v86, v115, v105
	v_min_u32_e32 v105, v115, v105
	v_max_u32_e32 v115, v90, v107
	v_min_u32_e32 v107, v90, v107
	v_max_u32_e32 v90, v103, v106
	v_min_u32_e32 v106, v103, v106
	v_max_u32_e32 v103, v108, v110
	v_min_u32_e32 v110, v108, v110
	v_max_u32_e32 v108, v112, v117
	v_min_u32_e32 v117, v112, v117
	v_max_u32_e32 v112, v109, v97
	v_min_u32_e32 v97, v109, v97
	v_max_u32_e32 v109, v101, v114
	v_min_u32_e32 v114, v101, v114
	v_max_u32_e32 v101, v100, v86
	v_min_u32_e32 v86, v100, v86
	v_max_u32_e32 v100, v104, v105
	v_min_u32_e32 v105, v104, v105
	v_max_u32_e32 v104, v115, v90
	v_min_u32_e32 v90, v115, v90
	v_max_u32_e32 v115, v107, v106
	v_min_u32_e32 v106, v107, v106
	v_max_u32_e32 v107, v103, v108
	v_min_u32_e32 v108, v103, v108
	v_max_u32_e32 v103, v110, v117
	v_min_u32_e32 v117, v110, v117
	s_waitcnt vmcnt(7)
	v_mfma_f32_32x32x16_bf16 v[128:143], v[144:147], v[176:179], 0
	s_waitcnt vmcnt(6)
	v_mfma_f32_32x32x16_bf16 v[128:143], v[148:151], v[180:183], v[128:143]
	s_waitcnt vmcnt(5)
	v_mfma_f32_32x32x16_bf16 v[128:143], v[152:155], v[184:187], v[128:143]
	s_waitcnt vmcnt(4)
	v_mfma_f32_32x32x16_bf16 v[128:143], v[156:159], v[188:191], v[128:143]
	s_waitcnt vmcnt(3)
	v_mfma_f32_32x32x16_bf16 v[128:143], v[160:163], v[192:195], v[128:143]
	s_waitcnt vmcnt(2)
	v_mfma_f32_32x32x16_bf16 v[128:143], v[164:167], v[196:199], v[128:143]
	s_waitcnt vmcnt(1)
	v_mfma_f32_32x32x16_bf16 v[128:143], v[168:171], v[200:203], v[128:143]
	s_waitcnt vmcnt(0)
; #define MFMA32(a, b, c) __builtin_amdgcn_mfma_f32_32x32x16_bf16((a), (b), (c), 0, 0, 0)
; DI int crow(int i, int hh) { return (i & 3) + 8 * (i >> 2) + 4 * hh; }
; DI unsigned f2ord(float f) {
;   unsigned u = __float_as_uint(f);
;   return (u & 0x80000000u) ? ~u : (u | 0x80000000u);
; }
; DI void peer_top16(const u16* __restrict__ PQrow, const u16* __restrict__ SK, unsigned (&top)[16], int lr, int hh) {
;     ...
;   for (int kt = 0; kt < 4; ++kt) {
;     f32x16 acc;
; #pragma unroll
;     for (int e = 0; e < 16; ++e) acc[e] = 0.f;
; #pragma unroll
;     for (int ks = 0; ks < 8; ++ks) {
;       bf16x8 a = *(const bf16x8*)(SK + (size_t)(kt * 32 + lr) * 128 + ks * 16 + hh * 8);
;       acc = MFMA32(a, qf[ks], acc);
;     }
; #pragma unroll
;     for (int e = 0; e < 16; ++e) {
;       int kidx = kt * 32 + crow(e, hh);
;       g[kt][e] = (f2ord(acc[e]) & ~127u) | (unsigned)(127 - kidx);
;     }
;     bitonic_sort_desc<4>(g[kt]);
	v_mfma_f32_32x32x16_bf16 v[128:143], v[172:175], v[204:207], v[128:143]
	s_add_u32 s4, s0, 49152
	s_addc_u32 s5, s1, 0
	global_load_dwordx4 v[144:147], v238, s[4:5] offset:0
	global_load_dwordx4 v[148:151], v238, s[4:5] offset:1024
	global_load_dwordx4 v[152:155], v238, s[4:5] offset:2048
	global_load_dwordx4 v[156:159], v238, s[4:5] offset:3072
	global_load_dwordx4 v[160:163], v208, s[4:5] offset:0
	global_load_dwordx4 v[164:167], v208, s[4:5] offset:1024
	global_load_dwordx4 v[168:171], v208, s[4:5] offset:2048
	global_load_dwordx4 v[172:175], v208, s[4:5] offset:3072
	s_nop 7
	s_nop 3
	v_ashrrev_i32_e32 v230, 31, v128
	v_or_b32_e32 v230, 0x80000000, v230
	v_xor_b32_e32 v229, v230, v128
	v_and_b32_e32 v229, 0xffffff80, v229
	v_or_b32_e32 v110, v229, v213
	v_ashrrev_i32_e32 v230, 31, v129
	v_or_b32_e32 v230, 0x80000000, v230
	v_xor_b32_e32 v229, v230, v129
	v_and_b32_e32 v229, 0xffffff80, v229
	v_or_b32_e32 v96, v229, v214
	v_ashrrev_i32_e32 v230, 31, v130
	v_or_b32_e32 v230, 0x80000000, v230
	v_xor_b32_e32 v229, v230, v130
	v_and_b32_e32 v229, 0xffffff80, v229
	v_or_b32_e32 v95, v229, v215
	v_ashrrev_i32_e32 v230, 31, v131
	v_or_b32_e32 v230, 0x80000000, v230
	v_xor_b32_e32 v229, v230, v131
	v_and_b32_e32 v229, 0xffffff80, v229
	v_or_b32_e32 v111, v229, v216
	v_ashrrev_i32_e32 v230, 31, v132
	v_or_b32_e32 v230, 0x80000000, v230
	v_xor_b32_e32 v229, v230, v132
	v_and_b32_e32 v229, 0xffffff80, v229
	v_or_b32_e32 v91, v229, v217
	v_ashrrev_i32_e32 v230, 31, v133
	v_or_b32_e32 v230, 0x80000000, v230
	v_xor_b32_e32 v229, v230, v133
	v_and_b32_e32 v229, 0xffffff80, v229
	v_or_b32_e32 v89, v229, v218
	v_ashrrev_i32_e32 v230, 31, v134
	v_or_b32_e32 v230, 0x80000000, v230
	v_xor_b32_e32 v229, v230, v134
	v_and_b32_e32 v229, 0xffffff80, v229
	v_or_b32_e32 v113, v229, v219
	v_ashrrev_i32_e32 v230, 31, v135
	v_or_b32_e32 v230, 0x80000000, v230
	v_xor_b32_e32 v229, v230, v135
	v_and_b32_e32 v229, 0xffffff80, v229
	v_or_b32_e32 v87, v229, v220
	v_ashrrev_i32_e32 v230, 31, v136
	v_or_b32_e32 v230, 0x80000000, v230
	v_xor_b32_e32 v229, v230, v136
	v_and_b32_e32 v229, 0xffffff80, v229
	v_or_b32_e32 v94, v229, v221
	v_ashrrev_i32_e32 v230, 31, v137
	v_or_b32_e32 v230, 0x80000000, v230
	v_xor_b32_e32 v229, v230, v137
	v_and_b32_e32 v229, 0xffffff80, v229
	v_or_b32_e32 v70, v229, v222
	v_ashrrev_i32_e32 v230, 31, v138
	v_or_b32_e32 v230, 0x80000000, v230
	v_xor_b32_e32 v229, v230, v138
	v_and_b32_e32 v229, 0xffffff80, v229
	v_or_b32_e32 v85, v229, v223
	v_ashrrev_i32_e32 v230, 31, v139
	v_or_b32_e32 v230, 0x80000000, v230
	v_xor_b32_e32 v229, v230, v139
	v_and_b32_e32 v229, 0xffffff80, v229
	v_or_b32_e32 v81, v229, v224
	v_ashrrev_i32_e32 v230, 31, v140
	v_or_b32_e32 v230, 0x80000000, v230
	v_xor_b32_e32 v229, v230, v140
	v_and_b32_e32 v229, 0xffffff80, v229
	v_or_b32_e32 v88, v229, v225
	v_ashrrev_i32_e32 v230, 31, v141
	v_or_b32_e32 v230, 0x80000000, v230
	v_xor_b32_e32 v229, v230, v141
	v_and_b32_e32 v229, 0xffffff80, v229
	v_or_b32_e32 v102, v229, v226
	v_ashrrev_i32_e32 v230, 31, v142
	v_or_b32_e32 v230, 0x80000000, v230
	v_xor_b32_e32 v229, v230, v142
	v_and_b32_e32 v229, 0xffffff80, v229
	v_or_b32_e32 v92, v229, v227
	v_ashrrev_i32_e32 v230, 31, v143
	v_or_b32_e32 v230, 0x80000000, v230
	v_xor_b32_e32 v229, v230, v143
	v_and_b32_e32 v229, 0xffffff80, v229
	v_or_b32_e32 v98, v229, v228
	v_subrev_u32_e32 v213, 32, v213
	v_subrev_u32_e32 v214, 32, v214
	v_subrev_u32_e32 v215, 32, v215
	v_subrev_u32_e32 v216, 32, v216
	v_subrev_u32_e32 v217, 32, v217
	v_subrev_u32_e32 v218, 32, v218
	v_subrev_u32_e32 v219, 32, v219
	v_subrev_u32_e32 v220, 32, v220
	v_subrev_u32_e32 v221, 32, v221
	v_subrev_u32_e32 v222, 32, v222
	v_subrev_u32_e32 v223, 32, v223
	v_subrev_u32_e32 v224, 32, v224
	v_subrev_u32_e32 v225, 32, v225
	v_subrev_u32_e32 v226, 32, v226
	v_subrev_u32_e32 v227, 32, v227
	v_subrev_u32_e32 v228, 32, v228
	v_max_u32_e32 v116, v110, v96
	v_min_u32_e32 v96, v110, v96
	v_min_u32_e32 v110, v95, v111
	v_max_u32_e32 v111, v95, v111
	v_max_u32_e32 v95, v91, v89
	v_min_u32_e32 v89, v91, v89
	v_min_u32_e32 v91, v113, v87
	v_max_u32_e32 v87, v113, v87
	v_max_u32_e32 v113, v94, v70
	v_min_u32_e32 v70, v94, v70
	v_min_u32_e32 v94, v85, v81
	v_max_u32_e32 v81, v85, v81
	v_max_u32_e32 v85, v88, v102
	v_min_u32_e32 v102, v88, v102
	v_min_u32_e32 v88, v92, v98
	v_max_u32_e32 v98, v92, v98
	v_max_u32_e32 v92, v116, v110
	v_min_u32_e32 v110, v116, v110
	v_max_u32_e32 v116, v96, v111
	v_min_u32_e32 v111, v96, v111
	v_min_u32_e32 v96, v95, v91
	v_max_u32_e32 v91, v95, v91
	v_min_u32_e32 v95, v89, v87
	v_max_u32_e32 v87, v89, v87
	v_max_u32_e32 v89, v113, v94
	v_min_u32_e32 v94, v113, v94
	v_max_u32_e32 v113, v70, v81
	v_min_u32_e32 v81, v70, v81
	v_min_u32_e32 v70, v85, v88
	v_max_u32_e32 v88, v85, v88
	v_min_u32_e32 v85, v102, v98
	v_max_u32_e32 v98, v102, v98
	v_max_u32_e32 v102, v92, v116
	v_min_u32_e32 v116, v92, v116
	v_max_u32_e32 v92, v110, v111
	v_min_u32_e32 v111, v110, v111
	v_min_u32_e32 v110, v96, v95
	v_max_u32_e32 v95, v96, v95
	v_min_u32_e32 v96, v91, v87
	v_max_u32_e32 v87, v91, v87
	v_max_u32_e32 v91, v89, v113
	v_min_u32_e32 v113, v89, v113
	v_max_u32_e32 v89, v94, v81
	v_min_u32_e32 v81, v94, v81
	v_min_u32_e32 v94, v70, v85
	v_max_u32_e32 v85, v70, v85
	v_min_u32_e32 v70, v88, v98
	v_max_u32_e32 v98, v88, v98
	v_max_u32_e32 v88, v102, v110
	v_min_u32_e32 v110, v102, v110
	v_max_u32_e32 v102, v116, v95
	v_min_u32_e32 v95, v116, v95
	v_max_u32_e32 v116, v92, v96
	v_min_u32_e32 v96, v92, v96
	v_max_u32_e32 v92, v111, v87
	v_min_u32_e32 v87, v111, v87
	v_min_u32_e32 v111, v91, v94
	v_max_u32_e32 v94, v91, v94
	v_min_u32_e32 v91, v113, v85
; template <int LOGN>
; DI void bitonic_sort_desc(unsigned (&a)[1 << LOGN]) {
;   constexpr int N = 1 << LOGN;
; #pragma unroll
;   for (int ks = 1; ks <= LOGN; ++ks)
; #pragma unroll
;     ...
; #pragma unroll
;       for (int i = 0; i < N; ++i) {
;         const int k = 1 << ks, j = 1 << js, l = i ^ j;
;         if (l > i) {
;           const bool desc = ((i & k) == 0) || (ks == LOGN);
;           const unsigned x = a[i], y = a[l];
;           const unsigned hi = max(x, y), lo = min(x, y);
;           a[i] = desc ? hi : lo;
;           a[l] = desc ? lo : hi;
;         }
;       }
; }
; DI void merge_top16(unsigned (&a)[16], const unsigned (&b)[16]) {
; #pragma unroll
;   for (int i = 0; i < 16; ++i) a[i] = max(a[i], b[15 - i]);
; #pragma unroll
;     ...
; #pragma unroll
;     for (int i = 0; i < 16; ++i) {
;       const int j = 1 << js, l = i ^ j;
;       if (l > i) {
;         const unsigned x = a[i], y = a[l];
;         a[i] = max(x, y);
;         a[l] = min(x, y);
;       }
;     }
; }
	v_max_u32_e32 v85, v113, v85
	v_min_u32_e32 v113, v89, v70
	v_max_u32_e32 v70, v89, v70
	v_min_u32_e32 v89, v81, v98
	v_max_u32_e32 v98, v81, v98
	v_max_u32_e32 v81, v88, v116
	v_min_u32_e32 v116, v88, v116
	v_max_u32_e32 v88, v102, v92
	v_min_u32_e32 v92, v102, v92
	v_max_u32_e32 v102, v110, v96
	v_min_u32_e32 v96, v110, v96
	v_max_u32_e32 v110, v95, v87
	v_min_u32_e32 v87, v95, v87
	v_min_u32_e32 v95, v111, v113
	v_max_u32_e32 v113, v111, v113
	v_min_u32_e32 v111, v91, v89
	v_max_u32_e32 v89, v91, v89
	v_min_u32_e32 v91, v94, v70
	v_max_u32_e32 v70, v94, v70
	v_min_u32_e32 v94, v85, v98
	v_max_u32_e32 v98, v85, v98
	v_max_u32_e32 v85, v81, v88
	v_min_u32_e32 v88, v81, v88
	v_max_u32_e32 v81, v116, v92
	v_min_u32_e32 v92, v116, v92
	v_max_u32_e32 v116, v102, v110
	v_min_u32_e32 v110, v102, v110
	v_max_u32_e32 v102, v96, v87
	v_min_u32_e32 v87, v96, v87
	v_min_u32_e32 v96, v95, v111
	v_max_u32_e32 v111, v95, v111
	v_min_u32_e32 v95, v113, v89
	v_max_u32_e32 v89, v113, v89
	v_min_u32_e32 v113, v91, v94
	v_max_u32_e32 v94, v91, v94
	v_min_u32_e32 v91, v70, v98
	v_max_u32_e32 v98, v70, v98
	v_max_u32_e32 v70, v85, v96
	v_min_u32_e32 v96, v85, v96
	v_max_u32_e32 v85, v88, v111
	v_min_u32_e32 v111, v88, v111
	v_max_u32_e32 v88, v81, v95
	v_min_u32_e32 v95, v81, v95
	v_max_u32_e32 v81, v92, v89
	v_min_u32_e32 v89, v92, v89
	v_max_u32_e32 v92, v116, v113
	v_min_u32_e32 v113, v116, v113
	v_max_u32_e32 v116, v110, v94
	v_min_u32_e32 v94, v110, v94
	v_max_u32_e32 v110, v102, v91
	v_min_u32_e32 v91, v102, v91
	v_max_u32_e32 v102, v87, v98
	v_min_u32_e32 v98, v87, v98
	v_max_u32_e32 v87, v70, v92
	v_min_u32_e32 v92, v70, v92
	v_max_u32_e32 v70, v85, v116
	v_min_u32_e32 v116, v85, v116
	v_max_u32_e32 v85, v88, v110
	v_min_u32_e32 v110, v88, v110
	v_max_u32_e32 v88, v81, v102
	v_min_u32_e32 v102, v81, v102
	v_max_u32_e32 v81, v96, v113
	v_min_u32_e32 v113, v96, v113
	v_max_u32_e32 v96, v111, v94
	v_min_u32_e32 v94, v111, v94
	v_max_u32_e32 v111, v95, v91
	v_min_u32_e32 v91, v95, v91
	v_max_u32_e32 v95, v89, v98
	v_min_u32_e32 v98, v89, v98
	v_max_u32_e32 v89, v87, v85
	v_min_u32_e32 v85, v87, v85
	v_max_u32_e32 v87, v70, v88
	v_min_u32_e32 v88, v70, v88
	v_max_u32_e32 v70, v92, v110
	v_min_u32_e32 v110, v92, v110
	v_max_u32_e32 v92, v116, v102
	v_min_u32_e32 v102, v116, v102
	v_max_u32_e32 v116, v81, v111
	v_min_u32_e32 v111, v81, v111
	v_max_u32_e32 v81, v96, v95
	v_min_u32_e32 v95, v96, v95
	v_max_u32_e32 v96, v113, v91
	v_min_u32_e32 v91, v113, v91
	v_max_u32_e32 v113, v94, v98
	v_min_u32_e32 v98, v94, v98
	v_max_u32_e32 v94, v89, v87
	v_min_u32_e32 v87, v89, v87
	v_max_u32_e32 v89, v85, v88
	v_min_u32_e32 v88, v85, v88
	v_max_u32_e32 v85, v70, v92
	v_min_u32_e32 v92, v70, v92
	v_max_u32_e32 v70, v110, v102
	v_min_u32_e32 v102, v110, v102
	v_max_u32_e32 v110, v116, v81
	v_min_u32_e32 v81, v116, v81
	v_max_u32_e32 v116, v111, v95
	v_min_u32_e32 v95, v111, v95
	v_max_u32_e32 v111, v96, v113
	v_min_u32_e32 v113, v96, v113
	v_max_u32_e32 v96, v91, v98
	v_min_u32_e32 v98, v91, v98
	v_max_u32_e32 v91, v112, v98
	v_max_u32_e32 v112, v97, v96
	v_max_u32_e32 v97, v109, v113
	v_max_u32_e32 v109, v114, v111
	v_max_u32_e32 v114, v101, v95
	v_max_u32_e32 v101, v86, v116
	v_max_u32_e32 v86, v100, v81
	v_max_u32_e32 v100, v105, v110
	v_max_u32_e32 v105, v104, v102
	v_max_u32_e32 v104, v90, v70
	v_max_u32_e32 v90, v115, v92
	v_max_u32_e32 v115, v106, v85
	v_max_u32_e32 v106, v107, v88
	v_max_u32_e32 v107, v108, v89
	v_max_u32_e32 v108, v103, v87
	v_max_u32_e32 v103, v117, v94
	v_max_u32_e32 v98, v91, v105
	v_min_u32_e32 v105, v91, v105
	v_max_u32_e32 v91, v112, v104
	v_min_u32_e32 v104, v112, v104
	v_max_u32_e32 v112, v97, v90
	v_min_u32_e32 v90, v97, v90
	v_max_u32_e32 v97, v109, v115
	v_min_u32_e32 v115, v109, v115
	v_max_u32_e32 v109, v114, v106
	v_min_u32_e32 v106, v114, v106
	v_max_u32_e32 v114, v101, v107
	v_min_u32_e32 v107, v101, v107
	v_max_u32_e32 v101, v86, v108
	v_min_u32_e32 v108, v86, v108
	v_max_u32_e32 v86, v100, v103
	v_min_u32_e32 v103, v100, v103
	v_max_u32_e32 v100, v98, v109
	v_min_u32_e32 v109, v98, v109
	v_max_u32_e32 v98, v91, v114
	v_min_u32_e32 v114, v91, v114
	v_max_u32_e32 v91, v112, v101
	v_min_u32_e32 v101, v112, v101
	v_max_u32_e32 v112, v97, v86
	v_min_u32_e32 v86, v97, v86
	v_max_u32_e32 v97, v105, v106
	v_min_u32_e32 v106, v105, v106
	v_max_u32_e32 v105, v104, v107
	v_min_u32_e32 v107, v104, v107
	v_max_u32_e32 v104, v90, v108
	v_min_u32_e32 v108, v90, v108
	v_max_u32_e32 v90, v115, v103
	v_min_u32_e32 v103, v115, v103
	v_max_u32_e32 v115, v100, v91
	v_min_u32_e32 v91, v100, v91
	v_max_u32_e32 v100, v98, v112
	v_min_u32_e32 v112, v98, v112
	v_max_u32_e32 v98, v109, v101
	v_min_u32_e32 v101, v109, v101
	v_max_u32_e32 v109, v114, v86
	v_min_u32_e32 v86, v114, v86
	v_max_u32_e32 v114, v97, v104
	v_min_u32_e32 v104, v97, v104
	v_max_u32_e32 v97, v105, v90
	v_min_u32_e32 v90, v105, v90
	v_max_u32_e32 v105, v106, v108
	v_min_u32_e32 v108, v106, v108
	v_max_u32_e32 v106, v107, v103
	v_min_u32_e32 v103, v107, v103
	v_max_u32_e32 v107, v115, v100
	v_min_u32_e32 v100, v115, v100
	v_max_u32_e32 v115, v91, v112
	v_min_u32_e32 v112, v91, v112
	v_max_u32_e32 v91, v98, v109
	v_min_u32_e32 v109, v98, v109
	v_max_u32_e32 v98, v101, v86
	v_min_u32_e32 v86, v101, v86
	v_max_u32_e32 v101, v114, v97
	v_min_u32_e32 v97, v114, v97
	v_max_u32_e32 v114, v104, v90
	v_min_u32_e32 v90, v104, v90
	v_max_u32_e32 v104, v105, v106
	v_min_u32_e32 v106, v105, v106
	v_max_u32_e32 v105, v108, v103
	v_min_u32_e32 v103, v108, v103
	s_waitcnt vmcnt(7)
	v_mfma_f32_32x32x16_bf16 v[128:143], v[144:147], v[176:179], 0
	s_waitcnt vmcnt(6)
; #define MFMA32(a, b, c) __builtin_amdgcn_mfma_f32_32x32x16_bf16((a), (b), (c), 0, 0, 0)
; DI int crow(int i, int hh) { return (i & 3) + 8 * (i >> 2) + 4 * hh; }
; DI unsigned f2ord(float f) {
;   unsigned u = __float_as_uint(f);
;   return (u & 0x80000000u) ? ~u : (u | 0x80000000u);
; }
; DI void peer_top16(const u16* __restrict__ PQrow, const u16* __restrict__ SK, unsigned (&top)[16], int lr, int hh) {
;     ...
;   for (int kt = 0; kt < 4; ++kt) {
;     f32x16 acc;
; #pragma unroll
;     for (int e = 0; e < 16; ++e) acc[e] = 0.f;
; #pragma unroll
;     for (int ks = 0; ks < 8; ++ks) {
;       bf16x8 a = *(const bf16x8*)(SK + (size_t)(kt * 32 + lr) * 128 + ks * 16 + hh * 8);
;       acc = MFMA32(a, qf[ks], acc);
;     }
; #pragma unroll
;     for (int e = 0; e < 16; ++e) {
;       int kidx = kt * 32 + crow(e, hh);
;       g[kt][e] = (f2ord(acc[e]) & ~127u) | (unsigned)(127 - kidx);
;     }
;     bitonic_sort_desc<4>(g[kt]);
	v_mfma_f32_32x32x16_bf16 v[128:143], v[148:151], v[180:183], v[128:143]
	s_waitcnt vmcnt(5)
	v_mfma_f32_32x32x16_bf16 v[128:143], v[152:155], v[184:187], v[128:143]
	s_waitcnt vmcnt(4)
	v_mfma_f32_32x32x16_bf16 v[128:143], v[156:159], v[188:191], v[128:143]
	s_waitcnt vmcnt(3)
	v_mfma_f32_32x32x16_bf16 v[128:143], v[160:163], v[192:195], v[128:143]
	s_waitcnt vmcnt(2)
	v_mfma_f32_32x32x16_bf16 v[128:143], v[164:167], v[196:199], v[128:143]
	s_waitcnt vmcnt(1)
	v_mfma_f32_32x32x16_bf16 v[128:143], v[168:171], v[200:203], v[128:143]
	s_waitcnt vmcnt(0)
	v_mfma_f32_32x32x16_bf16 v[128:143], v[172:175], v[204:207], v[128:143]
	s_add_u32 s4, s0, 57344
	s_addc_u32 s5, s1, 0
	global_load_dwordx4 v[144:147], v238, s[4:5] offset:0
	global_load_dwordx4 v[148:151], v238, s[4:5] offset:1024
	global_load_dwordx4 v[152:155], v238, s[4:5] offset:2048
	global_load_dwordx4 v[156:159], v238, s[4:5] offset:3072
	global_load_dwordx4 v[160:163], v208, s[4:5] offset:0
	global_load_dwordx4 v[164:167], v208, s[4:5] offset:1024
	global_load_dwordx4 v[168:171], v208, s[4:5] offset:2048
	global_load_dwordx4 v[172:175], v208, s[4:5] offset:3072
	s_nop 7
	s_nop 3
	v_ashrrev_i32_e32 v230, 31, v128
	v_or_b32_e32 v230, 0x80000000, v230
	v_xor_b32_e32 v229, v230, v128
	v_and_b32_e32 v229, 0xffffff80, v229
	v_or_b32_e32 v108, v229, v213
	v_ashrrev_i32_e32 v230, 31, v129
	v_or_b32_e32 v230, 0x80000000, v230
	v_xor_b32_e32 v229, v230, v129
	v_and_b32_e32 v229, 0xffffff80, v229
	v_or_b32_e32 v96, v229, v214
	v_ashrrev_i32_e32 v230, 31, v130
	v_or_b32_e32 v230, 0x80000000, v230
	v_xor_b32_e32 v229, v230, v130
	v_and_b32_e32 v229, 0xffffff80, v229
	v_or_b32_e32 v113, v229, v215
	v_ashrrev_i32_e32 v230, 31, v131
	v_or_b32_e32 v230, 0x80000000, v230
	v_xor_b32_e32 v229, v230, v131
	v_and_b32_e32 v229, 0xffffff80, v229
	v_or_b32_e32 v111, v229, v216
	v_ashrrev_i32_e32 v230, 31, v132
	v_or_b32_e32 v230, 0x80000000, v230
	v_xor_b32_e32 v229, v230, v132
	v_and_b32_e32 v229, 0xffffff80, v229
	v_or_b32_e32 v95, v229, v217
	v_ashrrev_i32_e32 v230, 31, v133
	v_or_b32_e32 v230, 0x80000000, v230
	v_xor_b32_e32 v229, v230, v133
	v_and_b32_e32 v229, 0xffffff80, v229
	v_or_b32_e32 v116, v229, v218
	v_ashrrev_i32_e32 v230, 31, v134
	v_or_b32_e32 v230, 0x80000000, v230
	v_xor_b32_e32 v229, v230, v134
	v_and_b32_e32 v229, 0xffffff80, v229
	v_or_b32_e32 v81, v229, v219
	v_ashrrev_i32_e32 v230, 31, v135
	v_or_b32_e32 v230, 0x80000000, v230
	v_xor_b32_e32 v229, v230, v135
	v_and_b32_e32 v229, 0xffffff80, v229
	v_or_b32_e32 v110, v229, v220
	v_ashrrev_i32_e32 v230, 31, v136
	v_or_b32_e32 v230, 0x80000000, v230
	v_xor_b32_e32 v229, v230, v136
	v_and_b32_e32 v229, 0xffffff80, v229
	v_or_b32_e32 v102, v229, v221
	v_ashrrev_i32_e32 v230, 31, v137
	v_or_b32_e32 v230, 0x80000000, v230
	v_xor_b32_e32 v229, v230, v137
	v_and_b32_e32 v229, 0xffffff80, v229
	v_or_b32_e32 v70, v229, v222
	v_ashrrev_i32_e32 v230, 31, v138
	v_or_b32_e32 v230, 0x80000000, v230
	v_xor_b32_e32 v229, v230, v138
	v_and_b32_e32 v229, 0xffffff80, v229
	v_or_b32_e32 v92, v229, v223
	v_ashrrev_i32_e32 v230, 31, v139
	v_or_b32_e32 v230, 0x80000000, v230
	v_xor_b32_e32 v229, v230, v139
	v_and_b32_e32 v229, 0xffffff80, v229
	v_or_b32_e32 v85, v229, v224
	v_ashrrev_i32_e32 v230, 31, v140
	v_or_b32_e32 v230, 0x80000000, v230
	v_xor_b32_e32 v229, v230, v140
	v_and_b32_e32 v229, 0xffffff80, v229
	v_or_b32_e32 v88, v229, v225
	v_ashrrev_i32_e32 v230, 31, v141
	v_or_b32_e32 v230, 0x80000000, v230
	v_xor_b32_e32 v229, v230, v141
	v_and_b32_e32 v229, 0xffffff80, v229
	v_or_b32_e32 v89, v229, v226
	v_ashrrev_i32_e32 v230, 31, v142
	v_or_b32_e32 v230, 0x80000000, v230
	v_xor_b32_e32 v229, v230, v142
	v_and_b32_e32 v229, 0xffffff80, v229
	v_or_b32_e32 v87, v229, v227
	v_ashrrev_i32_e32 v230, 31, v143
	v_or_b32_e32 v230, 0x80000000, v230
	v_xor_b32_e32 v229, v230, v143
	v_and_b32_e32 v229, 0xffffff80, v229
	v_or_b32_e32 v94, v229, v228
	v_subrev_u32_e32 v213, 32, v213
	v_subrev_u32_e32 v214, 32, v214
	v_subrev_u32_e32 v215, 32, v215
	v_subrev_u32_e32 v216, 32, v216
	v_subrev_u32_e32 v217, 32, v217
	v_subrev_u32_e32 v218, 32, v218
	v_subrev_u32_e32 v219, 32, v219
	v_subrev_u32_e32 v220, 32, v220
	v_subrev_u32_e32 v221, 32, v221
	v_subrev_u32_e32 v222, 32, v222
	v_subrev_u32_e32 v223, 32, v223
	v_subrev_u32_e32 v224, 32, v224
	v_subrev_u32_e32 v225, 32, v225
	v_subrev_u32_e32 v226, 32, v226
	v_subrev_u32_e32 v227, 32, v227
	v_subrev_u32_e32 v228, 32, v228
	v_max_u32_e32 v117, v108, v96
	v_min_u32_e32 v96, v108, v96
	v_min_u32_e32 v108, v113, v111
	v_max_u32_e32 v111, v113, v111
	v_max_u32_e32 v113, v95, v116
	v_min_u32_e32 v116, v95, v116
	v_min_u32_e32 v95, v81, v110
	v_max_u32_e32 v110, v81, v110
	v_max_u32_e32 v81, v102, v70
	v_min_u32_e32 v70, v102, v70
	v_min_u32_e32 v102, v92, v85
	v_max_u32_e32 v85, v92, v85
	v_max_u32_e32 v92, v88, v89
	v_min_u32_e32 v89, v88, v89
	v_min_u32_e32 v88, v87, v94
	v_max_u32_e32 v94, v87, v94
	v_max_u32_e32 v87, v117, v108
	v_min_u32_e32 v108, v117, v108
	v_max_u32_e32 v117, v96, v111
	v_min_u32_e32 v111, v96, v111
	v_min_u32_e32 v96, v113, v95
	v_max_u32_e32 v95, v113, v95
	v_min_u32_e32 v113, v116, v110
	v_max_u32_e32 v110, v116, v110
	v_max_u32_e32 v116, v81, v102
	v_min_u32_e32 v102, v81, v102
	v_max_u32_e32 v81, v70, v85
	v_min_u32_e32 v85, v70, v85
	v_min_u32_e32 v70, v92, v88
	v_max_u32_e32 v88, v92, v88
	v_min_u32_e32 v92, v89, v94
	v_max_u32_e32 v94, v89, v94
	v_max_u32_e32 v89, v87, v117
	v_min_u32_e32 v117, v87, v117
	v_max_u32_e32 v87, v108, v111
	v_min_u32_e32 v111, v108, v111
	v_min_u32_e32 v108, v96, v113
	v_max_u32_e32 v113, v96, v113
	v_min_u32_e32 v96, v95, v110
	v_max_u32_e32 v110, v95, v110
; #define MFMA32(a, b, c) __builtin_amdgcn_mfma_f32_32x32x16_bf16((a), (b), (c), 0, 0, 0)
; template <int LOGN>
; DI void bitonic_sort_desc(unsigned (&a)[1 << LOGN]) {
;   constexpr int N = 1 << LOGN;
; #pragma unroll
;   for (int ks = 1; ks <= LOGN; ++ks)
; #pragma unroll
;     ...
; #pragma unroll
;       for (int i = 0; i < N; ++i) {
;         const int k = 1 << ks, j = 1 << js, l = i ^ j;
;         if (l > i) {
;           const bool desc = ((i & k) == 0) || (ks == LOGN);
;           const unsigned x = a[i], y = a[l];
;           const unsigned hi = max(x, y), lo = min(x, y);
;           a[i] = desc ? hi : lo;
;           a[l] = desc ? lo : hi;
;         }
;       }
; }
; DI void peer_top16(const u16* __restrict__ PQrow, const u16* __restrict__ SK, unsigned (&top)[16], int lr, int hh) {
;     ...
;   for (int kt = 0; kt < 4; ++kt) {
;     f32x16 acc;
; #pragma unroll
;     for (int e = 0; e < 16; ++e) acc[e] = 0.f;
; #pragma unroll
;     for (int ks = 0; ks < 8; ++ks) {
;       bf16x8 a = *(const bf16x8*)(SK + (size_t)(kt * 32 + lr) * 128 + ks * 16 + hh * 8);
;       acc = MFMA32(a, qf[ks], acc);
;     }
	v_max_u32_e32 v95, v116, v81
	v_min_u32_e32 v81, v116, v81
	v_max_u32_e32 v116, v102, v85
	v_min_u32_e32 v85, v102, v85
	v_min_u32_e32 v102, v70, v92
	v_max_u32_e32 v92, v70, v92
	v_min_u32_e32 v70, v88, v94
	v_max_u32_e32 v94, v88, v94
	v_max_u32_e32 v88, v89, v108
	v_min_u32_e32 v108, v89, v108
	v_max_u32_e32 v89, v117, v113
	v_min_u32_e32 v113, v117, v113
	v_max_u32_e32 v117, v87, v96
	v_min_u32_e32 v96, v87, v96
	v_max_u32_e32 v87, v111, v110
	v_min_u32_e32 v110, v111, v110
	v_min_u32_e32 v111, v95, v102
	v_max_u32_e32 v102, v95, v102
	v_min_u32_e32 v95, v81, v92
	v_max_u32_e32 v92, v81, v92
	v_min_u32_e32 v81, v116, v70
	v_max_u32_e32 v70, v116, v70
	v_min_u32_e32 v116, v85, v94
	v_max_u32_e32 v94, v85, v94
	v_max_u32_e32 v85, v88, v117
	v_min_u32_e32 v117, v88, v117
	v_max_u32_e32 v88, v89, v87
	v_min_u32_e32 v87, v89, v87
	v_max_u32_e32 v89, v108, v96
	v_min_u32_e32 v96, v108, v96
	v_max_u32_e32 v108, v113, v110
	v_min_u32_e32 v110, v113, v110
	v_min_u32_e32 v113, v111, v81
	v_max_u32_e32 v81, v111, v81
	v_min_u32_e32 v111, v95, v116
	v_max_u32_e32 v116, v95, v116
	v_min_u32_e32 v95, v102, v70
	v_max_u32_e32 v70, v102, v70
	v_min_u32_e32 v102, v92, v94
	v_max_u32_e32 v94, v92, v94
	v_max_u32_e32 v92, v85, v88
	v_min_u32_e32 v88, v85, v88
	v_max_u32_e32 v85, v117, v87
	v_min_u32_e32 v87, v117, v87
	v_max_u32_e32 v117, v89, v108
	v_min_u32_e32 v108, v89, v108
	v_max_u32_e32 v89, v96, v110
	v_min_u32_e32 v110, v96, v110
	v_min_u32_e32 v96, v113, v111
	v_max_u32_e32 v111, v113, v111
	v_min_u32_e32 v113, v81, v116
	v_max_u32_e32 v116, v81, v116
	v_min_u32_e32 v81, v95, v102
	v_max_u32_e32 v102, v95, v102
	v_min_u32_e32 v95, v70, v94
	v_max_u32_e32 v94, v70, v94
	v_max_u32_e32 v70, v92, v96
	v_min_u32_e32 v96, v92, v96
	v_max_u32_e32 v92, v88, v111
	v_min_u32_e32 v111, v88, v111
	v_max_u32_e32 v88, v85, v113
	v_min_u32_e32 v113, v85, v113
	v_max_u32_e32 v85, v87, v116
	v_min_u32_e32 v116, v87, v116
	v_max_u32_e32 v87, v117, v81
	v_min_u32_e32 v81, v117, v81
	v_max_u32_e32 v117, v108, v102
	v_min_u32_e32 v102, v108, v102
	v_max_u32_e32 v108, v89, v95
	v_min_u32_e32 v95, v89, v95
	v_max_u32_e32 v89, v110, v94
	v_min_u32_e32 v94, v110, v94
	v_max_u32_e32 v110, v70, v87
	v_min_u32_e32 v87, v70, v87
	v_max_u32_e32 v70, v92, v117
	v_min_u32_e32 v117, v92, v117
	v_max_u32_e32 v92, v88, v108
	v_min_u32_e32 v108, v88, v108
	v_max_u32_e32 v88, v85, v89
	v_min_u32_e32 v89, v85, v89
	v_max_u32_e32 v85, v96, v81
	v_min_u32_e32 v81, v96, v81
	v_max_u32_e32 v96, v111, v102
	v_min_u32_e32 v102, v111, v102
	v_max_u32_e32 v111, v113, v95
	v_min_u32_e32 v95, v113, v95
	v_max_u32_e32 v113, v116, v94
	v_min_u32_e32 v94, v116, v94
	v_max_u32_e32 v116, v110, v92
	v_min_u32_e32 v92, v110, v92
	v_max_u32_e32 v110, v70, v88
	v_min_u32_e32 v88, v70, v88
	v_max_u32_e32 v70, v87, v108
	v_min_u32_e32 v108, v87, v108
	v_max_u32_e32 v87, v117, v89
	v_min_u32_e32 v89, v117, v89
	v_max_u32_e32 v117, v85, v111
	v_min_u32_e32 v111, v85, v111
	v_max_u32_e32 v85, v96, v113
	v_min_u32_e32 v113, v96, v113
	v_max_u32_e32 v96, v81, v95
	v_min_u32_e32 v95, v81, v95
	v_max_u32_e32 v81, v102, v94
	v_min_u32_e32 v94, v102, v94
	v_max_u32_e32 v102, v116, v110
	v_min_u32_e32 v110, v116, v110
	v_max_u32_e32 v116, v92, v88
	v_min_u32_e32 v88, v92, v88
	v_max_u32_e32 v92, v70, v87
	v_min_u32_e32 v87, v70, v87
	v_max_u32_e32 v70, v108, v89
	v_min_u32_e32 v89, v108, v89
	v_max_u32_e32 v108, v117, v85
	v_min_u32_e32 v85, v117, v85
	v_max_u32_e32 v117, v111, v113
	v_min_u32_e32 v113, v111, v113
	v_max_u32_e32 v111, v96, v81
	v_min_u32_e32 v81, v96, v81
	v_max_u32_e32 v96, v95, v94
	v_min_u32_e32 v94, v95, v94
	s_waitcnt vmcnt(7)
	v_mfma_f32_32x32x16_bf16 v[128:143], v[144:147], v[176:179], 0
	s_waitcnt vmcnt(6)
	v_mfma_f32_32x32x16_bf16 v[128:143], v[148:151], v[180:183], v[128:143]
	s_waitcnt vmcnt(5)
	v_mfma_f32_32x32x16_bf16 v[128:143], v[152:155], v[184:187], v[128:143]
	s_waitcnt vmcnt(4)
	v_mfma_f32_32x32x16_bf16 v[128:143], v[156:159], v[188:191], v[128:143]
	s_waitcnt vmcnt(3)
	v_mfma_f32_32x32x16_bf16 v[128:143], v[160:163], v[192:195], v[128:143]
	s_waitcnt vmcnt(2)
	v_mfma_f32_32x32x16_bf16 v[128:143], v[164:167], v[196:199], v[128:143]
	s_waitcnt vmcnt(1)
	v_mfma_f32_32x32x16_bf16 v[128:143], v[168:171], v[200:203], v[128:143]
	s_waitcnt vmcnt(0)
; #define MFMA32(a, b, c) __builtin_amdgcn_mfma_f32_32x32x16_bf16((a), (b), (c), 0, 0, 0)
; DI int crow(int i, int hh) { return (i & 3) + 8 * (i >> 2) + 4 * hh; }
; DI unsigned f2ord(float f) {
;   unsigned u = __float_as_uint(f);
;   return (u & 0x80000000u) ? ~u : (u | 0x80000000u);
; }
; DI void peer_top16(const u16* __restrict__ PQrow, const u16* __restrict__ SK, unsigned (&top)[16], int lr, int hh) {
;   bf16x8 qf[8];
; #pragma unroll
;   for (int ks = 0; ks < 8; ++ks) qf[ks] = *(const bf16x8*)(PQrow + ks * 16 + hh * 8);
;   unsigned g[4][16];
; #pragma unroll
;   for (int kt = 0; kt < 4; ++kt) {
;     f32x16 acc;
; #pragma unroll
;     for (int e = 0; e < 16; ++e) acc[e] = 0.f;
; #pragma unroll
;     for (int ks = 0; ks < 8; ++ks) {
;       bf16x8 a = *(const bf16x8*)(SK + (size_t)(kt * 32 + lr) * 128 + ks * 16 + hh * 8);
;       acc = MFMA32(a, qf[ks], acc);
;     }
; #pragma unroll
;     for (int e = 0; e < 16; ++e) {
;       int kidx = kt * 32 + crow(e, hh);
;       g[kt][e] = (f2ord(acc[e]) & ~127u) | (unsigned)(127 - kidx);
;     }
;     bitonic_sort_desc<4>(g[kt]);
	v_mfma_f32_32x32x16_bf16 v[128:143], v[172:175], v[204:207], v[128:143]
	global_load_dwordx4 v[176:179], v239, s[2:3] offset:512
	global_load_dwordx4 v[180:183], v239, s[2:3] offset:544
	global_load_dwordx4 v[184:187], v239, s[2:3] offset:576
	global_load_dwordx4 v[188:191], v239, s[2:3] offset:608
	global_load_dwordx4 v[192:195], v239, s[2:3] offset:640
	global_load_dwordx4 v[196:199], v239, s[2:3] offset:672
	global_load_dwordx4 v[200:203], v239, s[2:3] offset:704
	global_load_dwordx4 v[204:207], v239, s[2:3] offset:736
	s_add_u32 s4, s0, 65536
	s_addc_u32 s5, s1, 0
	global_load_dwordx4 v[144:147], v238, s[4:5] offset:0
	global_load_dwordx4 v[148:151], v238, s[4:5] offset:1024
	global_load_dwordx4 v[152:155], v238, s[4:5] offset:2048
	global_load_dwordx4 v[156:159], v238, s[4:5] offset:3072
	global_load_dwordx4 v[160:163], v208, s[4:5] offset:0
	global_load_dwordx4 v[164:167], v208, s[4:5] offset:1024
	global_load_dwordx4 v[168:171], v208, s[4:5] offset:2048
	global_load_dwordx4 v[172:175], v208, s[4:5] offset:3072
	s_nop 7
	s_nop 3
	v_ashrrev_i32_e32 v230, 31, v128
	v_or_b32_e32 v230, 0x80000000, v230
	v_xor_b32_e32 v229, v230, v128
	v_and_b32_e32 v229, 0xffffff80, v229
	v_or_b32_e32 v95, v229, v213
	v_ashrrev_i32_e32 v230, 31, v129
	v_or_b32_e32 v230, 0x80000000, v230
	v_xor_b32_e32 v229, v230, v129
	v_and_b32_e32 v229, 0xffffff80, v229
	v_or_b32_e32 v84, v229, v214
	v_ashrrev_i32_e32 v230, 31, v130
	v_or_b32_e32 v230, 0x80000000, v230
	v_xor_b32_e32 v229, v230, v130
	v_and_b32_e32 v229, 0xffffff80, v229
	v_or_b32_e32 v79, v229, v215
	v_ashrrev_i32_e32 v230, 31, v131
	v_or_b32_e32 v230, 0x80000000, v230
	v_xor_b32_e32 v229, v230, v131
	v_and_b32_e32 v229, 0xffffff80, v229
	v_or_b32_e32 v82, v229, v216
	v_ashrrev_i32_e32 v230, 31, v132
	v_or_b32_e32 v230, 0x80000000, v230
	v_xor_b32_e32 v229, v230, v132
	v_and_b32_e32 v229, 0xffffff80, v229
	v_or_b32_e32 v83, v229, v217
	v_ashrrev_i32_e32 v230, 31, v133
	v_or_b32_e32 v230, 0x80000000, v230
	v_xor_b32_e32 v229, v230, v133
	v_and_b32_e32 v229, 0xffffff80, v229
	v_or_b32_e32 v69, v229, v218
	v_ashrrev_i32_e32 v230, 31, v134
	v_or_b32_e32 v230, 0x80000000, v230
	v_xor_b32_e32 v229, v230, v134
	v_and_b32_e32 v229, 0xffffff80, v229
	v_or_b32_e32 v74, v229, v219
	v_ashrrev_i32_e32 v230, 31, v135
	v_or_b32_e32 v230, 0x80000000, v230
	v_xor_b32_e32 v229, v230, v135
	v_and_b32_e32 v229, 0xffffff80, v229
	v_or_b32_e32 v99, v229, v220
	v_ashrrev_i32_e32 v230, 31, v136
	v_or_b32_e32 v230, 0x80000000, v230
	v_xor_b32_e32 v229, v230, v136
	v_and_b32_e32 v229, 0xffffff80, v229
	v_or_b32_e32 v72, v229, v221
	v_ashrrev_i32_e32 v230, 31, v137
	v_or_b32_e32 v230, 0x80000000, v230
	v_xor_b32_e32 v229, v230, v137
	v_and_b32_e32 v229, 0xffffff80, v229
	v_or_b32_e32 v76, v229, v222
	v_ashrrev_i32_e32 v230, 31, v138
	v_or_b32_e32 v230, 0x80000000, v230
	v_xor_b32_e32 v229, v230, v138
	v_and_b32_e32 v229, 0xffffff80, v229
	v_or_b32_e32 v71, v229, v223
	v_ashrrev_i32_e32 v230, 31, v139
	v_or_b32_e32 v230, 0x80000000, v230
	v_xor_b32_e32 v229, v230, v139
	v_and_b32_e32 v229, 0xffffff80, v229
	v_or_b32_e32 v75, v229, v224
	v_ashrrev_i32_e32 v230, 31, v140
	v_or_b32_e32 v230, 0x80000000, v230
	v_xor_b32_e32 v229, v230, v140
	v_and_b32_e32 v229, 0xffffff80, v229
	v_or_b32_e32 v73, v229, v225
	v_ashrrev_i32_e32 v230, 31, v141
	v_or_b32_e32 v230, 0x80000000, v230
	v_xor_b32_e32 v229, v230, v141
	v_and_b32_e32 v229, 0xffffff80, v229
	v_or_b32_e32 v80, v229, v226
	v_ashrrev_i32_e32 v230, 31, v142
	v_or_b32_e32 v230, 0x80000000, v230
	v_xor_b32_e32 v229, v230, v142
	v_and_b32_e32 v229, 0xffffff80, v229
	v_or_b32_e32 v78, v229, v227
	v_ashrrev_i32_e32 v230, 31, v143
	v_or_b32_e32 v230, 0x80000000, v230
	v_xor_b32_e32 v229, v230, v143
	v_and_b32_e32 v229, 0xffffff80, v229
	v_or_b32_e32 v77, v229, v228
	v_max_u32_e32 v93, v95, v84
	v_min_u32_e32 v84, v95, v84
	v_min_u32_e32 v95, v79, v82
	v_max_u32_e32 v82, v79, v82
	v_max_u32_e32 v79, v83, v69
	v_min_u32_e32 v69, v83, v69
	v_min_u32_e32 v83, v74, v99
	v_max_u32_e32 v99, v74, v99
	v_max_u32_e32 v74, v72, v76
	v_min_u32_e32 v76, v72, v76
	v_min_u32_e32 v72, v71, v75
	v_max_u32_e32 v75, v71, v75
	v_max_u32_e32 v71, v73, v80
	v_min_u32_e32 v80, v73, v80
	v_min_u32_e32 v73, v78, v77
	v_max_u32_e32 v77, v78, v77
	v_max_u32_e32 v78, v93, v95
	v_min_u32_e32 v95, v93, v95
	v_max_u32_e32 v93, v84, v82
	v_min_u32_e32 v82, v84, v82
	v_min_u32_e32 v84, v79, v83
	v_max_u32_e32 v83, v79, v83
	v_min_u32_e32 v79, v69, v99
	v_max_u32_e32 v99, v69, v99
	v_max_u32_e32 v69, v74, v72
	v_min_u32_e32 v72, v74, v72
	v_max_u32_e32 v74, v76, v75
	v_min_u32_e32 v75, v76, v75
	v_min_u32_e32 v76, v71, v73
	v_max_u32_e32 v73, v71, v73
	v_min_u32_e32 v71, v80, v77
	v_max_u32_e32 v77, v80, v77
	v_max_u32_e32 v80, v78, v93
	v_min_u32_e32 v93, v78, v93
	v_max_u32_e32 v78, v95, v82
	v_min_u32_e32 v82, v95, v82
	v_min_u32_e32 v95, v84, v79
	v_max_u32_e32 v79, v84, v79
	v_min_u32_e32 v84, v83, v99
	v_max_u32_e32 v99, v83, v99
	v_max_u32_e32 v83, v69, v74
	v_min_u32_e32 v74, v69, v74
	v_max_u32_e32 v69, v72, v75
	v_min_u32_e32 v75, v72, v75
	v_min_u32_e32 v72, v76, v71
	v_max_u32_e32 v71, v76, v71
	v_min_u32_e32 v76, v73, v77
	v_max_u32_e32 v77, v73, v77
	v_max_u32_e32 v73, v80, v95
	v_min_u32_e32 v95, v80, v95
	v_max_u32_e32 v80, v93, v79
	v_min_u32_e32 v79, v93, v79
	v_max_u32_e32 v93, v78, v84
	v_min_u32_e32 v84, v78, v84
	v_max_u32_e32 v78, v82, v99
	v_min_u32_e32 v99, v82, v99
	v_min_u32_e32 v82, v83, v72
	v_max_u32_e32 v72, v83, v72
	v_min_u32_e32 v83, v74, v71
	v_max_u32_e32 v71, v74, v71
	v_min_u32_e32 v74, v69, v76
	v_max_u32_e32 v76, v69, v76
	v_min_u32_e32 v69, v75, v77
	v_max_u32_e32 v77, v75, v77
; template <int LOGN>
; DI void bitonic_sort_desc(unsigned (&a)[1 << LOGN]) {
;   constexpr int N = 1 << LOGN;
; #pragma unroll
;   for (int ks = 1; ks <= LOGN; ++ks)
; #pragma unroll
;     ...
; #pragma unroll
;       for (int i = 0; i < N; ++i) {
;         const int k = 1 << ks, j = 1 << js, l = i ^ j;
;         if (l > i) {
;           const bool desc = ((i & k) == 0) || (ks == LOGN);
;           const unsigned x = a[i], y = a[l];
;           const unsigned hi = max(x, y), lo = min(x, y);
;           a[i] = desc ? hi : lo;
;           a[l] = desc ? lo : hi;
;         }
;       }
; }
; DI void merge_top16(unsigned (&a)[16], const unsigned (&b)[16]) {
; #pragma unroll
;   for (int i = 0; i < 16; ++i) a[i] = max(a[i], b[15 - i]);
; #pragma unroll
;     ...
; #pragma unroll
;     for (int i = 0; i < 16; ++i) {
;       const int j = 1 << js, l = i ^ j;
;       if (l > i) {
;         const unsigned x = a[i], y = a[l];
;         a[i] = max(x, y);
;         a[l] = min(x, y);
;       }
;     }
; }
	v_max_u32_e32 v75, v73, v93
	v_min_u32_e32 v93, v73, v93
	v_max_u32_e32 v73, v80, v78
	v_min_u32_e32 v78, v80, v78
	v_max_u32_e32 v80, v95, v84
	v_min_u32_e32 v84, v95, v84
	v_max_u32_e32 v95, v79, v99
	v_min_u32_e32 v99, v79, v99
	v_min_u32_e32 v79, v82, v74
	v_max_u32_e32 v74, v82, v74
	v_min_u32_e32 v82, v83, v69
	v_max_u32_e32 v69, v83, v69
	v_min_u32_e32 v83, v72, v76
	v_max_u32_e32 v76, v72, v76
	v_min_u32_e32 v72, v71, v77
	v_max_u32_e32 v77, v71, v77
	v_max_u32_e32 v71, v75, v73
	v_min_u32_e32 v73, v75, v73
	v_max_u32_e32 v75, v93, v78
	v_min_u32_e32 v78, v93, v78
	v_max_u32_e32 v93, v80, v95
	v_min_u32_e32 v95, v80, v95
	v_max_u32_e32 v80, v84, v99
	v_min_u32_e32 v99, v84, v99
	v_min_u32_e32 v84, v79, v82
	v_max_u32_e32 v82, v79, v82
	v_min_u32_e32 v79, v74, v69
	v_max_u32_e32 v69, v74, v69
	v_min_u32_e32 v74, v83, v72
	v_max_u32_e32 v72, v83, v72
	v_min_u32_e32 v83, v76, v77
	v_max_u32_e32 v77, v76, v77
	v_max_u32_e32 v76, v71, v84
	v_min_u32_e32 v84, v71, v84
	v_max_u32_e32 v71, v73, v82
	v_min_u32_e32 v82, v73, v82
	v_max_u32_e32 v73, v75, v79
	v_min_u32_e32 v79, v75, v79
	v_max_u32_e32 v75, v78, v69
	v_min_u32_e32 v69, v78, v69
	v_max_u32_e32 v78, v93, v74
	v_min_u32_e32 v74, v93, v74
	v_max_u32_e32 v93, v95, v72
	v_min_u32_e32 v72, v95, v72
	v_max_u32_e32 v95, v80, v83
	v_min_u32_e32 v83, v80, v83
	v_max_u32_e32 v80, v99, v77
	v_min_u32_e32 v77, v99, v77
	v_max_u32_e32 v99, v76, v78
	v_min_u32_e32 v78, v76, v78
	v_max_u32_e32 v76, v71, v93
	v_min_u32_e32 v93, v71, v93
	v_max_u32_e32 v71, v73, v95
	v_min_u32_e32 v95, v73, v95
	v_max_u32_e32 v73, v75, v80
	v_min_u32_e32 v80, v75, v80
	v_max_u32_e32 v75, v84, v74
	v_min_u32_e32 v74, v84, v74
	v_max_u32_e32 v84, v82, v72
	v_min_u32_e32 v72, v82, v72
	v_max_u32_e32 v82, v79, v83
	v_min_u32_e32 v83, v79, v83
	v_max_u32_e32 v79, v69, v77
	v_min_u32_e32 v77, v69, v77
	v_max_u32_e32 v69, v99, v71
	v_min_u32_e32 v71, v99, v71
	v_max_u32_e32 v99, v76, v73
	v_min_u32_e32 v73, v76, v73
	v_max_u32_e32 v76, v78, v95
	v_min_u32_e32 v95, v78, v95
	v_max_u32_e32 v78, v93, v80
	v_min_u32_e32 v80, v93, v80
	v_max_u32_e32 v93, v75, v82
	v_min_u32_e32 v82, v75, v82
	v_max_u32_e32 v75, v84, v79
	v_min_u32_e32 v79, v84, v79
	v_max_u32_e32 v84, v74, v83
	v_min_u32_e32 v83, v74, v83
	v_max_u32_e32 v74, v72, v77
	v_min_u32_e32 v77, v72, v77
	v_max_u32_e32 v72, v69, v99
	v_min_u32_e32 v99, v69, v99
	v_max_u32_e32 v69, v71, v73
	v_min_u32_e32 v73, v71, v73
	v_max_u32_e32 v71, v76, v78
	v_min_u32_e32 v78, v76, v78
	v_max_u32_e32 v76, v95, v80
	v_min_u32_e32 v80, v95, v80
	v_max_u32_e32 v95, v93, v75
	v_min_u32_e32 v75, v93, v75
	v_max_u32_e32 v93, v82, v79
	v_min_u32_e32 v79, v82, v79
	v_max_u32_e32 v82, v84, v74
	v_min_u32_e32 v74, v84, v74
	v_max_u32_e32 v84, v83, v77
	v_min_u32_e32 v77, v83, v77
	v_max_u32_e32 v83, v102, v77
	v_max_u32_e32 v102, v110, v84
	v_max_u32_e32 v110, v116, v74
	v_max_u32_e32 v116, v88, v82
	v_max_u32_e32 v88, v92, v79
	v_max_u32_e32 v92, v87, v93
	v_max_u32_e32 v87, v70, v75
	v_max_u32_e32 v70, v89, v95
	v_max_u32_e32 v89, v108, v80
	v_max_u32_e32 v108, v85, v76
	v_max_u32_e32 v85, v117, v78
	v_max_u32_e32 v117, v113, v71
	v_max_u32_e32 v113, v111, v73
	v_max_u32_e32 v111, v81, v69
	v_max_u32_e32 v81, v96, v99
	v_max_u32_e32 v96, v94, v72
	v_max_u32_e32 v77, v83, v89
	v_min_u32_e32 v89, v83, v89
	v_max_u32_e32 v83, v102, v108
	v_min_u32_e32 v108, v102, v108
	v_max_u32_e32 v102, v110, v85
	v_min_u32_e32 v85, v110, v85
	v_max_u32_e32 v110, v116, v117
	v_min_u32_e32 v117, v116, v117
	v_max_u32_e32 v116, v88, v113
	v_min_u32_e32 v113, v88, v113
	v_max_u32_e32 v88, v92, v111
	v_min_u32_e32 v111, v92, v111
	v_max_u32_e32 v92, v87, v81
	v_min_u32_e32 v81, v87, v81
	v_max_u32_e32 v87, v70, v96
	v_min_u32_e32 v96, v70, v96
	v_max_u32_e32 v70, v77, v116
	v_min_u32_e32 v116, v77, v116
	v_max_u32_e32 v77, v83, v88
	v_min_u32_e32 v88, v83, v88
	v_max_u32_e32 v83, v102, v92
	v_min_u32_e32 v92, v102, v92
	v_max_u32_e32 v102, v110, v87
	v_min_u32_e32 v87, v110, v87
	v_max_u32_e32 v110, v89, v113
	v_min_u32_e32 v113, v89, v113
	v_max_u32_e32 v89, v108, v111
	v_min_u32_e32 v111, v108, v111
	v_max_u32_e32 v108, v85, v81
	v_min_u32_e32 v81, v85, v81
	v_max_u32_e32 v85, v117, v96
	v_min_u32_e32 v96, v117, v96
	v_max_u32_e32 v117, v70, v83
	v_min_u32_e32 v83, v70, v83
	v_max_u32_e32 v70, v77, v102
	v_min_u32_e32 v102, v77, v102
	v_max_u32_e32 v77, v116, v92
	v_min_u32_e32 v92, v116, v92
	v_max_u32_e32 v116, v88, v87
	v_min_u32_e32 v87, v88, v87
	v_max_u32_e32 v88, v110, v108
	v_min_u32_e32 v108, v110, v108
	v_max_u32_e32 v110, v89, v85
	v_min_u32_e32 v85, v89, v85
	v_max_u32_e32 v89, v113, v81
	v_min_u32_e32 v81, v113, v81
	v_max_u32_e32 v113, v111, v96
	v_min_u32_e32 v96, v111, v96
	v_max_u32_e32 v111, v117, v70
	v_min_u32_e32 v70, v117, v70
	v_max_u32_e32 v117, v83, v102
	v_min_u32_e32 v102, v83, v102
	v_max_u32_e32 v83, v77, v116
	v_min_u32_e32 v116, v77, v116
	v_max_u32_e32 v77, v92, v87
	v_min_u32_e32 v87, v92, v87
	v_max_u32_e32 v92, v88, v110
	v_min_u32_e32 v110, v88, v110
	v_max_u32_e32 v88, v108, v85
	v_min_u32_e32 v85, v108, v85
	v_max_u32_e32 v108, v89, v113
	v_min_u32_e32 v113, v89, v113
	v_max_u32_e32 v89, v81, v96
	v_min_u32_e32 v96, v81, v96
	v_max_u32_e32 v81, v107, v96
	v_max_u32_e32 v107, v100, v89
	v_max_u32_e32 v100, v115, v113
	v_max_u32_e32 v115, v112, v108
	v_max_u32_e32 v112, v91, v85
	v_max_u32_e32 v91, v109, v88
	v_max_u32_e32 v109, v98, v110
	v_max_u32_e32 v98, v86, v92
	v_max_u32_e32 v86, v101, v87
	v_max_u32_e32 v101, v97, v77
	v_max_u32_e32 v97, v114, v116
	v_max_u32_e32 v114, v90, v83
	v_max_u32_e32 v90, v104, v102
	v_max_u32_e32 v104, v106, v117
; #define MFMA32(a, b, c) __builtin_amdgcn_mfma_f32_32x32x16_bf16((a), (b), (c), 0, 0, 0)
; DI int crow(int i, int hh) { return (i & 3) + 8 * (i >> 2) + 4 * hh; }
; DI unsigned f2ord(float f) {
;   unsigned u = __float_as_uint(f);
;   return (u & 0x80000000u) ? ~u : (u | 0x80000000u);
; }
; DI void merge_top16(unsigned (&a)[16], const unsigned (&b)[16]) {
; #pragma unroll
;   for (int i = 0; i < 16; ++i) a[i] = max(a[i], b[15 - i]);
; #pragma unroll
;     ...
; #pragma unroll
;     for (int i = 0; i < 16; ++i) {
;       const int j = 1 << js, l = i ^ j;
;       if (l > i) {
;         const unsigned x = a[i], y = a[l];
;         a[i] = max(x, y);
;         a[l] = min(x, y);
;       }
;     }
; }
; DI void peer_top16(const u16* __restrict__ PQrow, const u16* __restrict__ SK, unsigned (&top)[16], int lr, int hh) {
;   bf16x8 qf[8];
; #pragma unroll
;   for (int ks = 0; ks < 8; ++ks) qf[ks] = *(const bf16x8*)(PQrow + ks * 16 + hh * 8);
;   unsigned g[4][16];
; #pragma unroll
;   for (int kt = 0; kt < 4; ++kt) {
;     f32x16 acc;
; #pragma unroll
;     for (int e = 0; e < 16; ++e) acc[e] = 0.f;
; #pragma unroll
;     for (int ks = 0; ks < 8; ++ks) {
;       bf16x8 a = *(const bf16x8*)(SK + (size_t)(kt * 32 + lr) * 128 + ks * 16 + hh * 8);
;       acc = MFMA32(a, qf[ks], acc);
;     }
; #pragma unroll
;     for (int e = 0; e < 16; ++e) {
;       int kidx = kt * 32 + crow(e, hh);
;       g[kt][e] = (f2ord(acc[e]) & ~127u) | (unsigned)(127 - kidx);
;     }
;     bitonic_sort_desc<4>(g[kt]);
	v_max_u32_e32 v106, v105, v70
	v_max_u32_e32 v105, v103, v111
	v_max_u32_e32 v96, v81, v86
	v_min_u32_e32 v86, v81, v86
	v_max_u32_e32 v81, v107, v101
	v_min_u32_e32 v101, v107, v101
	v_max_u32_e32 v107, v100, v97
	v_min_u32_e32 v97, v100, v97
	v_max_u32_e32 v100, v115, v114
	v_min_u32_e32 v114, v115, v114
	v_max_u32_e32 v115, v112, v90
	v_min_u32_e32 v90, v112, v90
	v_max_u32_e32 v112, v91, v104
	v_min_u32_e32 v104, v91, v104
	v_max_u32_e32 v91, v109, v106
	v_min_u32_e32 v106, v109, v106
	v_max_u32_e32 v109, v98, v105
	v_min_u32_e32 v105, v98, v105
	v_max_u32_e32 v98, v96, v115
	v_min_u32_e32 v115, v96, v115
	v_max_u32_e32 v96, v81, v112
	v_min_u32_e32 v112, v81, v112
	v_max_u32_e32 v81, v107, v91
	v_min_u32_e32 v91, v107, v91
	v_max_u32_e32 v107, v100, v109
	v_min_u32_e32 v109, v100, v109
	v_max_u32_e32 v100, v86, v90
	v_min_u32_e32 v90, v86, v90
	v_max_u32_e32 v86, v101, v104
	v_min_u32_e32 v104, v101, v104
	v_max_u32_e32 v101, v97, v106
	v_min_u32_e32 v106, v97, v106
	v_max_u32_e32 v97, v114, v105
	v_min_u32_e32 v105, v114, v105
	v_max_u32_e32 v114, v98, v81
	v_min_u32_e32 v81, v98, v81
	v_max_u32_e32 v98, v96, v107
	v_min_u32_e32 v107, v96, v107
	v_max_u32_e32 v96, v115, v91
	v_min_u32_e32 v91, v115, v91
	v_max_u32_e32 v115, v112, v109
	v_min_u32_e32 v109, v112, v109
	v_max_u32_e32 v112, v100, v101
	v_min_u32_e32 v101, v100, v101
	v_max_u32_e32 v100, v86, v97
	v_min_u32_e32 v97, v86, v97
	v_max_u32_e32 v86, v90, v106
	v_min_u32_e32 v106, v90, v106
	v_max_u32_e32 v90, v104, v105
	v_min_u32_e32 v105, v104, v105
	v_max_u32_e32 v104, v114, v98
	v_min_u32_e32 v98, v114, v98
	v_max_u32_e32 v114, v81, v107
	v_min_u32_e32 v107, v81, v107
	v_max_u32_e32 v81, v96, v115
	v_min_u32_e32 v115, v96, v115
	v_max_u32_e32 v96, v91, v109
	v_min_u32_e32 v109, v91, v109
	v_max_u32_e32 v91, v112, v100
	v_min_u32_e32 v100, v112, v100
	v_max_u32_e32 v112, v101, v97
	v_min_u32_e32 v97, v101, v97
	v_max_u32_e32 v101, v86, v90
	v_min_u32_e32 v90, v86, v90
	v_max_u32_e32 v86, v106, v105
	v_min_u32_e32 v105, v106, v105
	v_mov_b32_e32 v16, v104
	v_mov_b32_e32 v17, v98
	v_mov_b32_e32 v18, v114
	v_mov_b32_e32 v19, v107
	v_mov_b32_e32 v20, v81
	v_mov_b32_e32 v21, v115
	v_mov_b32_e32 v22, v96
	v_mov_b32_e32 v23, v109
	v_mov_b32_e32 v24, v91
	v_mov_b32_e32 v25, v100
	v_mov_b32_e32 v26, v112
	v_mov_b32_e32 v27, v97
	v_mov_b32_e32 v28, v101
	v_mov_b32_e32 v29, v90
	v_mov_b32_e32 v30, v86
	v_mov_b32_e32 v31, v105
	v_sub_u32_e32 v213, 127, v245
	v_sub_u32_e32 v214, 126, v245
	v_sub_u32_e32 v215, 125, v245
	v_sub_u32_e32 v216, 124, v245
	v_sub_u32_e32 v217, 119, v245
	v_sub_u32_e32 v218, 118, v245
	v_sub_u32_e32 v219, 117, v245
	v_sub_u32_e32 v220, 116, v245
	v_sub_u32_e32 v221, 111, v245
	v_sub_u32_e32 v222, 110, v245
	v_sub_u32_e32 v223, 109, v245
	v_sub_u32_e32 v224, 108, v245
	v_sub_u32_e32 v225, 103, v245
	v_sub_u32_e32 v226, 102, v245
	v_sub_u32_e32 v227, 101, v245
	v_sub_u32_e32 v228, 100, v245
	s_waitcnt vmcnt(7)
	v_mfma_f32_32x32x16_bf16 v[128:143], v[144:147], v[176:179], 0
	s_waitcnt vmcnt(6)
	v_mfma_f32_32x32x16_bf16 v[128:143], v[148:151], v[180:183], v[128:143]
	s_waitcnt vmcnt(5)
	v_mfma_f32_32x32x16_bf16 v[128:143], v[152:155], v[184:187], v[128:143]
	s_waitcnt vmcnt(4)
	v_mfma_f32_32x32x16_bf16 v[128:143], v[156:159], v[188:191], v[128:143]
	s_waitcnt vmcnt(3)
	v_mfma_f32_32x32x16_bf16 v[128:143], v[160:163], v[192:195], v[128:143]
	s_waitcnt vmcnt(2)
	v_mfma_f32_32x32x16_bf16 v[128:143], v[164:167], v[196:199], v[128:143]
	s_waitcnt vmcnt(1)
	v_mfma_f32_32x32x16_bf16 v[128:143], v[168:171], v[200:203], v[128:143]
	s_waitcnt vmcnt(0)
	v_mfma_f32_32x32x16_bf16 v[128:143], v[172:175], v[204:207], v[128:143]
	s_add_u32 s4, s0, 73728
	s_addc_u32 s5, s1, 0
	global_load_dwordx4 v[144:147], v238, s[4:5] offset:0
	global_load_dwordx4 v[148:151], v238, s[4:5] offset:1024
	global_load_dwordx4 v[152:155], v238, s[4:5] offset:2048
	global_load_dwordx4 v[156:159], v238, s[4:5] offset:3072
	global_load_dwordx4 v[160:163], v208, s[4:5] offset:0
	global_load_dwordx4 v[164:167], v208, s[4:5] offset:1024
	global_load_dwordx4 v[168:171], v208, s[4:5] offset:2048
	global_load_dwordx4 v[172:175], v208, s[4:5] offset:3072
	s_nop 7
	s_nop 3
	v_ashrrev_i32_e32 v230, 31, v128
	v_or_b32_e32 v230, 0x80000000, v230
	v_xor_b32_e32 v229, v230, v128
	v_and_b32_e32 v229, 0xffffff80, v229
	v_or_b32_e32 v105, v229, v213
	v_ashrrev_i32_e32 v230, 31, v129
	v_or_b32_e32 v230, 0x80000000, v230
	v_xor_b32_e32 v229, v230, v129
	v_and_b32_e32 v229, 0xffffff80, v229
	v_or_b32_e32 v86, v229, v214
	v_ashrrev_i32_e32 v230, 31, v130
	v_or_b32_e32 v230, 0x80000000, v230
	v_xor_b32_e32 v229, v230, v130
	v_and_b32_e32 v229, 0xffffff80, v229
	v_or_b32_e32 v90, v229, v215
	v_ashrrev_i32_e32 v230, 31, v131
	v_or_b32_e32 v230, 0x80000000, v230
	v_xor_b32_e32 v229, v230, v131
	v_and_b32_e32 v229, 0xffffff80, v229
	v_or_b32_e32 v101, v229, v216
	v_ashrrev_i32_e32 v230, 31, v132
	v_or_b32_e32 v230, 0x80000000, v230
	v_xor_b32_e32 v229, v230, v132
	v_and_b32_e32 v229, 0xffffff80, v229
	v_or_b32_e32 v97, v229, v217
	v_ashrrev_i32_e32 v230, 31, v133
	v_or_b32_e32 v230, 0x80000000, v230
	v_xor_b32_e32 v229, v230, v133
	v_and_b32_e32 v229, 0xffffff80, v229
	v_or_b32_e32 v112, v229, v218
	v_ashrrev_i32_e32 v230, 31, v134
	v_or_b32_e32 v230, 0x80000000, v230
	v_xor_b32_e32 v229, v230, v134
	v_and_b32_e32 v229, 0xffffff80, v229
	v_or_b32_e32 v100, v229, v219
	v_ashrrev_i32_e32 v230, 31, v135
	v_or_b32_e32 v230, 0x80000000, v230
	v_xor_b32_e32 v229, v230, v135
	v_and_b32_e32 v229, 0xffffff80, v229
	v_or_b32_e32 v91, v229, v220
	v_ashrrev_i32_e32 v230, 31, v136
	v_or_b32_e32 v230, 0x80000000, v230
	v_xor_b32_e32 v229, v230, v136
; DI int crow(int i, int hh) { return (i & 3) + 8 * (i >> 2) + 4 * hh; }
; template <int LOGN>
; DI void bitonic_sort_desc(unsigned (&a)[1 << LOGN]) {
;   constexpr int N = 1 << LOGN;
; #pragma unroll
;   for (int ks = 1; ks <= LOGN; ++ks)
; #pragma unroll
;     ...
; #pragma unroll
;       for (int i = 0; i < N; ++i) {
;         const int k = 1 << ks, j = 1 << js, l = i ^ j;
;         if (l > i) {
;           const bool desc = ((i & k) == 0) || (ks == LOGN);
;           const unsigned x = a[i], y = a[l];
;           const unsigned hi = max(x, y), lo = min(x, y);
;           a[i] = desc ? hi : lo;
;           a[l] = desc ? lo : hi;
;         }
;       }
; }
; DI void peer_top16(const u16* __restrict__ PQrow, const u16* __restrict__ SK, unsigned (&top)[16], int lr, int hh) {
;     ...
;     for (int e = 0; e < 16; ++e) {
;       int kidx = kt * 32 + crow(e, hh);
;       g[kt][e] = (f2ord(acc[e]) & ~127u) | (unsigned)(127 - kidx);
;     }
;     bitonic_sort_desc<4>(g[kt]);
	v_and_b32_e32 v229, 0xffffff80, v229
	v_or_b32_e32 v109, v229, v221
	v_ashrrev_i32_e32 v230, 31, v137
	v_or_b32_e32 v230, 0x80000000, v230
	v_xor_b32_e32 v229, v230, v137
	v_and_b32_e32 v229, 0xffffff80, v229
	v_or_b32_e32 v96, v229, v222
	v_ashrrev_i32_e32 v230, 31, v138
	v_or_b32_e32 v230, 0x80000000, v230
	v_xor_b32_e32 v229, v230, v138
	v_and_b32_e32 v229, 0xffffff80, v229
	v_or_b32_e32 v115, v229, v223
	v_ashrrev_i32_e32 v230, 31, v139
	v_or_b32_e32 v230, 0x80000000, v230
	v_xor_b32_e32 v229, v230, v139
	v_and_b32_e32 v229, 0xffffff80, v229
	v_or_b32_e32 v81, v229, v224
	v_ashrrev_i32_e32 v230, 31, v140
	v_or_b32_e32 v230, 0x80000000, v230
	v_xor_b32_e32 v229, v230, v140
	v_and_b32_e32 v229, 0xffffff80, v229
	v_or_b32_e32 v107, v229, v225
	v_ashrrev_i32_e32 v230, 31, v141
	v_or_b32_e32 v230, 0x80000000, v230
	v_xor_b32_e32 v229, v230, v141
	v_and_b32_e32 v229, 0xffffff80, v229
	v_or_b32_e32 v114, v229, v226
	v_ashrrev_i32_e32 v230, 31, v142
	v_or_b32_e32 v230, 0x80000000, v230
	v_xor_b32_e32 v229, v230, v142
	v_and_b32_e32 v229, 0xffffff80, v229
	v_or_b32_e32 v98, v229, v227
	v_ashrrev_i32_e32 v230, 31, v143
	v_or_b32_e32 v230, 0x80000000, v230
	v_xor_b32_e32 v229, v230, v143
	v_and_b32_e32 v229, 0xffffff80, v229
	v_or_b32_e32 v104, v229, v228
	v_subrev_u32_e32 v213, 32, v213
	v_subrev_u32_e32 v214, 32, v214
	v_subrev_u32_e32 v215, 32, v215
	v_subrev_u32_e32 v216, 32, v216
	v_subrev_u32_e32 v217, 32, v217
	v_subrev_u32_e32 v218, 32, v218
	v_subrev_u32_e32 v219, 32, v219
	v_subrev_u32_e32 v220, 32, v220
	v_subrev_u32_e32 v221, 32, v221
	v_subrev_u32_e32 v222, 32, v222
	v_subrev_u32_e32 v223, 32, v223
	v_subrev_u32_e32 v224, 32, v224
	v_subrev_u32_e32 v225, 32, v225
	v_subrev_u32_e32 v226, 32, v226
	v_subrev_u32_e32 v227, 32, v227
	v_subrev_u32_e32 v228, 32, v228
	v_max_u32_e32 v106, v105, v86
	v_min_u32_e32 v86, v105, v86
	v_min_u32_e32 v105, v90, v101
	v_max_u32_e32 v101, v90, v101
	v_max_u32_e32 v90, v97, v112
	v_min_u32_e32 v112, v97, v112
	v_min_u32_e32 v97, v100, v91
	v_max_u32_e32 v91, v100, v91
	v_max_u32_e32 v100, v109, v96
	v_min_u32_e32 v96, v109, v96
	v_min_u32_e32 v109, v115, v81
	v_max_u32_e32 v81, v115, v81
	v_max_u32_e32 v115, v107, v114
	v_min_u32_e32 v114, v107, v114
	v_min_u32_e32 v107, v98, v104
	v_max_u32_e32 v104, v98, v104
	v_max_u32_e32 v98, v106, v105
	v_min_u32_e32 v105, v106, v105
	v_max_u32_e32 v106, v86, v101
	v_min_u32_e32 v101, v86, v101
	v_min_u32_e32 v86, v90, v97
	v_max_u32_e32 v97, v90, v97
	v_min_u32_e32 v90, v112, v91
	v_max_u32_e32 v91, v112, v91
	v_max_u32_e32 v112, v100, v109
	v_min_u32_e32 v109, v100, v109
	v_max_u32_e32 v100, v96, v81
	v_min_u32_e32 v81, v96, v81
	v_min_u32_e32 v96, v115, v107
	v_max_u32_e32 v107, v115, v107
	v_min_u32_e32 v115, v114, v104
	v_max_u32_e32 v104, v114, v104
	v_max_u32_e32 v114, v98, v106
	v_min_u32_e32 v106, v98, v106
	v_max_u32_e32 v98, v105, v101
	v_min_u32_e32 v101, v105, v101
	v_min_u32_e32 v105, v86, v90
	v_max_u32_e32 v90, v86, v90
	v_min_u32_e32 v86, v97, v91
	v_max_u32_e32 v91, v97, v91
	v_max_u32_e32 v97, v112, v100
	v_min_u32_e32 v100, v112, v100
	v_max_u32_e32 v112, v109, v81
	v_min_u32_e32 v81, v109, v81
	v_min_u32_e32 v109, v96, v115
	v_max_u32_e32 v115, v96, v115
	v_min_u32_e32 v96, v107, v104
	v_max_u32_e32 v104, v107, v104
	v_max_u32_e32 v107, v114, v105
	v_min_u32_e32 v105, v114, v105
	v_max_u32_e32 v114, v106, v90
	v_min_u32_e32 v90, v106, v90
	v_max_u32_e32 v106, v98, v86
	v_min_u32_e32 v86, v98, v86
	v_max_u32_e32 v98, v101, v91
	v_min_u32_e32 v91, v101, v91
	v_min_u32_e32 v101, v97, v109
	v_max_u32_e32 v109, v97, v109
	v_min_u32_e32 v97, v100, v115
	v_max_u32_e32 v115, v100, v115
	v_min_u32_e32 v100, v112, v96
	v_max_u32_e32 v96, v112, v96
	v_min_u32_e32 v112, v81, v104
	v_max_u32_e32 v104, v81, v104
	v_max_u32_e32 v81, v107, v106
	v_min_u32_e32 v106, v107, v106
	v_max_u32_e32 v107, v114, v98
	v_min_u32_e32 v98, v114, v98
	v_max_u32_e32 v114, v105, v86
	v_min_u32_e32 v86, v105, v86
	v_max_u32_e32 v105, v90, v91
	v_min_u32_e32 v91, v90, v91
	v_min_u32_e32 v90, v101, v100
	v_max_u32_e32 v100, v101, v100
	v_min_u32_e32 v101, v97, v112
	v_max_u32_e32 v112, v97, v112
	v_min_u32_e32 v97, v109, v96
	v_max_u32_e32 v96, v109, v96
	v_min_u32_e32 v109, v115, v104
	v_max_u32_e32 v104, v115, v104
	v_max_u32_e32 v115, v81, v107
	v_min_u32_e32 v107, v81, v107
	v_max_u32_e32 v81, v106, v98
	v_min_u32_e32 v98, v106, v98
	v_max_u32_e32 v106, v114, v105
	v_min_u32_e32 v105, v114, v105
	v_max_u32_e32 v114, v86, v91
	v_min_u32_e32 v91, v86, v91
	v_min_u32_e32 v86, v90, v101
	v_max_u32_e32 v101, v90, v101
	v_min_u32_e32 v90, v100, v112
	v_max_u32_e32 v112, v100, v112
	v_min_u32_e32 v100, v97, v109
	v_max_u32_e32 v109, v97, v109
	v_min_u32_e32 v97, v96, v104
	v_max_u32_e32 v104, v96, v104
	v_max_u32_e32 v96, v115, v86
	v_min_u32_e32 v86, v115, v86
	v_max_u32_e32 v115, v107, v101
	v_min_u32_e32 v101, v107, v101
	v_max_u32_e32 v107, v81, v90
	v_min_u32_e32 v90, v81, v90
	v_max_u32_e32 v81, v98, v112
	v_min_u32_e32 v112, v98, v112
	v_max_u32_e32 v98, v106, v100
	v_min_u32_e32 v100, v106, v100
	v_max_u32_e32 v106, v105, v109
	v_min_u32_e32 v109, v105, v109
	v_max_u32_e32 v105, v114, v97
	v_min_u32_e32 v97, v114, v97
	v_max_u32_e32 v114, v91, v104
	v_min_u32_e32 v104, v91, v104
	v_max_u32_e32 v91, v96, v98
	v_min_u32_e32 v98, v96, v98
	v_max_u32_e32 v96, v115, v106
	v_min_u32_e32 v106, v115, v106
	v_max_u32_e32 v115, v107, v105
	v_min_u32_e32 v105, v107, v105
	v_max_u32_e32 v107, v81, v114
	v_min_u32_e32 v114, v81, v114
	v_max_u32_e32 v81, v86, v100
	v_min_u32_e32 v100, v86, v100
	v_max_u32_e32 v86, v101, v109
	v_min_u32_e32 v109, v101, v109
	v_max_u32_e32 v101, v90, v97
	v_min_u32_e32 v97, v90, v97
	v_max_u32_e32 v90, v112, v104
	v_min_u32_e32 v104, v112, v104
	v_max_u32_e32 v112, v91, v115
	v_min_u32_e32 v115, v91, v115
	v_max_u32_e32 v91, v96, v107
	v_min_u32_e32 v107, v96, v107
	v_max_u32_e32 v96, v98, v105
	v_min_u32_e32 v105, v98, v105
	v_max_u32_e32 v98, v106, v114
	v_min_u32_e32 v114, v106, v114
	v_max_u32_e32 v106, v81, v101
	v_min_u32_e32 v101, v81, v101
	v_max_u32_e32 v81, v86, v90
	v_min_u32_e32 v90, v86, v90
	v_max_u32_e32 v86, v100, v97
	v_min_u32_e32 v97, v100, v97
	v_max_u32_e32 v100, v109, v104
	v_min_u32_e32 v104, v109, v104
	v_max_u32_e32 v109, v112, v91
	v_min_u32_e32 v91, v112, v91
	v_max_u32_e32 v112, v115, v107
	v_min_u32_e32 v107, v115, v107
	v_max_u32_e32 v115, v96, v98
	v_min_u32_e32 v98, v96, v98
	v_max_u32_e32 v96, v105, v114
	v_min_u32_e32 v114, v105, v114
	v_max_u32_e32 v105, v106, v81
	v_min_u32_e32 v81, v106, v81
	v_max_u32_e32 v106, v101, v90
	v_min_u32_e32 v90, v101, v90
	v_max_u32_e32 v101, v86, v100
	v_min_u32_e32 v100, v86, v100
	v_max_u32_e32 v86, v97, v104
	v_min_u32_e32 v104, v97, v104
	s_waitcnt vmcnt(7)
; #define MFMA32(a, b, c) __builtin_amdgcn_mfma_f32_32x32x16_bf16((a), (b), (c), 0, 0, 0)
; DI int crow(int i, int hh) { return (i & 3) + 8 * (i >> 2) + 4 * hh; }
; DI unsigned f2ord(float f) {
;   unsigned u = __float_as_uint(f);
;   return (u & 0x80000000u) ? ~u : (u | 0x80000000u);
; }
; DI void peer_top16(const u16* __restrict__ PQrow, const u16* __restrict__ SK, unsigned (&top)[16], int lr, int hh) {
;     ...
;   for (int kt = 0; kt < 4; ++kt) {
;     f32x16 acc;
; #pragma unroll
;     for (int e = 0; e < 16; ++e) acc[e] = 0.f;
; #pragma unroll
;     for (int ks = 0; ks < 8; ++ks) {
;       bf16x8 a = *(const bf16x8*)(SK + (size_t)(kt * 32 + lr) * 128 + ks * 16 + hh * 8);
;       acc = MFMA32(a, qf[ks], acc);
;     }
; #pragma unroll
;     for (int e = 0; e < 16; ++e) {
;       int kidx = kt * 32 + crow(e, hh);
;       g[kt][e] = (f2ord(acc[e]) & ~127u) | (unsigned)(127 - kidx);
;     }
;     bitonic_sort_desc<4>(g[kt]);
	v_mfma_f32_32x32x16_bf16 v[128:143], v[144:147], v[176:179], 0
	s_waitcnt vmcnt(6)
	v_mfma_f32_32x32x16_bf16 v[128:143], v[148:151], v[180:183], v[128:143]
	s_waitcnt vmcnt(5)
	v_mfma_f32_32x32x16_bf16 v[128:143], v[152:155], v[184:187], v[128:143]
	s_waitcnt vmcnt(4)
	v_mfma_f32_32x32x16_bf16 v[128:143], v[156:159], v[188:191], v[128:143]
	s_waitcnt vmcnt(3)
	v_mfma_f32_32x32x16_bf16 v[128:143], v[160:163], v[192:195], v[128:143]
	s_waitcnt vmcnt(2)
	v_mfma_f32_32x32x16_bf16 v[128:143], v[164:167], v[196:199], v[128:143]
	s_waitcnt vmcnt(1)
	v_mfma_f32_32x32x16_bf16 v[128:143], v[168:171], v[200:203], v[128:143]
	s_waitcnt vmcnt(0)
	v_mfma_f32_32x32x16_bf16 v[128:143], v[172:175], v[204:207], v[128:143]
	s_add_u32 s4, s0, 81920
	s_addc_u32 s5, s1, 0
	global_load_dwordx4 v[144:147], v238, s[4:5] offset:0
	global_load_dwordx4 v[148:151], v238, s[4:5] offset:1024
	global_load_dwordx4 v[152:155], v238, s[4:5] offset:2048
	global_load_dwordx4 v[156:159], v238, s[4:5] offset:3072
	global_load_dwordx4 v[160:163], v208, s[4:5] offset:0
	global_load_dwordx4 v[164:167], v208, s[4:5] offset:1024
	global_load_dwordx4 v[168:171], v208, s[4:5] offset:2048
	global_load_dwordx4 v[172:175], v208, s[4:5] offset:3072
	s_nop 7
	s_nop 3
	v_ashrrev_i32_e32 v230, 31, v128
	v_or_b32_e32 v230, 0x80000000, v230
	v_xor_b32_e32 v229, v230, v128
	v_and_b32_e32 v229, 0xffffff80, v229
	v_or_b32_e32 v97, v229, v213
	v_ashrrev_i32_e32 v230, 31, v129
	v_or_b32_e32 v230, 0x80000000, v230
	v_xor_b32_e32 v229, v230, v129
	v_and_b32_e32 v229, 0xffffff80, v229
	v_or_b32_e32 v89, v229, v214
	v_ashrrev_i32_e32 v230, 31, v130
	v_or_b32_e32 v230, 0x80000000, v230
	v_xor_b32_e32 v229, v230, v130
	v_and_b32_e32 v229, 0xffffff80, v229
	v_or_b32_e32 v113, v229, v215
	v_ashrrev_i32_e32 v230, 31, v131
	v_or_b32_e32 v230, 0x80000000, v230
	v_xor_b32_e32 v229, v230, v131
	v_and_b32_e32 v229, 0xffffff80, v229
	v_or_b32_e32 v108, v229, v216
	v_ashrrev_i32_e32 v230, 31, v132
	v_or_b32_e32 v230, 0x80000000, v230
	v_xor_b32_e32 v229, v230, v132
	v_and_b32_e32 v229, 0xffffff80, v229
	v_or_b32_e32 v85, v229, v217
	v_ashrrev_i32_e32 v230, 31, v133
	v_or_b32_e32 v230, 0x80000000, v230
	v_xor_b32_e32 v229, v230, v133
	v_and_b32_e32 v229, 0xffffff80, v229
	v_or_b32_e32 v88, v229, v218
	v_ashrrev_i32_e32 v230, 31, v134
	v_or_b32_e32 v230, 0x80000000, v230
	v_xor_b32_e32 v229, v230, v134
	v_and_b32_e32 v229, 0xffffff80, v229
	v_or_b32_e32 v110, v229, v219
	v_ashrrev_i32_e32 v230, 31, v135
	v_or_b32_e32 v230, 0x80000000, v230
	v_xor_b32_e32 v229, v230, v135
	v_and_b32_e32 v229, 0xffffff80, v229
	v_or_b32_e32 v92, v229, v220
	v_ashrrev_i32_e32 v230, 31, v136
	v_or_b32_e32 v230, 0x80000000, v230
	v_xor_b32_e32 v229, v230, v136
	v_and_b32_e32 v229, 0xffffff80, v229
	v_or_b32_e32 v87, v229, v221
	v_ashrrev_i32_e32 v230, 31, v137
	v_or_b32_e32 v230, 0x80000000, v230
	v_xor_b32_e32 v229, v230, v137
	v_and_b32_e32 v229, 0xffffff80, v229
	v_or_b32_e32 v77, v229, v222
	v_ashrrev_i32_e32 v230, 31, v138
	v_or_b32_e32 v230, 0x80000000, v230
	v_xor_b32_e32 v229, v230, v138
	v_and_b32_e32 v229, 0xffffff80, v229
	v_or_b32_e32 v116, v229, v223
	v_ashrrev_i32_e32 v230, 31, v139
	v_or_b32_e32 v230, 0x80000000, v230
	v_xor_b32_e32 v229, v230, v139
	v_and_b32_e32 v229, 0xffffff80, v229
	v_or_b32_e32 v83, v229, v224
	v_ashrrev_i32_e32 v230, 31, v140
	v_or_b32_e32 v230, 0x80000000, v230
	v_xor_b32_e32 v229, v230, v140
	v_and_b32_e32 v229, 0xffffff80, v229
	v_or_b32_e32 v102, v229, v225
	v_ashrrev_i32_e32 v230, 31, v141
	v_or_b32_e32 v230, 0x80000000, v230
	v_xor_b32_e32 v229, v230, v141
	v_and_b32_e32 v229, 0xffffff80, v229
	v_or_b32_e32 v117, v229, v226
	v_ashrrev_i32_e32 v230, 31, v142
	v_or_b32_e32 v230, 0x80000000, v230
	v_xor_b32_e32 v229, v230, v142
	v_and_b32_e32 v229, 0xffffff80, v229
	v_or_b32_e32 v70, v229, v227
	v_ashrrev_i32_e32 v230, 31, v143
	v_or_b32_e32 v230, 0x80000000, v230
	v_xor_b32_e32 v229, v230, v143
	v_and_b32_e32 v229, 0xffffff80, v229
	v_or_b32_e32 v111, v229, v228
	v_subrev_u32_e32 v213, 32, v213
	v_subrev_u32_e32 v214, 32, v214
	v_subrev_u32_e32 v215, 32, v215
	v_subrev_u32_e32 v216, 32, v216
	v_subrev_u32_e32 v217, 32, v217
	v_subrev_u32_e32 v218, 32, v218
	v_subrev_u32_e32 v219, 32, v219
	v_subrev_u32_e32 v220, 32, v220
	v_subrev_u32_e32 v221, 32, v221
	v_subrev_u32_e32 v222, 32, v222
	v_subrev_u32_e32 v223, 32, v223
	v_subrev_u32_e32 v224, 32, v224
	v_subrev_u32_e32 v225, 32, v225
	v_subrev_u32_e32 v226, 32, v226
	v_subrev_u32_e32 v227, 32, v227
	v_subrev_u32_e32 v228, 32, v228
	v_max_u32_e32 v103, v97, v89
	v_min_u32_e32 v89, v97, v89
	v_min_u32_e32 v97, v113, v108
	v_max_u32_e32 v108, v113, v108
	v_max_u32_e32 v113, v85, v88
	v_min_u32_e32 v88, v85, v88
	v_min_u32_e32 v85, v110, v92
	v_max_u32_e32 v92, v110, v92
	v_max_u32_e32 v110, v87, v77
	v_min_u32_e32 v77, v87, v77
	v_min_u32_e32 v87, v116, v83
	v_max_u32_e32 v83, v116, v83
	v_max_u32_e32 v116, v102, v117
	v_min_u32_e32 v117, v102, v117
	v_min_u32_e32 v102, v70, v111
	v_max_u32_e32 v111, v70, v111
	v_max_u32_e32 v70, v103, v97
	v_min_u32_e32 v97, v103, v97
	v_max_u32_e32 v103, v89, v108
	v_min_u32_e32 v108, v89, v108
	v_min_u32_e32 v89, v113, v85
	v_max_u32_e32 v85, v113, v85
	v_min_u32_e32 v113, v88, v92
	v_max_u32_e32 v92, v88, v92
	v_max_u32_e32 v88, v110, v87
	v_min_u32_e32 v87, v110, v87
	v_max_u32_e32 v110, v77, v83
	v_min_u32_e32 v83, v77, v83
	v_min_u32_e32 v77, v116, v102
	v_max_u32_e32 v102, v116, v102
	v_min_u32_e32 v116, v117, v111
	v_max_u32_e32 v111, v117, v111
	v_max_u32_e32 v117, v70, v103
	v_min_u32_e32 v103, v70, v103
	v_max_u32_e32 v70, v97, v108
	v_min_u32_e32 v108, v97, v108
	v_min_u32_e32 v97, v89, v113
; template <int LOGN>
; DI void bitonic_sort_desc(unsigned (&a)[1 << LOGN]) {
;   constexpr int N = 1 << LOGN;
; #pragma unroll
;   for (int ks = 1; ks <= LOGN; ++ks)
; #pragma unroll
;     ...
; #pragma unroll
;       for (int i = 0; i < N; ++i) {
;         const int k = 1 << ks, j = 1 << js, l = i ^ j;
;         if (l > i) {
;           const bool desc = ((i & k) == 0) || (ks == LOGN);
;           const unsigned x = a[i], y = a[l];
;           const unsigned hi = max(x, y), lo = min(x, y);
;           a[i] = desc ? hi : lo;
;           a[l] = desc ? lo : hi;
;         }
;       }
; }
; DI void merge_top16(unsigned (&a)[16], const unsigned (&b)[16]) {
; #pragma unroll
;   for (int i = 0; i < 16; ++i) a[i] = max(a[i], b[15 - i]);
; #pragma unroll
;     ...
; #pragma unroll
;     for (int i = 0; i < 16; ++i) {
;       const int j = 1 << js, l = i ^ j;
;       if (l > i) {
;         const unsigned x = a[i], y = a[l];
;         a[i] = max(x, y);
;         a[l] = min(x, y);
;       }
;     }
; }
	v_max_u32_e32 v113, v89, v113
	v_min_u32_e32 v89, v85, v92
	v_max_u32_e32 v92, v85, v92
	v_max_u32_e32 v85, v88, v110
	v_min_u32_e32 v110, v88, v110
	v_max_u32_e32 v88, v87, v83
	v_min_u32_e32 v83, v87, v83
	v_min_u32_e32 v87, v77, v116
	v_max_u32_e32 v116, v77, v116
	v_min_u32_e32 v77, v102, v111
	v_max_u32_e32 v111, v102, v111
	v_max_u32_e32 v102, v117, v97
	v_min_u32_e32 v97, v117, v97
	v_max_u32_e32 v117, v103, v113
	v_min_u32_e32 v113, v103, v113
	v_max_u32_e32 v103, v70, v89
	v_min_u32_e32 v89, v70, v89
	v_max_u32_e32 v70, v108, v92
	v_min_u32_e32 v92, v108, v92
	v_min_u32_e32 v108, v85, v87
	v_max_u32_e32 v87, v85, v87
	v_min_u32_e32 v85, v110, v116
	v_max_u32_e32 v116, v110, v116
	v_min_u32_e32 v110, v88, v77
	v_max_u32_e32 v77, v88, v77
	v_min_u32_e32 v88, v83, v111
	v_max_u32_e32 v111, v83, v111
	v_max_u32_e32 v83, v102, v103
	v_min_u32_e32 v103, v102, v103
	v_max_u32_e32 v102, v117, v70
	v_min_u32_e32 v70, v117, v70
	v_max_u32_e32 v117, v97, v89
	v_min_u32_e32 v89, v97, v89
	v_max_u32_e32 v97, v113, v92
	v_min_u32_e32 v92, v113, v92
	v_min_u32_e32 v113, v108, v110
	v_max_u32_e32 v110, v108, v110
	v_min_u32_e32 v108, v85, v88
	v_max_u32_e32 v88, v85, v88
	v_min_u32_e32 v85, v87, v77
	v_max_u32_e32 v77, v87, v77
	v_min_u32_e32 v87, v116, v111
	v_max_u32_e32 v111, v116, v111
	v_max_u32_e32 v116, v83, v102
	v_min_u32_e32 v102, v83, v102
	v_max_u32_e32 v83, v103, v70
	v_min_u32_e32 v70, v103, v70
	v_max_u32_e32 v103, v117, v97
	v_min_u32_e32 v97, v117, v97
	v_max_u32_e32 v117, v89, v92
	v_min_u32_e32 v92, v89, v92
	v_min_u32_e32 v89, v113, v108
	v_max_u32_e32 v108, v113, v108
	v_min_u32_e32 v113, v110, v88
	v_max_u32_e32 v88, v110, v88
	v_min_u32_e32 v110, v85, v87
	v_max_u32_e32 v87, v85, v87
	v_min_u32_e32 v85, v77, v111
	v_max_u32_e32 v111, v77, v111
	v_max_u32_e32 v77, v116, v89
	v_min_u32_e32 v89, v116, v89
	v_max_u32_e32 v116, v102, v108
	v_min_u32_e32 v108, v102, v108
	v_max_u32_e32 v102, v83, v113
	v_min_u32_e32 v113, v83, v113
	v_max_u32_e32 v83, v70, v88
	v_min_u32_e32 v88, v70, v88
	v_max_u32_e32 v70, v103, v110
	v_min_u32_e32 v110, v103, v110
	v_max_u32_e32 v103, v97, v87
	v_min_u32_e32 v87, v97, v87
	v_max_u32_e32 v97, v117, v85
	v_min_u32_e32 v85, v117, v85
	v_max_u32_e32 v117, v92, v111
	v_min_u32_e32 v111, v92, v111
	v_max_u32_e32 v92, v77, v70
	v_min_u32_e32 v70, v77, v70
	v_max_u32_e32 v77, v116, v103
	v_min_u32_e32 v103, v116, v103
	v_max_u32_e32 v116, v102, v97
	v_min_u32_e32 v97, v102, v97
	v_max_u32_e32 v102, v83, v117
	v_min_u32_e32 v117, v83, v117
	v_max_u32_e32 v83, v89, v110
	v_min_u32_e32 v110, v89, v110
	v_max_u32_e32 v89, v108, v87
	v_min_u32_e32 v87, v108, v87
	v_max_u32_e32 v108, v113, v85
	v_min_u32_e32 v85, v113, v85
	v_max_u32_e32 v113, v88, v111
	v_min_u32_e32 v111, v88, v111
	v_max_u32_e32 v88, v92, v116
	v_min_u32_e32 v116, v92, v116
	v_max_u32_e32 v92, v77, v102
	v_min_u32_e32 v102, v77, v102
	v_max_u32_e32 v77, v70, v97
	v_min_u32_e32 v97, v70, v97
	v_max_u32_e32 v70, v103, v117
	v_min_u32_e32 v117, v103, v117
	v_max_u32_e32 v103, v83, v108
	v_min_u32_e32 v108, v83, v108
	v_max_u32_e32 v83, v89, v113
	v_min_u32_e32 v113, v89, v113
	v_max_u32_e32 v89, v110, v85
	v_min_u32_e32 v85, v110, v85
	v_max_u32_e32 v110, v87, v111
	v_min_u32_e32 v111, v87, v111
	v_max_u32_e32 v87, v88, v92
	v_min_u32_e32 v92, v88, v92
	v_max_u32_e32 v88, v116, v102
	v_min_u32_e32 v102, v116, v102
	v_max_u32_e32 v116, v77, v70
	v_min_u32_e32 v70, v77, v70
	v_max_u32_e32 v77, v97, v117
	v_min_u32_e32 v117, v97, v117
	v_max_u32_e32 v97, v103, v83
	v_min_u32_e32 v83, v103, v83
	v_max_u32_e32 v103, v108, v113
	v_min_u32_e32 v113, v108, v113
	v_max_u32_e32 v108, v89, v110
	v_min_u32_e32 v110, v89, v110
	v_max_u32_e32 v89, v85, v111
	v_min_u32_e32 v111, v85, v111
	v_max_u32_e32 v85, v109, v111
	v_max_u32_e32 v109, v91, v89
	v_max_u32_e32 v91, v112, v110
	v_max_u32_e32 v112, v107, v108
	v_max_u32_e32 v107, v115, v113
	v_max_u32_e32 v115, v98, v103
	v_max_u32_e32 v98, v96, v83
	v_max_u32_e32 v96, v114, v97
	v_max_u32_e32 v114, v105, v117
	v_max_u32_e32 v105, v81, v77
	v_max_u32_e32 v81, v106, v70
	v_max_u32_e32 v106, v90, v116
	v_max_u32_e32 v90, v101, v102
	v_max_u32_e32 v101, v100, v88
	v_max_u32_e32 v100, v86, v92
	v_max_u32_e32 v86, v104, v87
	v_max_u32_e32 v111, v85, v114
	v_min_u32_e32 v114, v85, v114
	v_max_u32_e32 v85, v109, v105
	v_min_u32_e32 v105, v109, v105
	v_max_u32_e32 v109, v91, v81
	v_min_u32_e32 v81, v91, v81
	v_max_u32_e32 v91, v112, v106
	v_min_u32_e32 v106, v112, v106
	v_max_u32_e32 v112, v107, v90
	v_min_u32_e32 v90, v107, v90
	v_max_u32_e32 v107, v115, v101
	v_min_u32_e32 v101, v115, v101
	v_max_u32_e32 v115, v98, v100
	v_min_u32_e32 v100, v98, v100
	v_max_u32_e32 v98, v96, v86
	v_min_u32_e32 v86, v96, v86
	v_max_u32_e32 v96, v111, v112
	v_min_u32_e32 v112, v111, v112
	v_max_u32_e32 v111, v85, v107
	v_min_u32_e32 v107, v85, v107
	v_max_u32_e32 v85, v109, v115
	v_min_u32_e32 v115, v109, v115
	v_max_u32_e32 v109, v91, v98
	v_min_u32_e32 v98, v91, v98
	v_max_u32_e32 v91, v114, v90
	v_min_u32_e32 v90, v114, v90
	v_max_u32_e32 v114, v105, v101
	v_min_u32_e32 v101, v105, v101
	v_max_u32_e32 v105, v81, v100
	v_min_u32_e32 v100, v81, v100
	v_max_u32_e32 v81, v106, v86
	v_min_u32_e32 v86, v106, v86
	v_max_u32_e32 v106, v96, v85
	v_min_u32_e32 v85, v96, v85
	v_max_u32_e32 v96, v111, v109
	v_min_u32_e32 v109, v111, v109
	v_max_u32_e32 v111, v112, v115
	v_min_u32_e32 v115, v112, v115
	v_max_u32_e32 v112, v107, v98
	v_min_u32_e32 v98, v107, v98
	v_max_u32_e32 v107, v91, v105
	v_min_u32_e32 v105, v91, v105
	v_max_u32_e32 v91, v114, v81
	v_min_u32_e32 v81, v114, v81
	v_max_u32_e32 v114, v90, v100
	v_min_u32_e32 v100, v90, v100
	v_max_u32_e32 v90, v101, v86
	v_min_u32_e32 v86, v101, v86
	v_max_u32_e32 v101, v106, v96
	v_min_u32_e32 v96, v106, v96
	v_max_u32_e32 v106, v85, v109
	v_min_u32_e32 v109, v85, v109
	v_max_u32_e32 v85, v111, v112
	v_min_u32_e32 v112, v111, v112
	v_max_u32_e32 v111, v115, v98
	v_min_u32_e32 v98, v115, v98
	v_max_u32_e32 v115, v107, v91
	v_min_u32_e32 v91, v107, v91
	v_max_u32_e32 v107, v105, v81
	v_min_u32_e32 v81, v105, v81
	v_max_u32_e32 v105, v114, v90
	v_min_u32_e32 v90, v114, v90
	v_max_u32_e32 v114, v100, v86
	v_min_u32_e32 v86, v100, v86
	s_waitcnt vmcnt(7)
; #define MFMA32(a, b, c) __builtin_amdgcn_mfma_f32_32x32x16_bf16((a), (b), (c), 0, 0, 0)
; DI int crow(int i, int hh) { return (i & 3) + 8 * (i >> 2) + 4 * hh; }
; DI unsigned f2ord(float f) {
;   unsigned u = __float_as_uint(f);
;   return (u & 0x80000000u) ? ~u : (u | 0x80000000u);
; }
; DI void peer_top16(const u16* __restrict__ PQrow, const u16* __restrict__ SK, unsigned (&top)[16], int lr, int hh) {
;     ...
;   for (int kt = 0; kt < 4; ++kt) {
;     f32x16 acc;
; #pragma unroll
;     for (int e = 0; e < 16; ++e) acc[e] = 0.f;
; #pragma unroll
;     for (int ks = 0; ks < 8; ++ks) {
;       bf16x8 a = *(const bf16x8*)(SK + (size_t)(kt * 32 + lr) * 128 + ks * 16 + hh * 8);
;       acc = MFMA32(a, qf[ks], acc);
;     }
; #pragma unroll
;     for (int e = 0; e < 16; ++e) {
;       int kidx = kt * 32 + crow(e, hh);
;       g[kt][e] = (f2ord(acc[e]) & ~127u) | (unsigned)(127 - kidx);
;     }
;     bitonic_sort_desc<4>(g[kt]);
	v_mfma_f32_32x32x16_bf16 v[128:143], v[144:147], v[176:179], 0
	s_waitcnt vmcnt(6)
	v_mfma_f32_32x32x16_bf16 v[128:143], v[148:151], v[180:183], v[128:143]
	s_waitcnt vmcnt(5)
	v_mfma_f32_32x32x16_bf16 v[128:143], v[152:155], v[184:187], v[128:143]
	s_waitcnt vmcnt(4)
	v_mfma_f32_32x32x16_bf16 v[128:143], v[156:159], v[188:191], v[128:143]
	s_waitcnt vmcnt(3)
	v_mfma_f32_32x32x16_bf16 v[128:143], v[160:163], v[192:195], v[128:143]
	s_waitcnt vmcnt(2)
	v_mfma_f32_32x32x16_bf16 v[128:143], v[164:167], v[196:199], v[128:143]
	s_waitcnt vmcnt(1)
	v_mfma_f32_32x32x16_bf16 v[128:143], v[168:171], v[200:203], v[128:143]
	s_waitcnt vmcnt(0)
	v_mfma_f32_32x32x16_bf16 v[128:143], v[172:175], v[204:207], v[128:143]
	s_add_u32 s4, s0, 90112
	s_addc_u32 s5, s1, 0
	global_load_dwordx4 v[144:147], v238, s[4:5] offset:0
	global_load_dwordx4 v[148:151], v238, s[4:5] offset:1024
	global_load_dwordx4 v[152:155], v238, s[4:5] offset:2048
	global_load_dwordx4 v[156:159], v238, s[4:5] offset:3072
	global_load_dwordx4 v[160:163], v208, s[4:5] offset:0
	global_load_dwordx4 v[164:167], v208, s[4:5] offset:1024
	global_load_dwordx4 v[168:171], v208, s[4:5] offset:2048
	global_load_dwordx4 v[172:175], v208, s[4:5] offset:3072
	s_nop 7
	s_nop 3
	v_ashrrev_i32_e32 v230, 31, v128
	v_or_b32_e32 v230, 0x80000000, v230
	v_xor_b32_e32 v229, v230, v128
	v_and_b32_e32 v229, 0xffffff80, v229
	v_or_b32_e32 v100, v229, v213
	v_ashrrev_i32_e32 v230, 31, v129
	v_or_b32_e32 v230, 0x80000000, v230
	v_xor_b32_e32 v229, v230, v129
	v_and_b32_e32 v229, 0xffffff80, v229
	v_or_b32_e32 v89, v229, v214
	v_ashrrev_i32_e32 v230, 31, v130
	v_or_b32_e32 v230, 0x80000000, v230
	v_xor_b32_e32 v229, v230, v130
	v_and_b32_e32 v229, 0xffffff80, v229
	v_or_b32_e32 v110, v229, v215
	v_ashrrev_i32_e32 v230, 31, v131
	v_or_b32_e32 v230, 0x80000000, v230
	v_xor_b32_e32 v229, v230, v131
	v_and_b32_e32 v229, 0xffffff80, v229
	v_or_b32_e32 v108, v229, v216
	v_ashrrev_i32_e32 v230, 31, v132
	v_or_b32_e32 v230, 0x80000000, v230
	v_xor_b32_e32 v229, v230, v132
	v_and_b32_e32 v229, 0xffffff80, v229
	v_or_b32_e32 v113, v229, v217
	v_ashrrev_i32_e32 v230, 31, v133
	v_or_b32_e32 v230, 0x80000000, v230
	v_xor_b32_e32 v229, v230, v133
	v_and_b32_e32 v229, 0xffffff80, v229
	v_or_b32_e32 v103, v229, v218
	v_ashrrev_i32_e32 v230, 31, v134
	v_or_b32_e32 v230, 0x80000000, v230
	v_xor_b32_e32 v229, v230, v134
	v_and_b32_e32 v229, 0xffffff80, v229
	v_or_b32_e32 v83, v229, v219
	v_ashrrev_i32_e32 v230, 31, v135
	v_or_b32_e32 v230, 0x80000000, v230
	v_xor_b32_e32 v229, v230, v135
	v_and_b32_e32 v229, 0xffffff80, v229
	v_or_b32_e32 v97, v229, v220
	v_ashrrev_i32_e32 v230, 31, v136
	v_or_b32_e32 v230, 0x80000000, v230
	v_xor_b32_e32 v229, v230, v136
	v_and_b32_e32 v229, 0xffffff80, v229
	v_or_b32_e32 v117, v229, v221
	v_ashrrev_i32_e32 v230, 31, v137
	v_or_b32_e32 v230, 0x80000000, v230
	v_xor_b32_e32 v229, v230, v137
	v_and_b32_e32 v229, 0xffffff80, v229
	v_or_b32_e32 v77, v229, v222
	v_ashrrev_i32_e32 v230, 31, v138
	v_or_b32_e32 v230, 0x80000000, v230
	v_xor_b32_e32 v229, v230, v138
	v_and_b32_e32 v229, 0xffffff80, v229
	v_or_b32_e32 v70, v229, v223
	v_ashrrev_i32_e32 v230, 31, v139
	v_or_b32_e32 v230, 0x80000000, v230
	v_xor_b32_e32 v229, v230, v139
	v_and_b32_e32 v229, 0xffffff80, v229
	v_or_b32_e32 v116, v229, v224
	v_ashrrev_i32_e32 v230, 31, v140
	v_or_b32_e32 v230, 0x80000000, v230
	v_xor_b32_e32 v229, v230, v140
	v_and_b32_e32 v229, 0xffffff80, v229
	v_or_b32_e32 v102, v229, v225
	v_ashrrev_i32_e32 v230, 31, v141
	v_or_b32_e32 v230, 0x80000000, v230
	v_xor_b32_e32 v229, v230, v141
	v_and_b32_e32 v229, 0xffffff80, v229
	v_or_b32_e32 v88, v229, v226
	v_ashrrev_i32_e32 v230, 31, v142
	v_or_b32_e32 v230, 0x80000000, v230
	v_xor_b32_e32 v229, v230, v142
	v_and_b32_e32 v229, 0xffffff80, v229
	v_or_b32_e32 v92, v229, v227
	v_ashrrev_i32_e32 v230, 31, v143
	v_or_b32_e32 v230, 0x80000000, v230
	v_xor_b32_e32 v229, v230, v143
	v_and_b32_e32 v229, 0xffffff80, v229
	v_or_b32_e32 v87, v229, v228
	v_subrev_u32_e32 v213, 32, v213
	v_subrev_u32_e32 v214, 32, v214
	v_subrev_u32_e32 v215, 32, v215
	v_subrev_u32_e32 v216, 32, v216
	v_subrev_u32_e32 v217, 32, v217
	v_subrev_u32_e32 v218, 32, v218
	v_subrev_u32_e32 v219, 32, v219
	v_subrev_u32_e32 v220, 32, v220
	v_subrev_u32_e32 v221, 32, v221
	v_subrev_u32_e32 v222, 32, v222
	v_subrev_u32_e32 v223, 32, v223
	v_subrev_u32_e32 v224, 32, v224
	v_subrev_u32_e32 v225, 32, v225
	v_subrev_u32_e32 v226, 32, v226
	v_subrev_u32_e32 v227, 32, v227
	v_subrev_u32_e32 v228, 32, v228
	v_max_u32_e32 v104, v100, v89
	v_min_u32_e32 v89, v100, v89
	v_min_u32_e32 v100, v110, v108
	v_max_u32_e32 v108, v110, v108
	v_max_u32_e32 v110, v113, v103
	v_min_u32_e32 v103, v113, v103
	v_min_u32_e32 v113, v83, v97
	v_max_u32_e32 v97, v83, v97
	v_max_u32_e32 v83, v117, v77
	v_min_u32_e32 v77, v117, v77
	v_min_u32_e32 v117, v70, v116
	v_max_u32_e32 v116, v70, v116
	v_max_u32_e32 v70, v102, v88
	v_min_u32_e32 v88, v102, v88
	v_min_u32_e32 v102, v92, v87
	v_max_u32_e32 v87, v92, v87
	v_max_u32_e32 v92, v104, v100
	v_min_u32_e32 v100, v104, v100
	v_max_u32_e32 v104, v89, v108
	v_min_u32_e32 v108, v89, v108
	v_min_u32_e32 v89, v110, v113
	v_max_u32_e32 v113, v110, v113
	v_min_u32_e32 v110, v103, v97
	v_max_u32_e32 v97, v103, v97
	v_max_u32_e32 v103, v83, v117
	v_min_u32_e32 v117, v83, v117
	v_max_u32_e32 v83, v77, v116
	v_min_u32_e32 v116, v77, v116
	v_min_u32_e32 v77, v70, v102
	v_max_u32_e32 v102, v70, v102
	v_min_u32_e32 v70, v88, v87
	v_max_u32_e32 v87, v88, v87
	v_max_u32_e32 v88, v92, v104
	v_min_u32_e32 v104, v92, v104
	v_max_u32_e32 v92, v100, v108
	v_min_u32_e32 v108, v100, v108
	v_min_u32_e32 v100, v89, v110
; #define MFMA32(a, b, c) __builtin_amdgcn_mfma_f32_32x32x16_bf16((a), (b), (c), 0, 0, 0)
; template <int LOGN>
; DI void bitonic_sort_desc(unsigned (&a)[1 << LOGN]) {
;   constexpr int N = 1 << LOGN;
; #pragma unroll
;   for (int ks = 1; ks <= LOGN; ++ks)
; #pragma unroll
;     ...
; #pragma unroll
;       for (int i = 0; i < N; ++i) {
;         const int k = 1 << ks, j = 1 << js, l = i ^ j;
;         if (l > i) {
;           const bool desc = ((i & k) == 0) || (ks == LOGN);
;           const unsigned x = a[i], y = a[l];
;           const unsigned hi = max(x, y), lo = min(x, y);
;           a[i] = desc ? hi : lo;
;           a[l] = desc ? lo : hi;
;         }
;       }
; }
; DI void peer_top16(const u16* __restrict__ PQrow, const u16* __restrict__ SK, unsigned (&top)[16], int lr, int hh) {
;     ...
;   for (int kt = 0; kt < 4; ++kt) {
;     f32x16 acc;
; #pragma unroll
;     for (int e = 0; e < 16; ++e) acc[e] = 0.f;
; #pragma unroll
;     for (int ks = 0; ks < 8; ++ks) {
;       bf16x8 a = *(const bf16x8*)(SK + (size_t)(kt * 32 + lr) * 128 + ks * 16 + hh * 8);
;       acc = MFMA32(a, qf[ks], acc);
;     }
	v_max_u32_e32 v110, v89, v110
	v_min_u32_e32 v89, v113, v97
	v_max_u32_e32 v97, v113, v97
	v_max_u32_e32 v113, v103, v83
	v_min_u32_e32 v83, v103, v83
	v_max_u32_e32 v103, v117, v116
	v_min_u32_e32 v116, v117, v116
	v_min_u32_e32 v117, v77, v70
	v_max_u32_e32 v70, v77, v70
	v_min_u32_e32 v77, v102, v87
	v_max_u32_e32 v87, v102, v87
	v_max_u32_e32 v102, v88, v100
	v_min_u32_e32 v100, v88, v100
	v_max_u32_e32 v88, v104, v110
	v_min_u32_e32 v110, v104, v110
	v_max_u32_e32 v104, v92, v89
	v_min_u32_e32 v89, v92, v89
	v_max_u32_e32 v92, v108, v97
	v_min_u32_e32 v97, v108, v97
	v_min_u32_e32 v108, v113, v117
	v_max_u32_e32 v117, v113, v117
	v_min_u32_e32 v113, v83, v70
	v_max_u32_e32 v70, v83, v70
	v_min_u32_e32 v83, v103, v77
	v_max_u32_e32 v77, v103, v77
	v_min_u32_e32 v103, v116, v87
	v_max_u32_e32 v87, v116, v87
	v_max_u32_e32 v116, v102, v104
	v_min_u32_e32 v104, v102, v104
	v_max_u32_e32 v102, v88, v92
	v_min_u32_e32 v92, v88, v92
	v_max_u32_e32 v88, v100, v89
	v_min_u32_e32 v89, v100, v89
	v_max_u32_e32 v100, v110, v97
	v_min_u32_e32 v97, v110, v97
	v_min_u32_e32 v110, v108, v83
	v_max_u32_e32 v83, v108, v83
	v_min_u32_e32 v108, v113, v103
	v_max_u32_e32 v103, v113, v103
	v_min_u32_e32 v113, v117, v77
	v_max_u32_e32 v77, v117, v77
	v_min_u32_e32 v117, v70, v87
	v_max_u32_e32 v87, v70, v87
	v_max_u32_e32 v70, v116, v102
	v_min_u32_e32 v102, v116, v102
	v_max_u32_e32 v116, v104, v92
	v_min_u32_e32 v92, v104, v92
	v_max_u32_e32 v104, v88, v100
	v_min_u32_e32 v100, v88, v100
	v_max_u32_e32 v88, v89, v97
	v_min_u32_e32 v97, v89, v97
	v_min_u32_e32 v89, v110, v108
	v_max_u32_e32 v108, v110, v108
	v_min_u32_e32 v110, v83, v103
	v_max_u32_e32 v103, v83, v103
	v_min_u32_e32 v83, v113, v117
	v_max_u32_e32 v117, v113, v117
	v_min_u32_e32 v113, v77, v87
	v_max_u32_e32 v87, v77, v87
	v_max_u32_e32 v77, v70, v89
	v_min_u32_e32 v89, v70, v89
	v_max_u32_e32 v70, v102, v108
	v_min_u32_e32 v108, v102, v108
	v_max_u32_e32 v102, v116, v110
	v_min_u32_e32 v110, v116, v110
	v_max_u32_e32 v116, v92, v103
	v_min_u32_e32 v103, v92, v103
	v_max_u32_e32 v92, v104, v83
	v_min_u32_e32 v83, v104, v83
	v_max_u32_e32 v104, v100, v117
	v_min_u32_e32 v117, v100, v117
	v_max_u32_e32 v100, v88, v113
	v_min_u32_e32 v113, v88, v113
	v_max_u32_e32 v88, v97, v87
	v_min_u32_e32 v87, v97, v87
	v_max_u32_e32 v97, v77, v92
	v_min_u32_e32 v92, v77, v92
	v_max_u32_e32 v77, v70, v104
	v_min_u32_e32 v104, v70, v104
	v_max_u32_e32 v70, v102, v100
	v_min_u32_e32 v100, v102, v100
	v_max_u32_e32 v102, v116, v88
	v_min_u32_e32 v88, v116, v88
	v_max_u32_e32 v116, v89, v83
	v_min_u32_e32 v83, v89, v83
	v_max_u32_e32 v89, v108, v117
	v_min_u32_e32 v117, v108, v117
	v_max_u32_e32 v108, v110, v113
	v_min_u32_e32 v113, v110, v113
	v_max_u32_e32 v110, v103, v87
	v_min_u32_e32 v87, v103, v87
	v_max_u32_e32 v103, v97, v70
	v_min_u32_e32 v70, v97, v70
	v_max_u32_e32 v97, v77, v102
	v_min_u32_e32 v102, v77, v102
	v_max_u32_e32 v77, v92, v100
	v_min_u32_e32 v100, v92, v100
	v_max_u32_e32 v92, v104, v88
	v_min_u32_e32 v88, v104, v88
	v_max_u32_e32 v104, v116, v108
	v_min_u32_e32 v108, v116, v108
	v_max_u32_e32 v116, v89, v110
	v_min_u32_e32 v110, v89, v110
	v_max_u32_e32 v89, v83, v113
	v_min_u32_e32 v113, v83, v113
	v_max_u32_e32 v83, v117, v87
	v_min_u32_e32 v87, v117, v87
	v_max_u32_e32 v117, v103, v97
	v_min_u32_e32 v97, v103, v97
	v_max_u32_e32 v103, v70, v102
	v_min_u32_e32 v102, v70, v102
	v_max_u32_e32 v70, v77, v92
	v_min_u32_e32 v92, v77, v92
	v_max_u32_e32 v77, v100, v88
	v_min_u32_e32 v88, v100, v88
	v_max_u32_e32 v100, v104, v116
	v_min_u32_e32 v116, v104, v116
	v_max_u32_e32 v104, v108, v110
	v_min_u32_e32 v110, v108, v110
	v_max_u32_e32 v108, v89, v83
	v_min_u32_e32 v83, v89, v83
	v_max_u32_e32 v89, v113, v87
	v_min_u32_e32 v87, v113, v87
	s_waitcnt vmcnt(7)
	v_mfma_f32_32x32x16_bf16 v[128:143], v[144:147], v[176:179], 0
	s_waitcnt vmcnt(6)
	v_mfma_f32_32x32x16_bf16 v[128:143], v[148:151], v[180:183], v[128:143]
	s_waitcnt vmcnt(5)
	v_mfma_f32_32x32x16_bf16 v[128:143], v[152:155], v[184:187], v[128:143]
	s_waitcnt vmcnt(4)
	v_mfma_f32_32x32x16_bf16 v[128:143], v[156:159], v[188:191], v[128:143]
	s_waitcnt vmcnt(3)
	v_mfma_f32_32x32x16_bf16 v[128:143], v[160:163], v[192:195], v[128:143]
	s_waitcnt vmcnt(2)
	v_mfma_f32_32x32x16_bf16 v[128:143], v[164:167], v[196:199], v[128:143]
	s_waitcnt vmcnt(1)
	v_mfma_f32_32x32x16_bf16 v[128:143], v[168:171], v[200:203], v[128:143]
	s_waitcnt vmcnt(0)
; #define MFMA32(a, b, c) __builtin_amdgcn_mfma_f32_32x32x16_bf16((a), (b), (c), 0, 0, 0)
; DI int crow(int i, int hh) { return (i & 3) + 8 * (i >> 2) + 4 * hh; }
; DI unsigned f2ord(float f) {
;   unsigned u = __float_as_uint(f);
;   return (u & 0x80000000u) ? ~u : (u | 0x80000000u);
; }
; DI void peer_top16(const u16* __restrict__ PQrow, const u16* __restrict__ SK, unsigned (&top)[16], int lr, int hh) {
;   bf16x8 qf[8];
; #pragma unroll
;   for (int ks = 0; ks < 8; ++ks) qf[ks] = *(const bf16x8*)(PQrow + ks * 16 + hh * 8);
;   unsigned g[4][16];
; #pragma unroll
;   for (int kt = 0; kt < 4; ++kt) {
;     f32x16 acc;
; #pragma unroll
;     for (int e = 0; e < 16; ++e) acc[e] = 0.f;
; #pragma unroll
;     for (int ks = 0; ks < 8; ++ks) {
;       bf16x8 a = *(const bf16x8*)(SK + (size_t)(kt * 32 + lr) * 128 + ks * 16 + hh * 8);
;       acc = MFMA32(a, qf[ks], acc);
;     }
; #pragma unroll
;     for (int e = 0; e < 16; ++e) {
;       int kidx = kt * 32 + crow(e, hh);
;       g[kt][e] = (f2ord(acc[e]) & ~127u) | (unsigned)(127 - kidx);
;     }
;     bitonic_sort_desc<4>(g[kt]);
	v_mfma_f32_32x32x16_bf16 v[128:143], v[172:175], v[204:207], v[128:143]
	global_load_dwordx4 v[176:179], v239, s[2:3] offset:768
	global_load_dwordx4 v[180:183], v239, s[2:3] offset:800
	global_load_dwordx4 v[184:187], v239, s[2:3] offset:832
	global_load_dwordx4 v[188:191], v239, s[2:3] offset:864
	global_load_dwordx4 v[192:195], v239, s[2:3] offset:896
	global_load_dwordx4 v[196:199], v239, s[2:3] offset:928
	global_load_dwordx4 v[200:203], v239, s[2:3] offset:960
	global_load_dwordx4 v[204:207], v239, s[2:3] offset:992
	s_add_u32 s4, s0, 98304
	s_addc_u32 s5, s1, 0
	global_load_dwordx4 v[144:147], v238, s[4:5] offset:0
	global_load_dwordx4 v[148:151], v238, s[4:5] offset:1024
	global_load_dwordx4 v[152:155], v238, s[4:5] offset:2048
	global_load_dwordx4 v[156:159], v238, s[4:5] offset:3072
	global_load_dwordx4 v[160:163], v208, s[4:5] offset:0
	global_load_dwordx4 v[164:167], v208, s[4:5] offset:1024
	global_load_dwordx4 v[168:171], v208, s[4:5] offset:2048
	global_load_dwordx4 v[172:175], v208, s[4:5] offset:3072
	s_nop 7
	s_nop 3
	v_ashrrev_i32_e32 v230, 31, v128
	v_or_b32_e32 v230, 0x80000000, v230
	v_xor_b32_e32 v229, v230, v128
	v_and_b32_e32 v229, 0xffffff80, v229
	v_or_b32_e32 v113, v229, v213
	v_ashrrev_i32_e32 v230, 31, v129
	v_or_b32_e32 v230, 0x80000000, v230
	v_xor_b32_e32 v229, v230, v129
	v_and_b32_e32 v229, 0xffffff80, v229
	v_or_b32_e32 v84, v229, v214
	v_ashrrev_i32_e32 v230, 31, v130
	v_or_b32_e32 v230, 0x80000000, v230
	v_xor_b32_e32 v229, v230, v130
	v_and_b32_e32 v229, 0xffffff80, v229
	v_or_b32_e32 v74, v229, v215
	v_ashrrev_i32_e32 v230, 31, v131
	v_or_b32_e32 v230, 0x80000000, v230
	v_xor_b32_e32 v229, v230, v131
	v_and_b32_e32 v229, 0xffffff80, v229
	v_or_b32_e32 v82, v229, v216
	v_ashrrev_i32_e32 v230, 31, v132
	v_or_b32_e32 v230, 0x80000000, v230
	v_xor_b32_e32 v229, v230, v132
	v_and_b32_e32 v229, 0xffffff80, v229
	v_or_b32_e32 v79, v229, v217
	v_ashrrev_i32_e32 v230, 31, v133
	v_or_b32_e32 v230, 0x80000000, v230
	v_xor_b32_e32 v229, v230, v133
	v_and_b32_e32 v229, 0xffffff80, v229
	v_or_b32_e32 v93, v229, v218
	v_ashrrev_i32_e32 v230, 31, v134
	v_or_b32_e32 v230, 0x80000000, v230
	v_xor_b32_e32 v229, v230, v134
	v_and_b32_e32 v229, 0xffffff80, v229
	v_or_b32_e32 v75, v229, v219
	v_ashrrev_i32_e32 v230, 31, v135
	v_or_b32_e32 v230, 0x80000000, v230
	v_xor_b32_e32 v229, v230, v135
	v_and_b32_e32 v229, 0xffffff80, v229
	v_or_b32_e32 v95, v229, v220
	v_ashrrev_i32_e32 v230, 31, v136
	v_or_b32_e32 v230, 0x80000000, v230
	v_xor_b32_e32 v229, v230, v136
	v_and_b32_e32 v229, 0xffffff80, v229
	v_or_b32_e32 v80, v229, v221
	v_ashrrev_i32_e32 v230, 31, v137
	v_or_b32_e32 v230, 0x80000000, v230
	v_xor_b32_e32 v229, v230, v137
	v_and_b32_e32 v229, 0xffffff80, v229
	v_or_b32_e32 v76, v229, v222
	v_ashrrev_i32_e32 v230, 31, v138
	v_or_b32_e32 v230, 0x80000000, v230
	v_xor_b32_e32 v229, v230, v138
	v_and_b32_e32 v229, 0xffffff80, v229
	v_or_b32_e32 v78, v229, v223
	v_ashrrev_i32_e32 v230, 31, v139
	v_or_b32_e32 v230, 0x80000000, v230
	v_xor_b32_e32 v229, v230, v139
	v_and_b32_e32 v229, 0xffffff80, v229
	v_or_b32_e32 v71, v229, v224
	v_ashrrev_i32_e32 v230, 31, v140
	v_or_b32_e32 v230, 0x80000000, v230
	v_xor_b32_e32 v229, v230, v140
	v_and_b32_e32 v229, 0xffffff80, v229
	v_or_b32_e32 v73, v229, v225
	v_ashrrev_i32_e32 v230, 31, v141
	v_or_b32_e32 v230, 0x80000000, v230
	v_xor_b32_e32 v229, v230, v141
	v_and_b32_e32 v229, 0xffffff80, v229
	v_or_b32_e32 v69, v229, v226
	v_ashrrev_i32_e32 v230, 31, v142
	v_or_b32_e32 v230, 0x80000000, v230
	v_xor_b32_e32 v229, v230, v142
	v_and_b32_e32 v229, 0xffffff80, v229
	v_or_b32_e32 v99, v229, v227
	v_ashrrev_i32_e32 v230, 31, v143
	v_or_b32_e32 v230, 0x80000000, v230
	v_xor_b32_e32 v229, v230, v143
	v_and_b32_e32 v229, 0xffffff80, v229
	v_or_b32_e32 v72, v229, v228
	v_max_u32_e32 v94, v113, v84
	v_min_u32_e32 v84, v113, v84
	v_min_u32_e32 v113, v74, v82
	v_max_u32_e32 v82, v74, v82
	v_max_u32_e32 v74, v79, v93
	v_min_u32_e32 v93, v79, v93
	v_min_u32_e32 v79, v75, v95
	v_max_u32_e32 v95, v75, v95
	v_max_u32_e32 v75, v80, v76
	v_min_u32_e32 v76, v80, v76
	v_min_u32_e32 v80, v78, v71
	v_max_u32_e32 v71, v78, v71
	v_max_u32_e32 v78, v73, v69
	v_min_u32_e32 v69, v73, v69
	v_min_u32_e32 v73, v99, v72
	v_max_u32_e32 v72, v99, v72
	v_max_u32_e32 v99, v94, v113
	v_min_u32_e32 v113, v94, v113
	v_max_u32_e32 v94, v84, v82
	v_min_u32_e32 v82, v84, v82
	v_min_u32_e32 v84, v74, v79
	v_max_u32_e32 v79, v74, v79
	v_min_u32_e32 v74, v93, v95
	v_max_u32_e32 v95, v93, v95
	v_max_u32_e32 v93, v75, v80
	v_min_u32_e32 v80, v75, v80
	v_max_u32_e32 v75, v76, v71
	v_min_u32_e32 v71, v76, v71
	v_min_u32_e32 v76, v78, v73
	v_max_u32_e32 v73, v78, v73
	v_min_u32_e32 v78, v69, v72
	v_max_u32_e32 v72, v69, v72
	v_max_u32_e32 v69, v99, v94
	v_min_u32_e32 v94, v99, v94
	v_max_u32_e32 v99, v113, v82
	v_min_u32_e32 v82, v113, v82
	v_min_u32_e32 v113, v84, v74
	v_max_u32_e32 v74, v84, v74
	v_min_u32_e32 v84, v79, v95
	v_max_u32_e32 v95, v79, v95
	v_max_u32_e32 v79, v93, v75
	v_min_u32_e32 v75, v93, v75
	v_max_u32_e32 v93, v80, v71
	v_min_u32_e32 v71, v80, v71
	v_min_u32_e32 v80, v76, v78
	v_max_u32_e32 v78, v76, v78
	v_min_u32_e32 v76, v73, v72
	v_max_u32_e32 v72, v73, v72
	v_max_u32_e32 v73, v69, v113
	v_min_u32_e32 v113, v69, v113
	v_max_u32_e32 v69, v94, v74
	v_min_u32_e32 v74, v94, v74
	v_max_u32_e32 v94, v99, v84
	v_min_u32_e32 v84, v99, v84
	v_max_u32_e32 v99, v82, v95
	v_min_u32_e32 v95, v82, v95
	v_min_u32_e32 v82, v79, v80
	v_max_u32_e32 v80, v79, v80
	v_min_u32_e32 v79, v75, v78
	v_max_u32_e32 v78, v75, v78
	v_min_u32_e32 v75, v93, v76
	v_max_u32_e32 v76, v93, v76
	v_min_u32_e32 v93, v71, v72
; template <int LOGN>
; DI void bitonic_sort_desc(unsigned (&a)[1 << LOGN]) {
;   constexpr int N = 1 << LOGN;
; #pragma unroll
;   for (int ks = 1; ks <= LOGN; ++ks)
; #pragma unroll
;     ...
; #pragma unroll
;       for (int i = 0; i < N; ++i) {
;         const int k = 1 << ks, j = 1 << js, l = i ^ j;
;         if (l > i) {
;           const bool desc = ((i & k) == 0) || (ks == LOGN);
;           const unsigned x = a[i], y = a[l];
;           const unsigned hi = max(x, y), lo = min(x, y);
;           a[i] = desc ? hi : lo;
;           a[l] = desc ? lo : hi;
;         }
;       }
; }
; DI void merge_top16(unsigned (&a)[16], const unsigned (&b)[16]) {
; #pragma unroll
;   for (int i = 0; i < 16; ++i) a[i] = max(a[i], b[15 - i]);
; #pragma unroll
;     ...
; #pragma unroll
;     for (int i = 0; i < 16; ++i) {
;       const int j = 1 << js, l = i ^ j;
;       if (l > i) {
;         const unsigned x = a[i], y = a[l];
;         a[i] = max(x, y);
;         a[l] = min(x, y);
;       }
;     }
; }
	v_max_u32_e32 v72, v71, v72
	v_max_u32_e32 v71, v73, v94
	v_min_u32_e32 v94, v73, v94
	v_max_u32_e32 v73, v69, v99
	v_min_u32_e32 v99, v69, v99
	v_max_u32_e32 v69, v113, v84
	v_min_u32_e32 v84, v113, v84
	v_max_u32_e32 v113, v74, v95
	v_min_u32_e32 v95, v74, v95
	v_min_u32_e32 v74, v82, v75
	v_max_u32_e32 v75, v82, v75
	v_min_u32_e32 v82, v79, v93
	v_max_u32_e32 v93, v79, v93
	v_min_u32_e32 v79, v80, v76
	v_max_u32_e32 v76, v80, v76
	v_min_u32_e32 v80, v78, v72
	v_max_u32_e32 v72, v78, v72
	v_max_u32_e32 v78, v71, v73
	v_min_u32_e32 v73, v71, v73
	v_max_u32_e32 v71, v94, v99
	v_min_u32_e32 v99, v94, v99
	v_max_u32_e32 v94, v69, v113
	v_min_u32_e32 v113, v69, v113
	v_max_u32_e32 v69, v84, v95
	v_min_u32_e32 v95, v84, v95
	v_min_u32_e32 v84, v74, v82
	v_max_u32_e32 v82, v74, v82
	v_min_u32_e32 v74, v75, v93
	v_max_u32_e32 v93, v75, v93
	v_min_u32_e32 v75, v79, v80
	v_max_u32_e32 v80, v79, v80
	v_min_u32_e32 v79, v76, v72
	v_max_u32_e32 v72, v76, v72
	v_max_u32_e32 v76, v78, v84
	v_min_u32_e32 v84, v78, v84
	v_max_u32_e32 v78, v73, v82
	v_min_u32_e32 v82, v73, v82
	v_max_u32_e32 v73, v71, v74
	v_min_u32_e32 v74, v71, v74
	v_max_u32_e32 v71, v99, v93
	v_min_u32_e32 v93, v99, v93
	v_max_u32_e32 v99, v94, v75
	v_min_u32_e32 v75, v94, v75
	v_max_u32_e32 v94, v113, v80
	v_min_u32_e32 v80, v113, v80
	v_max_u32_e32 v113, v69, v79
	v_min_u32_e32 v79, v69, v79
	v_max_u32_e32 v69, v95, v72
	v_min_u32_e32 v72, v95, v72
	v_max_u32_e32 v95, v76, v99
	v_min_u32_e32 v99, v76, v99
	v_max_u32_e32 v76, v78, v94
	v_min_u32_e32 v94, v78, v94
	v_max_u32_e32 v78, v73, v113
	v_min_u32_e32 v113, v73, v113
	v_max_u32_e32 v73, v71, v69
	v_min_u32_e32 v69, v71, v69
	v_max_u32_e32 v71, v84, v75
	v_min_u32_e32 v75, v84, v75
	v_max_u32_e32 v84, v82, v80
	v_min_u32_e32 v80, v82, v80
	v_max_u32_e32 v82, v74, v79
	v_min_u32_e32 v79, v74, v79
	v_max_u32_e32 v74, v93, v72
	v_min_u32_e32 v72, v93, v72
	v_max_u32_e32 v93, v95, v78
	v_min_u32_e32 v78, v95, v78
	v_max_u32_e32 v95, v76, v73
	v_min_u32_e32 v73, v76, v73
	v_max_u32_e32 v76, v99, v113
	v_min_u32_e32 v113, v99, v113
	v_max_u32_e32 v99, v94, v69
	v_min_u32_e32 v69, v94, v69
	v_max_u32_e32 v94, v71, v82
	v_min_u32_e32 v82, v71, v82
	v_max_u32_e32 v71, v84, v74
	v_min_u32_e32 v74, v84, v74
	v_max_u32_e32 v84, v75, v79
	v_min_u32_e32 v79, v75, v79
	v_max_u32_e32 v75, v80, v72
	v_min_u32_e32 v72, v80, v72
	v_max_u32_e32 v80, v93, v95
	v_min_u32_e32 v95, v93, v95
	v_max_u32_e32 v93, v78, v73
	v_min_u32_e32 v73, v78, v73
	v_max_u32_e32 v78, v76, v99
	v_min_u32_e32 v99, v76, v99
	v_max_u32_e32 v76, v113, v69
	v_min_u32_e32 v69, v113, v69
	v_max_u32_e32 v113, v94, v71
	v_min_u32_e32 v71, v94, v71
	v_max_u32_e32 v94, v82, v74
	v_min_u32_e32 v74, v82, v74
	v_max_u32_e32 v82, v84, v75
	v_min_u32_e32 v75, v84, v75
	v_max_u32_e32 v84, v79, v72
	v_min_u32_e32 v72, v79, v72
	v_max_u32_e32 v79, v117, v72
	v_max_u32_e32 v117, v97, v84
	v_max_u32_e32 v97, v103, v75
	v_max_u32_e32 v103, v102, v82
	v_max_u32_e32 v102, v70, v74
	v_max_u32_e32 v70, v92, v94
	v_max_u32_e32 v92, v77, v71
	v_max_u32_e32 v77, v88, v113
	v_max_u32_e32 v88, v100, v69
	v_max_u32_e32 v100, v116, v76
	v_max_u32_e32 v116, v104, v99
	v_max_u32_e32 v104, v110, v78
	v_max_u32_e32 v110, v108, v73
	v_max_u32_e32 v108, v83, v93
	v_max_u32_e32 v83, v89, v95
	v_max_u32_e32 v89, v87, v80
	v_max_u32_e32 v72, v79, v88
	v_min_u32_e32 v88, v79, v88
	v_max_u32_e32 v79, v117, v100
	v_min_u32_e32 v100, v117, v100
	v_max_u32_e32 v117, v97, v116
	v_min_u32_e32 v116, v97, v116
	v_max_u32_e32 v97, v103, v104
	v_min_u32_e32 v104, v103, v104
	v_max_u32_e32 v103, v102, v110
	v_min_u32_e32 v110, v102, v110
	v_max_u32_e32 v102, v70, v108
	v_min_u32_e32 v108, v70, v108
	v_max_u32_e32 v70, v92, v83
	v_min_u32_e32 v83, v92, v83
	v_max_u32_e32 v92, v77, v89
	v_min_u32_e32 v89, v77, v89
	v_max_u32_e32 v77, v72, v103
	v_min_u32_e32 v103, v72, v103
	v_max_u32_e32 v72, v79, v102
	v_min_u32_e32 v102, v79, v102
	v_max_u32_e32 v79, v117, v70
	v_min_u32_e32 v70, v117, v70
	v_max_u32_e32 v117, v97, v92
	v_min_u32_e32 v92, v97, v92
	v_max_u32_e32 v97, v88, v110
	v_min_u32_e32 v110, v88, v110
	v_max_u32_e32 v88, v100, v108
	v_min_u32_e32 v108, v100, v108
	v_max_u32_e32 v100, v116, v83
	v_min_u32_e32 v83, v116, v83
	v_max_u32_e32 v116, v104, v89
	v_min_u32_e32 v89, v104, v89
	v_max_u32_e32 v104, v77, v79
	v_min_u32_e32 v79, v77, v79
	v_max_u32_e32 v77, v72, v117
	v_min_u32_e32 v117, v72, v117
	v_max_u32_e32 v72, v103, v70
	v_min_u32_e32 v70, v103, v70
	v_max_u32_e32 v103, v102, v92
	v_min_u32_e32 v92, v102, v92
	v_max_u32_e32 v102, v97, v100
	v_min_u32_e32 v100, v97, v100
	v_max_u32_e32 v97, v88, v116
	v_min_u32_e32 v116, v88, v116
	v_max_u32_e32 v88, v110, v83
	v_min_u32_e32 v83, v110, v83
	v_max_u32_e32 v110, v108, v89
	v_min_u32_e32 v89, v108, v89
	v_max_u32_e32 v108, v104, v77
	v_min_u32_e32 v77, v104, v77
	v_max_u32_e32 v104, v79, v117
	v_min_u32_e32 v117, v79, v117
	v_max_u32_e32 v79, v72, v103
	v_min_u32_e32 v103, v72, v103
	v_max_u32_e32 v72, v70, v92
	v_min_u32_e32 v92, v70, v92
	v_max_u32_e32 v70, v102, v97
	v_min_u32_e32 v97, v102, v97
	v_max_u32_e32 v102, v100, v116
	v_min_u32_e32 v116, v100, v116
	v_max_u32_e32 v100, v88, v110
	v_min_u32_e32 v110, v88, v110
	v_max_u32_e32 v88, v83, v89
	v_min_u32_e32 v89, v83, v89
	v_max_u32_e32 v83, v101, v89
	v_max_u32_e32 v101, v96, v88
	v_max_u32_e32 v96, v106, v110
	v_max_u32_e32 v106, v109, v100
	v_max_u32_e32 v109, v85, v116
	v_max_u32_e32 v85, v112, v102
	v_max_u32_e32 v112, v111, v97
	v_max_u32_e32 v111, v98, v70
	v_max_u32_e32 v98, v115, v92
	v_max_u32_e32 v115, v91, v72
	v_max_u32_e32 v91, v107, v103
	v_max_u32_e32 v107, v81, v79
; #define MFMA32(a, b, c) __builtin_amdgcn_mfma_f32_32x32x16_bf16((a), (b), (c), 0, 0, 0)
; DI int crow(int i, int hh) { return (i & 3) + 8 * (i >> 2) + 4 * hh; }
; DI unsigned f2ord(float f) {
;   unsigned u = __float_as_uint(f);
;   return (u & 0x80000000u) ? ~u : (u | 0x80000000u);
; }
; DI void merge_top16(unsigned (&a)[16], const unsigned (&b)[16]) {
; #pragma unroll
;   for (int i = 0; i < 16; ++i) a[i] = max(a[i], b[15 - i]);
; #pragma unroll
;     ...
; #pragma unroll
;     for (int i = 0; i < 16; ++i) {
;       const int j = 1 << js, l = i ^ j;
;       if (l > i) {
;         const unsigned x = a[i], y = a[l];
;         a[i] = max(x, y);
;         a[l] = min(x, y);
;       }
;     }
; }
; DI void peer_top16(const u16* __restrict__ PQrow, const u16* __restrict__ SK, unsigned (&top)[16], int lr, int hh) {
;   bf16x8 qf[8];
; #pragma unroll
;   for (int ks = 0; ks < 8; ++ks) qf[ks] = *(const bf16x8*)(PQrow + ks * 16 + hh * 8);
;   unsigned g[4][16];
; #pragma unroll
;   for (int kt = 0; kt < 4; ++kt) {
;     f32x16 acc;
; #pragma unroll
;     for (int e = 0; e < 16; ++e) acc[e] = 0.f;
; #pragma unroll
;     for (int ks = 0; ks < 8; ++ks) {
;       bf16x8 a = *(const bf16x8*)(SK + (size_t)(kt * 32 + lr) * 128 + ks * 16 + hh * 8);
;       acc = MFMA32(a, qf[ks], acc);
;     }
; #pragma unroll
;     for (int e = 0; e < 16; ++e) {
;       int kidx = kt * 32 + crow(e, hh);
;       g[kt][e] = (f2ord(acc[e]) & ~127u) | (unsigned)(127 - kidx);
;     }
;     bitonic_sort_desc<4>(g[kt]);
	v_max_u32_e32 v81, v105, v117
	v_max_u32_e32 v105, v90, v104
	v_max_u32_e32 v90, v114, v77
	v_max_u32_e32 v114, v86, v108
	v_max_u32_e32 v89, v83, v98
	v_min_u32_e32 v98, v83, v98
	v_max_u32_e32 v83, v101, v115
	v_min_u32_e32 v115, v101, v115
	v_max_u32_e32 v101, v96, v91
	v_min_u32_e32 v91, v96, v91
	v_max_u32_e32 v96, v106, v107
	v_min_u32_e32 v107, v106, v107
	v_max_u32_e32 v106, v109, v81
	v_min_u32_e32 v81, v109, v81
	v_max_u32_e32 v109, v85, v105
	v_min_u32_e32 v105, v85, v105
	v_max_u32_e32 v85, v112, v90
	v_min_u32_e32 v90, v112, v90
	v_max_u32_e32 v112, v111, v114
	v_min_u32_e32 v114, v111, v114
	v_max_u32_e32 v111, v89, v106
	v_min_u32_e32 v106, v89, v106
	v_max_u32_e32 v89, v83, v109
	v_min_u32_e32 v109, v83, v109
	v_max_u32_e32 v83, v101, v85
	v_min_u32_e32 v85, v101, v85
	v_max_u32_e32 v101, v96, v112
	v_min_u32_e32 v112, v96, v112
	v_max_u32_e32 v96, v98, v81
	v_min_u32_e32 v81, v98, v81
	v_max_u32_e32 v98, v115, v105
	v_min_u32_e32 v105, v115, v105
	v_max_u32_e32 v115, v91, v90
	v_min_u32_e32 v90, v91, v90
	v_max_u32_e32 v91, v107, v114
	v_min_u32_e32 v114, v107, v114
	v_max_u32_e32 v107, v111, v83
	v_min_u32_e32 v83, v111, v83
	v_max_u32_e32 v111, v89, v101
	v_min_u32_e32 v101, v89, v101
	v_max_u32_e32 v89, v106, v85
	v_min_u32_e32 v85, v106, v85
	v_max_u32_e32 v106, v109, v112
	v_min_u32_e32 v112, v109, v112
	v_max_u32_e32 v109, v96, v115
	v_min_u32_e32 v115, v96, v115
	v_max_u32_e32 v96, v98, v91
	v_min_u32_e32 v91, v98, v91
	v_max_u32_e32 v98, v81, v90
	v_min_u32_e32 v90, v81, v90
	v_max_u32_e32 v81, v105, v114
	v_min_u32_e32 v114, v105, v114
	v_max_u32_e32 v105, v107, v111
	v_min_u32_e32 v111, v107, v111
	v_max_u32_e32 v107, v83, v101
	v_min_u32_e32 v101, v83, v101
	v_max_u32_e32 v83, v89, v106
	v_min_u32_e32 v106, v89, v106
	v_max_u32_e32 v89, v85, v112
	v_min_u32_e32 v112, v85, v112
	v_max_u32_e32 v85, v109, v96
	v_min_u32_e32 v96, v109, v96
	v_max_u32_e32 v109, v115, v91
	v_min_u32_e32 v91, v115, v91
	v_max_u32_e32 v115, v98, v81
	v_min_u32_e32 v81, v98, v81
	v_max_u32_e32 v98, v90, v114
	v_min_u32_e32 v114, v90, v114
	v_mov_b32_e32 v32, v105
	v_mov_b32_e32 v33, v111
	v_mov_b32_e32 v34, v107
	v_mov_b32_e32 v35, v101
	v_mov_b32_e32 v36, v83
	v_mov_b32_e32 v37, v106
	v_mov_b32_e32 v38, v89
	v_mov_b32_e32 v39, v112
	v_mov_b32_e32 v40, v85
	v_mov_b32_e32 v41, v96
	v_mov_b32_e32 v42, v109
	v_mov_b32_e32 v43, v91
	v_mov_b32_e32 v44, v115
	v_mov_b32_e32 v45, v81
	v_mov_b32_e32 v46, v98
	v_mov_b32_e32 v47, v114
	v_sub_u32_e32 v213, 127, v245
	v_sub_u32_e32 v214, 126, v245
	v_sub_u32_e32 v215, 125, v245
	v_sub_u32_e32 v216, 124, v245
	v_sub_u32_e32 v217, 119, v245
	v_sub_u32_e32 v218, 118, v245
	v_sub_u32_e32 v219, 117, v245
	v_sub_u32_e32 v220, 116, v245
	v_sub_u32_e32 v221, 111, v245
	v_sub_u32_e32 v222, 110, v245
	v_sub_u32_e32 v223, 109, v245
	v_sub_u32_e32 v224, 108, v245
	v_sub_u32_e32 v225, 103, v245
	v_sub_u32_e32 v226, 102, v245
	v_sub_u32_e32 v227, 101, v245
	v_sub_u32_e32 v228, 100, v245
	s_waitcnt vmcnt(7)
	v_mfma_f32_32x32x16_bf16 v[128:143], v[144:147], v[176:179], 0
	s_waitcnt vmcnt(6)
	v_mfma_f32_32x32x16_bf16 v[128:143], v[148:151], v[180:183], v[128:143]
	s_waitcnt vmcnt(5)
	v_mfma_f32_32x32x16_bf16 v[128:143], v[152:155], v[184:187], v[128:143]
	s_waitcnt vmcnt(4)
	v_mfma_f32_32x32x16_bf16 v[128:143], v[156:159], v[188:191], v[128:143]
	s_waitcnt vmcnt(3)
	v_mfma_f32_32x32x16_bf16 v[128:143], v[160:163], v[192:195], v[128:143]
	s_waitcnt vmcnt(2)
	v_mfma_f32_32x32x16_bf16 v[128:143], v[164:167], v[196:199], v[128:143]
	s_waitcnt vmcnt(1)
	v_mfma_f32_32x32x16_bf16 v[128:143], v[168:171], v[200:203], v[128:143]
	s_waitcnt vmcnt(0)
	v_mfma_f32_32x32x16_bf16 v[128:143], v[172:175], v[204:207], v[128:143]
	s_add_u32 s4, s0, 106496
	s_addc_u32 s5, s1, 0
	global_load_dwordx4 v[144:147], v238, s[4:5] offset:0
	global_load_dwordx4 v[148:151], v238, s[4:5] offset:1024
	global_load_dwordx4 v[152:155], v238, s[4:5] offset:2048
	global_load_dwordx4 v[156:159], v238, s[4:5] offset:3072
	global_load_dwordx4 v[160:163], v208, s[4:5] offset:0
	global_load_dwordx4 v[164:167], v208, s[4:5] offset:1024
	global_load_dwordx4 v[168:171], v208, s[4:5] offset:2048
	global_load_dwordx4 v[172:175], v208, s[4:5] offset:3072
	s_nop 7
	s_nop 3
	v_ashrrev_i32_e32 v230, 31, v128
	v_or_b32_e32 v230, 0x80000000, v230
	v_xor_b32_e32 v229, v230, v128
	v_and_b32_e32 v229, 0xffffff80, v229
	v_or_b32_e32 v114, v229, v213
	v_ashrrev_i32_e32 v230, 31, v129
	v_or_b32_e32 v230, 0x80000000, v230
	v_xor_b32_e32 v229, v230, v129
	v_and_b32_e32 v229, 0xffffff80, v229
	v_or_b32_e32 v98, v229, v214
	v_ashrrev_i32_e32 v230, 31, v130
	v_or_b32_e32 v230, 0x80000000, v230
	v_xor_b32_e32 v229, v230, v130
	v_and_b32_e32 v229, 0xffffff80, v229
	v_or_b32_e32 v81, v229, v215
	v_ashrrev_i32_e32 v230, 31, v131
	v_or_b32_e32 v230, 0x80000000, v230
	v_xor_b32_e32 v229, v230, v131
	v_and_b32_e32 v229, 0xffffff80, v229
	v_or_b32_e32 v115, v229, v216
	v_ashrrev_i32_e32 v230, 31, v132
	v_or_b32_e32 v230, 0x80000000, v230
	v_xor_b32_e32 v229, v230, v132
	v_and_b32_e32 v229, 0xffffff80, v229
	v_or_b32_e32 v91, v229, v217
	v_ashrrev_i32_e32 v230, 31, v133
	v_or_b32_e32 v230, 0x80000000, v230
	v_xor_b32_e32 v229, v230, v133
	v_and_b32_e32 v229, 0xffffff80, v229
	v_or_b32_e32 v109, v229, v218
	v_ashrrev_i32_e32 v230, 31, v134
	v_or_b32_e32 v230, 0x80000000, v230
	v_xor_b32_e32 v229, v230, v134
	v_and_b32_e32 v229, 0xffffff80, v229
	v_or_b32_e32 v96, v229, v219
	v_ashrrev_i32_e32 v230, 31, v135
	v_or_b32_e32 v230, 0x80000000, v230
	v_xor_b32_e32 v229, v230, v135
	v_and_b32_e32 v229, 0xffffff80, v229
	v_or_b32_e32 v85, v229, v220
	v_ashrrev_i32_e32 v230, 31, v136
; DI int crow(int i, int hh) { return (i & 3) + 8 * (i >> 2) + 4 * hh; }
; template <int LOGN>
; DI void bitonic_sort_desc(unsigned (&a)[1 << LOGN]) {
;   constexpr int N = 1 << LOGN;
; #pragma unroll
;   for (int ks = 1; ks <= LOGN; ++ks)
; #pragma unroll
;     ...
; #pragma unroll
;       for (int i = 0; i < N; ++i) {
;         const int k = 1 << ks, j = 1 << js, l = i ^ j;
;         if (l > i) {
;           const bool desc = ((i & k) == 0) || (ks == LOGN);
;           const unsigned x = a[i], y = a[l];
;           const unsigned hi = max(x, y), lo = min(x, y);
;           a[i] = desc ? hi : lo;
;           a[l] = desc ? lo : hi;
;         }
;       }
; }
; DI void peer_top16(const u16* __restrict__ PQrow, const u16* __restrict__ SK, unsigned (&top)[16], int lr, int hh) {
;     ...
;     for (int e = 0; e < 16; ++e) {
;       int kidx = kt * 32 + crow(e, hh);
;       g[kt][e] = (f2ord(acc[e]) & ~127u) | (unsigned)(127 - kidx);
;     }
;     bitonic_sort_desc<4>(g[kt]);
	v_or_b32_e32 v230, 0x80000000, v230
	v_xor_b32_e32 v229, v230, v136
	v_and_b32_e32 v229, 0xffffff80, v229
	v_or_b32_e32 v112, v229, v221
	v_ashrrev_i32_e32 v230, 31, v137
	v_or_b32_e32 v230, 0x80000000, v230
	v_xor_b32_e32 v229, v230, v137
	v_and_b32_e32 v229, 0xffffff80, v229
	v_or_b32_e32 v89, v229, v222
	v_ashrrev_i32_e32 v230, 31, v138
	v_or_b32_e32 v230, 0x80000000, v230
	v_xor_b32_e32 v229, v230, v138
	v_and_b32_e32 v229, 0xffffff80, v229
	v_or_b32_e32 v106, v229, v223
	v_ashrrev_i32_e32 v230, 31, v139
	v_or_b32_e32 v230, 0x80000000, v230
	v_xor_b32_e32 v229, v230, v139
	v_and_b32_e32 v229, 0xffffff80, v229
	v_or_b32_e32 v83, v229, v224
	v_ashrrev_i32_e32 v230, 31, v140
	v_or_b32_e32 v230, 0x80000000, v230
	v_xor_b32_e32 v229, v230, v140
	v_and_b32_e32 v229, 0xffffff80, v229
	v_or_b32_e32 v101, v229, v225
	v_ashrrev_i32_e32 v230, 31, v141
	v_or_b32_e32 v230, 0x80000000, v230
	v_xor_b32_e32 v229, v230, v141
	v_and_b32_e32 v229, 0xffffff80, v229
	v_or_b32_e32 v107, v229, v226
	v_ashrrev_i32_e32 v230, 31, v142
	v_or_b32_e32 v230, 0x80000000, v230
	v_xor_b32_e32 v229, v230, v142
	v_and_b32_e32 v229, 0xffffff80, v229
	v_or_b32_e32 v111, v229, v227
	v_ashrrev_i32_e32 v230, 31, v143
	v_or_b32_e32 v230, 0x80000000, v230
	v_xor_b32_e32 v229, v230, v143
	v_and_b32_e32 v229, 0xffffff80, v229
	v_or_b32_e32 v105, v229, v228
	v_subrev_u32_e32 v213, 32, v213
	v_subrev_u32_e32 v214, 32, v214
	v_subrev_u32_e32 v215, 32, v215
	v_subrev_u32_e32 v216, 32, v216
	v_subrev_u32_e32 v217, 32, v217
	v_subrev_u32_e32 v218, 32, v218
	v_subrev_u32_e32 v219, 32, v219
	v_subrev_u32_e32 v220, 32, v220
	v_subrev_u32_e32 v221, 32, v221
	v_subrev_u32_e32 v222, 32, v222
	v_subrev_u32_e32 v223, 32, v223
	v_subrev_u32_e32 v224, 32, v224
	v_subrev_u32_e32 v225, 32, v225
	v_subrev_u32_e32 v226, 32, v226
	v_subrev_u32_e32 v227, 32, v227
	v_subrev_u32_e32 v228, 32, v228
	v_max_u32_e32 v90, v114, v98
	v_min_u32_e32 v98, v114, v98
	v_min_u32_e32 v114, v81, v115
	v_max_u32_e32 v115, v81, v115
	v_max_u32_e32 v81, v91, v109
	v_min_u32_e32 v109, v91, v109
	v_min_u32_e32 v91, v96, v85
	v_max_u32_e32 v85, v96, v85
	v_max_u32_e32 v96, v112, v89
	v_min_u32_e32 v89, v112, v89
	v_min_u32_e32 v112, v106, v83
	v_max_u32_e32 v83, v106, v83
	v_max_u32_e32 v106, v101, v107
	v_min_u32_e32 v107, v101, v107
	v_min_u32_e32 v101, v111, v105
	v_max_u32_e32 v105, v111, v105
	v_max_u32_e32 v111, v90, v114
	v_min_u32_e32 v114, v90, v114
	v_max_u32_e32 v90, v98, v115
	v_min_u32_e32 v115, v98, v115
	v_min_u32_e32 v98, v81, v91
	v_max_u32_e32 v91, v81, v91
	v_min_u32_e32 v81, v109, v85
	v_max_u32_e32 v85, v109, v85
	v_max_u32_e32 v109, v96, v112
	v_min_u32_e32 v112, v96, v112
	v_max_u32_e32 v96, v89, v83
	v_min_u32_e32 v83, v89, v83
	v_min_u32_e32 v89, v106, v101
	v_max_u32_e32 v101, v106, v101
	v_min_u32_e32 v106, v107, v105
	v_max_u32_e32 v105, v107, v105
	v_max_u32_e32 v107, v111, v90
	v_min_u32_e32 v90, v111, v90
	v_max_u32_e32 v111, v114, v115
	v_min_u32_e32 v115, v114, v115
	v_min_u32_e32 v114, v98, v81
	v_max_u32_e32 v81, v98, v81
	v_min_u32_e32 v98, v91, v85
	v_max_u32_e32 v85, v91, v85
	v_max_u32_e32 v91, v109, v96
	v_min_u32_e32 v96, v109, v96
	v_max_u32_e32 v109, v112, v83
	v_min_u32_e32 v83, v112, v83
	v_min_u32_e32 v112, v89, v106
	v_max_u32_e32 v106, v89, v106
	v_min_u32_e32 v89, v101, v105
	v_max_u32_e32 v105, v101, v105
	v_max_u32_e32 v101, v107, v114
	v_min_u32_e32 v114, v107, v114
	v_max_u32_e32 v107, v90, v81
	v_min_u32_e32 v81, v90, v81
	v_max_u32_e32 v90, v111, v98
	v_min_u32_e32 v98, v111, v98
	v_max_u32_e32 v111, v115, v85
	v_min_u32_e32 v85, v115, v85
	v_min_u32_e32 v115, v91, v112
	v_max_u32_e32 v112, v91, v112
	v_min_u32_e32 v91, v96, v106
	v_max_u32_e32 v106, v96, v106
	v_min_u32_e32 v96, v109, v89
	v_max_u32_e32 v89, v109, v89
	v_min_u32_e32 v109, v83, v105
	v_max_u32_e32 v105, v83, v105
	v_max_u32_e32 v83, v101, v90
	v_min_u32_e32 v90, v101, v90
	v_max_u32_e32 v101, v107, v111
	v_min_u32_e32 v111, v107, v111
	v_max_u32_e32 v107, v114, v98
	v_min_u32_e32 v98, v114, v98
	v_max_u32_e32 v114, v81, v85
	v_min_u32_e32 v85, v81, v85
	v_min_u32_e32 v81, v115, v96
	v_max_u32_e32 v96, v115, v96
	v_min_u32_e32 v115, v91, v109
	v_max_u32_e32 v109, v91, v109
	v_min_u32_e32 v91, v112, v89
	v_max_u32_e32 v89, v112, v89
	v_min_u32_e32 v112, v106, v105
	v_max_u32_e32 v105, v106, v105
	v_max_u32_e32 v106, v83, v101
	v_min_u32_e32 v101, v83, v101
	v_max_u32_e32 v83, v90, v111
	v_min_u32_e32 v111, v90, v111
	v_max_u32_e32 v90, v107, v114
	v_min_u32_e32 v114, v107, v114
	v_max_u32_e32 v107, v98, v85
	v_min_u32_e32 v85, v98, v85
	v_min_u32_e32 v98, v81, v115
	v_max_u32_e32 v115, v81, v115
	v_min_u32_e32 v81, v96, v109
	v_max_u32_e32 v109, v96, v109
	v_min_u32_e32 v96, v91, v112
	v_max_u32_e32 v112, v91, v112
	v_min_u32_e32 v91, v89, v105
	v_max_u32_e32 v105, v89, v105
	v_max_u32_e32 v89, v106, v98
	v_min_u32_e32 v98, v106, v98
	v_max_u32_e32 v106, v101, v115
	v_min_u32_e32 v115, v101, v115
	v_max_u32_e32 v101, v83, v81
	v_min_u32_e32 v81, v83, v81
	v_max_u32_e32 v83, v111, v109
	v_min_u32_e32 v109, v111, v109
	v_max_u32_e32 v111, v90, v96
	v_min_u32_e32 v96, v90, v96
	v_max_u32_e32 v90, v114, v112
	v_min_u32_e32 v112, v114, v112
	v_max_u32_e32 v114, v107, v91
	v_min_u32_e32 v91, v107, v91
	v_max_u32_e32 v107, v85, v105
	v_min_u32_e32 v105, v85, v105
	v_max_u32_e32 v85, v89, v111
	v_min_u32_e32 v111, v89, v111
	v_max_u32_e32 v89, v106, v90
	v_min_u32_e32 v90, v106, v90
	v_max_u32_e32 v106, v101, v114
	v_min_u32_e32 v114, v101, v114
	v_max_u32_e32 v101, v83, v107
	v_min_u32_e32 v107, v83, v107
	v_max_u32_e32 v83, v98, v96
	v_min_u32_e32 v96, v98, v96
	v_max_u32_e32 v98, v115, v112
	v_min_u32_e32 v112, v115, v112
	v_max_u32_e32 v115, v81, v91
	v_min_u32_e32 v91, v81, v91
	v_max_u32_e32 v81, v109, v105
	v_min_u32_e32 v105, v109, v105
	v_max_u32_e32 v109, v85, v106
	v_min_u32_e32 v106, v85, v106
	v_max_u32_e32 v85, v89, v101
	v_min_u32_e32 v101, v89, v101
	v_max_u32_e32 v89, v111, v114
	v_min_u32_e32 v114, v111, v114
	v_max_u32_e32 v111, v90, v107
	v_min_u32_e32 v107, v90, v107
	v_max_u32_e32 v90, v83, v115
	v_min_u32_e32 v115, v83, v115
	v_max_u32_e32 v83, v98, v81
	v_min_u32_e32 v81, v98, v81
	v_max_u32_e32 v98, v96, v91
	v_min_u32_e32 v91, v96, v91
	v_max_u32_e32 v96, v112, v105
	v_min_u32_e32 v105, v112, v105
	v_max_u32_e32 v112, v109, v85
	v_min_u32_e32 v85, v109, v85
	v_max_u32_e32 v109, v106, v101
	v_min_u32_e32 v101, v106, v101
	v_max_u32_e32 v106, v89, v111
	v_min_u32_e32 v111, v89, v111
	v_max_u32_e32 v89, v114, v107
	v_min_u32_e32 v107, v114, v107
	v_max_u32_e32 v114, v90, v83
	v_min_u32_e32 v83, v90, v83
	v_max_u32_e32 v90, v115, v81
	v_min_u32_e32 v81, v115, v81
	v_max_u32_e32 v115, v98, v96
	v_min_u32_e32 v96, v98, v96
	v_max_u32_e32 v98, v91, v105
	v_min_u32_e32 v105, v91, v105
	s_waitcnt vmcnt(7)
; #define MFMA32(a, b, c) __builtin_amdgcn_mfma_f32_32x32x16_bf16((a), (b), (c), 0, 0, 0)
; DI int crow(int i, int hh) { return (i & 3) + 8 * (i >> 2) + 4 * hh; }
; DI unsigned f2ord(float f) {
;   unsigned u = __float_as_uint(f);
;   return (u & 0x80000000u) ? ~u : (u | 0x80000000u);
; }
; DI void peer_top16(const u16* __restrict__ PQrow, const u16* __restrict__ SK, unsigned (&top)[16], int lr, int hh) {
;     ...
;   for (int kt = 0; kt < 4; ++kt) {
;     f32x16 acc;
; #pragma unroll
;     for (int e = 0; e < 16; ++e) acc[e] = 0.f;
; #pragma unroll
;     for (int ks = 0; ks < 8; ++ks) {
;       bf16x8 a = *(const bf16x8*)(SK + (size_t)(kt * 32 + lr) * 128 + ks * 16 + hh * 8);
;       acc = MFMA32(a, qf[ks], acc);
;     }
; #pragma unroll
;     for (int e = 0; e < 16; ++e) {
;       int kidx = kt * 32 + crow(e, hh);
;       g[kt][e] = (f2ord(acc[e]) & ~127u) | (unsigned)(127 - kidx);
;     }
;     bitonic_sort_desc<4>(g[kt]);
	v_mfma_f32_32x32x16_bf16 v[128:143], v[144:147], v[176:179], 0
	s_waitcnt vmcnt(6)
	v_mfma_f32_32x32x16_bf16 v[128:143], v[148:151], v[180:183], v[128:143]
	s_waitcnt vmcnt(5)
	v_mfma_f32_32x32x16_bf16 v[128:143], v[152:155], v[184:187], v[128:143]
	s_waitcnt vmcnt(4)
	v_mfma_f32_32x32x16_bf16 v[128:143], v[156:159], v[188:191], v[128:143]
	s_waitcnt vmcnt(3)
	v_mfma_f32_32x32x16_bf16 v[128:143], v[160:163], v[192:195], v[128:143]
	s_waitcnt vmcnt(2)
	v_mfma_f32_32x32x16_bf16 v[128:143], v[164:167], v[196:199], v[128:143]
	s_waitcnt vmcnt(1)
	v_mfma_f32_32x32x16_bf16 v[128:143], v[168:171], v[200:203], v[128:143]
	s_waitcnt vmcnt(0)
	v_mfma_f32_32x32x16_bf16 v[128:143], v[172:175], v[204:207], v[128:143]
	s_add_u32 s4, s0, 114688
	s_addc_u32 s5, s1, 0
	global_load_dwordx4 v[144:147], v238, s[4:5] offset:0
	global_load_dwordx4 v[148:151], v238, s[4:5] offset:1024
	global_load_dwordx4 v[152:155], v238, s[4:5] offset:2048
	global_load_dwordx4 v[156:159], v238, s[4:5] offset:3072
	global_load_dwordx4 v[160:163], v208, s[4:5] offset:0
	global_load_dwordx4 v[164:167], v208, s[4:5] offset:1024
	global_load_dwordx4 v[168:171], v208, s[4:5] offset:2048
	global_load_dwordx4 v[172:175], v208, s[4:5] offset:3072
	s_nop 7
	s_nop 3
	v_ashrrev_i32_e32 v230, 31, v128
	v_or_b32_e32 v230, 0x80000000, v230
	v_xor_b32_e32 v229, v230, v128
	v_and_b32_e32 v229, 0xffffff80, v229
	v_or_b32_e32 v91, v229, v213
	v_ashrrev_i32_e32 v230, 31, v129
	v_or_b32_e32 v230, 0x80000000, v230
	v_xor_b32_e32 v229, v230, v129
	v_and_b32_e32 v229, 0xffffff80, v229
	v_or_b32_e32 v88, v229, v214
	v_ashrrev_i32_e32 v230, 31, v130
	v_or_b32_e32 v230, 0x80000000, v230
	v_xor_b32_e32 v229, v230, v130
	v_and_b32_e32 v229, 0xffffff80, v229
	v_or_b32_e32 v110, v229, v215
	v_ashrrev_i32_e32 v230, 31, v131
	v_or_b32_e32 v230, 0x80000000, v230
	v_xor_b32_e32 v229, v230, v131
	v_and_b32_e32 v229, 0xffffff80, v229
	v_or_b32_e32 v100, v229, v216
	v_ashrrev_i32_e32 v230, 31, v132
	v_or_b32_e32 v230, 0x80000000, v230
	v_xor_b32_e32 v229, v230, v132
	v_and_b32_e32 v229, 0xffffff80, v229
	v_or_b32_e32 v116, v229, v217
	v_ashrrev_i32_e32 v230, 31, v133
	v_or_b32_e32 v230, 0x80000000, v230
	v_xor_b32_e32 v229, v230, v133
	v_and_b32_e32 v229, 0xffffff80, v229
	v_or_b32_e32 v102, v229, v218
	v_ashrrev_i32_e32 v230, 31, v134
	v_or_b32_e32 v230, 0x80000000, v230
	v_xor_b32_e32 v229, v230, v134
	v_and_b32_e32 v229, 0xffffff80, v229
	v_or_b32_e32 v97, v229, v219
	v_ashrrev_i32_e32 v230, 31, v135
	v_or_b32_e32 v230, 0x80000000, v230
	v_xor_b32_e32 v229, v230, v135
	v_and_b32_e32 v229, 0xffffff80, v229
	v_or_b32_e32 v70, v229, v220
	v_ashrrev_i32_e32 v230, 31, v136
	v_or_b32_e32 v230, 0x80000000, v230
	v_xor_b32_e32 v229, v230, v136
	v_and_b32_e32 v229, 0xffffff80, v229
	v_or_b32_e32 v92, v229, v221
	v_ashrrev_i32_e32 v230, 31, v137
	v_or_b32_e32 v230, 0x80000000, v230
	v_xor_b32_e32 v229, v230, v137
	v_and_b32_e32 v229, 0xffffff80, v229
	v_or_b32_e32 v72, v229, v222
	v_ashrrev_i32_e32 v230, 31, v138
	v_or_b32_e32 v230, 0x80000000, v230
	v_xor_b32_e32 v229, v230, v138
	v_and_b32_e32 v229, 0xffffff80, v229
	v_or_b32_e32 v103, v229, v223
	v_ashrrev_i32_e32 v230, 31, v139
	v_or_b32_e32 v230, 0x80000000, v230
	v_xor_b32_e32 v229, v230, v139
	v_and_b32_e32 v229, 0xffffff80, v229
	v_or_b32_e32 v79, v229, v224
	v_ashrrev_i32_e32 v230, 31, v140
	v_or_b32_e32 v230, 0x80000000, v230
	v_xor_b32_e32 v229, v230, v140
	v_and_b32_e32 v229, 0xffffff80, v229
	v_or_b32_e32 v117, v229, v225
	v_ashrrev_i32_e32 v230, 31, v141
	v_or_b32_e32 v230, 0x80000000, v230
	v_xor_b32_e32 v229, v230, v141
	v_and_b32_e32 v229, 0xffffff80, v229
	v_or_b32_e32 v104, v229, v226
	v_ashrrev_i32_e32 v230, 31, v142
	v_or_b32_e32 v230, 0x80000000, v230
	v_xor_b32_e32 v229, v230, v142
	v_and_b32_e32 v229, 0xffffff80, v229
	v_or_b32_e32 v77, v229, v227
	v_ashrrev_i32_e32 v230, 31, v143
	v_or_b32_e32 v230, 0x80000000, v230
	v_xor_b32_e32 v229, v230, v143
	v_and_b32_e32 v229, 0xffffff80, v229
	v_or_b32_e32 v108, v229, v228
	v_subrev_u32_e32 v213, 32, v213
	v_subrev_u32_e32 v214, 32, v214
	v_subrev_u32_e32 v215, 32, v215
	v_subrev_u32_e32 v216, 32, v216
	v_subrev_u32_e32 v217, 32, v217
	v_subrev_u32_e32 v218, 32, v218
	v_subrev_u32_e32 v219, 32, v219
	v_subrev_u32_e32 v220, 32, v220
	v_subrev_u32_e32 v221, 32, v221
	v_subrev_u32_e32 v222, 32, v222
	v_subrev_u32_e32 v223, 32, v223
	v_subrev_u32_e32 v224, 32, v224
	v_subrev_u32_e32 v225, 32, v225
	v_subrev_u32_e32 v226, 32, v226
	v_subrev_u32_e32 v227, 32, v227
	v_subrev_u32_e32 v228, 32, v228
	v_max_u32_e32 v86, v91, v88
	v_min_u32_e32 v88, v91, v88
	v_min_u32_e32 v91, v110, v100
	v_max_u32_e32 v100, v110, v100
	v_max_u32_e32 v110, v116, v102
	v_min_u32_e32 v102, v116, v102
	v_min_u32_e32 v116, v97, v70
	v_max_u32_e32 v70, v97, v70
	v_max_u32_e32 v97, v92, v72
	v_min_u32_e32 v72, v92, v72
	v_min_u32_e32 v92, v103, v79
	v_max_u32_e32 v79, v103, v79
	v_max_u32_e32 v103, v117, v104
	v_min_u32_e32 v104, v117, v104
	v_min_u32_e32 v117, v77, v108
	v_max_u32_e32 v108, v77, v108
	v_max_u32_e32 v77, v86, v91
	v_min_u32_e32 v91, v86, v91
	v_max_u32_e32 v86, v88, v100
	v_min_u32_e32 v100, v88, v100
	v_min_u32_e32 v88, v110, v116
	v_max_u32_e32 v116, v110, v116
	v_min_u32_e32 v110, v102, v70
	v_max_u32_e32 v70, v102, v70
	v_max_u32_e32 v102, v97, v92
	v_min_u32_e32 v92, v97, v92
	v_max_u32_e32 v97, v72, v79
	v_min_u32_e32 v79, v72, v79
	v_min_u32_e32 v72, v103, v117
	v_max_u32_e32 v117, v103, v117
	v_min_u32_e32 v103, v104, v108
	v_max_u32_e32 v108, v104, v108
	v_max_u32_e32 v104, v77, v86
	v_min_u32_e32 v86, v77, v86
	v_max_u32_e32 v77, v91, v100
	v_min_u32_e32 v100, v91, v100
	v_min_u32_e32 v91, v88, v110
; template <int LOGN>
; DI void bitonic_sort_desc(unsigned (&a)[1 << LOGN]) {
;   constexpr int N = 1 << LOGN;
; #pragma unroll
;   for (int ks = 1; ks <= LOGN; ++ks)
; #pragma unroll
;     ...
; #pragma unroll
;       for (int i = 0; i < N; ++i) {
;         const int k = 1 << ks, j = 1 << js, l = i ^ j;
;         if (l > i) {
;           const bool desc = ((i & k) == 0) || (ks == LOGN);
;           const unsigned x = a[i], y = a[l];
;           const unsigned hi = max(x, y), lo = min(x, y);
;           a[i] = desc ? hi : lo;
;           a[l] = desc ? lo : hi;
;         }
;       }
; }
; DI void merge_top16(unsigned (&a)[16], const unsigned (&b)[16]) {
; #pragma unroll
;   for (int i = 0; i < 16; ++i) a[i] = max(a[i], b[15 - i]);
; #pragma unroll
;     ...
; #pragma unroll
;     for (int i = 0; i < 16; ++i) {
;       const int j = 1 << js, l = i ^ j;
;       if (l > i) {
;         const unsigned x = a[i], y = a[l];
;         a[i] = max(x, y);
;         a[l] = min(x, y);
;       }
;     }
; }
	v_max_u32_e32 v110, v88, v110
	v_min_u32_e32 v88, v116, v70
	v_max_u32_e32 v70, v116, v70
	v_max_u32_e32 v116, v102, v97
	v_min_u32_e32 v97, v102, v97
	v_max_u32_e32 v102, v92, v79
	v_min_u32_e32 v79, v92, v79
	v_min_u32_e32 v92, v72, v103
	v_max_u32_e32 v103, v72, v103
	v_min_u32_e32 v72, v117, v108
	v_max_u32_e32 v108, v117, v108
	v_max_u32_e32 v117, v104, v91
	v_min_u32_e32 v91, v104, v91
	v_max_u32_e32 v104, v86, v110
	v_min_u32_e32 v110, v86, v110
	v_max_u32_e32 v86, v77, v88
	v_min_u32_e32 v88, v77, v88
	v_max_u32_e32 v77, v100, v70
	v_min_u32_e32 v70, v100, v70
	v_min_u32_e32 v100, v116, v92
	v_max_u32_e32 v92, v116, v92
	v_min_u32_e32 v116, v97, v103
	v_max_u32_e32 v103, v97, v103
	v_min_u32_e32 v97, v102, v72
	v_max_u32_e32 v72, v102, v72
	v_min_u32_e32 v102, v79, v108
	v_max_u32_e32 v108, v79, v108
	v_max_u32_e32 v79, v117, v86
	v_min_u32_e32 v86, v117, v86
	v_max_u32_e32 v117, v104, v77
	v_min_u32_e32 v77, v104, v77
	v_max_u32_e32 v104, v91, v88
	v_min_u32_e32 v88, v91, v88
	v_max_u32_e32 v91, v110, v70
	v_min_u32_e32 v70, v110, v70
	v_min_u32_e32 v110, v100, v97
	v_max_u32_e32 v97, v100, v97
	v_min_u32_e32 v100, v116, v102
	v_max_u32_e32 v102, v116, v102
	v_min_u32_e32 v116, v92, v72
	v_max_u32_e32 v72, v92, v72
	v_min_u32_e32 v92, v103, v108
	v_max_u32_e32 v108, v103, v108
	v_max_u32_e32 v103, v79, v117
	v_min_u32_e32 v117, v79, v117
	v_max_u32_e32 v79, v86, v77
	v_min_u32_e32 v77, v86, v77
	v_max_u32_e32 v86, v104, v91
	v_min_u32_e32 v91, v104, v91
	v_max_u32_e32 v104, v88, v70
	v_min_u32_e32 v70, v88, v70
	v_min_u32_e32 v88, v110, v100
	v_max_u32_e32 v100, v110, v100
	v_min_u32_e32 v110, v97, v102
	v_max_u32_e32 v102, v97, v102
	v_min_u32_e32 v97, v116, v92
	v_max_u32_e32 v92, v116, v92
	v_min_u32_e32 v116, v72, v108
	v_max_u32_e32 v108, v72, v108
	v_max_u32_e32 v72, v103, v88
	v_min_u32_e32 v88, v103, v88
	v_max_u32_e32 v103, v117, v100
	v_min_u32_e32 v100, v117, v100
	v_max_u32_e32 v117, v79, v110
	v_min_u32_e32 v110, v79, v110
	v_max_u32_e32 v79, v77, v102
	v_min_u32_e32 v102, v77, v102
	v_max_u32_e32 v77, v86, v97
	v_min_u32_e32 v97, v86, v97
	v_max_u32_e32 v86, v91, v92
	v_min_u32_e32 v92, v91, v92
	v_max_u32_e32 v91, v104, v116
	v_min_u32_e32 v116, v104, v116
	v_max_u32_e32 v104, v70, v108
	v_min_u32_e32 v108, v70, v108
	v_max_u32_e32 v70, v72, v77
	v_min_u32_e32 v77, v72, v77
	v_max_u32_e32 v72, v103, v86
	v_min_u32_e32 v86, v103, v86
	v_max_u32_e32 v103, v117, v91
	v_min_u32_e32 v91, v117, v91
	v_max_u32_e32 v117, v79, v104
	v_min_u32_e32 v104, v79, v104
	v_max_u32_e32 v79, v88, v97
	v_min_u32_e32 v97, v88, v97
	v_max_u32_e32 v88, v100, v92
	v_min_u32_e32 v92, v100, v92
	v_max_u32_e32 v100, v110, v116
	v_min_u32_e32 v116, v110, v116
	v_max_u32_e32 v110, v102, v108
	v_min_u32_e32 v108, v102, v108
	v_max_u32_e32 v102, v70, v103
	v_min_u32_e32 v103, v70, v103
	v_max_u32_e32 v70, v72, v117
	v_min_u32_e32 v117, v72, v117
	v_max_u32_e32 v72, v77, v91
	v_min_u32_e32 v91, v77, v91
	v_max_u32_e32 v77, v86, v104
	v_min_u32_e32 v104, v86, v104
	v_max_u32_e32 v86, v79, v100
	v_min_u32_e32 v100, v79, v100
	v_max_u32_e32 v79, v88, v110
	v_min_u32_e32 v110, v88, v110
	v_max_u32_e32 v88, v97, v116
	v_min_u32_e32 v116, v97, v116
	v_max_u32_e32 v97, v92, v108
	v_min_u32_e32 v108, v92, v108
	v_max_u32_e32 v92, v102, v70
	v_min_u32_e32 v70, v102, v70
	v_max_u32_e32 v102, v103, v117
	v_min_u32_e32 v117, v103, v117
	v_max_u32_e32 v103, v72, v77
	v_min_u32_e32 v77, v72, v77
	v_max_u32_e32 v72, v91, v104
	v_min_u32_e32 v104, v91, v104
	v_max_u32_e32 v91, v86, v79
	v_min_u32_e32 v79, v86, v79
	v_max_u32_e32 v86, v100, v110
	v_min_u32_e32 v110, v100, v110
	v_max_u32_e32 v100, v88, v97
	v_min_u32_e32 v97, v88, v97
	v_max_u32_e32 v88, v116, v108
	v_min_u32_e32 v108, v116, v108
	v_max_u32_e32 v116, v112, v108
	v_max_u32_e32 v112, v85, v88
	v_max_u32_e32 v85, v109, v97
	v_max_u32_e32 v109, v101, v100
	v_max_u32_e32 v101, v106, v110
	v_max_u32_e32 v106, v111, v86
	v_max_u32_e32 v111, v89, v79
	v_max_u32_e32 v89, v107, v91
	v_max_u32_e32 v107, v114, v104
	v_max_u32_e32 v114, v83, v72
	v_max_u32_e32 v83, v90, v77
	v_max_u32_e32 v90, v81, v103
	v_max_u32_e32 v81, v115, v117
	v_max_u32_e32 v115, v96, v102
	v_max_u32_e32 v96, v98, v70
	v_max_u32_e32 v98, v105, v92
	v_max_u32_e32 v108, v116, v107
	v_min_u32_e32 v107, v116, v107
	v_max_u32_e32 v116, v112, v114
	v_min_u32_e32 v114, v112, v114
	v_max_u32_e32 v112, v85, v83
	v_min_u32_e32 v83, v85, v83
	v_max_u32_e32 v85, v109, v90
	v_min_u32_e32 v90, v109, v90
	v_max_u32_e32 v109, v101, v81
	v_min_u32_e32 v81, v101, v81
	v_max_u32_e32 v101, v106, v115
	v_min_u32_e32 v115, v106, v115
	v_max_u32_e32 v106, v111, v96
	v_min_u32_e32 v96, v111, v96
	v_max_u32_e32 v111, v89, v98
	v_min_u32_e32 v98, v89, v98
	v_max_u32_e32 v89, v108, v109
	v_min_u32_e32 v109, v108, v109
	v_max_u32_e32 v108, v116, v101
	v_min_u32_e32 v101, v116, v101
	v_max_u32_e32 v116, v112, v106
	v_min_u32_e32 v106, v112, v106
	v_max_u32_e32 v112, v85, v111
	v_min_u32_e32 v111, v85, v111
	v_max_u32_e32 v85, v107, v81
	v_min_u32_e32 v81, v107, v81
	v_max_u32_e32 v107, v114, v115
	v_min_u32_e32 v115, v114, v115
	v_max_u32_e32 v114, v83, v96
	v_min_u32_e32 v96, v83, v96
	v_max_u32_e32 v83, v90, v98
	v_min_u32_e32 v98, v90, v98
	v_max_u32_e32 v90, v89, v116
	v_min_u32_e32 v116, v89, v116
	v_max_u32_e32 v89, v108, v112
	v_min_u32_e32 v112, v108, v112
	v_max_u32_e32 v108, v109, v106
	v_min_u32_e32 v106, v109, v106
	v_max_u32_e32 v109, v101, v111
	v_min_u32_e32 v111, v101, v111
	v_max_u32_e32 v101, v85, v114
	v_min_u32_e32 v114, v85, v114
	v_max_u32_e32 v85, v107, v83
	v_min_u32_e32 v83, v107, v83
	v_max_u32_e32 v107, v81, v96
	v_min_u32_e32 v96, v81, v96
	v_max_u32_e32 v81, v115, v98
	v_min_u32_e32 v98, v115, v98
	v_max_u32_e32 v115, v90, v89
	v_min_u32_e32 v89, v90, v89
	v_max_u32_e32 v90, v116, v112
	v_min_u32_e32 v112, v116, v112
	v_max_u32_e32 v116, v108, v109
	v_min_u32_e32 v109, v108, v109
	v_max_u32_e32 v108, v106, v111
	v_min_u32_e32 v111, v106, v111
	v_max_u32_e32 v106, v101, v85
	v_min_u32_e32 v85, v101, v85
	v_max_u32_e32 v101, v114, v83
	v_min_u32_e32 v83, v114, v83
	v_max_u32_e32 v114, v107, v81
	v_min_u32_e32 v81, v107, v81
	v_max_u32_e32 v107, v96, v98
	v_min_u32_e32 v98, v96, v98
	s_waitcnt vmcnt(7)
; #define MFMA32(a, b, c) __builtin_amdgcn_mfma_f32_32x32x16_bf16((a), (b), (c), 0, 0, 0)
; DI int crow(int i, int hh) { return (i & 3) + 8 * (i >> 2) + 4 * hh; }
; DI void peer_top16(const u16* __restrict__ PQrow, const u16* __restrict__ SK, unsigned (&top)[16], int lr, int hh) {
;     ...
;   for (int kt = 0; kt < 4; ++kt) {
;     f32x16 acc;
; #pragma unroll
;     for (int e = 0; e < 16; ++e) acc[e] = 0.f;
; #pragma unroll
;     for (int ks = 0; ks < 8; ++ks) {
;       bf16x8 a = *(const bf16x8*)(SK + (size_t)(kt * 32 + lr) * 128 + ks * 16 + hh * 8);
;       acc = MFMA32(a, qf[ks], acc);
;     }
; #pragma unroll
;     for (int e = 0; e < 16; ++e) {
;       int kidx = kt * 32 + crow(e, hh);
;       g[kt][e] = (f2ord(acc[e]) & ~127u) | (unsigned)(127 - kidx);
;     }
;     bitonic_sort_desc<4>(g[kt]);
	v_mfma_f32_32x32x16_bf16 v[128:143], v[144:147], v[176:179], 0
	s_waitcnt vmcnt(6)
	v_mfma_f32_32x32x16_bf16 v[128:143], v[148:151], v[180:183], v[128:143]
	s_waitcnt vmcnt(5)
	v_mfma_f32_32x32x16_bf16 v[128:143], v[152:155], v[184:187], v[128:143]
	s_waitcnt vmcnt(4)
	v_mfma_f32_32x32x16_bf16 v[128:143], v[156:159], v[188:191], v[128:143]
	s_waitcnt vmcnt(3)
	v_mfma_f32_32x32x16_bf16 v[128:143], v[160:163], v[192:195], v[128:143]
	s_waitcnt vmcnt(2)
	v_mfma_f32_32x32x16_bf16 v[128:143], v[164:167], v[196:199], v[128:143]
	s_waitcnt vmcnt(1)
	v_mfma_f32_32x32x16_bf16 v[128:143], v[168:171], v[200:203], v[128:143]
	s_waitcnt vmcnt(0)
	v_mfma_f32_32x32x16_bf16 v[128:143], v[172:175], v[204:207], v[128:143]
	s_add_u32 s4, s0, 122880
	s_addc_u32 s5, s1, 0
	global_load_dwordx4 v[144:147], v238, s[4:5] offset:0
	global_load_dwordx4 v[148:151], v238, s[4:5] offset:1024
	global_load_dwordx4 v[152:155], v238, s[4:5] offset:2048
	global_load_dwordx4 v[156:159], v238, s[4:5] offset:3072
	global_load_dwordx4 v[160:163], v208, s[4:5] offset:0
	global_load_dwordx4 v[164:167], v208, s[4:5] offset:1024
	global_load_dwordx4 v[168:171], v208, s[4:5] offset:2048
	global_load_dwordx4 v[172:175], v208, s[4:5] offset:3072
	s_nop 7
	s_nop 3
	v_ashrrev_i32_e32 v230, 31, v128
	v_or_b32_e32 v230, 0x80000000, v230
	v_xor_b32_e32 v229, v230, v128
	v_and_b32_e32 v229, 0xffffff80, v229
	v_or_b32_e32 v96, v229, v213
	v_ashrrev_i32_e32 v230, 31, v129
	v_or_b32_e32 v230, 0x80000000, v230
	v_xor_b32_e32 v229, v230, v129
	v_and_b32_e32 v229, 0xffffff80, v229
	v_or_b32_e32 v88, v229, v214
	v_ashrrev_i32_e32 v230, 31, v130
	v_or_b32_e32 v230, 0x80000000, v230
	v_xor_b32_e32 v229, v230, v130
	v_and_b32_e32 v229, 0xffffff80, v229
	v_or_b32_e32 v97, v229, v215
	v_ashrrev_i32_e32 v230, 31, v131
	v_or_b32_e32 v230, 0x80000000, v230
	v_xor_b32_e32 v229, v230, v131
	v_and_b32_e32 v229, 0xffffff80, v229
	v_or_b32_e32 v100, v229, v216
	v_ashrrev_i32_e32 v230, 31, v132
	v_or_b32_e32 v230, 0x80000000, v230
	v_xor_b32_e32 v229, v230, v132
	v_and_b32_e32 v229, 0xffffff80, v229
	v_or_b32_e32 v110, v229, v217
	v_ashrrev_i32_e32 v230, 31, v133
	v_or_b32_e32 v230, 0x80000000, v230
	v_xor_b32_e32 v229, v230, v133
	v_and_b32_e32 v229, 0xffffff80, v229
	v_or_b32_e32 v86, v229, v218
	v_ashrrev_i32_e32 v230, 31, v134
	v_or_b32_e32 v230, 0x80000000, v230
	v_xor_b32_e32 v229, v230, v134
	v_and_b32_e32 v229, 0xffffff80, v229
	v_or_b32_e32 v79, v229, v219
	v_ashrrev_i32_e32 v230, 31, v135
	v_or_b32_e32 v230, 0x80000000, v230
	v_xor_b32_e32 v229, v230, v135
	v_and_b32_e32 v229, 0xffffff80, v229
	v_or_b32_e32 v91, v229, v220
	v_ashrrev_i32_e32 v230, 31, v136
	v_or_b32_e32 v230, 0x80000000, v230
	v_xor_b32_e32 v229, v230, v136
	v_and_b32_e32 v229, 0xffffff80, v229
	v_or_b32_e32 v104, v229, v221
	v_ashrrev_i32_e32 v230, 31, v137
	v_or_b32_e32 v230, 0x80000000, v230
	v_xor_b32_e32 v229, v230, v137
	v_and_b32_e32 v229, 0xffffff80, v229
	v_or_b32_e32 v72, v229, v222
	v_ashrrev_i32_e32 v230, 31, v138
	v_or_b32_e32 v230, 0x80000000, v230
	v_xor_b32_e32 v229, v230, v138
	v_and_b32_e32 v229, 0xffffff80, v229
	v_or_b32_e32 v77, v229, v223
	v_ashrrev_i32_e32 v230, 31, v139
	v_or_b32_e32 v230, 0x80000000, v230
	v_xor_b32_e32 v229, v230, v139
	v_and_b32_e32 v229, 0xffffff80, v229
	v_or_b32_e32 v103, v229, v224
	v_ashrrev_i32_e32 v230, 31, v140
	v_or_b32_e32 v230, 0x80000000, v230
	v_xor_b32_e32 v229, v230, v140
	v_and_b32_e32 v229, 0xffffff80, v229
	v_or_b32_e32 v117, v229, v225
	v_ashrrev_i32_e32 v230, 31, v141
	v_or_b32_e32 v230, 0x80000000, v230
	v_xor_b32_e32 v229, v230, v141
	v_and_b32_e32 v229, 0xffffff80, v229
	v_or_b32_e32 v102, v229, v226
	v_ashrrev_i32_e32 v230, 31, v142
	v_or_b32_e32 v230, 0x80000000, v230
	v_xor_b32_e32 v229, v230, v142
	v_and_b32_e32 v229, 0xffffff80, v229
	v_or_b32_e32 v70, v229, v227
	v_ashrrev_i32_e32 v230, 31, v143
	v_or_b32_e32 v230, 0x80000000, v230
	v_xor_b32_e32 v229, v230, v143
	v_and_b32_e32 v229, 0xffffff80, v229
	v_or_b32_e32 v92, v229, v228
	v_subrev_u32_e32 v213, 32, v213
	v_subrev_u32_e32 v214, 32, v214
	v_subrev_u32_e32 v215, 32, v215
	v_subrev_u32_e32 v216, 32, v216
	v_subrev_u32_e32 v217, 32, v217
	v_subrev_u32_e32 v218, 32, v218
	v_subrev_u32_e32 v219, 32, v219
	v_subrev_u32_e32 v220, 32, v220
	v_subrev_u32_e32 v221, 32, v221
	v_subrev_u32_e32 v222, 32, v222
	v_subrev_u32_e32 v223, 32, v223
	v_subrev_u32_e32 v224, 32, v224
	v_subrev_u32_e32 v225, 32, v225
	v_subrev_u32_e32 v226, 32, v226
	v_subrev_u32_e32 v227, 32, v227
	v_subrev_u32_e32 v228, 32, v228
	v_max_u32_e32 v105, v96, v88
	v_min_u32_e32 v88, v96, v88
	v_min_u32_e32 v96, v97, v100
	v_max_u32_e32 v100, v97, v100
	v_max_u32_e32 v97, v110, v86
	v_min_u32_e32 v86, v110, v86
	v_min_u32_e32 v110, v79, v91
	v_max_u32_e32 v91, v79, v91
	v_max_u32_e32 v79, v104, v72
	v_min_u32_e32 v72, v104, v72
	v_min_u32_e32 v104, v77, v103
	v_max_u32_e32 v103, v77, v103
	v_max_u32_e32 v77, v117, v102
	v_min_u32_e32 v102, v117, v102
	v_min_u32_e32 v117, v70, v92
	v_max_u32_e32 v92, v70, v92
	v_max_u32_e32 v70, v105, v96
	v_min_u32_e32 v96, v105, v96
	v_max_u32_e32 v105, v88, v100
	v_min_u32_e32 v100, v88, v100
	v_min_u32_e32 v88, v97, v110
	v_max_u32_e32 v110, v97, v110
	v_min_u32_e32 v97, v86, v91
	v_max_u32_e32 v91, v86, v91
	v_max_u32_e32 v86, v79, v104
	v_min_u32_e32 v104, v79, v104
	v_max_u32_e32 v79, v72, v103
	v_min_u32_e32 v103, v72, v103
	v_min_u32_e32 v72, v77, v117
	v_max_u32_e32 v117, v77, v117
	v_min_u32_e32 v77, v102, v92
	v_max_u32_e32 v92, v102, v92
	v_max_u32_e32 v102, v70, v105
	v_min_u32_e32 v105, v70, v105
	v_max_u32_e32 v70, v96, v100
	v_min_u32_e32 v100, v96, v100
	v_min_u32_e32 v96, v88, v97
; #define MFMA32(a, b, c) __builtin_amdgcn_mfma_f32_32x32x16_bf16((a), (b), (c), 0, 0, 0)
; template <int LOGN>
; DI void bitonic_sort_desc(unsigned (&a)[1 << LOGN]) {
;   constexpr int N = 1 << LOGN;
; #pragma unroll
;   for (int ks = 1; ks <= LOGN; ++ks)
; #pragma unroll
;     ...
; #pragma unroll
;       for (int i = 0; i < N; ++i) {
;         const int k = 1 << ks, j = 1 << js, l = i ^ j;
;         if (l > i) {
;           const bool desc = ((i & k) == 0) || (ks == LOGN);
;           const unsigned x = a[i], y = a[l];
;           const unsigned hi = max(x, y), lo = min(x, y);
;           a[i] = desc ? hi : lo;
;           a[l] = desc ? lo : hi;
;         }
;       }
; }
; DI void peer_top16(const u16* __restrict__ PQrow, const u16* __restrict__ SK, unsigned (&top)[16], int lr, int hh) {
;     ...
;     for (int ks = 0; ks < 8; ++ks) {
;       bf16x8 a = *(const bf16x8*)(SK + (size_t)(kt * 32 + lr) * 128 + ks * 16 + hh * 8);
;       acc = MFMA32(a, qf[ks], acc);
	v_max_u32_e32 v97, v88, v97
	v_min_u32_e32 v88, v110, v91
	v_max_u32_e32 v91, v110, v91
	v_max_u32_e32 v110, v86, v79
	v_min_u32_e32 v79, v86, v79
	v_max_u32_e32 v86, v104, v103
	v_min_u32_e32 v103, v104, v103
	v_min_u32_e32 v104, v72, v77
	v_max_u32_e32 v77, v72, v77
	v_min_u32_e32 v72, v117, v92
	v_max_u32_e32 v92, v117, v92
	v_max_u32_e32 v117, v102, v96
	v_min_u32_e32 v96, v102, v96
	v_max_u32_e32 v102, v105, v97
	v_min_u32_e32 v97, v105, v97
	v_max_u32_e32 v105, v70, v88
	v_min_u32_e32 v88, v70, v88
	v_max_u32_e32 v70, v100, v91
	v_min_u32_e32 v91, v100, v91
	v_min_u32_e32 v100, v110, v104
	v_max_u32_e32 v104, v110, v104
	v_min_u32_e32 v110, v79, v77
	v_max_u32_e32 v77, v79, v77
	v_min_u32_e32 v79, v86, v72
	v_max_u32_e32 v72, v86, v72
	v_min_u32_e32 v86, v103, v92
	v_max_u32_e32 v92, v103, v92
	v_max_u32_e32 v103, v117, v105
	v_min_u32_e32 v105, v117, v105
	v_max_u32_e32 v117, v102, v70
	v_min_u32_e32 v70, v102, v70
	v_max_u32_e32 v102, v96, v88
	v_min_u32_e32 v88, v96, v88
	v_max_u32_e32 v96, v97, v91
	v_min_u32_e32 v91, v97, v91
	v_min_u32_e32 v97, v100, v79
	v_max_u32_e32 v79, v100, v79
	v_min_u32_e32 v100, v110, v86
	v_max_u32_e32 v86, v110, v86
	v_min_u32_e32 v110, v104, v72
	v_max_u32_e32 v72, v104, v72
	v_min_u32_e32 v104, v77, v92
	v_max_u32_e32 v92, v77, v92
	v_max_u32_e32 v77, v103, v117
	v_min_u32_e32 v117, v103, v117
	v_max_u32_e32 v103, v105, v70
	v_min_u32_e32 v70, v105, v70
	v_max_u32_e32 v105, v102, v96
	v_min_u32_e32 v96, v102, v96
	v_max_u32_e32 v102, v88, v91
	v_min_u32_e32 v91, v88, v91
	v_min_u32_e32 v88, v97, v100
	v_max_u32_e32 v100, v97, v100
	v_min_u32_e32 v97, v79, v86
	v_max_u32_e32 v86, v79, v86
	v_min_u32_e32 v79, v110, v104
	v_max_u32_e32 v104, v110, v104
	v_min_u32_e32 v110, v72, v92
	v_max_u32_e32 v92, v72, v92
	v_max_u32_e32 v72, v77, v88
	v_min_u32_e32 v88, v77, v88
	v_max_u32_e32 v77, v117, v100
	v_min_u32_e32 v100, v117, v100
	v_max_u32_e32 v117, v103, v97
	v_min_u32_e32 v97, v103, v97
	v_max_u32_e32 v103, v70, v86
	v_min_u32_e32 v86, v70, v86
	v_max_u32_e32 v70, v105, v79
	v_min_u32_e32 v79, v105, v79
	v_max_u32_e32 v105, v96, v104
	v_min_u32_e32 v104, v96, v104
	v_max_u32_e32 v96, v102, v110
	v_min_u32_e32 v110, v102, v110
	v_max_u32_e32 v102, v91, v92
	v_min_u32_e32 v92, v91, v92
	v_max_u32_e32 v91, v72, v70
	v_min_u32_e32 v70, v72, v70
	v_max_u32_e32 v72, v77, v105
	v_min_u32_e32 v105, v77, v105
	v_max_u32_e32 v77, v117, v96
	v_min_u32_e32 v96, v117, v96
	v_max_u32_e32 v117, v103, v102
	v_min_u32_e32 v102, v103, v102
	v_max_u32_e32 v103, v88, v79
	v_min_u32_e32 v79, v88, v79
	v_max_u32_e32 v88, v100, v104
	v_min_u32_e32 v104, v100, v104
	v_max_u32_e32 v100, v97, v110
	v_min_u32_e32 v110, v97, v110
	v_max_u32_e32 v97, v86, v92
	v_min_u32_e32 v92, v86, v92
	v_max_u32_e32 v86, v91, v77
	v_min_u32_e32 v77, v91, v77
	v_max_u32_e32 v91, v72, v117
	v_min_u32_e32 v117, v72, v117
	v_max_u32_e32 v72, v70, v96
	v_min_u32_e32 v96, v70, v96
	v_max_u32_e32 v70, v105, v102
	v_min_u32_e32 v102, v105, v102
	v_max_u32_e32 v105, v103, v100
	v_min_u32_e32 v100, v103, v100
	v_max_u32_e32 v103, v88, v97
	v_min_u32_e32 v97, v88, v97
	v_max_u32_e32 v88, v79, v110
	v_min_u32_e32 v110, v79, v110
	v_max_u32_e32 v79, v104, v92
	v_min_u32_e32 v92, v104, v92
	v_max_u32_e32 v104, v86, v91
	v_min_u32_e32 v91, v86, v91
	v_max_u32_e32 v86, v77, v117
	v_min_u32_e32 v117, v77, v117
	v_max_u32_e32 v77, v72, v70
	v_min_u32_e32 v70, v72, v70
	v_max_u32_e32 v72, v96, v102
	v_min_u32_e32 v102, v96, v102
	v_max_u32_e32 v96, v105, v103
	v_min_u32_e32 v103, v105, v103
	v_max_u32_e32 v105, v100, v97
	v_min_u32_e32 v97, v100, v97
	v_max_u32_e32 v100, v88, v79
	v_min_u32_e32 v79, v88, v79
	v_max_u32_e32 v88, v110, v92
	v_min_u32_e32 v92, v110, v92
	s_waitcnt vmcnt(7)
	v_mfma_f32_32x32x16_bf16 v[128:143], v[144:147], v[176:179], 0
	s_waitcnt vmcnt(6)
	v_mfma_f32_32x32x16_bf16 v[128:143], v[148:151], v[180:183], v[128:143]
	s_waitcnt vmcnt(5)
	v_mfma_f32_32x32x16_bf16 v[128:143], v[152:155], v[184:187], v[128:143]
	s_waitcnt vmcnt(4)
	v_mfma_f32_32x32x16_bf16 v[128:143], v[156:159], v[188:191], v[128:143]
	s_waitcnt vmcnt(3)
	v_mfma_f32_32x32x16_bf16 v[128:143], v[160:163], v[192:195], v[128:143]
	s_waitcnt vmcnt(2)
	v_mfma_f32_32x32x16_bf16 v[128:143], v[164:167], v[196:199], v[128:143]
	s_waitcnt vmcnt(1)
	v_mfma_f32_32x32x16_bf16 v[128:143], v[168:171], v[200:203], v[128:143]
	s_waitcnt vmcnt(0)
; DI int crow(int i, int hh) { return (i & 3) + 8 * (i >> 2) + 4 * hh; }
; template <int LOGN>
; DI void bitonic_sort_desc(unsigned (&a)[1 << LOGN]) {
;   constexpr int N = 1 << LOGN;
; #pragma unroll
;   for (int ks = 1; ks <= LOGN; ++ks)
; #pragma unroll
;     ...
; #pragma unroll
;       for (int i = 0; i < N; ++i) {
;         const int k = 1 << ks, j = 1 << js, l = i ^ j;
;         if (l > i) {
;           const bool desc = ((i & k) == 0) || (ks == LOGN);
;           const unsigned x = a[i], y = a[l];
;           const unsigned hi = max(x, y), lo = min(x, y);
;           a[i] = desc ? hi : lo;
;           a[l] = desc ? lo : hi;
;         }
;       }
; }
; DI void peer_top16(const u16* __restrict__ PQrow, const u16* __restrict__ SK, unsigned (&top)[16], int lr, int hh) {
;     ...
; #pragma unroll
;     for (int e = 0; e < 16; ++e) {
;       int kidx = kt * 32 + crow(e, hh);
;       g[kt][e] = (f2ord(acc[e]) & ~127u) | (unsigned)(127 - kidx);
;     }
;     bitonic_sort_desc<4>(g[kt]);
	v_mfma_f32_32x32x16_bf16 v[128:143], v[172:175], v[204:207], v[128:143]
	s_nop 7
	s_nop 3
	v_ashrrev_i32_e32 v230, 31, v128
	v_or_b32_e32 v230, 0x80000000, v230
	v_xor_b32_e32 v229, v230, v128
	v_and_b32_e32 v229, 0xffffff80, v229
	v_or_b32_e32 v110, v229, v213
	v_ashrrev_i32_e32 v230, 31, v129
	v_or_b32_e32 v230, 0x80000000, v230
	v_xor_b32_e32 v229, v230, v129
	v_and_b32_e32 v229, 0xffffff80, v229
	v_or_b32_e32 v84, v229, v214
	v_ashrrev_i32_e32 v230, 31, v130
	v_or_b32_e32 v230, 0x80000000, v230
	v_xor_b32_e32 v229, v230, v130
	v_and_b32_e32 v229, 0xffffff80, v229
	v_or_b32_e32 v75, v229, v215
	v_ashrrev_i32_e32 v230, 31, v131
	v_or_b32_e32 v230, 0x80000000, v230
	v_xor_b32_e32 v229, v230, v131
	v_and_b32_e32 v229, 0xffffff80, v229
	v_or_b32_e32 v82, v229, v216
	v_ashrrev_i32_e32 v230, 31, v132
	v_or_b32_e32 v230, 0x80000000, v230
	v_xor_b32_e32 v229, v230, v132
	v_and_b32_e32 v229, 0xffffff80, v229
	v_or_b32_e32 v74, v229, v217
	v_ashrrev_i32_e32 v230, 31, v133
	v_or_b32_e32 v230, 0x80000000, v230
	v_xor_b32_e32 v229, v230, v133
	v_and_b32_e32 v229, 0xffffff80, v229
	v_or_b32_e32 v94, v229, v218
	v_ashrrev_i32_e32 v230, 31, v134
	v_or_b32_e32 v230, 0x80000000, v230
	v_xor_b32_e32 v229, v230, v134
	v_and_b32_e32 v229, 0xffffff80, v229
	v_or_b32_e32 v71, v229, v219
	v_ashrrev_i32_e32 v230, 31, v135
	v_or_b32_e32 v230, 0x80000000, v230
	v_xor_b32_e32 v229, v230, v135
	v_and_b32_e32 v229, 0xffffff80, v229
	v_or_b32_e32 v113, v229, v220
	v_ashrrev_i32_e32 v230, 31, v136
	v_or_b32_e32 v230, 0x80000000, v230
	v_xor_b32_e32 v229, v230, v136
	v_and_b32_e32 v229, 0xffffff80, v229
	v_or_b32_e32 v69, v229, v221
	v_ashrrev_i32_e32 v230, 31, v137
	v_or_b32_e32 v230, 0x80000000, v230
	v_xor_b32_e32 v229, v230, v137
	v_and_b32_e32 v229, 0xffffff80, v229
	v_or_b32_e32 v76, v229, v222
	v_ashrrev_i32_e32 v230, 31, v138
	v_or_b32_e32 v230, 0x80000000, v230
	v_xor_b32_e32 v229, v230, v138
	v_and_b32_e32 v229, 0xffffff80, v229
	v_or_b32_e32 v99, v229, v223
	v_ashrrev_i32_e32 v230, 31, v139
	v_or_b32_e32 v230, 0x80000000, v230
	v_xor_b32_e32 v229, v230, v139
	v_and_b32_e32 v229, 0xffffff80, v229
	v_or_b32_e32 v78, v229, v224
	v_ashrrev_i32_e32 v230, 31, v140
	v_or_b32_e32 v230, 0x80000000, v230
	v_xor_b32_e32 v229, v230, v140
	v_and_b32_e32 v229, 0xffffff80, v229
	v_or_b32_e32 v73, v229, v225
	v_ashrrev_i32_e32 v230, 31, v141
	v_or_b32_e32 v230, 0x80000000, v230
	v_xor_b32_e32 v229, v230, v141
	v_and_b32_e32 v229, 0xffffff80, v229
	v_or_b32_e32 v93, v229, v226
	v_ashrrev_i32_e32 v230, 31, v142
	v_or_b32_e32 v230, 0x80000000, v230
	v_xor_b32_e32 v229, v230, v142
	v_and_b32_e32 v229, 0xffffff80, v229
	v_or_b32_e32 v95, v229, v227
	v_ashrrev_i32_e32 v230, 31, v143
	v_or_b32_e32 v230, 0x80000000, v230
	v_xor_b32_e32 v229, v230, v143
	v_and_b32_e32 v229, 0xffffff80, v229
	v_or_b32_e32 v80, v229, v228
	v_max_u32_e32 v87, v110, v84
	v_min_u32_e32 v84, v110, v84
	v_min_u32_e32 v110, v75, v82
	v_max_u32_e32 v82, v75, v82
	v_max_u32_e32 v75, v74, v94
	v_min_u32_e32 v94, v74, v94
	v_min_u32_e32 v74, v71, v113
	v_max_u32_e32 v113, v71, v113
	v_max_u32_e32 v71, v69, v76
	v_min_u32_e32 v76, v69, v76
	v_min_u32_e32 v69, v99, v78
	v_max_u32_e32 v78, v99, v78
	v_max_u32_e32 v99, v73, v93
	v_min_u32_e32 v93, v73, v93
	v_min_u32_e32 v73, v95, v80
	v_max_u32_e32 v80, v95, v80
	v_max_u32_e32 v95, v87, v110
	v_min_u32_e32 v110, v87, v110
	v_max_u32_e32 v87, v84, v82
	v_min_u32_e32 v82, v84, v82
	v_min_u32_e32 v84, v75, v74
	v_max_u32_e32 v74, v75, v74
	v_min_u32_e32 v75, v94, v113
	v_max_u32_e32 v113, v94, v113
	v_max_u32_e32 v94, v71, v69
	v_min_u32_e32 v69, v71, v69
	v_max_u32_e32 v71, v76, v78
	v_min_u32_e32 v78, v76, v78
	v_min_u32_e32 v76, v99, v73
	v_max_u32_e32 v73, v99, v73
	v_min_u32_e32 v99, v93, v80
	v_max_u32_e32 v80, v93, v80
	v_max_u32_e32 v93, v95, v87
	v_min_u32_e32 v87, v95, v87
	v_max_u32_e32 v95, v110, v82
	v_min_u32_e32 v82, v110, v82
	v_min_u32_e32 v110, v84, v75
	v_max_u32_e32 v75, v84, v75
	v_min_u32_e32 v84, v74, v113
	v_max_u32_e32 v113, v74, v113
	v_max_u32_e32 v74, v94, v71
	v_min_u32_e32 v71, v94, v71
	v_max_u32_e32 v94, v69, v78
	v_min_u32_e32 v78, v69, v78
	v_min_u32_e32 v69, v76, v99
	v_max_u32_e32 v99, v76, v99
	v_min_u32_e32 v76, v73, v80
	v_max_u32_e32 v80, v73, v80
	v_max_u32_e32 v73, v93, v110
	v_min_u32_e32 v110, v93, v110
	v_max_u32_e32 v93, v87, v75
	v_min_u32_e32 v75, v87, v75
	v_max_u32_e32 v87, v95, v84
	v_min_u32_e32 v84, v95, v84
	v_max_u32_e32 v95, v82, v113
	v_min_u32_e32 v113, v82, v113
	v_min_u32_e32 v82, v74, v69
	v_max_u32_e32 v69, v74, v69
	v_min_u32_e32 v74, v71, v99
	v_max_u32_e32 v99, v71, v99
	v_min_u32_e32 v71, v94, v76
	v_max_u32_e32 v76, v94, v76
	v_min_u32_e32 v94, v78, v80
	v_max_u32_e32 v80, v78, v80
	v_max_u32_e32 v78, v73, v87
	v_min_u32_e32 v87, v73, v87
	v_max_u32_e32 v73, v93, v95
	v_min_u32_e32 v95, v93, v95
	v_max_u32_e32 v93, v110, v84
	v_min_u32_e32 v84, v110, v84
	v_max_u32_e32 v110, v75, v113
	v_min_u32_e32 v113, v75, v113
	v_min_u32_e32 v75, v82, v71
	v_max_u32_e32 v71, v82, v71
	v_min_u32_e32 v82, v74, v94
	v_max_u32_e32 v94, v74, v94
	v_min_u32_e32 v74, v69, v76
	v_max_u32_e32 v76, v69, v76
	v_min_u32_e32 v69, v99, v80
	v_max_u32_e32 v80, v99, v80
	v_max_u32_e32 v99, v78, v73
	v_min_u32_e32 v73, v78, v73
	v_max_u32_e32 v78, v87, v95
	v_min_u32_e32 v95, v87, v95
	v_max_u32_e32 v87, v93, v110
	v_min_u32_e32 v110, v93, v110
	v_max_u32_e32 v93, v84, v113
	v_min_u32_e32 v113, v84, v113
	v_min_u32_e32 v84, v75, v82
	v_max_u32_e32 v82, v75, v82
	v_min_u32_e32 v75, v71, v94
	v_max_u32_e32 v94, v71, v94
	v_min_u32_e32 v71, v74, v69
	v_max_u32_e32 v69, v74, v69
	v_min_u32_e32 v74, v76, v80
	v_max_u32_e32 v80, v76, v80
; template <int LOGN>
; DI void bitonic_sort_desc(unsigned (&a)[1 << LOGN]) {
;   constexpr int N = 1 << LOGN;
; #pragma unroll
;   for (int ks = 1; ks <= LOGN; ++ks)
; #pragma unroll
;     ...
; #pragma unroll
;       for (int i = 0; i < N; ++i) {
;         const int k = 1 << ks, j = 1 << js, l = i ^ j;
;         if (l > i) {
;           const bool desc = ((i & k) == 0) || (ks == LOGN);
;           const unsigned x = a[i], y = a[l];
;           const unsigned hi = max(x, y), lo = min(x, y);
;           a[i] = desc ? hi : lo;
;           a[l] = desc ? lo : hi;
;         }
;       }
; }
; DI void merge_top16(unsigned (&a)[16], const unsigned (&b)[16]) {
; #pragma unroll
;   for (int i = 0; i < 16; ++i) a[i] = max(a[i], b[15 - i]);
; #pragma unroll
;     ...
; #pragma unroll
;     for (int i = 0; i < 16; ++i) {
;       const int j = 1 << js, l = i ^ j;
;       if (l > i) {
;         const unsigned x = a[i], y = a[l];
;         a[i] = max(x, y);
;         a[l] = min(x, y);
;       }
;     }
; }
; DI void peer_top16(const u16* __restrict__ PQrow, const u16* __restrict__ SK, unsigned (&top)[16], int lr, int hh) {
;     ...
;   merge_top16(g[0], g[1]);
;   merge_top16(g[2], g[3]);
;   merge_top16(g[0], g[2]);
	v_max_u32_e32 v76, v99, v84
	v_min_u32_e32 v84, v99, v84
	v_max_u32_e32 v99, v73, v82
	v_min_u32_e32 v82, v73, v82
	v_max_u32_e32 v73, v78, v75
	v_min_u32_e32 v75, v78, v75
	v_max_u32_e32 v78, v95, v94
	v_min_u32_e32 v94, v95, v94
	v_max_u32_e32 v95, v87, v71
	v_min_u32_e32 v71, v87, v71
	v_max_u32_e32 v87, v110, v69
	v_min_u32_e32 v69, v110, v69
	v_max_u32_e32 v110, v93, v74
	v_min_u32_e32 v74, v93, v74
	v_max_u32_e32 v93, v113, v80
	v_min_u32_e32 v80, v113, v80
	v_max_u32_e32 v113, v76, v95
	v_min_u32_e32 v95, v76, v95
	v_max_u32_e32 v76, v99, v87
	v_min_u32_e32 v87, v99, v87
	v_max_u32_e32 v99, v73, v110
	v_min_u32_e32 v110, v73, v110
	v_max_u32_e32 v73, v78, v93
	v_min_u32_e32 v93, v78, v93
	v_max_u32_e32 v78, v84, v71
	v_min_u32_e32 v71, v84, v71
	v_max_u32_e32 v84, v82, v69
	v_min_u32_e32 v69, v82, v69
	v_max_u32_e32 v82, v75, v74
	v_min_u32_e32 v74, v75, v74
	v_max_u32_e32 v75, v94, v80
	v_min_u32_e32 v80, v94, v80
	v_max_u32_e32 v94, v113, v99
	v_min_u32_e32 v99, v113, v99
	v_max_u32_e32 v113, v76, v73
	v_min_u32_e32 v73, v76, v73
	v_max_u32_e32 v76, v95, v110
	v_min_u32_e32 v110, v95, v110
	v_max_u32_e32 v95, v87, v93
	v_min_u32_e32 v93, v87, v93
	v_max_u32_e32 v87, v78, v82
	v_min_u32_e32 v82, v78, v82
	v_max_u32_e32 v78, v84, v75
	v_min_u32_e32 v75, v84, v75
	v_max_u32_e32 v84, v71, v74
	v_min_u32_e32 v74, v71, v74
	v_max_u32_e32 v71, v69, v80
	v_min_u32_e32 v80, v69, v80
	v_max_u32_e32 v69, v94, v113
	v_min_u32_e32 v113, v94, v113
	v_max_u32_e32 v94, v99, v73
	v_min_u32_e32 v73, v99, v73
	v_max_u32_e32 v99, v76, v95
	v_min_u32_e32 v95, v76, v95
	v_max_u32_e32 v76, v110, v93
	v_min_u32_e32 v93, v110, v93
	v_max_u32_e32 v110, v87, v78
	v_min_u32_e32 v78, v87, v78
	v_max_u32_e32 v87, v82, v75
	v_min_u32_e32 v75, v82, v75
	v_max_u32_e32 v82, v84, v71
	v_min_u32_e32 v71, v84, v71
	v_max_u32_e32 v84, v74, v80
	v_min_u32_e32 v80, v74, v80
	v_max_u32_e32 v74, v104, v80
	v_max_u32_e32 v104, v91, v84
	v_max_u32_e32 v91, v86, v71
	v_max_u32_e32 v86, v117, v82
	v_max_u32_e32 v117, v77, v75
	v_max_u32_e32 v77, v70, v87
	v_max_u32_e32 v70, v72, v78
	v_max_u32_e32 v72, v102, v110
	v_max_u32_e32 v102, v96, v93
	v_max_u32_e32 v96, v103, v76
	v_max_u32_e32 v103, v105, v95
	v_max_u32_e32 v105, v97, v99
	v_max_u32_e32 v97, v100, v73
	v_max_u32_e32 v100, v79, v94
	v_max_u32_e32 v79, v88, v113
	v_max_u32_e32 v88, v92, v69
	v_max_u32_e32 v80, v74, v102
	v_min_u32_e32 v102, v74, v102
	v_max_u32_e32 v74, v104, v96
	v_min_u32_e32 v96, v104, v96
	v_max_u32_e32 v104, v91, v103
	v_min_u32_e32 v103, v91, v103
	v_max_u32_e32 v91, v86, v105
	v_min_u32_e32 v105, v86, v105
	v_max_u32_e32 v86, v117, v97
	v_min_u32_e32 v97, v117, v97
	v_max_u32_e32 v117, v77, v100
	v_min_u32_e32 v100, v77, v100
	v_max_u32_e32 v77, v70, v79
	v_min_u32_e32 v79, v70, v79
	v_max_u32_e32 v70, v72, v88
	v_min_u32_e32 v88, v72, v88
	v_max_u32_e32 v72, v80, v86
	v_min_u32_e32 v86, v80, v86
	v_max_u32_e32 v80, v74, v117
	v_min_u32_e32 v117, v74, v117
	v_max_u32_e32 v74, v104, v77
	v_min_u32_e32 v77, v104, v77
	v_max_u32_e32 v104, v91, v70
	v_min_u32_e32 v70, v91, v70
	v_max_u32_e32 v91, v102, v97
	v_min_u32_e32 v97, v102, v97
	v_max_u32_e32 v102, v96, v100
	v_min_u32_e32 v100, v96, v100
	v_max_u32_e32 v96, v103, v79
	v_min_u32_e32 v79, v103, v79
	v_max_u32_e32 v103, v105, v88
	v_min_u32_e32 v88, v105, v88
	v_max_u32_e32 v105, v72, v74
	v_min_u32_e32 v74, v72, v74
	v_max_u32_e32 v72, v80, v104
	v_min_u32_e32 v104, v80, v104
	v_max_u32_e32 v80, v86, v77
	v_min_u32_e32 v77, v86, v77
	v_max_u32_e32 v86, v117, v70
	v_min_u32_e32 v70, v117, v70
	v_max_u32_e32 v117, v91, v96
	v_min_u32_e32 v96, v91, v96
	v_max_u32_e32 v91, v102, v103
	v_min_u32_e32 v103, v102, v103
	v_max_u32_e32 v102, v97, v79
	v_min_u32_e32 v79, v97, v79
	v_max_u32_e32 v97, v100, v88
	v_min_u32_e32 v88, v100, v88
	v_max_u32_e32 v100, v105, v72
	v_min_u32_e32 v72, v105, v72
	v_max_u32_e32 v105, v74, v104
	v_min_u32_e32 v104, v74, v104
	v_max_u32_e32 v74, v80, v86
	v_min_u32_e32 v86, v80, v86
	v_max_u32_e32 v80, v77, v70
	v_min_u32_e32 v70, v77, v70
	v_max_u32_e32 v77, v117, v91
	v_min_u32_e32 v91, v117, v91
	v_max_u32_e32 v117, v96, v103
	v_min_u32_e32 v103, v96, v103
	v_max_u32_e32 v96, v102, v97
	v_min_u32_e32 v97, v102, v97
	v_max_u32_e32 v102, v79, v88
	v_min_u32_e32 v88, v79, v88
	v_max_u32_e32 v79, v115, v88
	v_max_u32_e32 v115, v89, v102
	v_max_u32_e32 v89, v90, v97
	v_max_u32_e32 v90, v112, v96
	v_max_u32_e32 v112, v116, v103
	v_max_u32_e32 v116, v109, v117
	v_max_u32_e32 v109, v108, v91
	v_max_u32_e32 v108, v111, v77
	v_max_u32_e32 v111, v106, v70
	v_max_u32_e32 v106, v85, v80
	v_max_u32_e32 v85, v101, v86
	v_max_u32_e32 v101, v83, v74
	v_max_u32_e32 v83, v114, v104
	v_max_u32_e32 v114, v81, v105
	v_max_u32_e32 v81, v107, v72
	v_max_u32_e32 v107, v98, v100
	v_max_u32_e32 v88, v79, v111
	v_min_u32_e32 v111, v79, v111
	v_max_u32_e32 v79, v115, v106
	v_min_u32_e32 v106, v115, v106
	v_max_u32_e32 v115, v89, v85
	v_min_u32_e32 v85, v89, v85
	v_max_u32_e32 v89, v90, v101
	v_min_u32_e32 v101, v90, v101
	v_max_u32_e32 v90, v112, v83
	v_min_u32_e32 v83, v112, v83
	v_max_u32_e32 v112, v116, v114
	v_min_u32_e32 v114, v116, v114
	v_max_u32_e32 v116, v109, v81
	v_min_u32_e32 v81, v109, v81
	v_max_u32_e32 v109, v108, v107
	v_min_u32_e32 v107, v108, v107
	v_max_u32_e32 v108, v88, v90
	v_min_u32_e32 v90, v88, v90
	v_max_u32_e32 v88, v79, v112
	v_min_u32_e32 v112, v79, v112
	v_max_u32_e32 v79, v115, v116
	v_min_u32_e32 v116, v115, v116
	v_max_u32_e32 v115, v89, v109
	v_min_u32_e32 v109, v89, v109
	v_max_u32_e32 v89, v111, v83
	v_min_u32_e32 v83, v111, v83
	v_max_u32_e32 v111, v106, v114
	v_min_u32_e32 v114, v106, v114
; DI void merge_top16(unsigned (&a)[16], const unsigned (&b)[16]) {
; #pragma unroll
;   for (int i = 0; i < 16; ++i) a[i] = max(a[i], b[15 - i]);
; #pragma unroll
;     ...
; #pragma unroll
;     for (int i = 0; i < 16; ++i) {
;       const int j = 1 << js, l = i ^ j;
;       if (l > i) {
;         const unsigned x = a[i], y = a[l];
;         a[i] = max(x, y);
;         a[l] = min(x, y);
;       }
;     }
; }
; DI void peer_top16(const u16* __restrict__ PQrow, const u16* __restrict__ SK, unsigned (&top)[16], int lr, int hh) {
;     ...
;   unsigned other[16];
; #pragma unroll
;   for (int i = 0; i < 16; ++i) other[i] = (unsigned)__shfl_xor((int)g[0][i], 32);
;   merge_top16(g[0], other);
; #pragma unroll
;   for (int i = 0; i < 16; ++i) top[i] = g[0][i];
	v_max_u32_e32 v106, v85, v81
	v_min_u32_e32 v81, v85, v81
	v_max_u32_e32 v85, v101, v107
	v_min_u32_e32 v107, v101, v107
	v_max_u32_e32 v101, v108, v79
	v_min_u32_e32 v79, v108, v79
	v_max_u32_e32 v108, v88, v115
	v_min_u32_e32 v115, v88, v115
	v_max_u32_e32 v88, v90, v116
	v_min_u32_e32 v116, v90, v116
	v_max_u32_e32 v90, v112, v109
	v_min_u32_e32 v109, v112, v109
	v_max_u32_e32 v112, v89, v106
	v_min_u32_e32 v106, v89, v106
	v_max_u32_e32 v89, v111, v85
	v_min_u32_e32 v85, v111, v85
	v_max_u32_e32 v111, v83, v81
	v_min_u32_e32 v81, v83, v81
	v_max_u32_e32 v83, v114, v107
	v_min_u32_e32 v107, v114, v107
	v_max_u32_e32 v114, v101, v108
	v_min_u32_e32 v108, v101, v108
	v_max_u32_e32 v101, v79, v115
	v_min_u32_e32 v115, v79, v115
	v_max_u32_e32 v79, v88, v90
	v_min_u32_e32 v90, v88, v90
	v_max_u32_e32 v88, v116, v109
	v_min_u32_e32 v109, v116, v109
	v_max_u32_e32 v116, v112, v89
	v_min_u32_e32 v89, v112, v89
	v_max_u32_e32 v112, v106, v85
	v_min_u32_e32 v85, v106, v85
	v_max_u32_e32 v106, v111, v83
	v_min_u32_e32 v83, v111, v83
	v_max_u32_e32 v111, v81, v107
	v_min_u32_e32 v107, v81, v107
	v_mov_b32_e32 v48, v114
	v_mov_b32_e32 v49, v108
	v_mov_b32_e32 v50, v101
	v_mov_b32_e32 v51, v115
	v_mov_b32_e32 v52, v79
	v_mov_b32_e32 v53, v90
	v_mov_b32_e32 v54, v88
	v_mov_b32_e32 v55, v109
	v_mov_b32_e32 v56, v116
	v_mov_b32_e32 v57, v89
	v_mov_b32_e32 v58, v112
	v_mov_b32_e32 v59, v85
	v_mov_b32_e32 v60, v106
	v_mov_b32_e32 v61, v83
	v_mov_b32_e32 v62, v111
	v_mov_b32_e32 v63, v107
	s_nop 1
	v_permlane32_swap_b32_e32 v0, v32
	v_permlane32_swap_b32_e32 v1, v33
	v_permlane32_swap_b32_e32 v2, v34
	v_permlane32_swap_b32_e32 v3, v35
	v_permlane32_swap_b32_e32 v4, v36
	v_permlane32_swap_b32_e32 v5, v37
	v_permlane32_swap_b32_e32 v6, v38
	v_permlane32_swap_b32_e32 v7, v39
	v_permlane32_swap_b32_e32 v8, v40
	v_permlane32_swap_b32_e32 v9, v41
	v_permlane32_swap_b32_e32 v10, v42
	v_permlane32_swap_b32_e32 v11, v43
	v_permlane32_swap_b32_e32 v12, v44
	v_permlane32_swap_b32_e32 v13, v45
	v_permlane32_swap_b32_e32 v14, v46
	v_permlane32_swap_b32_e32 v15, v47
	v_permlane32_swap_b32_e32 v16, v48
	v_permlane32_swap_b32_e32 v17, v49
	v_permlane32_swap_b32_e32 v18, v50
	v_permlane32_swap_b32_e32 v19, v51
	v_permlane32_swap_b32_e32 v20, v52
	v_permlane32_swap_b32_e32 v21, v53
	v_permlane32_swap_b32_e32 v22, v54
	v_permlane32_swap_b32_e32 v23, v55
	v_permlane32_swap_b32_e32 v24, v56
	v_permlane32_swap_b32_e32 v25, v57
	v_permlane32_swap_b32_e32 v26, v58
	v_permlane32_swap_b32_e32 v27, v59
	v_permlane32_swap_b32_e32 v28, v60
	v_permlane32_swap_b32_e32 v29, v61
	v_permlane32_swap_b32_e32 v30, v62
	v_permlane32_swap_b32_e32 v31, v63
	v_max_u32_e32 v107, v0, v47
	v_max_u32_e32 v0, v1, v46
	v_max_u32_e32 v1, v2, v45
	v_max_u32_e32 v2, v3, v44
	v_max_u32_e32 v3, v4, v43
	v_max_u32_e32 v4, v5, v42
	v_max_u32_e32 v5, v6, v41
	v_max_u32_e32 v6, v7, v40
	v_max_u32_e32 v7, v8, v39
	v_max_u32_e32 v8, v9, v38
	v_max_u32_e32 v9, v10, v37
	v_max_u32_e32 v10, v11, v36
	v_max_u32_e32 v11, v12, v35
	v_max_u32_e32 v12, v13, v34
	v_max_u32_e32 v13, v14, v33
	v_max_u32_e32 v14, v15, v32
	v_max_u32_e32 v47, v107, v7
	v_min_u32_e32 v7, v107, v7
	v_max_u32_e32 v107, v0, v8
	v_min_u32_e32 v8, v0, v8
	v_max_u32_e32 v0, v1, v9
	v_min_u32_e32 v9, v1, v9
	v_max_u32_e32 v1, v2, v10
	v_min_u32_e32 v10, v2, v10
	v_max_u32_e32 v2, v3, v11
	v_min_u32_e32 v11, v3, v11
	v_max_u32_e32 v3, v4, v12
	v_min_u32_e32 v12, v4, v12
	v_max_u32_e32 v4, v5, v13
	v_min_u32_e32 v13, v5, v13
	v_max_u32_e32 v5, v6, v14
	v_min_u32_e32 v14, v6, v14
	v_max_u32_e32 v6, v47, v2
	v_min_u32_e32 v2, v47, v2
	v_max_u32_e32 v47, v107, v3
	v_min_u32_e32 v3, v107, v3
	v_max_u32_e32 v107, v0, v4
	v_min_u32_e32 v4, v0, v4
	v_max_u32_e32 v0, v1, v5
	v_min_u32_e32 v5, v1, v5
	v_max_u32_e32 v1, v7, v11
	v_min_u32_e32 v11, v7, v11
	v_max_u32_e32 v7, v8, v12
	v_min_u32_e32 v12, v8, v12
	v_max_u32_e32 v8, v9, v13
	v_min_u32_e32 v13, v9, v13
	v_max_u32_e32 v9, v10, v14
	v_min_u32_e32 v14, v10, v14
	v_max_u32_e32 v10, v6, v107
	v_min_u32_e32 v107, v6, v107
	v_max_u32_e32 v6, v47, v0
	v_min_u32_e32 v0, v47, v0
	v_max_u32_e32 v47, v2, v4
	v_min_u32_e32 v4, v2, v4
	v_max_u32_e32 v2, v3, v5
	v_min_u32_e32 v5, v3, v5
	v_max_u32_e32 v3, v1, v8
	v_min_u32_e32 v8, v1, v8
	v_max_u32_e32 v1, v7, v9
	v_min_u32_e32 v9, v7, v9
	v_max_u32_e32 v7, v11, v13
	v_min_u32_e32 v13, v11, v13
	v_max_u32_e32 v11, v12, v14
	v_min_u32_e32 v14, v12, v14
	v_max_u32_e32 v12, v10, v6
	v_min_u32_e32 v6, v10, v6
	v_max_u32_e32 v10, v107, v0
	v_min_u32_e32 v0, v107, v0
	v_max_u32_e32 v107, v47, v2
	v_min_u32_e32 v2, v47, v2
	v_max_u32_e32 v47, v4, v5
	v_min_u32_e32 v5, v4, v5
	v_max_u32_e32 v4, v3, v1
	v_min_u32_e32 v1, v3, v1
	v_max_u32_e32 v3, v8, v9
	v_min_u32_e32 v9, v8, v9
	v_max_u32_e32 v8, v7, v11
	v_min_u32_e32 v11, v7, v11
	v_max_u32_e32 v7, v13, v14
	v_min_u32_e32 v14, v13, v14
	v_max_u32_e32 v13, v16, v63
	v_max_u32_e32 v16, v17, v62
	v_max_u32_e32 v17, v18, v61
	v_max_u32_e32 v18, v19, v60
	v_max_u32_e32 v19, v20, v59
	v_max_u32_e32 v20, v21, v58
	v_max_u32_e32 v21, v22, v57
	v_max_u32_e32 v22, v23, v56
	v_max_u32_e32 v23, v24, v55
	v_max_u32_e32 v24, v25, v54
	v_max_u32_e32 v25, v26, v53
	v_max_u32_e32 v26, v27, v52
	v_max_u32_e32 v27, v28, v51
	v_max_u32_e32 v28, v29, v50
	v_max_u32_e32 v29, v30, v49
	v_max_u32_e32 v30, v31, v48
	v_max_u32_e32 v63, v13, v23
	v_min_u32_e32 v23, v13, v23
	v_max_u32_e32 v13, v16, v24
	v_min_u32_e32 v24, v16, v24
	v_max_u32_e32 v16, v17, v25
	v_min_u32_e32 v25, v17, v25
	v_max_u32_e32 v17, v18, v26
	v_min_u32_e32 v26, v18, v26
	v_max_u32_e32 v18, v19, v27
	v_min_u32_e32 v27, v19, v27
	v_max_u32_e32 v19, v20, v28
; DI float ord2f(unsigned u) { return __uint_as_float((u & 0x80000000u) ? (u ^ 0x80000000u) : ~u); }
; DI void peer_top16(const u16* __restrict__ PQrow, const u16* __restrict__ SK, unsigned (&top)[16], int lr, int hh) {
;     ...
;   merge_top16(g[0], g[1]);
;   merge_top16(g[2], g[3]);
;   merge_top16(g[0], g[2]);
;   unsigned other[16];
; #pragma unroll
;   for (int i = 0; i < 16; ++i) other[i] = (unsigned)__shfl_xor((int)g[0][i], 32);
;   merge_top16(g[0], other);
; #pragma unroll
;   for (int i = 0; i < 16; ++i) top[i] = g[0][i];
; template <bool STORE>
; DI void peer_item(const Params& p, int item, char* smem) {
;     ...
;           ckey[a][bq] = (f2ord(ord2f(top1[a] & ~127u) + ord2f(top2[bq] & ~127u)) & ~255u) | (unsigned)(255 - (a * 16 + bq));
	v_min_u32_e32 v28, v20, v28
	v_max_u32_e32 v20, v21, v29
	v_min_u32_e32 v29, v21, v29
	v_max_u32_e32 v21, v22, v30
	v_min_u32_e32 v30, v22, v30
	v_max_u32_e32 v22, v63, v18
	v_min_u32_e32 v18, v63, v18
	v_max_u32_e32 v63, v13, v19
	v_min_u32_e32 v19, v13, v19
	v_max_u32_e32 v13, v16, v20
	v_min_u32_e32 v20, v16, v20
	v_max_u32_e32 v16, v17, v21
	v_min_u32_e32 v21, v17, v21
	v_max_u32_e32 v17, v23, v27
	v_min_u32_e32 v27, v23, v27
	v_max_u32_e32 v23, v24, v28
	v_min_u32_e32 v28, v24, v28
	v_max_u32_e32 v24, v25, v29
	v_min_u32_e32 v29, v25, v29
	v_max_u32_e32 v25, v26, v30
	v_min_u32_e32 v30, v26, v30
	v_max_u32_e32 v26, v22, v13
	v_min_u32_e32 v13, v22, v13
	v_max_u32_e32 v22, v63, v16
	v_min_u32_e32 v16, v63, v16
	v_max_u32_e32 v63, v18, v20
	v_min_u32_e32 v20, v18, v20
	v_max_u32_e32 v18, v19, v21
	v_min_u32_e32 v21, v19, v21
	v_max_u32_e32 v19, v17, v24
	v_min_u32_e32 v24, v17, v24
	v_max_u32_e32 v17, v23, v25
	v_min_u32_e32 v25, v23, v25
	v_max_u32_e32 v23, v27, v29
	v_min_u32_e32 v29, v27, v29
	v_max_u32_e32 v27, v28, v30
	v_min_u32_e32 v30, v28, v30
	v_max_u32_e32 v28, v26, v22
	v_min_u32_e32 v22, v26, v22
	v_max_u32_e32 v26, v13, v16
	v_min_u32_e32 v16, v13, v16
	v_max_u32_e32 v13, v63, v18
	v_min_u32_e32 v18, v63, v18
	v_max_u32_e32 v63, v20, v21
	v_min_u32_e32 v21, v20, v21
	v_max_u32_e32 v20, v19, v17
	v_min_u32_e32 v17, v19, v17
	v_max_u32_e32 v19, v24, v25
	v_min_u32_e32 v25, v24, v25
	v_max_u32_e32 v24, v23, v27
	v_min_u32_e32 v27, v23, v27
	v_max_u32_e32 v23, v29, v30
	v_min_u32_e32 v30, v29, v30
	v_xor_b32_e32 v229, 0x7f, v12
	v_and_b32_e32 v229, 0x7f, v229
	v_mov_b32_e32 v29, v229
	v_xor_b32_e32 v229, 0x7f, v6
	v_and_b32_e32 v229, 0x7f, v229
	v_lshl_or_b32 v29, v229, 8, v29
	v_xor_b32_e32 v229, 0x7f, v10
	v_and_b32_e32 v229, 0x7f, v229
	v_lshl_or_b32 v29, v229, 16, v29
	v_xor_b32_e32 v229, 0x7f, v0
	v_and_b32_e32 v229, 0x7f, v229
	v_lshl_or_b32 v29, v229, 24, v29
	v_xor_b32_e32 v229, 0x7f, v107
	v_and_b32_e32 v229, 0x7f, v229
	v_mov_b32_e32 v62, v229
	v_xor_b32_e32 v229, 0x7f, v2
	v_and_b32_e32 v229, 0x7f, v229
	v_lshl_or_b32 v62, v229, 8, v62
	v_xor_b32_e32 v229, 0x7f, v47
	v_and_b32_e32 v229, 0x7f, v229
	v_lshl_or_b32 v62, v229, 16, v62
	v_xor_b32_e32 v229, 0x7f, v5
	v_and_b32_e32 v229, 0x7f, v229
	v_lshl_or_b32 v62, v229, 24, v62
	v_xor_b32_e32 v229, 0x7f, v4
	v_and_b32_e32 v229, 0x7f, v229
	v_mov_b32_e32 v61, v229
	v_xor_b32_e32 v229, 0x7f, v1
	v_and_b32_e32 v229, 0x7f, v229
	v_lshl_or_b32 v61, v229, 8, v61
	v_xor_b32_e32 v229, 0x7f, v3
	v_and_b32_e32 v229, 0x7f, v229
	v_lshl_or_b32 v61, v229, 16, v61
	v_xor_b32_e32 v229, 0x7f, v9
	v_and_b32_e32 v229, 0x7f, v229
	v_lshl_or_b32 v61, v229, 24, v61
	v_xor_b32_e32 v229, 0x7f, v8
	v_and_b32_e32 v229, 0x7f, v229
	v_mov_b32_e32 v60, v229
	v_xor_b32_e32 v229, 0x7f, v11
	v_and_b32_e32 v229, 0x7f, v229
	v_lshl_or_b32 v60, v229, 8, v60
	v_xor_b32_e32 v229, 0x7f, v7
	v_and_b32_e32 v229, 0x7f, v229
	v_lshl_or_b32 v60, v229, 16, v60
	v_xor_b32_e32 v229, 0x7f, v14
	v_and_b32_e32 v229, 0x7f, v229
	v_lshl_or_b32 v60, v229, 24, v60
	v_xor_b32_e32 v229, 0x7f, v28
	v_and_b32_e32 v229, 0x7f, v229
	v_mov_b32_e32 v59, v229
	v_xor_b32_e32 v229, 0x7f, v22
	v_and_b32_e32 v229, 0x7f, v229
	v_lshl_or_b32 v59, v229, 8, v59
	v_xor_b32_e32 v229, 0x7f, v26
	v_and_b32_e32 v229, 0x7f, v229
	v_lshl_or_b32 v59, v229, 16, v59
	v_xor_b32_e32 v229, 0x7f, v16
	v_and_b32_e32 v229, 0x7f, v229
	v_lshl_or_b32 v59, v229, 24, v59
	v_xor_b32_e32 v229, 0x7f, v13
	v_and_b32_e32 v229, 0x7f, v229
	v_mov_b32_e32 v58, v229
	v_xor_b32_e32 v229, 0x7f, v18
	v_and_b32_e32 v229, 0x7f, v229
	v_lshl_or_b32 v58, v229, 8, v58
	v_xor_b32_e32 v229, 0x7f, v63
	v_and_b32_e32 v229, 0x7f, v229
	v_lshl_or_b32 v58, v229, 16, v58
	v_xor_b32_e32 v229, 0x7f, v21
	v_and_b32_e32 v229, 0x7f, v229
	v_lshl_or_b32 v58, v229, 24, v58
	v_xor_b32_e32 v229, 0x7f, v20
	v_and_b32_e32 v229, 0x7f, v229
	v_mov_b32_e32 v57, v229
	v_xor_b32_e32 v229, 0x7f, v17
	v_and_b32_e32 v229, 0x7f, v229
	v_lshl_or_b32 v57, v229, 8, v57
	v_xor_b32_e32 v229, 0x7f, v19
	v_and_b32_e32 v229, 0x7f, v229
	v_lshl_or_b32 v57, v229, 16, v57
	v_xor_b32_e32 v229, 0x7f, v25
	v_and_b32_e32 v229, 0x7f, v229
	v_lshl_or_b32 v57, v229, 24, v57
	v_xor_b32_e32 v229, 0x7f, v24
	v_and_b32_e32 v229, 0x7f, v229
	v_mov_b32_e32 v56, v229
	v_xor_b32_e32 v229, 0x7f, v27
	v_and_b32_e32 v229, 0x7f, v229
	v_lshl_or_b32 v56, v229, 8, v56
	v_xor_b32_e32 v229, 0x7f, v23
	v_and_b32_e32 v229, 0x7f, v229
	v_lshl_or_b32 v56, v229, 16, v56
	v_xor_b32_e32 v229, 0x7f, v30
	v_and_b32_e32 v229, 0x7f, v229
	v_lshl_or_b32 v56, v229, 24, v56
	ds_write_b32 v241, v29 offset:0
	ds_write_b32 v241, v62 offset:4
	ds_write_b32 v241, v61 offset:8
	ds_write_b32 v241, v60 offset:12
	ds_write_b32 v241, v59 offset:16
	ds_write_b32 v241, v58 offset:20
	ds_write_b32 v241, v57 offset:24
	ds_write_b32 v241, v56 offset:28
	v_and_b32_e32 v229, 0xffffff80, v12
	v_ashrrev_i32_e32 v230, 31, v229
	v_not_b32_e32 v230, v230
	v_or_b32_e32 v230, 0x80000000, v230
	v_xor_b32_e32 v56, v230, v229
	v_and_b32_e32 v229, 0xffffff80, v6
	v_ashrrev_i32_e32 v230, 31, v229
	v_not_b32_e32 v230, v230
	v_or_b32_e32 v230, 0x80000000, v230
	v_xor_b32_e32 v57, v230, v229
	v_and_b32_e32 v229, 0xffffff80, v10
	v_ashrrev_i32_e32 v230, 31, v229
	v_not_b32_e32 v230, v230
	v_or_b32_e32 v230, 0x80000000, v230
	v_xor_b32_e32 v58, v230, v229
	v_and_b32_e32 v229, 0xffffff80, v0
	v_ashrrev_i32_e32 v230, 31, v229
	v_not_b32_e32 v230, v230
	v_or_b32_e32 v230, 0x80000000, v230
	v_xor_b32_e32 v59, v230, v229
	v_and_b32_e32 v229, 0xffffff80, v107
	v_ashrrev_i32_e32 v230, 31, v229
	v_not_b32_e32 v230, v230
	v_or_b32_e32 v230, 0x80000000, v230
	v_xor_b32_e32 v60, v230, v229
; DI unsigned f2ord(float f) {
;   unsigned u = __float_as_uint(f);
;   return (u & 0x80000000u) ? ~u : (u | 0x80000000u);
; }
; DI float ord2f(unsigned u) { return __uint_as_float((u & 0x80000000u) ? (u ^ 0x80000000u) : ~u); }
; template <bool STORE>
; DI void peer_item(const Params& p, int item, char* smem) {
;     ...
;     unsigned ckey[16][16];
; #pragma unroll
;     for (int a = 0; a < 16; ++a)
; #pragma unroll
;       for (int bq = 0; bq < 16; ++bq)
;         if ((a + 1) * (bq + 1) <= 16)
;           ckey[a][bq] = (f2ord(ord2f(top1[a] & ~127u) + ord2f(top2[bq] & ~127u)) & ~255u) | (unsigned)(255 - (a * 16 + bq));
	v_and_b32_e32 v229, 0xffffff80, v2
	v_ashrrev_i32_e32 v230, 31, v229
	v_not_b32_e32 v230, v230
	v_or_b32_e32 v230, 0x80000000, v230
	v_xor_b32_e32 v61, v230, v229
	v_and_b32_e32 v229, 0xffffff80, v47
	v_ashrrev_i32_e32 v230, 31, v229
	v_not_b32_e32 v230, v230
	v_or_b32_e32 v230, 0x80000000, v230
	v_xor_b32_e32 v62, v230, v229
	v_and_b32_e32 v229, 0xffffff80, v5
	v_ashrrev_i32_e32 v230, 31, v229
	v_not_b32_e32 v230, v230
	v_or_b32_e32 v230, 0x80000000, v230
	v_xor_b32_e32 v29, v230, v229
	v_and_b32_e32 v229, 0xffffff80, v4
	v_ashrrev_i32_e32 v230, 31, v229
	v_not_b32_e32 v230, v230
	v_or_b32_e32 v230, 0x80000000, v230
	v_xor_b32_e32 v55, v230, v229
	v_and_b32_e32 v229, 0xffffff80, v1
	v_ashrrev_i32_e32 v230, 31, v229
	v_not_b32_e32 v230, v230
	v_or_b32_e32 v230, 0x80000000, v230
	v_xor_b32_e32 v54, v230, v229
	v_and_b32_e32 v229, 0xffffff80, v3
	v_ashrrev_i32_e32 v230, 31, v229
	v_not_b32_e32 v230, v230
	v_or_b32_e32 v230, 0x80000000, v230
	v_xor_b32_e32 v53, v230, v229
	v_and_b32_e32 v229, 0xffffff80, v9
	v_ashrrev_i32_e32 v230, 31, v229
	v_not_b32_e32 v230, v230
	v_or_b32_e32 v230, 0x80000000, v230
	v_xor_b32_e32 v52, v230, v229
	v_and_b32_e32 v229, 0xffffff80, v8
	v_ashrrev_i32_e32 v230, 31, v229
	v_not_b32_e32 v230, v230
	v_or_b32_e32 v230, 0x80000000, v230
	v_xor_b32_e32 v51, v230, v229
	v_and_b32_e32 v229, 0xffffff80, v11
	v_ashrrev_i32_e32 v230, 31, v229
	v_not_b32_e32 v230, v230
	v_or_b32_e32 v230, 0x80000000, v230
	v_xor_b32_e32 v50, v230, v229
	v_and_b32_e32 v229, 0xffffff80, v7
	v_ashrrev_i32_e32 v230, 31, v229
	v_not_b32_e32 v230, v230
	v_or_b32_e32 v230, 0x80000000, v230
	v_xor_b32_e32 v49, v230, v229
	v_and_b32_e32 v229, 0xffffff80, v14
	v_ashrrev_i32_e32 v230, 31, v229
	v_not_b32_e32 v230, v230
	v_or_b32_e32 v230, 0x80000000, v230
	v_xor_b32_e32 v48, v230, v229
	v_and_b32_e32 v229, 0xffffff80, v28
	v_ashrrev_i32_e32 v230, 31, v229
	v_not_b32_e32 v230, v230
	v_or_b32_e32 v230, 0x80000000, v230
	v_xor_b32_e32 v31, v230, v229
	v_and_b32_e32 v229, 0xffffff80, v22
	v_ashrrev_i32_e32 v230, 31, v229
	v_not_b32_e32 v230, v230
	v_or_b32_e32 v230, 0x80000000, v230
	v_xor_b32_e32 v46, v230, v229
	v_and_b32_e32 v229, 0xffffff80, v26
	v_ashrrev_i32_e32 v230, 31, v229
	v_not_b32_e32 v230, v230
	v_or_b32_e32 v230, 0x80000000, v230
	v_xor_b32_e32 v45, v230, v229
	v_and_b32_e32 v229, 0xffffff80, v16
	v_ashrrev_i32_e32 v230, 31, v229
	v_not_b32_e32 v230, v230
	v_or_b32_e32 v230, 0x80000000, v230
	v_xor_b32_e32 v44, v230, v229
	v_and_b32_e32 v229, 0xffffff80, v13
	v_ashrrev_i32_e32 v230, 31, v229
	v_not_b32_e32 v230, v230
	v_or_b32_e32 v230, 0x80000000, v230
	v_xor_b32_e32 v43, v230, v229
	v_and_b32_e32 v229, 0xffffff80, v18
	v_ashrrev_i32_e32 v230, 31, v229
	v_not_b32_e32 v230, v230
	v_or_b32_e32 v230, 0x80000000, v230
	v_xor_b32_e32 v42, v230, v229
	v_and_b32_e32 v229, 0xffffff80, v63
	v_ashrrev_i32_e32 v230, 31, v229
	v_not_b32_e32 v230, v230
	v_or_b32_e32 v230, 0x80000000, v230
	v_xor_b32_e32 v41, v230, v229
	v_and_b32_e32 v229, 0xffffff80, v21
	v_ashrrev_i32_e32 v230, 31, v229
	v_not_b32_e32 v230, v230
	v_or_b32_e32 v230, 0x80000000, v230
	v_xor_b32_e32 v40, v230, v229
	v_and_b32_e32 v229, 0xffffff80, v20
	v_ashrrev_i32_e32 v230, 31, v229
	v_not_b32_e32 v230, v230
	v_or_b32_e32 v230, 0x80000000, v230
	v_xor_b32_e32 v39, v230, v229
	v_and_b32_e32 v229, 0xffffff80, v17
	v_ashrrev_i32_e32 v230, 31, v229
	v_not_b32_e32 v230, v230
	v_or_b32_e32 v230, 0x80000000, v230
	v_xor_b32_e32 v38, v230, v229
	v_and_b32_e32 v229, 0xffffff80, v19
	v_ashrrev_i32_e32 v230, 31, v229
	v_not_b32_e32 v230, v230
	v_or_b32_e32 v230, 0x80000000, v230
	v_xor_b32_e32 v37, v230, v229
	v_and_b32_e32 v229, 0xffffff80, v25
	v_ashrrev_i32_e32 v230, 31, v229
	v_not_b32_e32 v230, v230
	v_or_b32_e32 v230, 0x80000000, v230
	v_xor_b32_e32 v36, v230, v229
	v_and_b32_e32 v229, 0xffffff80, v24
	v_ashrrev_i32_e32 v230, 31, v229
	v_not_b32_e32 v230, v230
	v_or_b32_e32 v230, 0x80000000, v230
	v_xor_b32_e32 v35, v230, v229
	v_and_b32_e32 v229, 0xffffff80, v27
	v_ashrrev_i32_e32 v230, 31, v229
	v_not_b32_e32 v230, v230
	v_or_b32_e32 v230, 0x80000000, v230
	v_xor_b32_e32 v34, v230, v229
	v_and_b32_e32 v229, 0xffffff80, v23
	v_ashrrev_i32_e32 v230, 31, v229
	v_not_b32_e32 v230, v230
	v_or_b32_e32 v230, 0x80000000, v230
	v_xor_b32_e32 v33, v230, v229
	v_and_b32_e32 v229, 0xffffff80, v30
	v_ashrrev_i32_e32 v230, 31, v229
	v_not_b32_e32 v230, v230
	v_or_b32_e32 v230, 0x80000000, v230
	v_xor_b32_e32 v32, v230, v229
	v_add_f32_e32 v229, v56, v31
	v_ashrrev_i32_e32 v230, 31, v229
	v_or_b32_e32 v230, 0x80000000, v230
	v_xor_b32_e32 v231, v230, v229
	v_and_b32_e32 v231, 0xffffff00, v231
	v_or_b32_e32 v15, 0xff, v231
	v_add_f32_e32 v229, v56, v46
	v_ashrrev_i32_e32 v230, 31, v229
	v_or_b32_e32 v230, 0x80000000, v230
	v_xor_b32_e32 v231, v230, v229
	v_and_b32_e32 v231, 0xffffff00, v231
	v_or_b32_e32 v111, 0xfe, v231
	v_add_f32_e32 v229, v56, v45
	v_ashrrev_i32_e32 v230, 31, v229
	v_or_b32_e32 v230, 0x80000000, v230
	v_xor_b32_e32 v231, v230, v229
	v_and_b32_e32 v231, 0xffffff00, v231
	v_or_b32_e32 v83, 0xfd, v231
	v_add_f32_e32 v229, v56, v44
	v_ashrrev_i32_e32 v230, 31, v229
	v_or_b32_e32 v230, 0x80000000, v230
	v_xor_b32_e32 v231, v230, v229
	v_and_b32_e32 v231, 0xffffff00, v231
	v_or_b32_e32 v106, 0xfc, v231
	v_add_f32_e32 v229, v56, v43
	v_ashrrev_i32_e32 v230, 31, v229
	v_or_b32_e32 v230, 0x80000000, v230
	v_xor_b32_e32 v231, v230, v229
	v_and_b32_e32 v231, 0xffffff00, v231
	v_or_b32_e32 v85, 0xfb, v231
	v_add_f32_e32 v229, v56, v42
	v_ashrrev_i32_e32 v230, 31, v229
	v_or_b32_e32 v230, 0x80000000, v230
	v_xor_b32_e32 v231, v230, v229
	v_and_b32_e32 v231, 0xffffff00, v231
; DI float ord2f(unsigned u) { return __uint_as_float((u & 0x80000000u) ? (u ^ 0x80000000u) : ~u); }
; template <bool STORE>
; DI void peer_item(const Params& p, int item, char* smem) {
;     ...
;     unsigned ckey[16][16];
; #pragma unroll
;     for (int a = 0; a < 16; ++a)
; #pragma unroll
;       for (int bq = 0; bq < 16; ++bq)
;         if ((a + 1) * (bq + 1) <= 16)
;           ckey[a][bq] = (f2ord(ord2f(top1[a] & ~127u) + ord2f(top2[bq] & ~127u)) & ~255u) | (unsigned)(255 - (a * 16 + bq));
;     unsigned wkey[16];
;     int we[16];
; #pragma unroll
;     for (int r = 0; r < 16; ++r) {
;       unsigned mx = 0u;
; #pragma unroll
;       for (int a = 0; a < 16; ++a)
; #pragma unroll
;         for (int bq = 0; bq < 16; ++bq)
;           if ((a + 1) * (bq + 1) <= 16) mx = max(mx, ckey[a][bq]);
; #pragma unroll
;       for (int a = 0; a < 16; ++a)
; #pragma unroll
;         for (int bq = 0; bq < 16; ++bq)
;           if ((a + 1) * (bq + 1) <= 16) ckey[a][bq] = (ckey[a][bq] == mx) ? 0u : ckey[a][bq];
	v_or_b32_e32 v112, 0xfa, v231
	v_add_f32_e32 v229, v56, v41
	v_ashrrev_i32_e32 v230, 31, v229
	v_or_b32_e32 v230, 0x80000000, v230
	v_xor_b32_e32 v231, v230, v229
	v_and_b32_e32 v231, 0xffffff00, v231
	v_or_b32_e32 v89, 0xf9, v231
	v_add_f32_e32 v229, v56, v40
	v_ashrrev_i32_e32 v230, 31, v229
	v_or_b32_e32 v230, 0x80000000, v230
	v_xor_b32_e32 v231, v230, v229
	v_and_b32_e32 v231, 0xffffff00, v231
	v_or_b32_e32 v116, 0xf8, v231
	v_add_f32_e32 v229, v56, v39
	v_ashrrev_i32_e32 v230, 31, v229
	v_or_b32_e32 v230, 0x80000000, v230
	v_xor_b32_e32 v231, v230, v229
	v_and_b32_e32 v231, 0xffffff00, v231
	v_or_b32_e32 v109, 0xf7, v231
	v_add_f32_e32 v229, v56, v38
	v_ashrrev_i32_e32 v230, 31, v229
	v_or_b32_e32 v230, 0x80000000, v230
	v_xor_b32_e32 v231, v230, v229
	v_and_b32_e32 v231, 0xffffff00, v231
	v_or_b32_e32 v88, 0xf6, v231
	v_add_f32_e32 v229, v56, v37
	v_ashrrev_i32_e32 v230, 31, v229
	v_or_b32_e32 v230, 0x80000000, v230
	v_xor_b32_e32 v231, v230, v229
	v_and_b32_e32 v231, 0xffffff00, v231
	v_or_b32_e32 v90, 0xf5, v231
	v_add_f32_e32 v229, v56, v36
	v_ashrrev_i32_e32 v230, 31, v229
	v_or_b32_e32 v230, 0x80000000, v230
	v_xor_b32_e32 v231, v230, v229
	v_and_b32_e32 v231, 0xffffff00, v231
	v_or_b32_e32 v79, 0xf4, v231
	v_add_f32_e32 v229, v56, v35
	v_ashrrev_i32_e32 v230, 31, v229
	v_or_b32_e32 v230, 0x80000000, v230
	v_xor_b32_e32 v231, v230, v229
	v_and_b32_e32 v231, 0xffffff00, v231
	v_or_b32_e32 v115, 0xf3, v231
	v_add_f32_e32 v229, v56, v34
	v_ashrrev_i32_e32 v230, 31, v229
	v_or_b32_e32 v230, 0x80000000, v230
	v_xor_b32_e32 v231, v230, v229
	v_and_b32_e32 v231, 0xffffff00, v231
	v_or_b32_e32 v101, 0xf2, v231
	v_add_f32_e32 v229, v56, v33
	v_ashrrev_i32_e32 v230, 31, v229
	v_or_b32_e32 v230, 0x80000000, v230
	v_xor_b32_e32 v231, v230, v229
	v_and_b32_e32 v231, 0xffffff00, v231
	v_or_b32_e32 v108, 0xf1, v231
	v_add_f32_e32 v229, v56, v32
	v_ashrrev_i32_e32 v230, 31, v229
	v_or_b32_e32 v230, 0x80000000, v230
	v_xor_b32_e32 v231, v230, v229
	v_and_b32_e32 v231, 0xffffff00, v231
	v_or_b32_e32 v114, 0xf0, v231
	v_add_f32_e32 v229, v57, v31
	v_ashrrev_i32_e32 v230, 31, v229
	v_or_b32_e32 v230, 0x80000000, v230
	v_xor_b32_e32 v231, v230, v229
	v_and_b32_e32 v231, 0xffffff00, v231
	v_or_b32_e32 v81, 0xef, v231
	v_add_f32_e32 v229, v57, v46
	v_ashrrev_i32_e32 v230, 31, v229
	v_or_b32_e32 v230, 0x80000000, v230
	v_xor_b32_e32 v231, v230, v229
	v_and_b32_e32 v231, 0xffffff00, v231
	v_or_b32_e32 v102, 0xee, v231
	v_add_f32_e32 v229, v57, v45
	v_ashrrev_i32_e32 v230, 31, v229
	v_or_b32_e32 v230, 0x80000000, v230
	v_xor_b32_e32 v231, v230, v229
	v_and_b32_e32 v231, 0xffffff00, v231
	v_or_b32_e32 v97, 0xed, v231
	v_add_f32_e32 v229, v57, v44
	v_ashrrev_i32_e32 v230, 31, v229
	v_or_b32_e32 v230, 0x80000000, v230
	v_xor_b32_e32 v231, v230, v229
	v_and_b32_e32 v231, 0xffffff00, v231
	v_or_b32_e32 v96, 0xec, v231
	v_add_f32_e32 v229, v57, v43
	v_ashrrev_i32_e32 v230, 31, v229
	v_or_b32_e32 v230, 0x80000000, v230
	v_xor_b32_e32 v231, v230, v229
	v_and_b32_e32 v231, 0xffffff00, v231
	v_or_b32_e32 v103, 0xeb, v231
	v_add_f32_e32 v229, v57, v42
	v_ashrrev_i32_e32 v230, 31, v229
	v_or_b32_e32 v230, 0x80000000, v230
	v_xor_b32_e32 v231, v230, v229
	v_and_b32_e32 v231, 0xffffff00, v231
	v_or_b32_e32 v117, 0xea, v231
	v_add_f32_e32 v229, v57, v41
	v_ashrrev_i32_e32 v230, 31, v229
	v_or_b32_e32 v230, 0x80000000, v230
	v_xor_b32_e32 v231, v230, v229
	v_and_b32_e32 v231, 0xffffff00, v231
	v_or_b32_e32 v91, 0xe9, v231
	v_add_f32_e32 v229, v57, v40
	v_ashrrev_i32_e32 v230, 31, v229
	v_or_b32_e32 v230, 0x80000000, v230
	v_xor_b32_e32 v231, v230, v229
	v_and_b32_e32 v231, 0xffffff00, v231
	v_or_b32_e32 v77, 0xe8, v231
	v_add_f32_e32 v229, v58, v31
	v_ashrrev_i32_e32 v230, 31, v229
	v_or_b32_e32 v230, 0x80000000, v230
	v_xor_b32_e32 v231, v230, v229
	v_and_b32_e32 v231, 0xffffff00, v231
	v_or_b32_e32 v70, 0xdf, v231
	v_add_f32_e32 v229, v58, v46
	v_ashrrev_i32_e32 v230, 31, v229
	v_or_b32_e32 v230, 0x80000000, v230
	v_xor_b32_e32 v231, v230, v229
	v_and_b32_e32 v231, 0xffffff00, v231
	v_or_b32_e32 v80, 0xde, v231
	v_add_f32_e32 v229, v58, v45
	v_ashrrev_i32_e32 v230, 31, v229
	v_or_b32_e32 v230, 0x80000000, v230
	v_xor_b32_e32 v231, v230, v229
	v_and_b32_e32 v231, 0xffffff00, v231
	v_or_b32_e32 v86, 0xdd, v231
	v_add_f32_e32 v229, v58, v44
	v_ashrrev_i32_e32 v230, 31, v229
	v_or_b32_e32 v230, 0x80000000, v230
	v_xor_b32_e32 v231, v230, v229
	v_and_b32_e32 v231, 0xffffff00, v231
	v_or_b32_e32 v74, 0xdc, v231
	v_add_f32_e32 v229, v58, v43
	v_ashrrev_i32_e32 v230, 31, v229
	v_or_b32_e32 v230, 0x80000000, v230
	v_xor_b32_e32 v231, v230, v229
	v_and_b32_e32 v231, 0xffffff00, v231
	v_or_b32_e32 v104, 0xdb, v231
	v_add_f32_e32 v229, v59, v31
	v_ashrrev_i32_e32 v230, 31, v229
	v_or_b32_e32 v230, 0x80000000, v230
	v_xor_b32_e32 v231, v230, v229
	v_and_b32_e32 v231, 0xffffff00, v231
	v_or_b32_e32 v105, 0xcf, v231
	v_add_f32_e32 v229, v59, v46
	v_ashrrev_i32_e32 v230, 31, v229
	v_or_b32_e32 v230, 0x80000000, v230
	v_xor_b32_e32 v231, v230, v229
	v_and_b32_e32 v231, 0xffffff00, v231
	v_or_b32_e32 v72, 0xce, v231
	v_add_f32_e32 v229, v59, v45
	v_ashrrev_i32_e32 v230, 31, v229
	v_or_b32_e32 v230, 0x80000000, v230
	v_xor_b32_e32 v231, v230, v229
	v_and_b32_e32 v231, 0xffffff00, v231
	v_or_b32_e32 v100, 0xcd, v231
	v_max_u32_e32 v98, v81, v102
	v_min_u32_e32 v102, v81, v102
	v_min_u32_e32 v81, v97, v96
	v_max_u32_e32 v96, v97, v96
	v_max_u32_e32 v97, v103, v117
	v_min_u32_e32 v117, v103, v117
	v_min_u32_e32 v103, v91, v77
	v_max_u32_e32 v77, v91, v77
	v_max_u32_e32 v91, v70, v80
	v_min_u32_e32 v80, v70, v80
	v_min_u32_e32 v70, v86, v74
	v_max_u32_e32 v74, v86, v74
; DI void merge_top16(unsigned (&a)[16], const unsigned (&b)[16]) {
; #pragma unroll
;   for (int i = 0; i < 16; ++i) a[i] = max(a[i], b[15 - i]);
; #pragma unroll
;     ...
; #pragma unroll
;     for (int i = 0; i < 16; ++i) {
;       const int j = 1 << js, l = i ^ j;
;       if (l > i) {
;         const unsigned x = a[i], y = a[l];
;         a[i] = max(x, y);
;         a[l] = min(x, y);
;       }
;     }
; }
; template <bool STORE>
; DI void peer_item(const Params& p, int item, char* smem) {
;     ...
;     unsigned wkey[16];
;     int we[16];
; #pragma unroll
;     for (int r = 0; r < 16; ++r) {
;       unsigned mx = 0u;
; #pragma unroll
;       for (int a = 0; a < 16; ++a)
; #pragma unroll
;         for (int bq = 0; bq < 16; ++bq)
;           if ((a + 1) * (bq + 1) <= 16) mx = max(mx, ckey[a][bq]);
; #pragma unroll
;       for (int a = 0; a < 16; ++a)
; #pragma unroll
;         for (int bq = 0; bq < 16; ++bq)
;           if ((a + 1) * (bq + 1) <= 16) ckey[a][bq] = (ckey[a][bq] == mx) ? 0u : ckey[a][bq];
;       wkey[r] = mx;
	v_max_u32_e32 v86, v104, v105
	v_min_u32_e32 v105, v104, v105
	v_min_u32_e32 v104, v72, v100
	v_max_u32_e32 v100, v72, v100
	v_max_u32_e32 v72, v98, v81
	v_min_u32_e32 v81, v98, v81
	v_max_u32_e32 v98, v102, v96
	v_min_u32_e32 v96, v102, v96
	v_min_u32_e32 v102, v97, v103
	v_max_u32_e32 v103, v97, v103
	v_min_u32_e32 v97, v117, v77
	v_max_u32_e32 v77, v117, v77
	v_max_u32_e32 v117, v91, v70
	v_min_u32_e32 v70, v91, v70
	v_max_u32_e32 v91, v80, v74
	v_min_u32_e32 v74, v80, v74
	v_min_u32_e32 v80, v86, v104
	v_max_u32_e32 v104, v86, v104
	v_min_u32_e32 v86, v105, v100
	v_max_u32_e32 v100, v105, v100
	v_max_u32_e32 v105, v72, v98
	v_min_u32_e32 v98, v72, v98
	v_max_u32_e32 v72, v81, v96
	v_min_u32_e32 v96, v81, v96
	v_min_u32_e32 v81, v102, v97
	v_max_u32_e32 v97, v102, v97
	v_min_u32_e32 v102, v103, v77
	v_max_u32_e32 v77, v103, v77
	v_max_u32_e32 v103, v117, v91
	v_min_u32_e32 v91, v117, v91
	v_max_u32_e32 v117, v70, v74
	v_min_u32_e32 v74, v70, v74
	v_min_u32_e32 v70, v80, v86
	v_max_u32_e32 v86, v80, v86
	v_min_u32_e32 v80, v104, v100
	v_max_u32_e32 v100, v104, v100
	v_max_u32_e32 v104, v105, v81
	v_min_u32_e32 v81, v105, v81
	v_max_u32_e32 v105, v98, v97
	v_min_u32_e32 v97, v98, v97
	v_max_u32_e32 v98, v72, v102
	v_min_u32_e32 v102, v72, v102
	v_max_u32_e32 v72, v96, v77
	v_min_u32_e32 v77, v96, v77
	v_min_u32_e32 v96, v103, v70
	v_max_u32_e32 v70, v103, v70
	v_min_u32_e32 v103, v91, v86
	v_max_u32_e32 v86, v91, v86
	v_min_u32_e32 v91, v117, v80
	v_max_u32_e32 v80, v117, v80
	v_min_u32_e32 v117, v74, v100
	v_max_u32_e32 v100, v74, v100
	v_max_u32_e32 v74, v104, v98
	v_min_u32_e32 v98, v104, v98
	v_max_u32_e32 v104, v105, v72
	v_min_u32_e32 v72, v105, v72
	v_max_u32_e32 v105, v81, v102
	v_min_u32_e32 v102, v81, v102
	v_max_u32_e32 v81, v97, v77
	v_min_u32_e32 v77, v97, v77
	v_min_u32_e32 v97, v96, v91
	v_max_u32_e32 v91, v96, v91
	v_min_u32_e32 v96, v103, v117
	v_max_u32_e32 v117, v103, v117
	v_min_u32_e32 v103, v70, v80
	v_max_u32_e32 v80, v70, v80
	v_min_u32_e32 v70, v86, v100
	v_max_u32_e32 v100, v86, v100
	v_max_u32_e32 v86, v74, v104
	v_min_u32_e32 v104, v74, v104
	v_max_u32_e32 v74, v98, v72
	v_min_u32_e32 v72, v98, v72
	v_max_u32_e32 v98, v105, v81
	v_min_u32_e32 v81, v105, v81
	v_max_u32_e32 v105, v102, v77
	v_min_u32_e32 v77, v102, v77
	v_min_u32_e32 v102, v97, v96
	v_max_u32_e32 v96, v97, v96
	v_min_u32_e32 v97, v91, v117
	v_max_u32_e32 v117, v91, v117
	v_min_u32_e32 v91, v103, v70
	v_max_u32_e32 v70, v103, v70
	v_min_u32_e32 v103, v80, v100
	v_max_u32_e32 v100, v80, v100
	v_max_u32_e32 v80, v86, v102
	v_min_u32_e32 v102, v86, v102
	v_max_u32_e32 v86, v104, v96
	v_min_u32_e32 v96, v104, v96
	v_max_u32_e32 v104, v74, v97
	v_min_u32_e32 v97, v74, v97
	v_max_u32_e32 v74, v72, v117
	v_min_u32_e32 v117, v72, v117
	v_max_u32_e32 v72, v98, v91
	v_min_u32_e32 v91, v98, v91
	v_max_u32_e32 v98, v81, v70
	v_min_u32_e32 v70, v81, v70
	v_max_u32_e32 v81, v105, v103
	v_min_u32_e32 v103, v105, v103
	v_max_u32_e32 v105, v77, v100
	v_min_u32_e32 v100, v77, v100
	v_max_u32_e32 v77, v80, v72
	v_min_u32_e32 v72, v80, v72
	v_max_u32_e32 v80, v86, v98
	v_min_u32_e32 v98, v86, v98
	v_max_u32_e32 v86, v104, v81
	v_min_u32_e32 v81, v104, v81
	v_max_u32_e32 v104, v74, v105
	v_min_u32_e32 v105, v74, v105
	v_max_u32_e32 v74, v102, v91
	v_min_u32_e32 v91, v102, v91
	v_max_u32_e32 v102, v96, v70
	v_min_u32_e32 v70, v96, v70
	v_max_u32_e32 v96, v97, v103
	v_min_u32_e32 v103, v97, v103
	v_max_u32_e32 v97, v117, v100
	v_min_u32_e32 v100, v117, v100
	v_max_u32_e32 v117, v77, v86
	v_min_u32_e32 v86, v77, v86
	v_max_u32_e32 v77, v80, v104
	v_min_u32_e32 v104, v80, v104
	v_max_u32_e32 v80, v72, v81
	v_min_u32_e32 v81, v72, v81
	v_max_u32_e32 v72, v98, v105
	v_min_u32_e32 v105, v98, v105
	v_max_u32_e32 v98, v74, v96
	v_min_u32_e32 v96, v74, v96
	v_max_u32_e32 v74, v102, v97
	v_min_u32_e32 v97, v102, v97
	v_max_u32_e32 v102, v91, v103
	v_min_u32_e32 v103, v91, v103
	v_max_u32_e32 v91, v70, v100
	v_min_u32_e32 v100, v70, v100
	v_max_u32_e32 v70, v117, v77
	v_min_u32_e32 v77, v117, v77
	v_max_u32_e32 v117, v86, v104
	v_min_u32_e32 v104, v86, v104
	v_max_u32_e32 v86, v80, v72
	v_min_u32_e32 v72, v80, v72
	v_max_u32_e32 v80, v81, v105
	v_min_u32_e32 v105, v81, v105
	v_max_u32_e32 v81, v98, v74
	v_min_u32_e32 v74, v98, v74
	v_max_u32_e32 v98, v96, v97
	v_min_u32_e32 v97, v96, v97
	v_max_u32_e32 v96, v102, v91
	v_min_u32_e32 v91, v102, v91
	v_max_u32_e32 v102, v103, v100
	v_min_u32_e32 v100, v103, v100
	v_max_u32_e32 v103, v15, v100
	v_max_u32_e32 v15, v111, v102
	v_max_u32_e32 v111, v83, v91
	v_max_u32_e32 v83, v106, v96
	v_max_u32_e32 v106, v85, v97
	v_max_u32_e32 v85, v112, v98
	v_max_u32_e32 v112, v89, v74
	v_max_u32_e32 v89, v116, v81
	v_max_u32_e32 v116, v109, v105
	v_max_u32_e32 v109, v88, v80
	v_max_u32_e32 v88, v90, v72
	v_max_u32_e32 v90, v79, v86
	v_max_u32_e32 v79, v115, v104
	v_max_u32_e32 v115, v101, v117
	v_max_u32_e32 v101, v108, v77
	v_max_u32_e32 v108, v114, v70
	v_max_u32_e32 v100, v103, v116
	v_min_u32_e32 v116, v103, v116
	v_max_u32_e32 v103, v15, v109
	v_min_u32_e32 v109, v15, v109
	v_max_u32_e32 v15, v111, v88
	v_min_u32_e32 v88, v111, v88
	v_max_u32_e32 v111, v83, v90
	v_min_u32_e32 v90, v83, v90
	v_max_u32_e32 v83, v106, v79
	v_min_u32_e32 v79, v106, v79
	v_max_u32_e32 v106, v85, v115
	v_min_u32_e32 v115, v85, v115
	v_max_u32_e32 v85, v112, v101
	v_min_u32_e32 v101, v112, v101
	v_max_u32_e32 v112, v89, v108
	v_min_u32_e32 v108, v89, v108
	v_max_u32_e32 v89, v100, v83
	v_min_u32_e32 v83, v100, v83
	v_max_u32_e32 v100, v103, v106
	v_min_u32_e32 v106, v103, v106
	v_max_u32_e32 v103, v15, v85
	v_min_u32_e32 v85, v15, v85
	v_max_u32_e32 v15, v111, v112
; DI float ord2f(unsigned u) { return __uint_as_float((u & 0x80000000u) ? (u ^ 0x80000000u) : ~u); }
; template <bool STORE>
; DI void peer_item(const Params& p, int item, char* smem) {
;     ...
;     unsigned ckey[16][16];
; #pragma unroll
;     for (int a = 0; a < 16; ++a)
; #pragma unroll
;       for (int bq = 0; bq < 16; ++bq)
;         if ((a + 1) * (bq + 1) <= 16)
;           ckey[a][bq] = (f2ord(ord2f(top1[a] & ~127u) + ord2f(top2[bq] & ~127u)) & ~255u) | (unsigned)(255 - (a * 16 + bq));
;     unsigned wkey[16];
;     int we[16];
; #pragma unroll
;     for (int r = 0; r < 16; ++r) {
;       unsigned mx = 0u;
; #pragma unroll
;       for (int a = 0; a < 16; ++a)
; #pragma unroll
;         for (int bq = 0; bq < 16; ++bq)
;           if ((a + 1) * (bq + 1) <= 16) mx = max(mx, ckey[a][bq]);
; #pragma unroll
;       for (int a = 0; a < 16; ++a)
; #pragma unroll
;         for (int bq = 0; bq < 16; ++bq)
;           if ((a + 1) * (bq + 1) <= 16) ckey[a][bq] = (ckey[a][bq] == mx) ? 0u : ckey[a][bq];
;       wkey[r] = mx;
	v_min_u32_e32 v112, v111, v112
	v_max_u32_e32 v111, v116, v79
	v_min_u32_e32 v79, v116, v79
	v_max_u32_e32 v116, v109, v115
	v_min_u32_e32 v115, v109, v115
	v_max_u32_e32 v109, v88, v101
	v_min_u32_e32 v101, v88, v101
	v_max_u32_e32 v88, v90, v108
	v_min_u32_e32 v108, v90, v108
	v_max_u32_e32 v90, v89, v103
	v_min_u32_e32 v103, v89, v103
	v_max_u32_e32 v89, v100, v15
	v_min_u32_e32 v15, v100, v15
	v_max_u32_e32 v100, v83, v85
	v_min_u32_e32 v85, v83, v85
	v_max_u32_e32 v83, v106, v112
	v_min_u32_e32 v112, v106, v112
	v_max_u32_e32 v106, v111, v109
	v_min_u32_e32 v109, v111, v109
	v_max_u32_e32 v111, v116, v88
	v_min_u32_e32 v88, v116, v88
	v_max_u32_e32 v116, v79, v101
	v_min_u32_e32 v101, v79, v101
	v_max_u32_e32 v79, v115, v108
	v_min_u32_e32 v108, v115, v108
	v_max_u32_e32 v115, v90, v89
	v_min_u32_e32 v89, v90, v89
	v_max_u32_e32 v90, v103, v15
	v_min_u32_e32 v15, v103, v15
	v_max_u32_e32 v103, v100, v83
	v_min_u32_e32 v83, v100, v83
	v_max_u32_e32 v100, v85, v112
	v_min_u32_e32 v112, v85, v112
	v_max_u32_e32 v85, v106, v111
	v_min_u32_e32 v111, v106, v111
	v_max_u32_e32 v106, v109, v88
	v_min_u32_e32 v88, v109, v88
	v_max_u32_e32 v109, v116, v79
	v_min_u32_e32 v79, v116, v79
	v_max_u32_e32 v116, v101, v108
	v_min_u32_e32 v108, v101, v108
	v_add_f32_e32 v229, v59, v44
	v_ashrrev_i32_e32 v230, 31, v229
	v_or_b32_e32 v230, 0x80000000, v230
	v_xor_b32_e32 v231, v230, v229
	v_and_b32_e32 v231, 0xffffff00, v231
	v_or_b32_e32 v101, 0xcc, v231
	v_add_f32_e32 v229, v60, v31
	v_ashrrev_i32_e32 v230, 31, v229
	v_or_b32_e32 v230, 0x80000000, v230
	v_xor_b32_e32 v231, v230, v229
	v_and_b32_e32 v231, 0xffffff00, v231
	v_or_b32_e32 v102, 0xbf, v231
	v_add_f32_e32 v229, v60, v46
	v_ashrrev_i32_e32 v230, 31, v229
	v_or_b32_e32 v230, 0x80000000, v230
	v_xor_b32_e32 v231, v230, v229
	v_and_b32_e32 v231, 0xffffff00, v231
	v_or_b32_e32 v91, 0xbe, v231
	v_add_f32_e32 v229, v60, v45
	v_ashrrev_i32_e32 v230, 31, v229
	v_or_b32_e32 v230, 0x80000000, v230
	v_xor_b32_e32 v231, v230, v229
	v_and_b32_e32 v231, 0xffffff00, v231
	v_or_b32_e32 v96, 0xbd, v231
	v_add_f32_e32 v229, v61, v31
	v_ashrrev_i32_e32 v230, 31, v229
	v_or_b32_e32 v230, 0x80000000, v230
	v_xor_b32_e32 v231, v230, v229
	v_and_b32_e32 v231, 0xffffff00, v231
	v_or_b32_e32 v97, 0xaf, v231
	v_add_f32_e32 v229, v61, v46
	v_ashrrev_i32_e32 v230, 31, v229
	v_or_b32_e32 v230, 0x80000000, v230
	v_xor_b32_e32 v231, v230, v229
	v_and_b32_e32 v231, 0xffffff00, v231
	v_or_b32_e32 v98, 0xae, v231
	v_add_f32_e32 v229, v62, v31
	v_ashrrev_i32_e32 v230, 31, v229
	v_or_b32_e32 v230, 0x80000000, v230
	v_xor_b32_e32 v231, v230, v229
	v_and_b32_e32 v231, 0xffffff00, v231
	v_or_b32_e32 v74, 0x9f, v231
	v_add_f32_e32 v229, v62, v46
	v_ashrrev_i32_e32 v230, 31, v229
	v_or_b32_e32 v230, 0x80000000, v230
	v_xor_b32_e32 v231, v230, v229
	v_and_b32_e32 v231, 0xffffff00, v231
	v_or_b32_e32 v81, 0x9e, v231
	v_add_f32_e32 v229, v29, v31
	v_ashrrev_i32_e32 v230, 31, v229
	v_or_b32_e32 v230, 0x80000000, v230
	v_xor_b32_e32 v231, v230, v229
	v_and_b32_e32 v231, 0xffffff00, v231
	v_or_b32_e32 v105, 0x8f, v231
	v_add_f32_e32 v229, v29, v46
	v_ashrrev_i32_e32 v230, 31, v229
	v_or_b32_e32 v230, 0x80000000, v230
	v_xor_b32_e32 v231, v230, v229
	v_and_b32_e32 v231, 0xffffff00, v231
	v_or_b32_e32 v80, 0x8e, v231
	v_add_f32_e32 v229, v55, v31
	v_ashrrev_i32_e32 v230, 31, v229
	v_or_b32_e32 v230, 0x80000000, v230
	v_xor_b32_e32 v231, v230, v229
	v_and_b32_e32 v231, 0xffffff00, v231
	v_or_b32_e32 v72, 0x7f, v231
	v_add_f32_e32 v229, v54, v31
	v_ashrrev_i32_e32 v230, 31, v229
	v_or_b32_e32 v230, 0x80000000, v230
	v_xor_b32_e32 v231, v230, v229
	v_and_b32_e32 v231, 0xffffff00, v231
	v_or_b32_e32 v86, 0x6f, v231
	v_add_f32_e32 v229, v53, v31
	v_ashrrev_i32_e32 v230, 31, v229
	v_or_b32_e32 v230, 0x80000000, v230
	v_xor_b32_e32 v231, v230, v229
	v_and_b32_e32 v231, 0xffffff00, v231
	v_or_b32_e32 v104, 0x5f, v231
	v_add_f32_e32 v229, v52, v31
	v_ashrrev_i32_e32 v230, 31, v229
	v_or_b32_e32 v230, 0x80000000, v230
	v_xor_b32_e32 v231, v230, v229
	v_and_b32_e32 v231, 0xffffff00, v231
	v_or_b32_e32 v117, 0x4f, v231
	v_add_f32_e32 v229, v51, v31
	v_ashrrev_i32_e32 v230, 31, v229
	v_or_b32_e32 v230, 0x80000000, v230
	v_xor_b32_e32 v231, v230, v229
	v_and_b32_e32 v231, 0xffffff00, v231
	v_or_b32_e32 v77, 0x3f, v231
	v_add_f32_e32 v229, v50, v31
	v_ashrrev_i32_e32 v230, 31, v229
	v_or_b32_e32 v230, 0x80000000, v230
	v_xor_b32_e32 v231, v230, v229
	v_and_b32_e32 v231, 0xffffff00, v231
	v_or_b32_e32 v70, 0x2f, v231
	v_max_u32_e32 v114, v101, v102
	v_min_u32_e32 v102, v101, v102
	v_min_u32_e32 v101, v91, v96
	v_max_u32_e32 v96, v91, v96
	v_max_u32_e32 v91, v97, v98
	v_min_u32_e32 v98, v97, v98
	v_min_u32_e32 v97, v74, v81
	v_max_u32_e32 v81, v74, v81
	v_max_u32_e32 v74, v105, v80
	v_min_u32_e32 v80, v105, v80
	v_min_u32_e32 v105, v72, v86
	v_max_u32_e32 v86, v72, v86
	v_max_u32_e32 v72, v104, v117
	v_min_u32_e32 v117, v104, v117
	v_min_u32_e32 v104, v77, v70
	v_max_u32_e32 v70, v77, v70
	v_max_u32_e32 v77, v114, v101
	v_min_u32_e32 v101, v114, v101
	v_max_u32_e32 v114, v102, v96
	v_min_u32_e32 v96, v102, v96
	v_min_u32_e32 v102, v91, v97
	v_max_u32_e32 v97, v91, v97
	v_min_u32_e32 v91, v98, v81
	v_max_u32_e32 v81, v98, v81
	v_max_u32_e32 v98, v74, v105
	v_min_u32_e32 v105, v74, v105
	v_max_u32_e32 v74, v80, v86
	v_min_u32_e32 v86, v80, v86
	v_min_u32_e32 v80, v72, v104
	v_max_u32_e32 v104, v72, v104
	v_min_u32_e32 v72, v117, v70
	v_max_u32_e32 v70, v117, v70
	v_max_u32_e32 v117, v77, v114
	v_min_u32_e32 v114, v77, v114
	v_max_u32_e32 v77, v101, v96
	v_min_u32_e32 v96, v101, v96
	v_min_u32_e32 v101, v102, v91
	v_max_u32_e32 v91, v102, v91
; DI float ord2f(unsigned u) { return __uint_as_float((u & 0x80000000u) ? (u ^ 0x80000000u) : ~u); }
; DI void merge_top16(unsigned (&a)[16], const unsigned (&b)[16]) {
; #pragma unroll
;   for (int i = 0; i < 16; ++i) a[i] = max(a[i], b[15 - i]);
; #pragma unroll
;     ...
; #pragma unroll
;     for (int i = 0; i < 16; ++i) {
;       const int j = 1 << js, l = i ^ j;
;       if (l > i) {
;         const unsigned x = a[i], y = a[l];
;         a[i] = max(x, y);
;         a[l] = min(x, y);
;       }
;     }
; }
; template <bool STORE>
; DI void peer_item(const Params& p, int item, char* smem) {
;     ...
;     unsigned ckey[16][16];
; #pragma unroll
;     for (int a = 0; a < 16; ++a)
; #pragma unroll
;       for (int bq = 0; bq < 16; ++bq)
;         if ((a + 1) * (bq + 1) <= 16)
;           ckey[a][bq] = (f2ord(ord2f(top1[a] & ~127u) + ord2f(top2[bq] & ~127u)) & ~255u) | (unsigned)(255 - (a * 16 + bq));
;     unsigned wkey[16];
;     int we[16];
; #pragma unroll
;     for (int r = 0; r < 16; ++r) {
;       unsigned mx = 0u;
; #pragma unroll
;       for (int a = 0; a < 16; ++a)
; #pragma unroll
;         for (int bq = 0; bq < 16; ++bq)
;           if ((a + 1) * (bq + 1) <= 16) mx = max(mx, ckey[a][bq]);
; #pragma unroll
;       for (int a = 0; a < 16; ++a)
; #pragma unroll
;         for (int bq = 0; bq < 16; ++bq)
;           if ((a + 1) * (bq + 1) <= 16) ckey[a][bq] = (ckey[a][bq] == mx) ? 0u : ckey[a][bq];
;       wkey[r] = mx;
	v_min_u32_e32 v102, v97, v81
	v_max_u32_e32 v81, v97, v81
	v_max_u32_e32 v97, v98, v74
	v_min_u32_e32 v74, v98, v74
	v_max_u32_e32 v98, v105, v86
	v_min_u32_e32 v86, v105, v86
	v_min_u32_e32 v105, v80, v72
	v_max_u32_e32 v72, v80, v72
	v_min_u32_e32 v80, v104, v70
	v_max_u32_e32 v70, v104, v70
	v_max_u32_e32 v104, v117, v101
	v_min_u32_e32 v101, v117, v101
	v_max_u32_e32 v117, v114, v91
	v_min_u32_e32 v91, v114, v91
	v_max_u32_e32 v114, v77, v102
	v_min_u32_e32 v102, v77, v102
	v_max_u32_e32 v77, v96, v81
	v_min_u32_e32 v81, v96, v81
	v_min_u32_e32 v96, v97, v105
	v_max_u32_e32 v105, v97, v105
	v_min_u32_e32 v97, v74, v72
	v_max_u32_e32 v72, v74, v72
	v_min_u32_e32 v74, v98, v80
	v_max_u32_e32 v80, v98, v80
	v_min_u32_e32 v98, v86, v70
	v_max_u32_e32 v70, v86, v70
	v_max_u32_e32 v86, v104, v114
	v_min_u32_e32 v114, v104, v114
	v_max_u32_e32 v104, v117, v77
	v_min_u32_e32 v77, v117, v77
	v_max_u32_e32 v117, v101, v102
	v_min_u32_e32 v102, v101, v102
	v_max_u32_e32 v101, v91, v81
	v_min_u32_e32 v81, v91, v81
	v_min_u32_e32 v91, v96, v74
	v_max_u32_e32 v74, v96, v74
	v_min_u32_e32 v96, v97, v98
	v_max_u32_e32 v98, v97, v98
	v_min_u32_e32 v97, v105, v80
	v_max_u32_e32 v80, v105, v80
	v_min_u32_e32 v105, v72, v70
	v_max_u32_e32 v70, v72, v70
	v_max_u32_e32 v72, v86, v104
	v_min_u32_e32 v104, v86, v104
	v_max_u32_e32 v86, v114, v77
	v_min_u32_e32 v77, v114, v77
	v_max_u32_e32 v114, v117, v101
	v_min_u32_e32 v101, v117, v101
	v_max_u32_e32 v117, v102, v81
	v_min_u32_e32 v81, v102, v81
	v_min_u32_e32 v102, v91, v96
	v_max_u32_e32 v96, v91, v96
	v_min_u32_e32 v91, v74, v98
	v_max_u32_e32 v98, v74, v98
	v_min_u32_e32 v74, v97, v105
	v_max_u32_e32 v105, v97, v105
	v_min_u32_e32 v97, v80, v70
	v_max_u32_e32 v70, v80, v70
	v_max_u32_e32 v80, v72, v102
	v_min_u32_e32 v102, v72, v102
	v_max_u32_e32 v72, v104, v96
	v_min_u32_e32 v96, v104, v96
	v_max_u32_e32 v104, v86, v91
	v_min_u32_e32 v91, v86, v91
	v_max_u32_e32 v86, v77, v98
	v_min_u32_e32 v98, v77, v98
	v_max_u32_e32 v77, v114, v74
	v_min_u32_e32 v74, v114, v74
	v_max_u32_e32 v114, v101, v105
	v_min_u32_e32 v105, v101, v105
	v_max_u32_e32 v101, v117, v97
	v_min_u32_e32 v97, v117, v97
	v_max_u32_e32 v117, v81, v70
	v_min_u32_e32 v70, v81, v70
	v_max_u32_e32 v81, v80, v77
	v_min_u32_e32 v77, v80, v77
	v_max_u32_e32 v80, v72, v114
	v_min_u32_e32 v114, v72, v114
	v_max_u32_e32 v72, v104, v101
	v_min_u32_e32 v101, v104, v101
	v_max_u32_e32 v104, v86, v117
	v_min_u32_e32 v117, v86, v117
	v_max_u32_e32 v86, v102, v74
	v_min_u32_e32 v74, v102, v74
	v_max_u32_e32 v102, v96, v105
	v_min_u32_e32 v105, v96, v105
	v_max_u32_e32 v96, v91, v97
	v_min_u32_e32 v97, v91, v97
	v_max_u32_e32 v91, v98, v70
	v_min_u32_e32 v70, v98, v70
	v_max_u32_e32 v98, v81, v72
	v_min_u32_e32 v72, v81, v72
	v_max_u32_e32 v81, v80, v104
	v_min_u32_e32 v104, v80, v104
	v_max_u32_e32 v80, v77, v101
	v_min_u32_e32 v101, v77, v101
	v_max_u32_e32 v77, v114, v117
	v_min_u32_e32 v117, v114, v117
	v_max_u32_e32 v114, v86, v96
	v_min_u32_e32 v96, v86, v96
	v_max_u32_e32 v86, v102, v91
	v_min_u32_e32 v91, v102, v91
	v_max_u32_e32 v102, v74, v97
	v_min_u32_e32 v97, v74, v97
	v_max_u32_e32 v74, v105, v70
	v_min_u32_e32 v70, v105, v70
	v_max_u32_e32 v105, v98, v81
	v_min_u32_e32 v81, v98, v81
	v_max_u32_e32 v98, v72, v104
	v_min_u32_e32 v104, v72, v104
	v_max_u32_e32 v72, v80, v77
	v_min_u32_e32 v77, v80, v77
	v_max_u32_e32 v80, v101, v117
	v_min_u32_e32 v117, v101, v117
	v_max_u32_e32 v101, v114, v86
	v_min_u32_e32 v86, v114, v86
	v_max_u32_e32 v114, v96, v91
	v_min_u32_e32 v91, v96, v91
	v_max_u32_e32 v96, v102, v74
	v_min_u32_e32 v74, v102, v74
	v_max_u32_e32 v102, v97, v70
	v_min_u32_e32 v70, v97, v70
	v_add_f32_e32 v229, v49, v31
	v_ashrrev_i32_e32 v230, 31, v229
	v_or_b32_e32 v230, 0x80000000, v230
	v_xor_b32_e32 v231, v230, v229
	v_and_b32_e32 v231, 0xffffff00, v231
	v_or_b32_e32 v97, 0x1f, v231
	v_add_f32_e32 v229, v48, v31
	v_ashrrev_i32_e32 v230, 31, v229
	v_or_b32_e32 v230, 0x80000000, v230
	v_xor_b32_e32 v231, v230, v229
	v_and_b32_e32 v231, 0xffffff00, v231
	v_or_b32_e32 v84, 0xf, v231
	v_mov_b32_e32 v71, 0
	v_mov_b32_e32 v82, 0
	v_mov_b32_e32 v75, 0
	v_mov_b32_e32 v87, 0
	v_mov_b32_e32 v78, 0
	v_mov_b32_e32 v110, 0
	v_mov_b32_e32 v93, 0
	v_mov_b32_e32 v76, 0
	v_mov_b32_e32 v95, 0
	v_mov_b32_e32 v99, 0
	v_mov_b32_e32 v73, 0
	v_mov_b32_e32 v94, 0
	v_mov_b32_e32 v113, 0
	v_mov_b32_e32 v69, 0
	v_max_u32_e32 v92, v97, v84
	v_min_u32_e32 v84, v97, v84
	v_max_u32_e32 v97, v105, v69
	v_max_u32_e32 v105, v81, v113
	v_max_u32_e32 v81, v98, v94
	v_max_u32_e32 v98, v104, v73
	v_max_u32_e32 v104, v72, v99
	v_max_u32_e32 v72, v77, v95
	v_max_u32_e32 v77, v80, v76
	v_max_u32_e32 v80, v117, v93
	v_max_u32_e32 v117, v101, v110
	v_max_u32_e32 v101, v86, v78
	v_max_u32_e32 v86, v114, v87
	v_max_u32_e32 v114, v91, v75
	v_max_u32_e32 v91, v96, v82
	v_max_u32_e32 v96, v74, v71
	v_max_u32_e32 v74, v102, v84
	v_max_u32_e32 v102, v70, v92
	v_max_u32_e32 v69, v97, v117
	v_min_u32_e32 v117, v97, v117
	v_max_u32_e32 v97, v105, v101
	v_min_u32_e32 v101, v105, v101
	v_max_u32_e32 v105, v81, v86
	v_min_u32_e32 v86, v81, v86
	v_max_u32_e32 v81, v98, v114
	v_min_u32_e32 v114, v98, v114
	v_max_u32_e32 v98, v104, v91
	v_min_u32_e32 v91, v104, v91
	v_max_u32_e32 v104, v72, v96
	v_min_u32_e32 v96, v72, v96
	v_max_u32_e32 v72, v77, v74
	v_min_u32_e32 v74, v77, v74
	v_max_u32_e32 v77, v80, v102
	v_min_u32_e32 v102, v80, v102
	v_max_u32_e32 v80, v69, v98
	v_min_u32_e32 v98, v69, v98
	v_max_u32_e32 v69, v97, v104
	v_min_u32_e32 v104, v97, v104
	v_max_u32_e32 v97, v105, v72
	v_min_u32_e32 v72, v105, v72
	v_max_u32_e32 v105, v81, v77
	v_min_u32_e32 v77, v81, v77
; template <bool STORE>
; DI void peer_item(const Params& p, int item, char* smem) {
;     ...
;     unsigned wkey[16];
;     int we[16];
; #pragma unroll
;     for (int r = 0; r < 16; ++r) {
;       unsigned mx = 0u;
; #pragma unroll
;       for (int a = 0; a < 16; ++a)
; #pragma unroll
;         for (int bq = 0; bq < 16; ++bq)
;           if ((a + 1) * (bq + 1) <= 16) mx = max(mx, ckey[a][bq]);
; #pragma unroll
;       for (int a = 0; a < 16; ++a)
; #pragma unroll
;         for (int bq = 0; bq < 16; ++bq)
;           if ((a + 1) * (bq + 1) <= 16) ckey[a][bq] = (ckey[a][bq] == mx) ? 0u : ckey[a][bq];
;       wkey[r] = mx;
;       const int cidx = 255 - (int)(mx & 255u);
;       const int wa = cidx >> 4, wb = cidx & 15;
;       unsigned t1 = top1[0], t2 = top2[0];
; #pragma unroll
;       for (int a = 1; a < 16; ++a) { t1 = (wa == a) ? top1[a] : t1; t2 = (wb == a) ? top2[a] : t2; }
;       we[r] = (127 - (int)(t1 & 127u)) * 128 + (127 - (int)(t2 & 127u));
	v_max_u32_e32 v81, v117, v91
	v_min_u32_e32 v91, v117, v91
	v_max_u32_e32 v117, v101, v96
	v_min_u32_e32 v96, v101, v96
	v_max_u32_e32 v101, v86, v74
	v_min_u32_e32 v74, v86, v74
	v_max_u32_e32 v86, v114, v102
	v_min_u32_e32 v102, v114, v102
	v_max_u32_e32 v114, v80, v97
	v_min_u32_e32 v97, v80, v97
	v_max_u32_e32 v80, v69, v105
	v_min_u32_e32 v105, v69, v105
	v_max_u32_e32 v69, v98, v72
	v_min_u32_e32 v72, v98, v72
	v_max_u32_e32 v98, v104, v77
	v_min_u32_e32 v77, v104, v77
	v_max_u32_e32 v104, v81, v101
	v_min_u32_e32 v101, v81, v101
	v_max_u32_e32 v81, v117, v86
	v_min_u32_e32 v86, v117, v86
	v_max_u32_e32 v117, v91, v74
	v_min_u32_e32 v74, v91, v74
	v_max_u32_e32 v91, v96, v102
	v_min_u32_e32 v102, v96, v102
	v_max_u32_e32 v96, v114, v80
	v_min_u32_e32 v80, v114, v80
	v_max_u32_e32 v114, v97, v105
	v_min_u32_e32 v105, v97, v105
	v_max_u32_e32 v97, v69, v98
	v_min_u32_e32 v98, v69, v98
	v_max_u32_e32 v69, v72, v77
	v_min_u32_e32 v77, v72, v77
	v_max_u32_e32 v72, v104, v81
	v_min_u32_e32 v81, v104, v81
	v_max_u32_e32 v104, v101, v86
	v_min_u32_e32 v86, v101, v86
	v_max_u32_e32 v101, v117, v91
	v_min_u32_e32 v91, v117, v91
	v_max_u32_e32 v117, v74, v102
	v_min_u32_e32 v102, v74, v102
	v_max_u32_e32 v74, v115, v102
	v_max_u32_e32 v115, v89, v117
	v_max_u32_e32 v89, v90, v91
	v_max_u32_e32 v90, v15, v101
	v_max_u32_e32 v15, v103, v86
	v_max_u32_e32 v103, v83, v104
	v_max_u32_e32 v83, v100, v81
	v_max_u32_e32 v100, v112, v72
	v_max_u32_e32 v112, v85, v77
	v_max_u32_e32 v85, v111, v69
	v_max_u32_e32 v111, v106, v98
	v_max_u32_e32 v106, v88, v97
	v_max_u32_e32 v88, v109, v105
	v_max_u32_e32 v109, v79, v114
	v_max_u32_e32 v79, v116, v80
	v_max_u32_e32 v116, v108, v96
	v_max_u32_e32 v102, v74, v112
	v_min_u32_e32 v112, v74, v112
	v_max_u32_e32 v74, v115, v85
	v_min_u32_e32 v85, v115, v85
	v_max_u32_e32 v115, v89, v111
	v_min_u32_e32 v111, v89, v111
	v_max_u32_e32 v89, v90, v106
	v_min_u32_e32 v106, v90, v106
	v_max_u32_e32 v90, v15, v88
	v_min_u32_e32 v88, v15, v88
	v_max_u32_e32 v15, v103, v109
	v_min_u32_e32 v109, v103, v109
	v_max_u32_e32 v103, v83, v79
	v_min_u32_e32 v79, v83, v79
	v_max_u32_e32 v83, v100, v116
	v_min_u32_e32 v116, v100, v116
	v_max_u32_e32 v100, v102, v90
	v_min_u32_e32 v90, v102, v90
	v_max_u32_e32 v102, v74, v15
	v_min_u32_e32 v15, v74, v15
	v_max_u32_e32 v74, v115, v103
	v_min_u32_e32 v103, v115, v103
	v_max_u32_e32 v115, v89, v83
	v_min_u32_e32 v83, v89, v83
	v_max_u32_e32 v89, v112, v88
	v_min_u32_e32 v88, v112, v88
	v_max_u32_e32 v112, v85, v109
	v_min_u32_e32 v109, v85, v109
	v_max_u32_e32 v85, v111, v79
	v_min_u32_e32 v79, v111, v79
	v_max_u32_e32 v111, v106, v116
	v_min_u32_e32 v116, v106, v116
	v_max_u32_e32 v106, v100, v74
	v_min_u32_e32 v74, v100, v74
	v_max_u32_e32 v100, v102, v115
	v_min_u32_e32 v115, v102, v115
	v_max_u32_e32 v102, v90, v103
	v_min_u32_e32 v103, v90, v103
	v_max_u32_e32 v90, v15, v83
	v_min_u32_e32 v83, v15, v83
	v_max_u32_e32 v15, v89, v85
	v_min_u32_e32 v85, v89, v85
	v_max_u32_e32 v89, v112, v111
	v_min_u32_e32 v111, v112, v111
	v_max_u32_e32 v112, v88, v79
	v_min_u32_e32 v79, v88, v79
	v_max_u32_e32 v88, v109, v116
	v_min_u32_e32 v116, v109, v116
	v_max_u32_e32 v109, v106, v100
	v_min_u32_e32 v100, v106, v100
	v_max_u32_e32 v106, v74, v115
	v_min_u32_e32 v115, v74, v115
	v_max_u32_e32 v74, v102, v90
	v_min_u32_e32 v90, v102, v90
	v_max_u32_e32 v102, v103, v83
	v_min_u32_e32 v83, v103, v83
	v_max_u32_e32 v103, v15, v89
	v_min_u32_e32 v89, v15, v89
	v_max_u32_e32 v15, v85, v111
	v_min_u32_e32 v111, v85, v111
	v_max_u32_e32 v85, v112, v88
	v_min_u32_e32 v88, v112, v88
	v_max_u32_e32 v112, v79, v116
	v_min_u32_e32 v116, v79, v116
	s_waitcnt lgkmcnt(0)
	v_not_b32_e32 v229, v109
	v_bfe_u32 v230, v229, 4, 4
	v_and_b32_e32 v231, 15, v229
	v_add_u32_e32 v230, v241, v230
	v_add_u32_e32 v231, v241, v231
	ds_read_u8 v79, v230
	ds_read_u8 v108, v231 offset:16
	v_not_b32_e32 v229, v100
	v_bfe_u32 v230, v229, 4, 4
	v_and_b32_e32 v231, 15, v229
	v_add_u32_e32 v230, v241, v230
	v_add_u32_e32 v231, v241, v231
	ds_read_u8 v117, v230
	ds_read_u8 v113, v231 offset:16
	v_not_b32_e32 v229, v106
	v_bfe_u32 v230, v229, 4, 4
	v_and_b32_e32 v231, 15, v229
	v_add_u32_e32 v230, v241, v230
	v_add_u32_e32 v231, v241, v231
	ds_read_u8 v91, v230
	ds_read_u8 v94, v231 offset:16
	v_not_b32_e32 v229, v115
	v_bfe_u32 v230, v229, 4, 4
	v_and_b32_e32 v231, 15, v229
	v_add_u32_e32 v230, v241, v230
	v_add_u32_e32 v231, v241, v231
	ds_read_u8 v101, v230
	ds_read_u8 v73, v231 offset:16
	v_not_b32_e32 v229, v74
	v_bfe_u32 v230, v229, 4, 4
	v_and_b32_e32 v231, 15, v229
	v_add_u32_e32 v230, v241, v230
	v_add_u32_e32 v231, v241, v231
	ds_read_u8 v86, v230
	ds_read_u8 v99, v231 offset:16
	v_not_b32_e32 v229, v90
	v_bfe_u32 v230, v229, 4, 4
	v_and_b32_e32 v231, 15, v229
	v_add_u32_e32 v230, v241, v230
	v_add_u32_e32 v231, v241, v231
	ds_read_u8 v104, v230
	ds_read_u8 v95, v231 offset:16
	v_not_b32_e32 v229, v102
	v_bfe_u32 v230, v229, 4, 4
	v_and_b32_e32 v231, 15, v229
	v_add_u32_e32 v230, v241, v230
	v_add_u32_e32 v231, v241, v231
	ds_read_u8 v81, v230
	ds_read_u8 v76, v231 offset:16
	v_not_b32_e32 v229, v83
	v_bfe_u32 v230, v229, 4, 4
	v_and_b32_e32 v231, 15, v229
	v_add_u32_e32 v230, v241, v230
	v_add_u32_e32 v231, v241, v231
	ds_read_u8 v72, v230
	ds_read_u8 v93, v231 offset:16
	v_not_b32_e32 v229, v103
	v_bfe_u32 v230, v229, 4, 4
	v_and_b32_e32 v231, 15, v229
	v_add_u32_e32 v230, v241, v230
	v_add_u32_e32 v231, v241, v231
	ds_read_u8 v77, v230
	ds_read_u8 v110, v231 offset:16
	v_not_b32_e32 v229, v89
	v_bfe_u32 v230, v229, 4, 4
	v_and_b32_e32 v231, 15, v229
	v_add_u32_e32 v230, v241, v230
	v_add_u32_e32 v231, v241, v231
; DI float ord2f(unsigned u) { return __uint_as_float((u & 0x80000000u) ? (u ^ 0x80000000u) : ~u); }
; template <bool STORE>
; DI void peer_item(const Params& p, int item, char* smem) {
;     ...
;     float cs0 = ord2f(wkey[0] & ~255u);
;     float ex[16], sum = 0.f;
; #pragma unroll
;     for (int r = 0; r < 16; ++r) { ex[r] = __expf(ord2f(wkey[r] & ~255u) - cs0); sum += ex[r]; }
;     float inv = 1.f / sum;
	ds_read_u8 v69, v230
	ds_read_u8 v78, v231 offset:16
	v_not_b32_e32 v229, v15
	v_bfe_u32 v230, v229, 4, 4
	v_and_b32_e32 v231, 15, v229
	v_add_u32_e32 v230, v241, v230
	v_add_u32_e32 v231, v241, v231
	ds_read_u8 v98, v230
	ds_read_u8 v87, v231 offset:16
	v_not_b32_e32 v229, v111
	v_bfe_u32 v230, v229, 4, 4
	v_and_b32_e32 v231, 15, v229
	v_add_u32_e32 v230, v241, v230
	v_add_u32_e32 v231, v241, v231
	ds_read_u8 v97, v230
	ds_read_u8 v75, v231 offset:16
	v_not_b32_e32 v229, v85
	v_bfe_u32 v230, v229, 4, 4
	v_and_b32_e32 v231, 15, v229
	v_add_u32_e32 v230, v241, v230
	v_add_u32_e32 v231, v241, v231
	ds_read_u8 v105, v230
	ds_read_u8 v82, v231 offset:16
	v_not_b32_e32 v229, v88
	v_bfe_u32 v230, v229, 4, 4
	v_and_b32_e32 v231, 15, v229
	v_add_u32_e32 v230, v241, v230
	v_add_u32_e32 v231, v241, v231
	ds_read_u8 v114, v230
	ds_read_u8 v71, v231 offset:16
	v_not_b32_e32 v229, v112
	v_bfe_u32 v230, v229, 4, 4
	v_and_b32_e32 v231, 15, v229
	v_add_u32_e32 v230, v241, v230
	v_add_u32_e32 v231, v241, v231
	ds_read_u8 v80, v230
	ds_read_u8 v84, v231 offset:16
	v_not_b32_e32 v229, v116
	v_bfe_u32 v230, v229, 4, 4
	v_and_b32_e32 v231, 15, v229
	v_add_u32_e32 v230, v241, v230
	v_add_u32_e32 v231, v241, v231
	ds_read_u8 v96, v230
	ds_read_u8 v92, v231 offset:16
	v_and_b32_e32 v229, 0xffffff00, v109
	v_ashrrev_i32_e32 v230, 31, v229
	v_not_b32_e32 v230, v230
	v_or_b32_e32 v230, 0x80000000, v230
	v_xor_b32_e32 v48, v230, v229
	v_and_b32_e32 v229, 0xffffff00, v100
	v_ashrrev_i32_e32 v230, 31, v229
	v_not_b32_e32 v230, v230
	v_or_b32_e32 v230, 0x80000000, v230
	v_xor_b32_e32 v49, v230, v229
	v_and_b32_e32 v229, 0xffffff00, v106
	v_ashrrev_i32_e32 v230, 31, v229
	v_not_b32_e32 v230, v230
	v_or_b32_e32 v230, 0x80000000, v230
	v_xor_b32_e32 v50, v230, v229
	v_and_b32_e32 v229, 0xffffff00, v115
	v_ashrrev_i32_e32 v230, 31, v229
	v_not_b32_e32 v230, v230
	v_or_b32_e32 v230, 0x80000000, v230
	v_xor_b32_e32 v51, v230, v229
	v_and_b32_e32 v229, 0xffffff00, v74
	v_ashrrev_i32_e32 v230, 31, v229
	v_not_b32_e32 v230, v230
	v_or_b32_e32 v230, 0x80000000, v230
	v_xor_b32_e32 v52, v230, v229
	v_and_b32_e32 v229, 0xffffff00, v90
	v_ashrrev_i32_e32 v230, 31, v229
	v_not_b32_e32 v230, v230
	v_or_b32_e32 v230, 0x80000000, v230
	v_xor_b32_e32 v53, v230, v229
	v_and_b32_e32 v229, 0xffffff00, v102
	v_ashrrev_i32_e32 v230, 31, v229
	v_not_b32_e32 v230, v230
	v_or_b32_e32 v230, 0x80000000, v230
	v_xor_b32_e32 v54, v230, v229
	v_and_b32_e32 v229, 0xffffff00, v83
	v_ashrrev_i32_e32 v230, 31, v229
	v_not_b32_e32 v230, v230
	v_or_b32_e32 v230, 0x80000000, v230
	v_xor_b32_e32 v55, v230, v229
	v_and_b32_e32 v229, 0xffffff00, v103
	v_ashrrev_i32_e32 v230, 31, v229
	v_not_b32_e32 v230, v230
	v_or_b32_e32 v230, 0x80000000, v230
	v_xor_b32_e32 v29, v230, v229
	v_and_b32_e32 v229, 0xffffff00, v89
	v_ashrrev_i32_e32 v230, 31, v229
	v_not_b32_e32 v230, v230
	v_or_b32_e32 v230, 0x80000000, v230
	v_xor_b32_e32 v62, v230, v229
	v_and_b32_e32 v229, 0xffffff00, v15
	v_ashrrev_i32_e32 v230, 31, v229
	v_not_b32_e32 v230, v230
	v_or_b32_e32 v230, 0x80000000, v230
	v_xor_b32_e32 v61, v230, v229
	v_and_b32_e32 v229, 0xffffff00, v111
	v_ashrrev_i32_e32 v230, 31, v229
	v_not_b32_e32 v230, v230
	v_or_b32_e32 v230, 0x80000000, v230
	v_xor_b32_e32 v60, v230, v229
	v_and_b32_e32 v229, 0xffffff00, v85
	v_ashrrev_i32_e32 v230, 31, v229
	v_not_b32_e32 v230, v230
	v_or_b32_e32 v230, 0x80000000, v230
	v_xor_b32_e32 v59, v230, v229
	v_and_b32_e32 v229, 0xffffff00, v88
	v_ashrrev_i32_e32 v230, 31, v229
	v_not_b32_e32 v230, v230
	v_or_b32_e32 v230, 0x80000000, v230
	v_xor_b32_e32 v58, v230, v229
	v_and_b32_e32 v229, 0xffffff00, v112
	v_ashrrev_i32_e32 v230, 31, v229
	v_not_b32_e32 v230, v230
	v_or_b32_e32 v230, 0x80000000, v230
	v_xor_b32_e32 v57, v230, v229
	v_and_b32_e32 v229, 0xffffff00, v116
	v_ashrrev_i32_e32 v230, 31, v229
	v_not_b32_e32 v230, v230
	v_or_b32_e32 v230, 0x80000000, v230
	v_xor_b32_e32 v56, v230, v229
	v_sub_f32_e32 v56, v56, v48
	v_sub_f32_e32 v57, v57, v48
	v_sub_f32_e32 v58, v58, v48
	v_sub_f32_e32 v59, v59, v48
	v_sub_f32_e32 v60, v60, v48
	v_sub_f32_e32 v61, v61, v48
	v_sub_f32_e32 v62, v62, v48
	v_sub_f32_e32 v29, v29, v48
	v_sub_f32_e32 v55, v55, v48
	v_sub_f32_e32 v54, v54, v48
	v_sub_f32_e32 v53, v53, v48
	v_sub_f32_e32 v52, v52, v48
	v_sub_f32_e32 v51, v51, v48
	v_sub_f32_e32 v50, v50, v48
	v_sub_f32_e32 v49, v49, v48
	v_sub_f32_e32 v48, v48, v48
	v_mul_f32_e32 v48, 0x3fb8aa3b, v48
	v_mul_f32_e32 v49, 0x3fb8aa3b, v49
	v_mul_f32_e32 v50, 0x3fb8aa3b, v50
	v_mul_f32_e32 v51, 0x3fb8aa3b, v51
	v_mul_f32_e32 v52, 0x3fb8aa3b, v52
	v_mul_f32_e32 v53, 0x3fb8aa3b, v53
	v_mul_f32_e32 v54, 0x3fb8aa3b, v54
	v_mul_f32_e32 v55, 0x3fb8aa3b, v55
	v_mul_f32_e32 v29, 0x3fb8aa3b, v29
	v_mul_f32_e32 v62, 0x3fb8aa3b, v62
	v_mul_f32_e32 v61, 0x3fb8aa3b, v61
	v_mul_f32_e32 v60, 0x3fb8aa3b, v60
	v_mul_f32_e32 v59, 0x3fb8aa3b, v59
	v_mul_f32_e32 v58, 0x3fb8aa3b, v58
	v_mul_f32_e32 v57, 0x3fb8aa3b, v57
	v_mul_f32_e32 v56, 0x3fb8aa3b, v56
	v_exp_f32_e32 v48, v48
	v_exp_f32_e32 v49, v49
	v_exp_f32_e32 v50, v50
	v_exp_f32_e32 v51, v51
	v_exp_f32_e32 v52, v52
	v_exp_f32_e32 v53, v53
	v_exp_f32_e32 v54, v54
	v_exp_f32_e32 v55, v55
	v_exp_f32_e32 v29, v29
	v_exp_f32_e32 v62, v62
	v_exp_f32_e32 v61, v61
	v_exp_f32_e32 v60, v60
	v_exp_f32_e32 v59, v59
	v_exp_f32_e32 v58, v58
	v_exp_f32_e32 v57, v57
	v_exp_f32_e32 v56, v56
	s_nop 0
	v_add_f32_e32 v232, v48, v49
	v_add_f32_e32 v232, v232, v50
	v_add_f32_e32 v232, v232, v51
	v_add_f32_e32 v232, v232, v52
	v_add_f32_e32 v232, v232, v53
	v_add_f32_e32 v232, v232, v54
	v_add_f32_e32 v232, v232, v55
	v_add_f32_e32 v232, v232, v29
	v_add_f32_e32 v232, v232, v62
	v_add_f32_e32 v232, v232, v61
	v_add_f32_e32 v232, v232, v60
	v_add_f32_e32 v232, v232, v59
	v_add_f32_e32 v232, v232, v58
	v_add_f32_e32 v232, v232, v57
	v_add_f32_e32 v232, v232, v56
	v_div_scale_f32 v246, s[8:9], v232, v232, 1.0
	v_rcp_f32_e32 v247, v246
	s_nop 0
	v_fma_f32 v248, -v246, v247, 1.0
	v_fmac_f32_e32 v247, v248, v247
	v_div_scale_f32 v249, vcc, 1.0, v232, 1.0
	v_mul_f32_e32 v250, v249, v247
	v_fma_f32 v251, -v246, v250, v249
	v_fmac_f32_e32 v250, v251, v247
	v_fma_f32 v246, -v246, v250, v249
	s_nop 1
	v_div_fmas_f32 v246, v246, v247, v250
	v_div_fixup_f32 v247, v246, v232, 1.0
	v_mul_f32_e32 v48, v48, v247
	v_mul_f32_e32 v49, v49, v247
	v_mul_f32_e32 v50, v50, v247
	v_mul_f32_e32 v51, v51, v247
	v_mul_f32_e32 v52, v52, v247
	v_mul_f32_e32 v53, v53, v247
	v_mul_f32_e32 v54, v54, v247
	v_mul_f32_e32 v55, v55, v247
	v_mul_f32_e32 v29, v29, v247
	v_mul_f32_e32 v62, v62, v247
	v_mul_f32_e32 v61, v61, v247
	v_mul_f32_e32 v60, v60, v247
	v_mul_f32_e32 v59, v59, v247
	v_mul_f32_e32 v58, v58, v247
	v_mul_f32_e32 v57, v57, v247
	v_mul_f32_e32 v56, v56, v247
	s_waitcnt lgkmcnt(0)
; DI float ord2f(unsigned u) { return __uint_as_float((u & 0x80000000u) ? (u ^ 0x80000000u) : ~u); }
; template <bool STORE>
; DI void peer_item(const Params& p, int item, char* smem) {
;     ...
;       we[r] = (127 - (int)(t1 & 127u)) * 128 + (127 - (int)(t2 & 127u));
;     }
;     float cs0 = ord2f(wkey[0] & ~255u);
;     float ex[16], sum = 0.f;
; #pragma unroll
;     for (int r = 0; r < 16; ++r) { ex[r] = __expf(ord2f(wkey[r] & ~255u) - cs0); sum += ex[r]; }
;     float inv = 1.f / sum;
;     if (hh == 0) {
; #pragma unroll
;       for (int r = 0; r < 16; ++r) {
;         e_s[lr * 128 + hd * 16 + r] = we[r];
;         g_s[lr * 128 + hd * 16 + r] = ex[r] * inv;
;       }
;     }
	v_lshl_or_b32 v32, v79, 7, v108
	v_lshl_or_b32 v33, v117, 7, v113
	v_lshl_or_b32 v34, v91, 7, v94
	v_lshl_or_b32 v35, v101, 7, v73
	v_lshl_or_b32 v36, v86, 7, v99
	v_lshl_or_b32 v37, v104, 7, v95
	v_lshl_or_b32 v38, v81, 7, v76
	v_lshl_or_b32 v39, v72, 7, v93
	v_lshl_or_b32 v40, v77, 7, v110
	v_lshl_or_b32 v41, v69, 7, v78
	v_lshl_or_b32 v42, v98, 7, v87
	v_lshl_or_b32 v43, v97, 7, v75
	v_lshl_or_b32 v44, v105, 7, v82
	v_lshl_or_b32 v45, v114, 7, v71
	v_lshl_or_b32 v46, v80, 7, v84
	v_lshl_or_b32 v31, v96, 7, v92
	ds_write_b32 v242, v32 offset:0
	ds_write_b32 v242, v48 offset:16384
	ds_write_b32 v242, v33 offset:4
	ds_write_b32 v242, v49 offset:16388
	ds_write_b32 v242, v34 offset:8
	ds_write_b32 v242, v50 offset:16392
	ds_write_b32 v242, v35 offset:12
	ds_write_b32 v242, v51 offset:16396
	ds_write_b32 v242, v36 offset:16
	ds_write_b32 v242, v52 offset:16400
	ds_write_b32 v242, v37 offset:20
	ds_write_b32 v242, v53 offset:16404
	ds_write_b32 v242, v38 offset:24
	ds_write_b32 v242, v54 offset:16408
	ds_write_b32 v242, v39 offset:28
	ds_write_b32 v242, v55 offset:16412
	ds_write_b32 v242, v40 offset:32
	ds_write_b32 v242, v29 offset:16416
	ds_write_b32 v242, v41 offset:36
	ds_write_b32 v242, v62 offset:16420
	ds_write_b32 v242, v42 offset:40
	ds_write_b32 v242, v61 offset:16424
	ds_write_b32 v242, v43 offset:44
	ds_write_b32 v242, v60 offset:16428
	ds_write_b32 v242, v44 offset:48
	ds_write_b32 v242, v59 offset:16432
	ds_write_b32 v242, v45 offset:52
	ds_write_b32 v242, v58 offset:16436
	ds_write_b32 v242, v46 offset:56
	ds_write_b32 v242, v57 offset:16440
	ds_write_b32 v242, v31 offset:60
	ds_write_b32 v242, v56 offset:16444
	ds_read_b32 v3, v240 offset:512
	ds_read_b32 v53, v240 offset:768
	ds_read_b32 v64, v240 offset:1024
	ds_read_b32 v65, v240 offset:1280
	ds_read_b32 v66, v240 offset:1536
	ds_read_b32 v67, v240 offset:1792
	ds_read_b32 v68, v240 offset:2048
	ds_read_b32 v69, v240 offset:2304
	ds_read_b32 v70, v240 offset:2560
	ds_read_b32 v71, v240 offset:2816
	ds_read_b32 v72, v240 offset:3072
	ds_read_b32 v73, v240 offset:3328
	ds_read_b32 v74, v240 offset:3584
	ds_read_b32 v75, v240 offset:3840
	ds_read_b32 v76, v240 offset:4096
	ds_read_b32 v77, v240 offset:4352
	ds_read_b32 v78, v240 offset:4608
	ds_read_b32 v79, v240 offset:4864
	ds_read_b32 v80, v240 offset:5120
	ds_read_b32 v81, v240 offset:5376
	ds_read_b32 v82, v240 offset:5632
	ds_read_b32 v83, v240 offset:5888
	ds_read_b32 v84, v240 offset:6144
	ds_read_b32 v96, v240 offset:6400
	v_readlane_b32 s6, v254, 0
	v_readlane_b32 s7, v254, 1
	v_readlane_b32 s12, v254, 2
	v_readlane_b32 s13, v254, 3
	v_readlane_b32 s14, v254, 4
	v_readlane_b32 s15, v254, 5
	v_readlane_b32 s16, v254, 6
	v_readlane_b32 s17, v254, 7
	v_readlane_b32 s18, v254, 8
	v_readlane_b32 s19, v254, 9
	v_readlane_b32 s20, v254, 10
	v_readlane_b32 s21, v254, 11
	v_readlane_b32 s22, v254, 12
	v_readlane_b32 s23, v254, 13
	v_readlane_b32 s24, v254, 14
	v_readlane_b32 s25, v254, 15
	v_readlane_b32 s26, v254, 16
	v_readlane_b32 s27, v254, 17
	v_readlane_b32 s28, v254, 18
	v_readlane_b32 s29, v254, 19
	v_readlane_b32 s30, v254, 20
	v_readlane_b32 s31, v254, 21
	v_readlane_b32 s33, v254, 22
	v_readlane_b32 s34, v254, 23
	v_readlane_b32 s35, v254, 24
	v_readlane_b32 s36, v254, 25
	v_readlane_b32 s37, v254, 26
	v_readlane_b32 s38, v254, 27
	v_readlane_b32 s39, v254, 28
	v_readlane_b32 s40, v254, 29
	v_readlane_b32 s41, v254, 30
	v_readlane_b32 s42, v254, 31
	v_readlane_b32 s44, v254, 32
	v_readlane_b32 s45, v254, 33
	v_readlane_b32 s48, v254, 34
	v_readlane_b32 s49, v254, 35
	v_readlane_b32 s50, v254, 36
	v_readlane_b32 s51, v254, 37
	v_readlane_b32 s52, v254, 38
	v_readlane_b32 s53, v254, 39
	v_readlane_b32 s55, v254, 40
	v_readlane_b32 s60, v254, 41
	v_readlane_b32 s61, v254, 42
	v_readlane_b32 s62, v254, 43
	v_readlane_b32 s63, v254, 44
	v_readlane_b32 s66, v254, 45
	v_readlane_b32 s67, v254, 46
	v_readlane_b32 s68, v254, 47
	v_readlane_b32 s69, v254, 48
	v_readlane_b32 s74, v254, 49
	v_readlane_b32 s75, v254, 50
	v_readlane_b32 s76, v254, 51
	v_readlane_b32 s77, v254, 52
	v_readlane_b32 s78, v254, 53
	v_readlane_b32 s79, v254, 54
	v_readlane_b32 s88, v254, 55
	s_waitcnt vmcnt(0) lgkmcnt(0)
	s_nop 3
